# P4c plus write-through sc0 sc1 on all 16-byte global stores to cheapen grid-barrier L2 writeback
# baseline (speedup 1.0000x reference)
; #define LAS __attribute__((address_space(3)))
; __device__ __forceinline__ unsigned pk2(float lo, float hi) { return pg8::cvt_pk_bf16(lo, hi); }
; __device__ __forceinline__ void transpose_item(const float* W, int K, int N, bf16* WT, int k0, int n0, int drow0, LAS float* scr, int lane) {
;     float wv[32];
; #pragma unroll
;     for (int i = 0; i < 32; ++i) wv[i] = W[(size_t)(k0 + 2 * i + (lane >> 5)) * N + n0 + (lane & 31)];
; #pragma unroll
;     for (int i = 0; i < 32; ++i) scr[(2 * i + (lane >> 5)) * 33 + (lane & 31)] = wv[i];
;     asm volatile("s_waitcnt lgkmcnt(0)" ::: "memory");
;     const int c = lane & 7;
; #pragma unroll
;     for (int j = 0; j < 4; ++j) { const int n = (lane >> 3) + 8 * j; const LAS float* s = scr + (8 * c) * 33 + n;
;         u32x4 o; o.x = pk2(s[0 * 33], s[1 * 33]); o.y = pk2(s[2 * 33], s[3 * 33]); o.z = pk2(s[4 * 33], s[5 * 33]); o.w = pk2(s[6 * 33], s[7 * 33]);
;         *(u32x4*)(WT + (size_t)(drow0 + n) * K + k0 + 8 * c) = o; }
;     asm volatile("s_waitcnt lgkmcnt(0)" ::: "memory");
; }
; __device__ __forceinline__ bool transpose_job(int& it, const float* W, int K, int N, bf16* WT, int mode, LAS float* scr, int lane) {
;     const int nblk = N / 32, items = (K / 64) * nblk;
;     if (it >= items) { it -= items; return false; }
;     const int kb = it / nblk, nb = it % nblk, n0 = 32 * nb;
;     const int drow0 = mode == 0 ? n0 : (256 * (n0 >> 7) + (n0 & 127) + (mode == 2 ? 128 : 0));
;     transpose_item(W, K, N, WT, 64 * kb, n0, drow0, scr, lane);
.LBB0_26:
	v_cmp_lt_i32_e32 vcc, s3, v48
	s_and_saveexec_b64 s[22:23], vcc
	s_xor_b64 s[22:23], exec, s[22:23]
	v_add_u32_e32 v48, 0xfffffa80, v48
	s_andn2_saveexec_b64 s[22:23], s[22:23]
	s_cbranch_execz .LBB0_30
	v_mul_hi_i32 v4, v48, s33
	v_lshrrev_b32_e32 v26, 31, v4
	v_ashrrev_i32_e32 v4, 4, v4
	v_add_u32_e32 v4, v4, v26
	v_mul_lo_u32 v26, v4, s34
	v_sub_u32_e32 v27, v48, v26
	v_lshlrev_b32_e32 v28, 5, v27
	v_lshlrev_b32_e32 v26, 6, v4
	v_or_b32_e32 v4, v26, v34
	v_ashrrev_i32_e32 v29, 31, v28
	v_lshlrev_b64 v[30:31], 2, v[28:29]
	v_or_b32_e32 v29, 2, v4
	v_mad_i64_i32 v[50:51], s[26:27], v29, s36, v[30:31]
	v_or_b32_e32 v29, 4, v4
	v_mad_i64_i32 v[52:53], s[26:27], v29, s36, v[30:31]
	v_or_b32_e32 v29, 6, v4
	s_load_dwordx2 s[24:25], s[10:11], 0x70
	v_mad_i64_i32 v[54:55], s[26:27], v29, s36, v[30:31]
	v_or_b32_e32 v29, 8, v4
	v_mad_i64_i32 v[56:57], s[26:27], v29, s36, v[30:31]
	v_or_b32_e32 v29, 10, v4
	v_mad_i64_i32 v[58:59], s[26:27], v29, s36, v[30:31]
	v_or_b32_e32 v29, 12, v4
	v_mad_i64_i32 v[60:61], s[26:27], v29, s36, v[30:31]
	v_or_b32_e32 v29, 14, v4
	v_mad_i64_i32 v[32:33], s[26:27], v4, s36, v[30:31]
	v_mad_i64_i32 v[62:63], s[26:27], v29, s36, v[30:31]
	s_waitcnt lgkmcnt(0)
	v_lshl_add_u64 v[32:33], s[24:25], 0, v[32:33]
	v_lshl_add_u64 v[50:51], s[24:25], 0, v[50:51]
	v_lshl_add_u64 v[52:53], s[24:25], 0, v[52:53]
	v_lshl_add_u64 v[54:55], s[24:25], 0, v[54:55]
	v_lshl_add_u64 v[56:57], s[24:25], 0, v[56:57]
	v_lshl_add_u64 v[58:59], s[24:25], 0, v[58:59]
	v_lshl_add_u64 v[60:61], s[24:25], 0, v[60:61]
	v_lshl_add_u64 v[62:63], s[24:25], 0, v[62:63]
	v_lshl_add_u64 v[32:33], v[32:33], 0, v[6:7]
	v_lshl_add_u64 v[50:51], v[50:51], 0, v[6:7]
	v_lshl_add_u64 v[52:53], v[52:53], 0, v[6:7]
	v_lshl_add_u64 v[54:55], v[54:55], 0, v[6:7]
	v_lshl_add_u64 v[56:57], v[56:57], 0, v[6:7]
	v_lshl_add_u64 v[58:59], v[58:59], 0, v[6:7]
	v_lshl_add_u64 v[60:61], v[60:61], 0, v[6:7]
	v_lshl_add_u64 v[62:63], v[62:63], 0, v[6:7]
	v_lshl_add_u64 v[32:33], v[32:33], 0, s[20:21]
	v_lshl_add_u64 v[50:51], v[50:51], 0, s[20:21]
	v_lshl_add_u64 v[52:53], v[52:53], 0, s[20:21]
	v_lshl_add_u64 v[54:55], v[54:55], 0, s[20:21]
	v_lshl_add_u64 v[56:57], v[56:57], 0, s[20:21]
	v_lshl_add_u64 v[58:59], v[58:59], 0, s[20:21]
	v_lshl_add_u64 v[60:61], v[60:61], 0, s[20:21]
	v_lshl_add_u64 v[62:63], v[62:63], 0, s[20:21]
	global_load_dword v29, v[32:33], off
	global_load_dword v49, v[50:51], off
	global_load_dword v64, v[52:53], off
	global_load_dword v65, v[54:55], off
	global_load_dword v66, v[56:57], off
	global_load_dword v67, v[58:59], off
	global_load_dword v68, v[60:61], off
	global_load_dword v69, v[62:63], off
	v_or_b32_e32 v32, 16, v4
	v_or_b32_e32 v50, 18, v4
	v_or_b32_e32 v52, 20, v4
	v_or_b32_e32 v54, 22, v4
	v_or_b32_e32 v56, 24, v4
	v_or_b32_e32 v58, 26, v4
	v_or_b32_e32 v60, 28, v4
	v_or_b32_e32 v62, 30, v4
	v_mad_i64_i32 v[32:33], s[26:27], v32, s36, v[30:31]
	v_mad_i64_i32 v[50:51], s[26:27], v50, s36, v[30:31]
	v_mad_i64_i32 v[52:53], s[26:27], v52, s36, v[30:31]
	v_mad_i64_i32 v[54:55], s[26:27], v54, s36, v[30:31]
	v_mad_i64_i32 v[56:57], s[26:27], v56, s36, v[30:31]
	v_mad_i64_i32 v[58:59], s[26:27], v58, s36, v[30:31]
	v_mad_i64_i32 v[60:61], s[26:27], v60, s36, v[30:31]
	v_mad_i64_i32 v[62:63], s[26:27], v62, s36, v[30:31]
	v_lshl_add_u64 v[32:33], s[24:25], 0, v[32:33]
	v_lshl_add_u64 v[50:51], s[24:25], 0, v[50:51]
	v_lshl_add_u64 v[52:53], s[24:25], 0, v[52:53]
	v_lshl_add_u64 v[54:55], s[24:25], 0, v[54:55]
	v_lshl_add_u64 v[56:57], s[24:25], 0, v[56:57]
	v_lshl_add_u64 v[58:59], s[24:25], 0, v[58:59]
	v_lshl_add_u64 v[60:61], s[24:25], 0, v[60:61]
	v_lshl_add_u64 v[62:63], s[24:25], 0, v[62:63]
	v_lshl_add_u64 v[32:33], v[32:33], 0, v[6:7]
	v_lshl_add_u64 v[50:51], v[50:51], 0, v[6:7]
	v_lshl_add_u64 v[52:53], v[52:53], 0, v[6:7]
	v_lshl_add_u64 v[54:55], v[54:55], 0, v[6:7]
	v_lshl_add_u64 v[56:57], v[56:57], 0, v[6:7]
	v_lshl_add_u64 v[58:59], v[58:59], 0, v[6:7]
	v_lshl_add_u64 v[60:61], v[60:61], 0, v[6:7]
	v_lshl_add_u64 v[62:63], v[62:63], 0, v[6:7]
	v_lshl_add_u64 v[32:33], v[32:33], 0, s[20:21]
	v_lshl_add_u64 v[50:51], v[50:51], 0, s[20:21]
	v_lshl_add_u64 v[52:53], v[52:53], 0, s[20:21]
	v_lshl_add_u64 v[54:55], v[54:55], 0, s[20:21]
	v_lshl_add_u64 v[56:57], v[56:57], 0, s[20:21]
	v_lshl_add_u64 v[58:59], v[58:59], 0, s[20:21]
	v_lshl_add_u64 v[60:61], v[60:61], 0, s[20:21]
	v_lshl_add_u64 v[62:63], v[62:63], 0, s[20:21]
	global_load_dword v70, v[32:33], off
	global_load_dword v71, v[50:51], off
	global_load_dword v72, v[52:53], off
	global_load_dword v73, v[54:55], off
	global_load_dword v74, v[56:57], off
	global_load_dword v75, v[58:59], off
	global_load_dword v76, v[60:61], off
	global_load_dword v77, v[62:63], off
	v_or_b32_e32 v32, 32, v4
	v_or_b32_e32 v50, 34, v4
	v_or_b32_e32 v52, 36, v4
	v_or_b32_e32 v54, 38, v4
	v_or_b32_e32 v56, 40, v4
	v_or_b32_e32 v58, 42, v4
	v_or_b32_e32 v60, 44, v4
	v_or_b32_e32 v62, 46, v4
	v_mad_i64_i32 v[32:33], s[26:27], v32, s36, v[30:31]
	v_mad_i64_i32 v[50:51], s[26:27], v50, s36, v[30:31]
	v_mad_i64_i32 v[52:53], s[26:27], v52, s36, v[30:31]
	v_mad_i64_i32 v[54:55], s[26:27], v54, s36, v[30:31]
	v_mad_i64_i32 v[56:57], s[26:27], v56, s36, v[30:31]
	v_mad_i64_i32 v[58:59], s[26:27], v58, s36, v[30:31]
	v_mad_i64_i32 v[60:61], s[26:27], v60, s36, v[30:31]
	v_mad_i64_i32 v[62:63], s[26:27], v62, s36, v[30:31]
	v_lshl_add_u64 v[32:33], s[24:25], 0, v[32:33]
	v_lshl_add_u64 v[50:51], s[24:25], 0, v[50:51]
	v_lshl_add_u64 v[52:53], s[24:25], 0, v[52:53]
	v_lshl_add_u64 v[54:55], s[24:25], 0, v[54:55]
	v_lshl_add_u64 v[56:57], s[24:25], 0, v[56:57]
	v_lshl_add_u64 v[58:59], s[24:25], 0, v[58:59]
; #define LAS __attribute__((address_space(3)))
; __device__ __forceinline__ unsigned pk2(float lo, float hi) { return pg8::cvt_pk_bf16(lo, hi); }
; __device__ __forceinline__ void transpose_item(const float* W, int K, int N, bf16* WT, int k0, int n0, int drow0, LAS float* scr, int lane) {
;     ...
;     for (int i = 0; i < 32; ++i) wv[i] = W[(size_t)(k0 + 2 * i + (lane >> 5)) * N + n0 + (lane & 31)];
; #pragma unroll
;     for (int i = 0; i < 32; ++i) scr[(2 * i + (lane >> 5)) * 33 + (lane & 31)] = wv[i];
;     asm volatile("s_waitcnt lgkmcnt(0)" ::: "memory");
;     const int c = lane & 7;
; #pragma unroll
;     for (int j = 0; j < 4; ++j) { const int n = (lane >> 3) + 8 * j; const LAS float* s = scr + (8 * c) * 33 + n;
;         u32x4 o; o.x = pk2(s[0 * 33], s[1 * 33]); o.y = pk2(s[2 * 33], s[3 * 33]); o.z = pk2(s[4 * 33], s[5 * 33]); o.w = pk2(s[6 * 33], s[7 * 33]);
;         *(u32x4*)(WT + (size_t)(drow0 + n) * K + k0 + 8 * c) = o; }
	v_lshl_add_u64 v[60:61], s[24:25], 0, v[60:61]
	v_lshl_add_u64 v[62:63], s[24:25], 0, v[62:63]
	v_lshl_add_u64 v[32:33], v[32:33], 0, v[6:7]
	v_lshl_add_u64 v[50:51], v[50:51], 0, v[6:7]
	v_lshl_add_u64 v[52:53], v[52:53], 0, v[6:7]
	v_lshl_add_u64 v[54:55], v[54:55], 0, v[6:7]
	v_lshl_add_u64 v[56:57], v[56:57], 0, v[6:7]
	v_lshl_add_u64 v[58:59], v[58:59], 0, v[6:7]
	v_lshl_add_u64 v[60:61], v[60:61], 0, v[6:7]
	v_lshl_add_u64 v[62:63], v[62:63], 0, v[6:7]
	v_lshl_add_u64 v[32:33], v[32:33], 0, s[20:21]
	v_lshl_add_u64 v[50:51], v[50:51], 0, s[20:21]
	v_lshl_add_u64 v[52:53], v[52:53], 0, s[20:21]
	v_lshl_add_u64 v[54:55], v[54:55], 0, s[20:21]
	v_lshl_add_u64 v[56:57], v[56:57], 0, s[20:21]
	v_lshl_add_u64 v[58:59], v[58:59], 0, s[20:21]
	v_lshl_add_u64 v[60:61], v[60:61], 0, s[20:21]
	v_lshl_add_u64 v[62:63], v[62:63], 0, s[20:21]
	global_load_dword v78, v[32:33], off
	global_load_dword v79, v[50:51], off
	global_load_dword v81, v[52:53], off
	global_load_dword v82, v[54:55], off
	global_load_dword v83, v[56:57], off
	global_load_dword v84, v[58:59], off
	global_load_dword v85, v[60:61], off
	s_nop 0
	global_load_dword v62, v[62:63], off
	v_or_b32_e32 v32, 48, v4
	v_or_b32_e32 v50, 50, v4
	v_or_b32_e32 v52, 52, v4
	v_or_b32_e32 v54, 54, v4
	v_or_b32_e32 v56, 56, v4
	v_or_b32_e32 v58, 58, v4
	v_or_b32_e32 v60, 60, v4
	v_or_b32_e32 v4, 62, v4
	v_mad_i64_i32 v[32:33], s[26:27], v32, s36, v[30:31]
	v_mad_i64_i32 v[50:51], s[26:27], v50, s36, v[30:31]
	v_mad_i64_i32 v[52:53], s[26:27], v52, s36, v[30:31]
	v_mad_i64_i32 v[54:55], s[26:27], v54, s36, v[30:31]
	v_mad_i64_i32 v[56:57], s[26:27], v56, s36, v[30:31]
	v_mad_i64_i32 v[58:59], s[26:27], v58, s36, v[30:31]
	v_mad_i64_i32 v[60:61], s[26:27], v60, s36, v[30:31]
	v_mad_i64_i32 v[30:31], s[26:27], v4, s36, v[30:31]
	v_lshl_add_u64 v[32:33], s[24:25], 0, v[32:33]
	v_lshl_add_u64 v[50:51], s[24:25], 0, v[50:51]
	v_lshl_add_u64 v[52:53], s[24:25], 0, v[52:53]
	v_lshl_add_u64 v[30:31], s[24:25], 0, v[30:31]
	v_lshl_add_u64 v[32:33], v[32:33], 0, v[6:7]
	v_lshl_add_u64 v[50:51], v[50:51], 0, v[6:7]
	v_lshl_add_u64 v[52:53], v[52:53], 0, v[6:7]
	v_lshl_add_u64 v[54:55], s[24:25], 0, v[54:55]
	v_lshl_add_u64 v[56:57], s[24:25], 0, v[56:57]
	v_lshl_add_u64 v[58:59], s[24:25], 0, v[58:59]
	v_lshl_add_u64 v[60:61], s[24:25], 0, v[60:61]
	v_lshl_add_u64 v[30:31], v[30:31], 0, v[6:7]
	v_lshl_add_u64 v[32:33], v[32:33], 0, s[20:21]
	v_lshl_add_u64 v[50:51], v[50:51], 0, s[20:21]
	v_lshl_add_u64 v[52:53], v[52:53], 0, s[20:21]
	v_lshl_add_u64 v[54:55], v[54:55], 0, v[6:7]
	v_lshl_add_u64 v[56:57], v[56:57], 0, v[6:7]
	v_lshl_add_u64 v[58:59], v[58:59], 0, v[6:7]
	v_lshl_add_u64 v[60:61], v[60:61], 0, v[6:7]
	v_lshl_add_u64 v[30:31], v[30:31], 0, s[20:21]
	v_lshl_add_u64 v[54:55], v[54:55], 0, s[20:21]
	v_lshl_add_u64 v[56:57], v[56:57], 0, s[20:21]
	v_lshl_add_u64 v[58:59], v[58:59], 0, s[20:21]
	v_lshl_add_u64 v[60:61], v[60:61], 0, s[20:21]
	global_load_dword v4, v[32:33], off
	s_nop 0
	global_load_dword v32, v[50:51], off
	global_load_dword v33, v[52:53], off
	s_nop 0
	global_load_dword v50, v[54:55], off
	global_load_dword v51, v[56:57], off
	global_load_dword v52, v[58:59], off
	global_load_dword v53, v[60:61], off
	s_nop 0
	global_load_dword v30, v[30:31], off
	s_waitcnt vmcnt(30)
	ds_write2_b32 v35, v29, v49 offset1:66
	s_waitcnt vmcnt(28)
	ds_write2_b32 v35, v64, v65 offset0:132 offset1:198
	s_waitcnt vmcnt(26)
	ds_write2_b32 v41, v66, v67 offset0:8 offset1:74
	s_waitcnt vmcnt(24)
	ds_write2_b32 v41, v68, v69 offset0:140 offset1:206
	s_waitcnt vmcnt(22)
	ds_write2_b32 v42, v70, v71 offset0:16 offset1:82
	s_waitcnt vmcnt(20)
	ds_write2_b32 v42, v72, v73 offset0:148 offset1:214
	s_waitcnt vmcnt(18)
	ds_write2_b32 v43, v74, v75 offset0:24 offset1:90
	s_waitcnt vmcnt(16)
	ds_write2_b32 v43, v76, v77 offset0:156 offset1:222
	s_waitcnt vmcnt(14)
	ds_write2_b32 v44, v78, v79 offset0:32 offset1:98
	s_waitcnt vmcnt(12)
	ds_write2_b32 v44, v81, v82 offset0:164 offset1:230
	s_waitcnt vmcnt(10)
	ds_write2_b32 v45, v83, v84 offset0:40 offset1:106
	s_waitcnt vmcnt(8)
	ds_write2_b32 v45, v85, v62 offset0:172 offset1:238
	s_waitcnt vmcnt(6)
	ds_write2_b32 v46, v4, v32 offset0:48 offset1:114
	s_waitcnt vmcnt(4)
	ds_write2_b32 v46, v33, v50 offset0:180 offset1:246
	s_waitcnt vmcnt(2)
	ds_write2_b32 v47, v51, v52 offset0:56 offset1:122
	s_waitcnt vmcnt(0)
	ds_write2_b32 v47, v53, v30 offset0:188 offset1:254
	s_waitcnt lgkmcnt(0)
	v_lshlrev_b32_e32 v4, 6, v27
	ds_read2_b32 v[30:31], v37 offset1:33
	v_and_b32_e32 v4, 0xffffff00, v4
	s_waitcnt lgkmcnt(0)
	v_cvt_pk_bf16_f32 v30, v30, v31
	ds_read2_b32 v[32:33], v37 offset0:66 offset1:99
	v_and_or_b32 v4, v28, s35, v4
	s_waitcnt lgkmcnt(0)
	v_cvt_pk_bf16_f32 v31, v32, v33
	ds_read2_b32 v[32:33], v37 offset0:132 offset1:165
	v_or_b32_e32 v28, v4, v36
	s_waitcnt lgkmcnt(0)
	v_cvt_pk_bf16_f32 v32, v32, v33
	ds_read2_b32 v[50:51], v37 offset0:198 offset1:231
	v_ashrrev_i32_e32 v27, 31, v26
	v_ashrrev_i32_e32 v29, 31, v28
	s_waitcnt lgkmcnt(0)
	v_cvt_pk_bf16_f32 v33, v50, v51
	v_lshlrev_b64 v[28:29], 11, v[28:29]
	v_lshlrev_b64 v[50:51], 1, v[26:27]
	v_lshl_add_u64 v[28:29], v[28:29], 0, v[50:51]
	v_lshl_add_u64 v[28:29], s[20:21], 0, v[28:29]
	ds_read2_b32 v[26:27], v37 offset0:8 offset1:41
	v_lshl_add_u64 v[28:29], v[20:21], 0, v[28:29]
	global_store_dwordx4 v[28:29], v[30:33], off sc0 sc1
	s_waitcnt lgkmcnt(0)
	v_cvt_pk_bf16_f32 v26, v26, v27
	ds_read2_b32 v[28:29], v37 offset0:74 offset1:107
	s_waitcnt lgkmcnt(0)
	v_cvt_pk_bf16_f32 v27, v28, v29
	ds_read2_b32 v[28:29], v37 offset0:140 offset1:173
	s_waitcnt lgkmcnt(0)
; #define LAS __attribute__((address_space(3)))
; __device__ __forceinline__ unsigned pk2(float lo, float hi) { return pg8::cvt_pk_bf16(lo, hi); }
; __device__ __forceinline__ void transpose_item(const float* W, int K, int N, bf16* WT, int k0, int n0, int drow0, LAS float* scr, int lane) {
;     ...
;     for (int i = 0; i < 32; ++i) wv[i] = W[(size_t)(k0 + 2 * i + (lane >> 5)) * N + n0 + (lane & 31)];
; #pragma unroll
;     for (int i = 0; i < 32; ++i) scr[(2 * i + (lane >> 5)) * 33 + (lane & 31)] = wv[i];
;     asm volatile("s_waitcnt lgkmcnt(0)" ::: "memory");
;     const int c = lane & 7;
; #pragma unroll
;     for (int j = 0; j < 4; ++j) { const int n = (lane >> 3) + 8 * j; const LAS float* s = scr + (8 * c) * 33 + n;
;         u32x4 o; o.x = pk2(s[0 * 33], s[1 * 33]); o.y = pk2(s[2 * 33], s[3 * 33]); o.z = pk2(s[4 * 33], s[5 * 33]); o.w = pk2(s[6 * 33], s[7 * 33]);
;         *(u32x4*)(WT + (size_t)(drow0 + n) * K + k0 + 8 * c) = o; }
;     asm volatile("s_waitcnt lgkmcnt(0)" ::: "memory");
; }
; __device__ __forceinline__ bool transpose_job(int& it, const float* W, int K, int N, bf16* WT, int mode, LAS float* scr, int lane) {
;     const int nblk = N / 32, items = (K / 64) * nblk;
;     if (it >= items) { it -= items; return false; }
;     const int kb = it / nblk, nb = it % nblk, n0 = 32 * nb;
;     const int drow0 = mode == 0 ? n0 : (256 * (n0 >> 7) + (n0 & 127) + (mode == 2 ? 128 : 0));
;     transpose_item(W, K, N, WT, 64 * kb, n0, drow0, scr, lane);
	v_cvt_pk_bf16_f32 v28, v28, v29
	ds_read2_b32 v[30:31], v37 offset0:206 offset1:239
	s_waitcnt lgkmcnt(0)
	v_cvt_pk_bf16_f32 v29, v30, v31
	v_or_b32_e32 v30, v4, v38
	v_ashrrev_i32_e32 v31, 31, v30
	v_lshlrev_b64 v[30:31], 11, v[30:31]
	v_lshl_add_u64 v[30:31], v[30:31], 0, v[50:51]
	v_lshl_add_u64 v[30:31], s[20:21], 0, v[30:31]
	v_lshl_add_u64 v[30:31], v[20:21], 0, v[30:31]
	ds_read2_b32 v[32:33], v37 offset0:16 offset1:49
	global_store_dwordx4 v[30:31], v[26:29], off sc0 sc1
	s_waitcnt lgkmcnt(0)
	s_nop 0
	v_cvt_pk_bf16_f32 v26, v32, v33
	ds_read2_b32 v[28:29], v37 offset0:82 offset1:115
	s_waitcnt lgkmcnt(0)
	v_cvt_pk_bf16_f32 v27, v28, v29
	ds_read2_b32 v[28:29], v37 offset0:148 offset1:181
	s_waitcnt lgkmcnt(0)
	v_cvt_pk_bf16_f32 v28, v28, v29
	ds_read2_b32 v[30:31], v37 offset0:214 offset1:247
	s_waitcnt lgkmcnt(0)
	v_cvt_pk_bf16_f32 v29, v30, v31
	v_or_b32_e32 v30, v4, v39
	v_ashrrev_i32_e32 v31, 31, v30
	v_lshlrev_b64 v[30:31], 11, v[30:31]
	v_lshl_add_u64 v[30:31], v[30:31], 0, v[50:51]
	v_lshl_add_u64 v[30:31], s[20:21], 0, v[30:31]
	v_lshl_add_u64 v[30:31], v[20:21], 0, v[30:31]
	ds_read2_b32 v[32:33], v37 offset0:24 offset1:57
	global_store_dwordx4 v[30:31], v[26:29], off sc0 sc1
	s_waitcnt lgkmcnt(0)
	s_nop 0
	v_cvt_pk_bf16_f32 v26, v32, v33
	ds_read2_b32 v[28:29], v37 offset0:90 offset1:123
	s_waitcnt lgkmcnt(0)
	v_cvt_pk_bf16_f32 v27, v28, v29
	ds_read2_b32 v[28:29], v37 offset0:156 offset1:189
	s_waitcnt lgkmcnt(0)
	v_cvt_pk_bf16_f32 v28, v28, v29
	ds_read2_b32 v[30:31], v37 offset0:222 offset1:255
	s_waitcnt lgkmcnt(0)
	v_cvt_pk_bf16_f32 v29, v30, v31
	v_or_b32_e32 v30, v4, v40
	v_ashrrev_i32_e32 v31, 31, v30
	v_lshlrev_b64 v[30:31], 11, v[30:31]
	v_lshl_add_u64 v[30:31], v[30:31], 0, v[50:51]
	v_lshl_add_u64 v[30:31], s[20:21], 0, v[30:31]
	v_lshl_add_u64 v[30:31], v[20:21], 0, v[30:31]
	global_store_dwordx4 v[30:31], v[26:29], off sc0 sc1
	s_waitcnt lgkmcnt(0)
.LBB0_30:
	s_or_b64 exec, exec, s[22:23]
	s_mov_b64 s[24:25], -1
	s_mov_b64 s[26:27], -1
	s_and_saveexec_b64 s[22:23], vcc
	s_cbranch_execz .LBB0_36
	v_cmp_lt_i32_e32 vcc, s3, v48
	s_and_saveexec_b64 s[26:27], vcc
	s_xor_b64 s[26:27], exec, s[26:27]
	v_add_u32_e32 v48, 0xfffffa80, v48
	s_or_saveexec_b64 s[26:27], s[26:27]
	s_mov_b64 s[28:29], 0
	s_xor_b64 exec, exec, s[26:27]
	s_cbranch_execz .LBB0_35
	v_mul_hi_i32 v4, v48, s33
	v_lshrrev_b32_e32 v26, 31, v4
	v_ashrrev_i32_e32 v4, 4, v4
	v_add_u32_e32 v4, v4, v26
	v_mul_lo_u32 v26, v4, s34
	v_sub_u32_e32 v27, v48, v26
	v_lshlrev_b32_e32 v28, 5, v27
	v_lshlrev_b32_e32 v26, 6, v4
	v_or_b32_e32 v4, v26, v34
	v_ashrrev_i32_e32 v29, 31, v28
	v_lshlrev_b64 v[30:31], 2, v[28:29]
	v_or_b32_e32 v29, 2, v4
	v_mad_i64_i32 v[50:51], s[56:57], v29, s36, v[30:31]
	v_or_b32_e32 v29, 4, v4
	v_mad_i64_i32 v[52:53], s[56:57], v29, s36, v[30:31]
	v_or_b32_e32 v29, 6, v4
	s_load_dwordx2 s[30:31], s[10:11], 0x78
	v_mad_i64_i32 v[54:55], s[56:57], v29, s36, v[30:31]
	v_or_b32_e32 v29, 8, v4
	v_mad_i64_i32 v[56:57], s[56:57], v29, s36, v[30:31]
	v_or_b32_e32 v29, 10, v4
	v_mad_i64_i32 v[58:59], s[56:57], v29, s36, v[30:31]
	v_or_b32_e32 v29, 12, v4
	v_mad_i64_i32 v[60:61], s[56:57], v29, s36, v[30:31]
	v_or_b32_e32 v29, 14, v4
	v_mad_i64_i32 v[32:33], s[56:57], v4, s36, v[30:31]
	v_mad_i64_i32 v[62:63], s[56:57], v29, s36, v[30:31]
	s_waitcnt lgkmcnt(0)
	v_lshl_add_u64 v[32:33], s[30:31], 0, v[32:33]
	v_lshl_add_u64 v[50:51], s[30:31], 0, v[50:51]
	v_lshl_add_u64 v[52:53], s[30:31], 0, v[52:53]
	v_lshl_add_u64 v[54:55], s[30:31], 0, v[54:55]
	v_lshl_add_u64 v[56:57], s[30:31], 0, v[56:57]
	v_lshl_add_u64 v[58:59], s[30:31], 0, v[58:59]
	v_lshl_add_u64 v[60:61], s[30:31], 0, v[60:61]
	v_lshl_add_u64 v[62:63], s[30:31], 0, v[62:63]
	v_lshl_add_u64 v[32:33], v[32:33], 0, v[6:7]
	v_lshl_add_u64 v[50:51], v[50:51], 0, v[6:7]
	v_lshl_add_u64 v[52:53], v[52:53], 0, v[6:7]
	v_lshl_add_u64 v[54:55], v[54:55], 0, v[6:7]
	v_lshl_add_u64 v[56:57], v[56:57], 0, v[6:7]
	v_lshl_add_u64 v[58:59], v[58:59], 0, v[6:7]
	v_lshl_add_u64 v[60:61], v[60:61], 0, v[6:7]
	v_lshl_add_u64 v[62:63], v[62:63], 0, v[6:7]
	v_lshl_add_u64 v[32:33], v[32:33], 0, s[20:21]
	v_lshl_add_u64 v[50:51], v[50:51], 0, s[20:21]
	v_lshl_add_u64 v[52:53], v[52:53], 0, s[20:21]
	v_lshl_add_u64 v[54:55], v[54:55], 0, s[20:21]
	v_lshl_add_u64 v[56:57], v[56:57], 0, s[20:21]
	v_lshl_add_u64 v[58:59], v[58:59], 0, s[20:21]
	v_lshl_add_u64 v[60:61], v[60:61], 0, s[20:21]
	v_lshl_add_u64 v[62:63], v[62:63], 0, s[20:21]
	global_load_dword v29, v[32:33], off
	global_load_dword v49, v[50:51], off
	global_load_dword v64, v[52:53], off
	global_load_dword v65, v[54:55], off
	global_load_dword v66, v[56:57], off
	global_load_dword v67, v[58:59], off
	global_load_dword v68, v[60:61], off
	global_load_dword v69, v[62:63], off
	v_or_b32_e32 v32, 16, v4
	v_or_b32_e32 v50, 18, v4
	v_or_b32_e32 v52, 20, v4
	v_or_b32_e32 v54, 22, v4
	v_or_b32_e32 v56, 24, v4
	v_or_b32_e32 v58, 26, v4
	v_or_b32_e32 v60, 28, v4
	v_or_b32_e32 v62, 30, v4
	v_mad_i64_i32 v[32:33], s[56:57], v32, s36, v[30:31]
	v_mad_i64_i32 v[50:51], s[56:57], v50, s36, v[30:31]
	v_mad_i64_i32 v[52:53], s[56:57], v52, s36, v[30:31]
	v_mad_i64_i32 v[54:55], s[56:57], v54, s36, v[30:31]
	v_mad_i64_i32 v[56:57], s[56:57], v56, s36, v[30:31]
	v_mad_i64_i32 v[58:59], s[56:57], v58, s36, v[30:31]
	v_mad_i64_i32 v[60:61], s[56:57], v60, s36, v[30:31]
	v_mad_i64_i32 v[62:63], s[56:57], v62, s36, v[30:31]
	v_lshl_add_u64 v[32:33], s[30:31], 0, v[32:33]
	v_lshl_add_u64 v[50:51], s[30:31], 0, v[50:51]
	v_lshl_add_u64 v[52:53], s[30:31], 0, v[52:53]
	v_lshl_add_u64 v[54:55], s[30:31], 0, v[54:55]
	v_lshl_add_u64 v[56:57], s[30:31], 0, v[56:57]
; #define LAS __attribute__((address_space(3)))
; __device__ __forceinline__ void transpose_item(const float* W, int K, int N, bf16* WT, int k0, int n0, int drow0, LAS float* scr, int lane) {
;     float wv[32];
; #pragma unroll
;     for (int i = 0; i < 32; ++i) wv[i] = W[(size_t)(k0 + 2 * i + (lane >> 5)) * N + n0 + (lane & 31)];
; #pragma unroll
;     for (int i = 0; i < 32; ++i) scr[(2 * i + (lane >> 5)) * 33 + (lane & 31)] = wv[i];
	v_lshl_add_u64 v[58:59], s[30:31], 0, v[58:59]
	v_lshl_add_u64 v[60:61], s[30:31], 0, v[60:61]
	v_lshl_add_u64 v[62:63], s[30:31], 0, v[62:63]
	v_lshl_add_u64 v[32:33], v[32:33], 0, v[6:7]
	v_lshl_add_u64 v[50:51], v[50:51], 0, v[6:7]
	v_lshl_add_u64 v[52:53], v[52:53], 0, v[6:7]
	v_lshl_add_u64 v[54:55], v[54:55], 0, v[6:7]
	v_lshl_add_u64 v[56:57], v[56:57], 0, v[6:7]
	v_lshl_add_u64 v[58:59], v[58:59], 0, v[6:7]
	v_lshl_add_u64 v[60:61], v[60:61], 0, v[6:7]
	v_lshl_add_u64 v[62:63], v[62:63], 0, v[6:7]
	v_lshl_add_u64 v[32:33], v[32:33], 0, s[20:21]
	v_lshl_add_u64 v[50:51], v[50:51], 0, s[20:21]
	v_lshl_add_u64 v[52:53], v[52:53], 0, s[20:21]
	v_lshl_add_u64 v[54:55], v[54:55], 0, s[20:21]
	v_lshl_add_u64 v[56:57], v[56:57], 0, s[20:21]
	v_lshl_add_u64 v[58:59], v[58:59], 0, s[20:21]
	v_lshl_add_u64 v[60:61], v[60:61], 0, s[20:21]
	v_lshl_add_u64 v[62:63], v[62:63], 0, s[20:21]
	global_load_dword v70, v[32:33], off
	global_load_dword v71, v[50:51], off
	global_load_dword v72, v[52:53], off
	global_load_dword v73, v[54:55], off
	global_load_dword v74, v[56:57], off
	global_load_dword v75, v[58:59], off
	global_load_dword v76, v[60:61], off
	global_load_dword v77, v[62:63], off
	v_or_b32_e32 v32, 32, v4
	v_or_b32_e32 v50, 34, v4
	v_or_b32_e32 v52, 36, v4
	v_or_b32_e32 v54, 38, v4
	v_or_b32_e32 v56, 40, v4
	v_or_b32_e32 v58, 42, v4
	v_or_b32_e32 v60, 44, v4
	v_or_b32_e32 v62, 46, v4
	v_mad_i64_i32 v[32:33], s[56:57], v32, s36, v[30:31]
	v_mad_i64_i32 v[50:51], s[56:57], v50, s36, v[30:31]
	v_mad_i64_i32 v[52:53], s[56:57], v52, s36, v[30:31]
	v_mad_i64_i32 v[54:55], s[56:57], v54, s36, v[30:31]
	v_mad_i64_i32 v[56:57], s[56:57], v56, s36, v[30:31]
	v_mad_i64_i32 v[58:59], s[56:57], v58, s36, v[30:31]
	v_mad_i64_i32 v[60:61], s[56:57], v60, s36, v[30:31]
	v_mad_i64_i32 v[62:63], s[56:57], v62, s36, v[30:31]
	v_lshl_add_u64 v[32:33], s[30:31], 0, v[32:33]
	v_lshl_add_u64 v[50:51], s[30:31], 0, v[50:51]
	v_lshl_add_u64 v[52:53], s[30:31], 0, v[52:53]
	v_lshl_add_u64 v[54:55], s[30:31], 0, v[54:55]
	v_lshl_add_u64 v[56:57], s[30:31], 0, v[56:57]
	v_lshl_add_u64 v[58:59], s[30:31], 0, v[58:59]
	v_lshl_add_u64 v[60:61], s[30:31], 0, v[60:61]
	v_lshl_add_u64 v[62:63], s[30:31], 0, v[62:63]
	v_lshl_add_u64 v[32:33], v[32:33], 0, v[6:7]
	v_lshl_add_u64 v[50:51], v[50:51], 0, v[6:7]
	v_lshl_add_u64 v[52:53], v[52:53], 0, v[6:7]
	v_lshl_add_u64 v[54:55], v[54:55], 0, v[6:7]
	v_lshl_add_u64 v[56:57], v[56:57], 0, v[6:7]
	v_lshl_add_u64 v[58:59], v[58:59], 0, v[6:7]
	v_lshl_add_u64 v[60:61], v[60:61], 0, v[6:7]
	v_lshl_add_u64 v[62:63], v[62:63], 0, v[6:7]
	v_lshl_add_u64 v[32:33], v[32:33], 0, s[20:21]
	v_lshl_add_u64 v[50:51], v[50:51], 0, s[20:21]
	v_lshl_add_u64 v[52:53], v[52:53], 0, s[20:21]
	v_lshl_add_u64 v[54:55], v[54:55], 0, s[20:21]
	v_lshl_add_u64 v[56:57], v[56:57], 0, s[20:21]
	v_lshl_add_u64 v[58:59], v[58:59], 0, s[20:21]
	v_lshl_add_u64 v[60:61], v[60:61], 0, s[20:21]
	v_lshl_add_u64 v[62:63], v[62:63], 0, s[20:21]
	global_load_dword v78, v[32:33], off
	global_load_dword v79, v[50:51], off
	global_load_dword v81, v[52:53], off
	global_load_dword v82, v[54:55], off
	global_load_dword v83, v[56:57], off
	global_load_dword v84, v[58:59], off
	global_load_dword v85, v[60:61], off
	s_nop 0
	global_load_dword v62, v[62:63], off
	v_or_b32_e32 v32, 48, v4
	v_or_b32_e32 v50, 50, v4
	v_or_b32_e32 v52, 52, v4
	v_or_b32_e32 v54, 54, v4
	v_or_b32_e32 v56, 56, v4
	v_or_b32_e32 v58, 58, v4
	v_or_b32_e32 v60, 60, v4
	v_or_b32_e32 v4, 62, v4
	v_mad_i64_i32 v[32:33], s[56:57], v32, s36, v[30:31]
	v_mad_i64_i32 v[50:51], s[56:57], v50, s36, v[30:31]
	v_mad_i64_i32 v[52:53], s[56:57], v52, s36, v[30:31]
	v_mad_i64_i32 v[54:55], s[56:57], v54, s36, v[30:31]
	v_mad_i64_i32 v[56:57], s[56:57], v56, s36, v[30:31]
	v_mad_i64_i32 v[58:59], s[56:57], v58, s36, v[30:31]
	v_mad_i64_i32 v[60:61], s[56:57], v60, s36, v[30:31]
	v_mad_i64_i32 v[30:31], s[56:57], v4, s36, v[30:31]
	v_lshl_add_u64 v[32:33], s[30:31], 0, v[32:33]
	v_lshl_add_u64 v[50:51], s[30:31], 0, v[50:51]
	v_lshl_add_u64 v[52:53], s[30:31], 0, v[52:53]
	v_lshl_add_u64 v[30:31], s[30:31], 0, v[30:31]
	v_lshl_add_u64 v[32:33], v[32:33], 0, v[6:7]
	v_lshl_add_u64 v[50:51], v[50:51], 0, v[6:7]
	v_lshl_add_u64 v[52:53], v[52:53], 0, v[6:7]
	v_lshl_add_u64 v[54:55], s[30:31], 0, v[54:55]
	v_lshl_add_u64 v[56:57], s[30:31], 0, v[56:57]
	v_lshl_add_u64 v[58:59], s[30:31], 0, v[58:59]
	v_lshl_add_u64 v[60:61], s[30:31], 0, v[60:61]
	v_lshl_add_u64 v[30:31], v[30:31], 0, v[6:7]
	v_lshl_add_u64 v[32:33], v[32:33], 0, s[20:21]
	v_lshl_add_u64 v[50:51], v[50:51], 0, s[20:21]
	v_lshl_add_u64 v[52:53], v[52:53], 0, s[20:21]
	v_lshl_add_u64 v[54:55], v[54:55], 0, v[6:7]
	v_lshl_add_u64 v[56:57], v[56:57], 0, v[6:7]
	v_lshl_add_u64 v[58:59], v[58:59], 0, v[6:7]
	v_lshl_add_u64 v[60:61], v[60:61], 0, v[6:7]
	v_lshl_add_u64 v[30:31], v[30:31], 0, s[20:21]
	v_lshl_add_u64 v[54:55], v[54:55], 0, s[20:21]
	v_lshl_add_u64 v[56:57], v[56:57], 0, s[20:21]
	v_lshl_add_u64 v[58:59], v[58:59], 0, s[20:21]
	v_lshl_add_u64 v[60:61], v[60:61], 0, s[20:21]
	global_load_dword v4, v[32:33], off
	s_nop 0
	global_load_dword v32, v[50:51], off
	global_load_dword v33, v[52:53], off
	s_nop 0
	global_load_dword v50, v[54:55], off
	global_load_dword v51, v[56:57], off
	global_load_dword v52, v[58:59], off
	global_load_dword v53, v[60:61], off
	s_nop 0
	global_load_dword v30, v[30:31], off
	s_waitcnt vmcnt(30)
; #define LAS __attribute__((address_space(3)))
; __device__ __forceinline__ unsigned pk2(float lo, float hi) { return pg8::cvt_pk_bf16(lo, hi); }
; __device__ __forceinline__ void transpose_item(const float* W, int K, int N, bf16* WT, int k0, int n0, int drow0, LAS float* scr, int lane) {
;     ...
;     for (int i = 0; i < 32; ++i) scr[(2 * i + (lane >> 5)) * 33 + (lane & 31)] = wv[i];
;     asm volatile("s_waitcnt lgkmcnt(0)" ::: "memory");
;     const int c = lane & 7;
; #pragma unroll
;     for (int j = 0; j < 4; ++j) { const int n = (lane >> 3) + 8 * j; const LAS float* s = scr + (8 * c) * 33 + n;
;         u32x4 o; o.x = pk2(s[0 * 33], s[1 * 33]); o.y = pk2(s[2 * 33], s[3 * 33]); o.z = pk2(s[4 * 33], s[5 * 33]); o.w = pk2(s[6 * 33], s[7 * 33]);
;         *(u32x4*)(WT + (size_t)(drow0 + n) * K + k0 + 8 * c) = o; }
;     asm volatile("s_waitcnt lgkmcnt(0)" ::: "memory");
	ds_write2_b32 v35, v29, v49 offset1:66
	s_waitcnt vmcnt(28)
	ds_write2_b32 v35, v64, v65 offset0:132 offset1:198
	s_waitcnt vmcnt(26)
	ds_write2_b32 v41, v66, v67 offset0:8 offset1:74
	s_waitcnt vmcnt(24)
	ds_write2_b32 v41, v68, v69 offset0:140 offset1:206
	s_waitcnt vmcnt(22)
	ds_write2_b32 v42, v70, v71 offset0:16 offset1:82
	s_waitcnt vmcnt(20)
	ds_write2_b32 v42, v72, v73 offset0:148 offset1:214
	s_waitcnt vmcnt(18)
	ds_write2_b32 v43, v74, v75 offset0:24 offset1:90
	s_waitcnt vmcnt(16)
	ds_write2_b32 v43, v76, v77 offset0:156 offset1:222
	s_waitcnt vmcnt(14)
	ds_write2_b32 v44, v78, v79 offset0:32 offset1:98
	s_waitcnt vmcnt(12)
	ds_write2_b32 v44, v81, v82 offset0:164 offset1:230
	s_waitcnt vmcnt(10)
	ds_write2_b32 v45, v83, v84 offset0:40 offset1:106
	s_waitcnt vmcnt(8)
	ds_write2_b32 v45, v85, v62 offset0:172 offset1:238
	s_waitcnt vmcnt(6)
	ds_write2_b32 v46, v4, v32 offset0:48 offset1:114
	s_waitcnt vmcnt(4)
	ds_write2_b32 v46, v33, v50 offset0:180 offset1:246
	s_waitcnt vmcnt(2)
	ds_write2_b32 v47, v51, v52 offset0:56 offset1:122
	s_waitcnt vmcnt(0)
	ds_write2_b32 v47, v53, v30 offset0:188 offset1:254
	s_waitcnt lgkmcnt(0)
	v_lshlrev_b32_e32 v4, 6, v27
	ds_read2_b32 v[30:31], v37 offset1:33
	v_and_b32_e32 v4, 0xffffff00, v4
	v_and_b32_e32 v27, 0x60, v28
	s_waitcnt lgkmcnt(0)
	v_cvt_pk_bf16_f32 v30, v30, v31
	ds_read2_b32 v[32:33], v37 offset0:66 offset1:99
	v_or3_b32 v4, v27, v4, s37
	s_waitcnt lgkmcnt(0)
	v_cvt_pk_bf16_f32 v31, v32, v33
	ds_read2_b32 v[32:33], v37 offset0:132 offset1:165
	v_or_b32_e32 v28, v4, v36
	s_waitcnt lgkmcnt(0)
	v_cvt_pk_bf16_f32 v32, v32, v33
	ds_read2_b32 v[50:51], v37 offset0:198 offset1:231
	v_ashrrev_i32_e32 v27, 31, v26
	v_ashrrev_i32_e32 v29, 31, v28
	s_waitcnt lgkmcnt(0)
	v_cvt_pk_bf16_f32 v33, v50, v51
	v_lshlrev_b64 v[28:29], 11, v[28:29]
	v_lshlrev_b64 v[50:51], 1, v[26:27]
	v_lshl_add_u64 v[28:29], v[28:29], 0, v[50:51]
	v_lshl_add_u64 v[28:29], s[20:21], 0, v[28:29]
	ds_read2_b32 v[26:27], v37 offset0:8 offset1:41
	v_lshl_add_u64 v[28:29], v[20:21], 0, v[28:29]
	global_store_dwordx4 v[28:29], v[30:33], off sc0 sc1
	s_waitcnt lgkmcnt(0)
	v_cvt_pk_bf16_f32 v26, v26, v27
	ds_read2_b32 v[28:29], v37 offset0:74 offset1:107
	s_waitcnt lgkmcnt(0)
	v_cvt_pk_bf16_f32 v27, v28, v29
	ds_read2_b32 v[28:29], v37 offset0:140 offset1:173
	s_waitcnt lgkmcnt(0)
	v_cvt_pk_bf16_f32 v28, v28, v29
	ds_read2_b32 v[30:31], v37 offset0:206 offset1:239
	s_waitcnt lgkmcnt(0)
	v_cvt_pk_bf16_f32 v29, v30, v31
	v_or_b32_e32 v30, v4, v38
	v_ashrrev_i32_e32 v31, 31, v30
	v_lshlrev_b64 v[30:31], 11, v[30:31]
	v_lshl_add_u64 v[30:31], v[30:31], 0, v[50:51]
	v_lshl_add_u64 v[30:31], s[20:21], 0, v[30:31]
	v_lshl_add_u64 v[30:31], v[20:21], 0, v[30:31]
	ds_read2_b32 v[32:33], v37 offset0:16 offset1:49
	global_store_dwordx4 v[30:31], v[26:29], off sc0 sc1
	s_mov_b64 s[28:29], exec
	s_waitcnt lgkmcnt(0)
	v_cvt_pk_bf16_f32 v26, v32, v33
	ds_read2_b32 v[28:29], v37 offset0:82 offset1:115
	s_waitcnt lgkmcnt(0)
	v_cvt_pk_bf16_f32 v27, v28, v29
	ds_read2_b32 v[28:29], v37 offset0:148 offset1:181
	s_waitcnt lgkmcnt(0)
	v_cvt_pk_bf16_f32 v28, v28, v29
	ds_read2_b32 v[30:31], v37 offset0:214 offset1:247
	s_waitcnt lgkmcnt(0)
	v_cvt_pk_bf16_f32 v29, v30, v31
	v_or_b32_e32 v30, v4, v39
	v_ashrrev_i32_e32 v31, 31, v30
	v_lshlrev_b64 v[30:31], 11, v[30:31]
	v_lshl_add_u64 v[30:31], v[30:31], 0, v[50:51]
	v_lshl_add_u64 v[30:31], s[20:21], 0, v[30:31]
	v_lshl_add_u64 v[30:31], v[20:21], 0, v[30:31]
	ds_read2_b32 v[32:33], v37 offset0:24 offset1:57
	global_store_dwordx4 v[30:31], v[26:29], off sc0 sc1
	s_waitcnt lgkmcnt(0)
	s_nop 0
	v_cvt_pk_bf16_f32 v26, v32, v33
	ds_read2_b32 v[28:29], v37 offset0:90 offset1:123
	s_waitcnt lgkmcnt(0)
	v_cvt_pk_bf16_f32 v27, v28, v29
	ds_read2_b32 v[28:29], v37 offset0:156 offset1:189
	s_waitcnt lgkmcnt(0)
	v_cvt_pk_bf16_f32 v28, v28, v29
	ds_read2_b32 v[30:31], v37 offset0:222 offset1:255
	s_waitcnt lgkmcnt(0)
	v_cvt_pk_bf16_f32 v29, v30, v31
	v_or_b32_e32 v30, v4, v40
	v_ashrrev_i32_e32 v31, 31, v30
	v_lshlrev_b64 v[30:31], 11, v[30:31]
	v_lshl_add_u64 v[30:31], v[30:31], 0, v[50:51]
	v_lshl_add_u64 v[30:31], s[20:21], 0, v[30:31]
	v_lshl_add_u64 v[30:31], v[20:21], 0, v[30:31]
	global_store_dwordx4 v[30:31], v[26:29], off sc0 sc1
	s_waitcnt lgkmcnt(0)

; #define LAS __attribute__((address_space(3)))
; __device__ __forceinline__ unsigned pk2(float lo, float hi) { return pg8::cvt_pk_bf16(lo, hi); }
; __device__ __forceinline__ void transpose_item(const float* W, int K, int N, bf16* WT, int k0, int n0, int drow0, LAS float* scr, int lane) {
;     float wv[32];
; #pragma unroll
;     for (int i = 0; i < 32; ++i) wv[i] = W[(size_t)(k0 + 2 * i + (lane >> 5)) * N + n0 + (lane & 31)];
; #pragma unroll
;     for (int i = 0; i < 32; ++i) scr[(2 * i + (lane >> 5)) * 33 + (lane & 31)] = wv[i];
;     asm volatile("s_waitcnt lgkmcnt(0)" ::: "memory");
;     const int c = lane & 7;
; #pragma unroll
;     for (int j = 0; j < 4; ++j) { const int n = (lane >> 3) + 8 * j; const LAS float* s = scr + (8 * c) * 33 + n;
;         u32x4 o; o.x = pk2(s[0 * 33], s[1 * 33]); o.y = pk2(s[2 * 33], s[3 * 33]); o.z = pk2(s[4 * 33], s[5 * 33]); o.w = pk2(s[6 * 33], s[7 * 33]);
;         *(u32x4*)(WT + (size_t)(drow0 + n) * K + k0 + 8 * c) = o; }
;     asm volatile("s_waitcnt lgkmcnt(0)" ::: "memory");
; }
; __device__ __forceinline__ bool transpose_job(int& it, const float* W, int K, int N, bf16* WT, int mode, LAS float* scr, int lane) {
;     const int nblk = N / 32, items = (K / 64) * nblk;
;     if (it >= items) { it -= items; return false; }
;     const int kb = it / nblk, nb = it % nblk, n0 = 32 * nb;
;     const int drow0 = mode == 0 ? n0 : (256 * (n0 >> 7) + (n0 & 127) + (mode == 2 ? 128 : 0));
;     transpose_item(W, K, N, WT, 64 * kb, n0, drow0, scr, lane);
.LBB0_36:
	s_or_b64 exec, exec, s[22:23]
	s_xor_b64 s[26:27], s[26:27], -1
	s_and_saveexec_b64 s[22:23], s[26:27]
	s_cbranch_execz .LBB0_25
	v_cmp_lt_i32_e32 vcc, s3, v48
	s_and_saveexec_b64 s[24:25], vcc
	s_xor_b64 s[24:25], exec, s[24:25]
	v_add_u32_e32 v48, 0xfffffa80, v48
	s_or_saveexec_b64 s[24:25], s[24:25]
	s_mov_b64 s[26:27], 0
	s_xor_b64 exec, exec, s[24:25]
	s_cbranch_execz .LBB0_24
	v_ashrrev_i32_e32 v4, 31, v48
	v_lshrrev_b32_e32 v4, 27, v4
	v_add_u32_e32 v4, v48, v4
	v_and_b32_e32 v26, 0x7ffffe0, v4
	v_lshlrev_b32_e32 v4, 1, v4
	v_and_b32_e32 v28, 0xffffffc0, v4
	s_load_dwordx2 s[28:29], s[10:11], 0x80
	v_sub_u32_e32 v26, v48, v26
	v_or_b32_e32 v30, v28, v34
	v_lshlrev_b32_e32 v26, 5, v26
	v_or_b32_e32 v52, 2, v30
	v_or_b32_e32 v54, 4, v30
	v_or_b32_e32 v56, 6, v30
	v_or_b32_e32 v58, 8, v30
	v_or_b32_e32 v60, 10, v30
	v_or_b32_e32 v62, 12, v30
	v_or_b32_e32 v64, 14, v30
	v_ashrrev_i32_e32 v27, 31, v26
	v_ashrrev_i32_e32 v31, 31, v30
	v_ashrrev_i32_e32 v53, 31, v52
	v_ashrrev_i32_e32 v55, 31, v54
	v_ashrrev_i32_e32 v57, 31, v56
	v_ashrrev_i32_e32 v59, 31, v58
	v_ashrrev_i32_e32 v61, 31, v60
	v_ashrrev_i32_e32 v63, 31, v62
	v_ashrrev_i32_e32 v65, 31, v64
	v_lshlrev_b64 v[50:51], 12, v[30:31]
	v_lshlrev_b64 v[32:33], 2, v[26:27]
	v_lshlrev_b64 v[52:53], 12, v[52:53]
	v_lshlrev_b64 v[54:55], 12, v[54:55]
	v_lshlrev_b64 v[56:57], 12, v[56:57]
	v_lshlrev_b64 v[58:59], 12, v[58:59]
	v_lshlrev_b64 v[60:61], 12, v[60:61]
	v_lshlrev_b64 v[62:63], 12, v[62:63]
	v_lshlrev_b64 v[64:65], 12, v[64:65]
	v_lshl_add_u64 v[50:51], v[50:51], 0, v[32:33]
	v_lshl_add_u64 v[52:53], v[52:53], 0, v[32:33]
	v_lshl_add_u64 v[54:55], v[54:55], 0, v[32:33]
	v_lshl_add_u64 v[56:57], v[56:57], 0, v[32:33]
	v_lshl_add_u64 v[58:59], v[58:59], 0, v[32:33]
	v_lshl_add_u64 v[60:61], v[60:61], 0, v[32:33]
	v_lshl_add_u64 v[62:63], v[62:63], 0, v[32:33]
	v_lshl_add_u64 v[64:65], v[64:65], 0, v[32:33]
	s_waitcnt lgkmcnt(0)
	v_lshl_add_u64 v[50:51], s[28:29], 0, v[50:51]
	v_lshl_add_u64 v[52:53], s[28:29], 0, v[52:53]
	v_lshl_add_u64 v[54:55], s[28:29], 0, v[54:55]
	v_lshl_add_u64 v[56:57], s[28:29], 0, v[56:57]
	v_lshl_add_u64 v[58:59], s[28:29], 0, v[58:59]
	v_lshl_add_u64 v[60:61], s[28:29], 0, v[60:61]
	v_lshl_add_u64 v[62:63], s[28:29], 0, v[62:63]
	v_lshl_add_u64 v[64:65], s[28:29], 0, v[64:65]
	v_lshl_add_u64 v[50:51], v[50:51], 0, v[6:7]
	v_lshl_add_u64 v[52:53], v[52:53], 0, v[6:7]
	v_lshl_add_u64 v[54:55], v[54:55], 0, v[6:7]
	v_lshl_add_u64 v[56:57], v[56:57], 0, v[6:7]
	v_lshl_add_u64 v[58:59], v[58:59], 0, v[6:7]
	v_lshl_add_u64 v[60:61], v[60:61], 0, v[6:7]
	v_lshl_add_u64 v[62:63], v[62:63], 0, v[6:7]
	v_lshl_add_u64 v[64:65], v[64:65], 0, v[6:7]
	v_lshl_add_u64 v[50:51], v[50:51], 0, s[20:21]
	v_lshl_add_u64 v[52:53], v[52:53], 0, s[20:21]
	v_lshl_add_u64 v[54:55], v[54:55], 0, s[20:21]
	v_lshl_add_u64 v[56:57], v[56:57], 0, s[20:21]
	v_lshl_add_u64 v[58:59], v[58:59], 0, s[20:21]
	v_lshl_add_u64 v[60:61], v[60:61], 0, s[20:21]
	v_lshl_add_u64 v[62:63], v[62:63], 0, s[20:21]
	v_lshl_add_u64 v[64:65], v[64:65], 0, s[20:21]
	global_load_dword v4, v[50:51], off
	global_load_dword v27, v[52:53], off
	global_load_dword v29, v[54:55], off
	global_load_dword v49, v[56:57], off
	global_load_dword v66, v[58:59], off
	global_load_dword v67, v[60:61], off
	global_load_dword v68, v[62:63], off
	global_load_dword v69, v[64:65], off
	v_or_b32_e32 v50, 16, v30
	v_or_b32_e32 v52, 18, v30
	v_or_b32_e32 v54, 20, v30
	v_or_b32_e32 v56, 22, v30
	v_or_b32_e32 v58, 24, v30
	v_or_b32_e32 v60, 26, v30
	v_or_b32_e32 v62, 28, v30
	v_or_b32_e32 v64, 30, v30
	v_ashrrev_i32_e32 v51, 31, v50
	v_ashrrev_i32_e32 v53, 31, v52
	v_ashrrev_i32_e32 v55, 31, v54
	v_ashrrev_i32_e32 v57, 31, v56
	v_ashrrev_i32_e32 v59, 31, v58
	v_ashrrev_i32_e32 v61, 31, v60
	v_ashrrev_i32_e32 v63, 31, v62
	v_ashrrev_i32_e32 v65, 31, v64
	v_lshlrev_b64 v[50:51], 12, v[50:51]
	v_lshlrev_b64 v[52:53], 12, v[52:53]
	v_lshlrev_b64 v[54:55], 12, v[54:55]
	v_lshlrev_b64 v[56:57], 12, v[56:57]
	v_lshlrev_b64 v[58:59], 12, v[58:59]
	v_lshlrev_b64 v[60:61], 12, v[60:61]
	v_lshlrev_b64 v[62:63], 12, v[62:63]
	v_lshlrev_b64 v[64:65], 12, v[64:65]
	v_lshl_add_u64 v[50:51], v[50:51], 0, v[32:33]
	v_lshl_add_u64 v[52:53], v[52:53], 0, v[32:33]
	v_lshl_add_u64 v[54:55], v[54:55], 0, v[32:33]
	v_lshl_add_u64 v[56:57], v[56:57], 0, v[32:33]
	v_lshl_add_u64 v[58:59], v[58:59], 0, v[32:33]
	v_lshl_add_u64 v[60:61], v[60:61], 0, v[32:33]
	v_lshl_add_u64 v[62:63], v[62:63], 0, v[32:33]
	v_lshl_add_u64 v[64:65], v[64:65], 0, v[32:33]
	v_lshl_add_u64 v[50:51], s[28:29], 0, v[50:51]
	v_lshl_add_u64 v[52:53], s[28:29], 0, v[52:53]
	v_lshl_add_u64 v[54:55], s[28:29], 0, v[54:55]
	v_lshl_add_u64 v[56:57], s[28:29], 0, v[56:57]
	v_lshl_add_u64 v[58:59], s[28:29], 0, v[58:59]
	v_lshl_add_u64 v[60:61], s[28:29], 0, v[60:61]
	v_lshl_add_u64 v[62:63], s[28:29], 0, v[62:63]
	v_lshl_add_u64 v[64:65], s[28:29], 0, v[64:65]
	v_lshl_add_u64 v[50:51], v[50:51], 0, v[6:7]
	v_lshl_add_u64 v[52:53], v[52:53], 0, v[6:7]
	v_lshl_add_u64 v[54:55], v[54:55], 0, v[6:7]
	v_lshl_add_u64 v[56:57], v[56:57], 0, v[6:7]
	v_lshl_add_u64 v[58:59], v[58:59], 0, v[6:7]
	v_lshl_add_u64 v[60:61], v[60:61], 0, v[6:7]
	v_lshl_add_u64 v[62:63], v[62:63], 0, v[6:7]
	v_lshl_add_u64 v[64:65], v[64:65], 0, v[6:7]
	v_lshl_add_u64 v[50:51], v[50:51], 0, s[20:21]
	v_lshl_add_u64 v[52:53], v[52:53], 0, s[20:21]
	v_lshl_add_u64 v[54:55], v[54:55], 0, s[20:21]
	v_lshl_add_u64 v[56:57], v[56:57], 0, s[20:21]
	v_lshl_add_u64 v[58:59], v[58:59], 0, s[20:21]
	v_lshl_add_u64 v[60:61], v[60:61], 0, s[20:21]
	v_lshl_add_u64 v[62:63], v[62:63], 0, s[20:21]
; #define LAS __attribute__((address_space(3)))
; __device__ __forceinline__ void transpose_item(const float* W, int K, int N, bf16* WT, int k0, int n0, int drow0, LAS float* scr, int lane) {
;     float wv[32];
; #pragma unroll
;     for (int i = 0; i < 32; ++i) wv[i] = W[(size_t)(k0 + 2 * i + (lane >> 5)) * N + n0 + (lane & 31)];
	v_lshl_add_u64 v[64:65], v[64:65], 0, s[20:21]
	global_load_dword v70, v[50:51], off
	global_load_dword v71, v[52:53], off
	global_load_dword v72, v[54:55], off
	global_load_dword v73, v[56:57], off
	global_load_dword v74, v[58:59], off
	global_load_dword v75, v[60:61], off
	global_load_dword v76, v[62:63], off
	global_load_dword v77, v[64:65], off
	v_or_b32_e32 v50, 32, v30
	v_or_b32_e32 v52, 34, v30
	v_or_b32_e32 v54, 36, v30
	v_or_b32_e32 v56, 38, v30
	v_or_b32_e32 v58, 40, v30
	v_or_b32_e32 v60, 42, v30
	v_or_b32_e32 v62, 44, v30
	v_or_b32_e32 v64, 46, v30
	v_ashrrev_i32_e32 v51, 31, v50
	v_ashrrev_i32_e32 v53, 31, v52
	v_ashrrev_i32_e32 v55, 31, v54
	v_ashrrev_i32_e32 v57, 31, v56
	v_ashrrev_i32_e32 v59, 31, v58
	v_ashrrev_i32_e32 v61, 31, v60
	v_ashrrev_i32_e32 v63, 31, v62
	v_ashrrev_i32_e32 v65, 31, v64
	v_lshlrev_b64 v[50:51], 12, v[50:51]
	v_lshlrev_b64 v[52:53], 12, v[52:53]
	v_lshlrev_b64 v[54:55], 12, v[54:55]
	v_lshlrev_b64 v[56:57], 12, v[56:57]
	v_lshlrev_b64 v[58:59], 12, v[58:59]
	v_lshlrev_b64 v[60:61], 12, v[60:61]
	v_lshlrev_b64 v[62:63], 12, v[62:63]
	v_lshlrev_b64 v[64:65], 12, v[64:65]
	v_lshl_add_u64 v[50:51], v[50:51], 0, v[32:33]
	v_lshl_add_u64 v[52:53], v[52:53], 0, v[32:33]
	v_lshl_add_u64 v[54:55], v[54:55], 0, v[32:33]
	v_lshl_add_u64 v[56:57], v[56:57], 0, v[32:33]
	v_lshl_add_u64 v[58:59], v[58:59], 0, v[32:33]
	v_lshl_add_u64 v[60:61], v[60:61], 0, v[32:33]
	v_lshl_add_u64 v[62:63], v[62:63], 0, v[32:33]
	v_lshl_add_u64 v[64:65], v[64:65], 0, v[32:33]
	v_lshl_add_u64 v[50:51], s[28:29], 0, v[50:51]
	v_lshl_add_u64 v[52:53], s[28:29], 0, v[52:53]
	v_lshl_add_u64 v[54:55], s[28:29], 0, v[54:55]
	v_lshl_add_u64 v[56:57], s[28:29], 0, v[56:57]
	v_lshl_add_u64 v[58:59], s[28:29], 0, v[58:59]
	v_lshl_add_u64 v[60:61], s[28:29], 0, v[60:61]
	v_lshl_add_u64 v[62:63], s[28:29], 0, v[62:63]
	v_lshl_add_u64 v[64:65], s[28:29], 0, v[64:65]
	v_lshl_add_u64 v[50:51], v[50:51], 0, v[6:7]
	v_lshl_add_u64 v[52:53], v[52:53], 0, v[6:7]
	v_lshl_add_u64 v[54:55], v[54:55], 0, v[6:7]
	v_lshl_add_u64 v[56:57], v[56:57], 0, v[6:7]
	v_lshl_add_u64 v[58:59], v[58:59], 0, v[6:7]
	v_lshl_add_u64 v[60:61], v[60:61], 0, v[6:7]
	v_lshl_add_u64 v[62:63], v[62:63], 0, v[6:7]
	v_lshl_add_u64 v[64:65], v[64:65], 0, v[6:7]
	v_lshl_add_u64 v[50:51], v[50:51], 0, s[20:21]
	v_lshl_add_u64 v[52:53], v[52:53], 0, s[20:21]
	v_lshl_add_u64 v[54:55], v[54:55], 0, s[20:21]
	v_lshl_add_u64 v[56:57], v[56:57], 0, s[20:21]
	v_lshl_add_u64 v[58:59], v[58:59], 0, s[20:21]
	v_lshl_add_u64 v[60:61], v[60:61], 0, s[20:21]
	v_lshl_add_u64 v[62:63], v[62:63], 0, s[20:21]
	v_lshl_add_u64 v[64:65], v[64:65], 0, s[20:21]
	global_load_dword v78, v[50:51], off
	global_load_dword v79, v[52:53], off
	global_load_dword v81, v[54:55], off
	global_load_dword v82, v[56:57], off
	global_load_dword v83, v[58:59], off
	global_load_dword v84, v[60:61], off
	global_load_dword v85, v[62:63], off
	s_nop 0
	global_load_dword v64, v[64:65], off
	v_or_b32_e32 v50, 48, v30
	v_or_b32_e32 v52, 50, v30
	v_or_b32_e32 v54, 52, v30
	v_or_b32_e32 v56, 54, v30
	v_or_b32_e32 v58, 56, v30
	v_or_b32_e32 v60, 58, v30
	v_or_b32_e32 v62, 60, v30
	v_or_b32_e32 v30, 62, v30
	v_ashrrev_i32_e32 v51, 31, v50
	v_ashrrev_i32_e32 v53, 31, v52
	v_ashrrev_i32_e32 v55, 31, v54
	v_ashrrev_i32_e32 v31, 31, v30
	v_lshlrev_b64 v[50:51], 12, v[50:51]
	v_lshlrev_b64 v[52:53], 12, v[52:53]
	v_lshlrev_b64 v[54:55], 12, v[54:55]
	v_ashrrev_i32_e32 v57, 31, v56
	v_ashrrev_i32_e32 v59, 31, v58
	v_ashrrev_i32_e32 v61, 31, v60
	v_ashrrev_i32_e32 v63, 31, v62
	v_lshlrev_b64 v[30:31], 12, v[30:31]
	v_lshl_add_u64 v[50:51], v[50:51], 0, v[32:33]
	v_lshl_add_u64 v[52:53], v[52:53], 0, v[32:33]
	v_lshl_add_u64 v[54:55], v[54:55], 0, v[32:33]
	v_lshlrev_b64 v[56:57], 12, v[56:57]
	v_lshlrev_b64 v[58:59], 12, v[58:59]
	v_lshlrev_b64 v[60:61], 12, v[60:61]
	v_lshlrev_b64 v[62:63], 12, v[62:63]
	v_lshl_add_u64 v[30:31], v[30:31], 0, v[32:33]
	v_lshl_add_u64 v[50:51], s[28:29], 0, v[50:51]
	v_lshl_add_u64 v[52:53], s[28:29], 0, v[52:53]
	v_lshl_add_u64 v[54:55], s[28:29], 0, v[54:55]
	v_lshl_add_u64 v[56:57], v[56:57], 0, v[32:33]
	v_lshl_add_u64 v[58:59], v[58:59], 0, v[32:33]
	v_lshl_add_u64 v[60:61], v[60:61], 0, v[32:33]
	v_lshl_add_u64 v[62:63], v[62:63], 0, v[32:33]
	v_lshl_add_u64 v[30:31], s[28:29], 0, v[30:31]
	v_lshl_add_u64 v[50:51], v[50:51], 0, v[6:7]
	v_lshl_add_u64 v[52:53], v[52:53], 0, v[6:7]
	v_lshl_add_u64 v[54:55], v[54:55], 0, v[6:7]
	v_lshl_add_u64 v[56:57], s[28:29], 0, v[56:57]
	v_lshl_add_u64 v[58:59], s[28:29], 0, v[58:59]
	v_lshl_add_u64 v[60:61], s[28:29], 0, v[60:61]
	v_lshl_add_u64 v[62:63], s[28:29], 0, v[62:63]
	v_lshl_add_u64 v[30:31], v[30:31], 0, v[6:7]
	v_lshl_add_u64 v[50:51], v[50:51], 0, s[20:21]
	v_lshl_add_u64 v[52:53], v[52:53], 0, s[20:21]
	v_lshl_add_u64 v[54:55], v[54:55], 0, s[20:21]
	v_lshl_add_u64 v[56:57], v[56:57], 0, v[6:7]
	v_lshl_add_u64 v[58:59], v[58:59], 0, v[6:7]
	v_lshl_add_u64 v[60:61], v[60:61], 0, v[6:7]
	v_lshl_add_u64 v[62:63], v[62:63], 0, v[6:7]
	v_lshl_add_u64 v[30:31], v[30:31], 0, s[20:21]
	v_lshl_add_u64 v[56:57], v[56:57], 0, s[20:21]
	v_lshl_add_u64 v[58:59], v[58:59], 0, s[20:21]
	v_lshl_add_u64 v[60:61], v[60:61], 0, s[20:21]
	v_lshl_add_u64 v[62:63], v[62:63], 0, s[20:21]
	global_load_dword v32, v[50:51], off
	global_load_dword v33, v[52:53], off
	s_nop 0
	global_load_dword v50, v[54:55], off
	global_load_dword v51, v[56:57], off
	global_load_dword v52, v[58:59], off
	global_load_dword v53, v[60:61], off
	s_nop 0
	global_load_dword v54, v[62:63], off
	s_nop 0
	global_load_dword v30, v[30:31], off
	s_waitcnt vmcnt(30)
; #define LAS __attribute__((address_space(3)))
; __device__ __forceinline__ unsigned pk2(float lo, float hi) { return pg8::cvt_pk_bf16(lo, hi); }
; __device__ __forceinline__ void transpose_item(const float* W, int K, int N, bf16* WT, int k0, int n0, int drow0, LAS float* scr, int lane) {
;     ...
;     for (int i = 0; i < 32; ++i) scr[(2 * i + (lane >> 5)) * 33 + (lane & 31)] = wv[i];
;     asm volatile("s_waitcnt lgkmcnt(0)" ::: "memory");
;     const int c = lane & 7;
; #pragma unroll
;     for (int j = 0; j < 4; ++j) { const int n = (lane >> 3) + 8 * j; const LAS float* s = scr + (8 * c) * 33 + n;
;         u32x4 o; o.x = pk2(s[0 * 33], s[1 * 33]); o.y = pk2(s[2 * 33], s[3 * 33]); o.z = pk2(s[4 * 33], s[5 * 33]); o.w = pk2(s[6 * 33], s[7 * 33]);
;         *(u32x4*)(WT + (size_t)(drow0 + n) * K + k0 + 8 * c) = o; }
;     asm volatile("s_waitcnt lgkmcnt(0)" ::: "memory");
	ds_write2_b32 v35, v4, v27 offset1:66
	s_waitcnt vmcnt(28)
	ds_write2_b32 v35, v29, v49 offset0:132 offset1:198
	s_waitcnt vmcnt(26)
	ds_write2_b32 v41, v66, v67 offset0:8 offset1:74
	s_waitcnt vmcnt(24)
	ds_write2_b32 v41, v68, v69 offset0:140 offset1:206
	s_waitcnt vmcnt(22)
	ds_write2_b32 v42, v70, v71 offset0:16 offset1:82
	s_waitcnt vmcnt(20)
	ds_write2_b32 v42, v72, v73 offset0:148 offset1:214
	s_waitcnt vmcnt(18)
	ds_write2_b32 v43, v74, v75 offset0:24 offset1:90
	s_waitcnt vmcnt(16)
	ds_write2_b32 v43, v76, v77 offset0:156 offset1:222
	s_waitcnt vmcnt(14)
	ds_write2_b32 v44, v78, v79 offset0:32 offset1:98
	s_waitcnt vmcnt(12)
	ds_write2_b32 v44, v81, v82 offset0:164 offset1:230
	s_waitcnt vmcnt(10)
	ds_write2_b32 v45, v83, v84 offset0:40 offset1:106
	s_waitcnt vmcnt(8)
	ds_write2_b32 v45, v85, v64 offset0:172 offset1:238
	s_waitcnt vmcnt(6)
	ds_write2_b32 v46, v32, v33 offset0:48 offset1:114
	s_waitcnt vmcnt(4)
	ds_write2_b32 v46, v50, v51 offset0:180 offset1:246
	s_waitcnt vmcnt(2)
	ds_write2_b32 v47, v52, v53 offset0:56 offset1:122
	s_waitcnt vmcnt(0)
	ds_write2_b32 v47, v54, v30 offset0:188 offset1:254
	s_waitcnt lgkmcnt(0)
	ds_read2_b32 v[30:31], v37 offset1:33
	s_waitcnt lgkmcnt(0)
	v_cvt_pk_bf16_f32 v30, v30, v31
	ds_read2_b32 v[32:33], v37 offset0:66 offset1:99
	s_waitcnt lgkmcnt(0)
	v_cvt_pk_bf16_f32 v31, v32, v33
	ds_read2_b32 v[32:33], v37 offset0:132 offset1:165
	s_waitcnt lgkmcnt(0)
	v_cvt_pk_bf16_f32 v32, v32, v33
	ds_read2_b32 v[50:51], v37 offset0:198 offset1:231
	v_or_b32_e32 v4, v26, v36
	v_ashrrev_i32_e32 v29, 31, v28
	s_waitcnt lgkmcnt(0)
	v_cvt_pk_bf16_f32 v33, v50, v51
	v_mul_lo_u32 v50, v4, s38
	v_ashrrev_i32_e32 v51, 31, v50
	v_lshlrev_b64 v[54:55], 1, v[28:29]
	v_lshl_add_u64 v[28:29], v[50:51], 1, v[54:55]
	v_lshl_add_u64 v[28:29], v[24:25], 0, v[28:29]
	ds_read2_b32 v[52:53], v37 offset0:8 offset1:41
	global_store_dwordx4 v[28:29], v[30:33], off sc0 sc1
	s_waitcnt lgkmcnt(0)
	v_cvt_pk_bf16_f32 v28, v52, v53
	ds_read2_b32 v[30:31], v37 offset0:74 offset1:107
	s_waitcnt lgkmcnt(0)
	v_cvt_pk_bf16_f32 v29, v30, v31
	ds_read2_b32 v[30:31], v37 offset0:140 offset1:173
	s_waitcnt lgkmcnt(0)
	v_cvt_pk_bf16_f32 v30, v30, v31
	ds_read2_b32 v[32:33], v37 offset0:206 offset1:239
	v_or_b32_e32 v4, v26, v38
	s_waitcnt lgkmcnt(0)
	v_cvt_pk_bf16_f32 v31, v32, v33
	v_mul_lo_u32 v32, v4, s38
	v_ashrrev_i32_e32 v33, 31, v32
	v_lshl_add_u64 v[32:33], v[32:33], 1, v[54:55]
	v_lshl_add_u64 v[32:33], v[24:25], 0, v[32:33]
	ds_read2_b32 v[50:51], v37 offset0:16 offset1:49
	global_store_dwordx4 v[32:33], v[28:31], off sc0 sc1
	v_or_b32_e32 v4, v26, v39
	s_mov_b64 s[26:27], exec
	s_waitcnt lgkmcnt(0)
	v_cvt_pk_bf16_f32 v28, v50, v51
	ds_read2_b32 v[30:31], v37 offset0:82 offset1:115
	s_waitcnt lgkmcnt(0)
	v_cvt_pk_bf16_f32 v29, v30, v31
	ds_read2_b32 v[30:31], v37 offset0:148 offset1:181
	s_waitcnt lgkmcnt(0)
	v_cvt_pk_bf16_f32 v30, v30, v31
	ds_read2_b32 v[32:33], v37 offset0:214 offset1:247
	s_waitcnt lgkmcnt(0)
	v_cvt_pk_bf16_f32 v31, v32, v33
	v_mul_lo_u32 v32, v4, s38
	v_ashrrev_i32_e32 v33, 31, v32
	v_or_b32_e32 v4, v26, v40
	v_lshl_add_u64 v[32:33], v[32:33], 1, v[54:55]
	v_mul_lo_u32 v26, v4, s38
	v_lshl_add_u64 v[32:33], v[24:25], 0, v[32:33]
	v_ashrrev_i32_e32 v27, 31, v26
	ds_read2_b32 v[50:51], v37 offset0:24 offset1:57
	global_store_dwordx4 v[32:33], v[28:31], off sc0 sc1
	v_lshl_add_u64 v[26:27], v[26:27], 1, v[54:55]
	v_lshl_add_u64 v[26:27], v[24:25], 0, v[26:27]
	s_waitcnt lgkmcnt(0)
	v_cvt_pk_bf16_f32 v28, v50, v51
	ds_read2_b32 v[30:31], v37 offset0:90 offset1:123
	s_waitcnt lgkmcnt(0)
	v_cvt_pk_bf16_f32 v29, v30, v31
	ds_read2_b32 v[30:31], v37 offset0:156 offset1:189
	s_waitcnt lgkmcnt(0)
	v_cvt_pk_bf16_f32 v30, v30, v31
	ds_read2_b32 v[32:33], v37 offset0:222 offset1:255
	s_waitcnt lgkmcnt(0)
	v_cvt_pk_bf16_f32 v31, v32, v33
	global_store_dwordx4 v[26:27], v[28:31], off sc0 sc1
	s_waitcnt lgkmcnt(0)
	s_branch .LBB0_24

; #define LAS __attribute__((address_space(3)))
; __device__ __forceinline__ unsigned pk2(float lo, float hi) { return pg8::cvt_pk_bf16(lo, hi); }
; __device__ __forceinline__ void transpose_item(const float* W, int K, int N, bf16* WT, int k0, int n0, int drow0, LAS float* scr, int lane) {
;     float wv[32];
; #pragma unroll
;     for (int i = 0; i < 32; ++i) wv[i] = W[(size_t)(k0 + 2 * i + (lane >> 5)) * N + n0 + (lane & 31)];
; #pragma unroll
;     for (int i = 0; i < 32; ++i) scr[(2 * i + (lane >> 5)) * 33 + (lane & 31)] = wv[i];
;     asm volatile("s_waitcnt lgkmcnt(0)" ::: "memory");
;     const int c = lane & 7;
; #pragma unroll
;     for (int j = 0; j < 4; ++j) { const int n = (lane >> 3) + 8 * j; const LAS float* s = scr + (8 * c) * 33 + n;
;         u32x4 o; o.x = pk2(s[0 * 33], s[1 * 33]); o.y = pk2(s[2 * 33], s[3 * 33]); o.z = pk2(s[4 * 33], s[5 * 33]); o.w = pk2(s[6 * 33], s[7 * 33]);
;         *(u32x4*)(WT + (size_t)(drow0 + n) * K + k0 + 8 * c) = o; }
;     asm volatile("s_waitcnt lgkmcnt(0)" ::: "memory");
; }
; __device__ __forceinline__ bool transpose_job(int& it, const float* W, int K, int N, bf16* WT, int mode, LAS float* scr, int lane) {
;     const int nblk = N / 32, items = (K / 64) * nblk;
;     if (it >= items) { it -= items; return false; }
;     const int kb = it / nblk, nb = it % nblk, n0 = 32 * nb;
;     const int drow0 = mode == 0 ? n0 : (256 * (n0 >> 7) + (n0 & 127) + (mode == 2 ? 128 : 0));
;     transpose_item(W, K, N, WT, 64 * kb, n0, drow0, scr, lane);
.LBB0_46:
	v_mul_hi_i32 v24, v48, s40
	v_lshrrev_b32_e32 v25, 31, v24
	v_ashrrev_i32_e32 v24, 4, v24
	s_load_dwordx2 s[20:21], s[10:11], 0x88
	v_add_u32_e32 v25, v24, v25
	v_mul_lo_u32 v24, v25, s41
	v_sub_u32_e32 v24, v48, v24
	v_lshlrev_b32_e32 v24, 5, v24
	v_lshlrev_b32_e32 v30, 6, v25
	v_ashrrev_i32_e32 v25, 31, v24
	v_or_b32_e32 v31, v30, v34
	s_waitcnt lgkmcnt(0)
	v_lshl_add_u64 v[26:27], v[24:25], 2, s[20:21]
	v_lshl_add_u64 v[26:27], v[26:27], 0, v[4:5]
	v_or_b32_e32 v25, 2, v31
	v_mad_i64_i32 v[32:33], s[20:21], v25, s42, v[26:27]
	v_or_b32_e32 v25, 4, v31
	v_mad_i64_i32 v[50:51], s[20:21], v25, s42, v[26:27]
	v_or_b32_e32 v25, 6, v31
	v_mad_i64_i32 v[52:53], s[20:21], v25, s42, v[26:27]
	v_or_b32_e32 v25, 8, v31
	v_mad_i64_i32 v[54:55], s[20:21], v25, s42, v[26:27]
	v_or_b32_e32 v25, 10, v31
	v_mad_i64_i32 v[56:57], s[20:21], v25, s42, v[26:27]
	v_or_b32_e32 v25, 12, v31
	v_mad_i64_i32 v[58:59], s[20:21], v25, s42, v[26:27]
	v_or_b32_e32 v25, 14, v31
	v_mad_i64_i32 v[28:29], s[20:21], v31, s42, v[26:27]
	v_mad_i64_i32 v[60:61], s[20:21], v25, s42, v[26:27]
	global_load_dword v25, v[28:29], off
	global_load_dword v49, v[32:33], off
	global_load_dword v62, v[50:51], off
	global_load_dword v63, v[52:53], off
	global_load_dword v64, v[54:55], off
	global_load_dword v65, v[56:57], off
	global_load_dword v66, v[58:59], off
	global_load_dword v67, v[60:61], off
	v_or_b32_e32 v28, 16, v31
	v_or_b32_e32 v32, 18, v31
	v_or_b32_e32 v50, 20, v31
	v_or_b32_e32 v52, 22, v31
	v_or_b32_e32 v54, 24, v31
	v_or_b32_e32 v56, 26, v31
	v_or_b32_e32 v58, 28, v31
	v_or_b32_e32 v60, 30, v31
	v_mad_i64_i32 v[28:29], s[20:21], v28, s42, v[26:27]
	v_mad_i64_i32 v[32:33], s[20:21], v32, s42, v[26:27]
	v_mad_i64_i32 v[50:51], s[20:21], v50, s42, v[26:27]
	v_mad_i64_i32 v[52:53], s[20:21], v52, s42, v[26:27]
	v_mad_i64_i32 v[54:55], s[20:21], v54, s42, v[26:27]
	v_mad_i64_i32 v[56:57], s[20:21], v56, s42, v[26:27]
	v_mad_i64_i32 v[58:59], s[20:21], v58, s42, v[26:27]
	v_mad_i64_i32 v[60:61], s[20:21], v60, s42, v[26:27]
	global_load_dword v68, v[28:29], off
	global_load_dword v69, v[32:33], off
	global_load_dword v70, v[50:51], off
	global_load_dword v71, v[52:53], off
	global_load_dword v72, v[54:55], off
	global_load_dword v73, v[56:57], off
	global_load_dword v74, v[58:59], off
	global_load_dword v75, v[60:61], off
	v_or_b32_e32 v28, 32, v31
	v_or_b32_e32 v32, 34, v31
	v_or_b32_e32 v50, 36, v31
	v_or_b32_e32 v52, 38, v31
	v_or_b32_e32 v54, 40, v31
	v_or_b32_e32 v56, 42, v31
	v_or_b32_e32 v58, 44, v31
	v_or_b32_e32 v60, 46, v31
	v_mad_i64_i32 v[28:29], s[20:21], v28, s42, v[26:27]
	v_mad_i64_i32 v[32:33], s[20:21], v32, s42, v[26:27]
	v_mad_i64_i32 v[50:51], s[20:21], v50, s42, v[26:27]
	v_mad_i64_i32 v[52:53], s[20:21], v52, s42, v[26:27]
	v_mad_i64_i32 v[54:55], s[20:21], v54, s42, v[26:27]
	v_mad_i64_i32 v[56:57], s[20:21], v56, s42, v[26:27]
	v_mad_i64_i32 v[58:59], s[20:21], v58, s42, v[26:27]
	v_mad_i64_i32 v[60:61], s[20:21], v60, s42, v[26:27]
	global_load_dword v76, v[28:29], off
	global_load_dword v77, v[32:33], off
	global_load_dword v78, v[50:51], off
	global_load_dword v79, v[52:53], off
	global_load_dword v81, v[54:55], off
	global_load_dword v82, v[56:57], off
	global_load_dword v83, v[58:59], off
	s_nop 0
	global_load_dword v60, v[60:61], off
	v_or_b32_e32 v28, 48, v31
	v_or_b32_e32 v32, 50, v31
	v_or_b32_e32 v50, 52, v31
	v_or_b32_e32 v52, 54, v31
	v_or_b32_e32 v54, 56, v31
	v_or_b32_e32 v56, 58, v31
	v_or_b32_e32 v58, 60, v31
	v_or_b32_e32 v31, 62, v31
	v_mad_i64_i32 v[28:29], s[20:21], v28, s42, v[26:27]
	v_mad_i64_i32 v[32:33], s[20:21], v32, s42, v[26:27]
	v_mad_i64_i32 v[50:51], s[20:21], v50, s42, v[26:27]
	v_mad_i64_i32 v[52:53], s[20:21], v52, s42, v[26:27]
	v_mad_i64_i32 v[54:55], s[20:21], v54, s42, v[26:27]
	v_mad_i64_i32 v[56:57], s[20:21], v56, s42, v[26:27]
	v_mad_i64_i32 v[58:59], s[20:21], v58, s42, v[26:27]
	v_mad_i64_i32 v[26:27], s[20:21], v31, s42, v[26:27]
	global_load_dword v28, v[28:29], off
	s_nop 0
	global_load_dword v29, v[32:33], off
	global_load_dword v31, v[50:51], off
	s_nop 0
	global_load_dword v32, v[52:53], off
	global_load_dword v33, v[54:55], off
	global_load_dword v50, v[56:57], off
	global_load_dword v51, v[58:59], off
	s_nop 0
	global_load_dword v26, v[26:27], off
	s_waitcnt vmcnt(30)
; #define LAS __attribute__((address_space(3)))
; __device__ __forceinline__ unsigned pk2(float lo, float hi) { return pg8::cvt_pk_bf16(lo, hi); }
; __device__ __forceinline__ void transpose_item(const float* W, int K, int N, bf16* WT, int k0, int n0, int drow0, LAS float* scr, int lane) {
;     ...
;     for (int i = 0; i < 32; ++i) scr[(2 * i + (lane >> 5)) * 33 + (lane & 31)] = wv[i];
;     asm volatile("s_waitcnt lgkmcnt(0)" ::: "memory");
;     const int c = lane & 7;
; #pragma unroll
;     for (int j = 0; j < 4; ++j) { const int n = (lane >> 3) + 8 * j; const LAS float* s = scr + (8 * c) * 33 + n;
;         u32x4 o; o.x = pk2(s[0 * 33], s[1 * 33]); o.y = pk2(s[2 * 33], s[3 * 33]); o.z = pk2(s[4 * 33], s[5 * 33]); o.w = pk2(s[6 * 33], s[7 * 33]);
;         *(u32x4*)(WT + (size_t)(drow0 + n) * K + k0 + 8 * c) = o; }
;     asm volatile("s_waitcnt lgkmcnt(0)" ::: "memory");
	ds_write2_b32 v35, v25, v49 offset1:66
	s_waitcnt vmcnt(28)
	ds_write2_b32 v35, v62, v63 offset0:132 offset1:198
	s_waitcnt vmcnt(26)
	ds_write2_b32 v41, v64, v65 offset0:8 offset1:74
	s_waitcnt vmcnt(24)
	ds_write2_b32 v41, v66, v67 offset0:140 offset1:206
	s_waitcnt vmcnt(22)
	ds_write2_b32 v42, v68, v69 offset0:16 offset1:82
	s_waitcnt vmcnt(20)
	ds_write2_b32 v42, v70, v71 offset0:148 offset1:214
	s_waitcnt vmcnt(18)
	ds_write2_b32 v43, v72, v73 offset0:24 offset1:90
	s_waitcnt vmcnt(16)
	ds_write2_b32 v43, v74, v75 offset0:156 offset1:222
	s_waitcnt vmcnt(14)
	ds_write2_b32 v44, v76, v77 offset0:32 offset1:98
	s_waitcnt vmcnt(12)
	ds_write2_b32 v44, v78, v79 offset0:164 offset1:230
	s_waitcnt vmcnt(10)
	ds_write2_b32 v45, v81, v82 offset0:40 offset1:106
	s_waitcnt vmcnt(8)
	ds_write2_b32 v45, v83, v60 offset0:172 offset1:238
	s_waitcnt vmcnt(6)
	ds_write2_b32 v46, v28, v29 offset0:48 offset1:114
	s_waitcnt vmcnt(4)
	ds_write2_b32 v46, v31, v32 offset0:180 offset1:246
	s_waitcnt vmcnt(2)
	ds_write2_b32 v47, v33, v50 offset0:56 offset1:122
	s_waitcnt vmcnt(0)
	ds_write2_b32 v47, v51, v26 offset0:188 offset1:254
	s_waitcnt lgkmcnt(0)
	ds_read2_b32 v[26:27], v37 offset1:33
	s_waitcnt lgkmcnt(0)
	v_cvt_pk_bf16_f32 v26, v26, v27
	ds_read2_b32 v[28:29], v37 offset0:66 offset1:99
	s_waitcnt lgkmcnt(0)
	v_cvt_pk_bf16_f32 v27, v28, v29
	ds_read2_b32 v[28:29], v37 offset0:132 offset1:165
	s_waitcnt lgkmcnt(0)
	v_cvt_pk_bf16_f32 v28, v28, v29
	ds_read2_b32 v[32:33], v37 offset0:198 offset1:231
	s_waitcnt lgkmcnt(0)
	v_cvt_pk_bf16_f32 v29, v32, v33
	v_or_b32_e32 v32, v24, v36
	v_ashrrev_i32_e32 v31, 31, v30
	v_ashrrev_i32_e32 v33, 31, v32
	v_lshl_add_u64 v[30:31], v[30:31], 1, v[8:9]
	v_lshlrev_b64 v[32:33], 11, v[32:33]
	v_lshl_add_u64 v[32:33], v[30:31], 0, v[32:33]
	ds_read2_b32 v[50:51], v37 offset0:8 offset1:41
	global_store_dwordx4 v[32:33], v[26:29], off sc0 sc1
	s_waitcnt lgkmcnt(0)
	s_nop 0
	v_cvt_pk_bf16_f32 v26, v50, v51
	ds_read2_b32 v[28:29], v37 offset0:74 offset1:107
	s_waitcnt lgkmcnt(0)
	v_cvt_pk_bf16_f32 v27, v28, v29
	ds_read2_b32 v[28:29], v37 offset0:140 offset1:173
	s_waitcnt lgkmcnt(0)
	v_cvt_pk_bf16_f32 v28, v28, v29
	ds_read2_b32 v[32:33], v37 offset0:206 offset1:239
	s_waitcnt lgkmcnt(0)
	v_cvt_pk_bf16_f32 v29, v32, v33
	v_or_b32_e32 v32, v24, v38
	v_ashrrev_i32_e32 v33, 31, v32
	v_lshlrev_b64 v[32:33], 11, v[32:33]
	v_lshl_add_u64 v[32:33], v[30:31], 0, v[32:33]
	ds_read2_b32 v[50:51], v37 offset0:16 offset1:49
	global_store_dwordx4 v[32:33], v[26:29], off sc0 sc1
	s_waitcnt lgkmcnt(0)
	s_nop 0
	v_cvt_pk_bf16_f32 v26, v50, v51
	ds_read2_b32 v[28:29], v37 offset0:82 offset1:115
	s_waitcnt lgkmcnt(0)
	v_cvt_pk_bf16_f32 v27, v28, v29
	ds_read2_b32 v[28:29], v37 offset0:148 offset1:181
	s_waitcnt lgkmcnt(0)
	v_cvt_pk_bf16_f32 v28, v28, v29
	ds_read2_b32 v[32:33], v37 offset0:214 offset1:247
	s_waitcnt lgkmcnt(0)
	v_cvt_pk_bf16_f32 v29, v32, v33
	v_or_b32_e32 v32, v24, v39
	v_ashrrev_i32_e32 v33, 31, v32
	v_lshlrev_b64 v[32:33], 11, v[32:33]
	v_or_b32_e32 v24, v24, v40
	v_lshl_add_u64 v[32:33], v[30:31], 0, v[32:33]
	v_ashrrev_i32_e32 v25, 31, v24
	ds_read2_b32 v[50:51], v37 offset0:24 offset1:57
	global_store_dwordx4 v[32:33], v[26:29], off sc0 sc1
	v_lshlrev_b64 v[24:25], 11, v[24:25]
	v_lshl_add_u64 v[24:25], v[30:31], 0, v[24:25]
	s_waitcnt lgkmcnt(0)
	v_cvt_pk_bf16_f32 v26, v50, v51
	ds_read2_b32 v[28:29], v37 offset0:90 offset1:123
	s_waitcnt lgkmcnt(0)
	v_cvt_pk_bf16_f32 v27, v28, v29
	ds_read2_b32 v[28:29], v37 offset0:156 offset1:189
	s_waitcnt lgkmcnt(0)
	v_cvt_pk_bf16_f32 v28, v28, v29
	ds_read2_b32 v[32:33], v37 offset0:222 offset1:255
	s_waitcnt lgkmcnt(0)
	v_cvt_pk_bf16_f32 v29, v32, v33
	global_store_dwordx4 v[24:25], v[26:29], off sc0 sc1
	s_waitcnt lgkmcnt(0)
	s_nop 1
	v_mov_b32_e32 v28, v48
	s_or_b64 exec, exec, s[4:5]
	s_and_b64 exec, exec, vcc
	s_cbranch_execz .LBB0_22

; #define LAS __attribute__((address_space(3)))
; __device__ __forceinline__ unsigned pk2(float lo, float hi) { return pg8::cvt_pk_bf16(lo, hi); }
; __device__ __forceinline__ void transpose_item(const float* W, int K, int N, bf16* WT, int k0, int n0, int drow0, LAS float* scr, int lane) {
;     float wv[32];
; #pragma unroll
;     for (int i = 0; i < 32; ++i) wv[i] = W[(size_t)(k0 + 2 * i + (lane >> 5)) * N + n0 + (lane & 31)];
; #pragma unroll
;     for (int i = 0; i < 32; ++i) scr[(2 * i + (lane >> 5)) * 33 + (lane & 31)] = wv[i];
;     asm volatile("s_waitcnt lgkmcnt(0)" ::: "memory");
;     const int c = lane & 7;
; #pragma unroll
;     for (int j = 0; j < 4; ++j) { const int n = (lane >> 3) + 8 * j; const LAS float* s = scr + (8 * c) * 33 + n;
;         u32x4 o; o.x = pk2(s[0 * 33], s[1 * 33]); o.y = pk2(s[2 * 33], s[3 * 33]); o.z = pk2(s[4 * 33], s[5 * 33]); o.w = pk2(s[6 * 33], s[7 * 33]);
;         *(u32x4*)(WT + (size_t)(drow0 + n) * K + k0 + 8 * c) = o; }
;     asm volatile("s_waitcnt lgkmcnt(0)" ::: "memory");
; }
; __device__ __forceinline__ bool transpose_job(int& it, const float* W, int K, int N, bf16* WT, int mode, LAS float* scr, int lane) {
;     const int nblk = N / 32, items = (K / 64) * nblk;
;     if (it >= items) { it -= items; return false; }
;     const int kb = it / nblk, nb = it % nblk, n0 = 32 * nb;
;     const int drow0 = mode == 0 ? n0 : (256 * (n0 >> 7) + (n0 & 127) + (mode == 2 ? 128 : 0));
;     transpose_item(W, K, N, WT, 64 * kb, n0, drow0, scr, lane);
.LBB0_51:
	v_ashrrev_i32_e32 v24, 31, v28
	v_lshrrev_b32_e32 v24, 27, v24
	s_load_dwordx2 s[20:21], s[10:11], 0x90
	v_add_u32_e32 v25, v28, v24
	v_and_b32_e32 v24, 0x7ffffe0, v25
	v_lshlrev_b32_e32 v25, 1, v25
	v_sub_u32_e32 v24, v28, v24
	v_and_b32_e32 v26, 0xffffffc0, v25
	v_lshlrev_b32_e32 v24, 5, v24
	v_or_b32_e32 v30, v26, v34
	v_ashrrev_i32_e32 v25, 31, v24
	v_or_b32_e32 v50, 2, v30
	v_or_b32_e32 v52, 4, v30
	v_or_b32_e32 v54, 6, v30
	v_or_b32_e32 v56, 8, v30
	v_or_b32_e32 v58, 10, v30
	v_or_b32_e32 v60, 12, v30
	v_or_b32_e32 v62, 14, v30
	s_waitcnt lgkmcnt(0)
	v_lshl_add_u64 v[32:33], v[24:25], 2, s[20:21]
	v_ashrrev_i32_e32 v31, 31, v30
	v_ashrrev_i32_e32 v51, 31, v50
	v_ashrrev_i32_e32 v53, 31, v52
	v_ashrrev_i32_e32 v55, 31, v54
	v_ashrrev_i32_e32 v57, 31, v56
	v_ashrrev_i32_e32 v59, 31, v58
	v_ashrrev_i32_e32 v61, 31, v60
	v_ashrrev_i32_e32 v63, 31, v62
	v_lshl_add_u64 v[32:33], v[32:33], 0, v[4:5]
	v_lshlrev_b64 v[48:49], 12, v[30:31]
	v_lshlrev_b64 v[50:51], 12, v[50:51]
	v_lshlrev_b64 v[52:53], 12, v[52:53]
	v_lshlrev_b64 v[54:55], 12, v[54:55]
	v_lshlrev_b64 v[56:57], 12, v[56:57]
	v_lshlrev_b64 v[58:59], 12, v[58:59]
	v_lshlrev_b64 v[60:61], 12, v[60:61]
	v_lshlrev_b64 v[62:63], 12, v[62:63]
	v_lshl_add_u64 v[48:49], v[32:33], 0, v[48:49]
	v_lshl_add_u64 v[50:51], v[32:33], 0, v[50:51]
	v_lshl_add_u64 v[52:53], v[32:33], 0, v[52:53]
	v_lshl_add_u64 v[54:55], v[32:33], 0, v[54:55]
	v_lshl_add_u64 v[56:57], v[32:33], 0, v[56:57]
	v_lshl_add_u64 v[58:59], v[32:33], 0, v[58:59]
	v_lshl_add_u64 v[60:61], v[32:33], 0, v[60:61]
	v_lshl_add_u64 v[62:63], v[32:33], 0, v[62:63]
	global_load_dword v25, v[48:49], off
	global_load_dword v27, v[50:51], off
	global_load_dword v29, v[52:53], off
	global_load_dword v64, v[54:55], off
	global_load_dword v65, v[56:57], off
	global_load_dword v66, v[58:59], off
	global_load_dword v67, v[60:61], off
	global_load_dword v68, v[62:63], off
	v_or_b32_e32 v48, 16, v30
	v_or_b32_e32 v50, 18, v30
	v_or_b32_e32 v52, 20, v30
	v_or_b32_e32 v54, 22, v30
	v_or_b32_e32 v56, 24, v30
	v_or_b32_e32 v58, 26, v30
	v_or_b32_e32 v60, 28, v30
	v_or_b32_e32 v62, 30, v30
	v_ashrrev_i32_e32 v49, 31, v48
	v_ashrrev_i32_e32 v51, 31, v50
	v_ashrrev_i32_e32 v53, 31, v52
	v_ashrrev_i32_e32 v55, 31, v54
	v_ashrrev_i32_e32 v57, 31, v56
	v_ashrrev_i32_e32 v59, 31, v58
	v_ashrrev_i32_e32 v61, 31, v60
	v_ashrrev_i32_e32 v63, 31, v62
	v_lshlrev_b64 v[48:49], 12, v[48:49]
	v_lshlrev_b64 v[50:51], 12, v[50:51]
	v_lshlrev_b64 v[52:53], 12, v[52:53]
	v_lshlrev_b64 v[54:55], 12, v[54:55]
	v_lshlrev_b64 v[56:57], 12, v[56:57]
	v_lshlrev_b64 v[58:59], 12, v[58:59]
	v_lshlrev_b64 v[60:61], 12, v[60:61]
	v_lshlrev_b64 v[62:63], 12, v[62:63]
	v_lshl_add_u64 v[48:49], v[32:33], 0, v[48:49]
	v_lshl_add_u64 v[50:51], v[32:33], 0, v[50:51]
	v_lshl_add_u64 v[52:53], v[32:33], 0, v[52:53]
	v_lshl_add_u64 v[54:55], v[32:33], 0, v[54:55]
	v_lshl_add_u64 v[56:57], v[32:33], 0, v[56:57]
	v_lshl_add_u64 v[58:59], v[32:33], 0, v[58:59]
	v_lshl_add_u64 v[60:61], v[32:33], 0, v[60:61]
	v_lshl_add_u64 v[62:63], v[32:33], 0, v[62:63]
	global_load_dword v69, v[48:49], off
	global_load_dword v70, v[50:51], off
	global_load_dword v71, v[52:53], off
	global_load_dword v72, v[54:55], off
	global_load_dword v73, v[56:57], off
	global_load_dword v74, v[58:59], off
	global_load_dword v75, v[60:61], off
	global_load_dword v76, v[62:63], off
	v_or_b32_e32 v48, 32, v30
	v_or_b32_e32 v50, 34, v30
	v_or_b32_e32 v52, 36, v30
	v_or_b32_e32 v54, 38, v30
	v_or_b32_e32 v56, 40, v30
	v_or_b32_e32 v58, 42, v30
	v_or_b32_e32 v60, 44, v30
	v_or_b32_e32 v62, 46, v30
	v_ashrrev_i32_e32 v49, 31, v48
	v_ashrrev_i32_e32 v51, 31, v50
	v_ashrrev_i32_e32 v53, 31, v52
	v_ashrrev_i32_e32 v55, 31, v54
	v_ashrrev_i32_e32 v57, 31, v56
	v_ashrrev_i32_e32 v59, 31, v58
	v_ashrrev_i32_e32 v61, 31, v60
	v_ashrrev_i32_e32 v63, 31, v62
	v_lshlrev_b64 v[48:49], 12, v[48:49]
	v_lshlrev_b64 v[50:51], 12, v[50:51]
	v_lshlrev_b64 v[52:53], 12, v[52:53]
	v_lshlrev_b64 v[54:55], 12, v[54:55]
	v_lshlrev_b64 v[56:57], 12, v[56:57]
	v_lshlrev_b64 v[58:59], 12, v[58:59]
	v_lshlrev_b64 v[60:61], 12, v[60:61]
	v_lshlrev_b64 v[62:63], 12, v[62:63]
	v_lshl_add_u64 v[48:49], v[32:33], 0, v[48:49]
	v_lshl_add_u64 v[50:51], v[32:33], 0, v[50:51]
	v_lshl_add_u64 v[52:53], v[32:33], 0, v[52:53]
	v_lshl_add_u64 v[54:55], v[32:33], 0, v[54:55]
	v_lshl_add_u64 v[56:57], v[32:33], 0, v[56:57]
	v_lshl_add_u64 v[58:59], v[32:33], 0, v[58:59]
	v_lshl_add_u64 v[60:61], v[32:33], 0, v[60:61]
	v_lshl_add_u64 v[62:63], v[32:33], 0, v[62:63]
	global_load_dword v77, v[48:49], off
	global_load_dword v78, v[50:51], off
	global_load_dword v79, v[52:53], off
	global_load_dword v81, v[54:55], off
	global_load_dword v82, v[56:57], off
	global_load_dword v83, v[58:59], off
	global_load_dword v84, v[60:61], off
	s_nop 0
	global_load_dword v62, v[62:63], off
	v_or_b32_e32 v48, 48, v30
	v_or_b32_e32 v50, 50, v30
	v_or_b32_e32 v52, 52, v30
	v_or_b32_e32 v54, 54, v30
	v_or_b32_e32 v56, 56, v30
	v_or_b32_e32 v58, 58, v30
	v_or_b32_e32 v60, 60, v30
	v_or_b32_e32 v30, 62, v30
	v_ashrrev_i32_e32 v49, 31, v48
	v_ashrrev_i32_e32 v51, 31, v50
	v_ashrrev_i32_e32 v53, 31, v52
	v_ashrrev_i32_e32 v31, 31, v30
	v_lshlrev_b64 v[48:49], 12, v[48:49]
	v_lshlrev_b64 v[50:51], 12, v[50:51]
	v_lshlrev_b64 v[52:53], 12, v[52:53]
	v_ashrrev_i32_e32 v55, 31, v54
	v_ashrrev_i32_e32 v57, 31, v56
	v_ashrrev_i32_e32 v59, 31, v58
	v_ashrrev_i32_e32 v61, 31, v60
	v_lshlrev_b64 v[30:31], 12, v[30:31]
	v_lshl_add_u64 v[48:49], v[32:33], 0, v[48:49]
	v_lshl_add_u64 v[50:51], v[32:33], 0, v[50:51]
	v_lshl_add_u64 v[52:53], v[32:33], 0, v[52:53]
	v_lshlrev_b64 v[54:55], 12, v[54:55]
	v_lshlrev_b64 v[56:57], 12, v[56:57]
	v_lshlrev_b64 v[58:59], 12, v[58:59]
	v_lshlrev_b64 v[60:61], 12, v[60:61]
	v_lshl_add_u64 v[30:31], v[32:33], 0, v[30:31]
	v_lshl_add_u64 v[54:55], v[32:33], 0, v[54:55]
	v_lshl_add_u64 v[56:57], v[32:33], 0, v[56:57]
	v_lshl_add_u64 v[58:59], v[32:33], 0, v[58:59]
	v_lshl_add_u64 v[60:61], v[32:33], 0, v[60:61]
	global_load_dword v32, v[48:49], off
	global_load_dword v33, v[50:51], off
	s_nop 0
	global_load_dword v48, v[52:53], off
	global_load_dword v49, v[54:55], off
	global_load_dword v50, v[56:57], off
	global_load_dword v51, v[58:59], off
	s_nop 0
	global_load_dword v52, v[60:61], off
	s_nop 0
	global_load_dword v30, v[30:31], off
	s_waitcnt vmcnt(30)
; #define LAS __attribute__((address_space(3)))
; __device__ __forceinline__ unsigned pk2(float lo, float hi) { return pg8::cvt_pk_bf16(lo, hi); }
; __device__ __forceinline__ void transpose_item(const float* W, int K, int N, bf16* WT, int k0, int n0, int drow0, LAS float* scr, int lane) {
;     ...
;     for (int i = 0; i < 32; ++i) scr[(2 * i + (lane >> 5)) * 33 + (lane & 31)] = wv[i];
;     asm volatile("s_waitcnt lgkmcnt(0)" ::: "memory");
;     const int c = lane & 7;
; #pragma unroll
;     for (int j = 0; j < 4; ++j) { const int n = (lane >> 3) + 8 * j; const LAS float* s = scr + (8 * c) * 33 + n;
;         u32x4 o; o.x = pk2(s[0 * 33], s[1 * 33]); o.y = pk2(s[2 * 33], s[3 * 33]); o.z = pk2(s[4 * 33], s[5 * 33]); o.w = pk2(s[6 * 33], s[7 * 33]);
;         *(u32x4*)(WT + (size_t)(drow0 + n) * K + k0 + 8 * c) = o; }
;     asm volatile("s_waitcnt lgkmcnt(0)" ::: "memory");
	ds_write2_b32 v35, v25, v27 offset1:66
	s_waitcnt vmcnt(28)
	ds_write2_b32 v35, v29, v64 offset0:132 offset1:198
	s_waitcnt vmcnt(26)
	ds_write2_b32 v41, v65, v66 offset0:8 offset1:74
	s_waitcnt vmcnt(24)
	ds_write2_b32 v41, v67, v68 offset0:140 offset1:206
	s_waitcnt vmcnt(22)
	ds_write2_b32 v42, v69, v70 offset0:16 offset1:82
	s_waitcnt vmcnt(20)
	ds_write2_b32 v42, v71, v72 offset0:148 offset1:214
	s_waitcnt vmcnt(18)
	ds_write2_b32 v43, v73, v74 offset0:24 offset1:90
	s_waitcnt vmcnt(16)
	ds_write2_b32 v43, v75, v76 offset0:156 offset1:222
	s_waitcnt vmcnt(14)
	ds_write2_b32 v44, v77, v78 offset0:32 offset1:98
	s_waitcnt vmcnt(12)
	ds_write2_b32 v44, v79, v81 offset0:164 offset1:230
	s_waitcnt vmcnt(10)
	ds_write2_b32 v45, v82, v83 offset0:40 offset1:106
	s_waitcnt vmcnt(8)
	ds_write2_b32 v45, v84, v62 offset0:172 offset1:238
	s_waitcnt vmcnt(6)
	ds_write2_b32 v46, v32, v33 offset0:48 offset1:114
	s_waitcnt vmcnt(4)
	ds_write2_b32 v46, v48, v49 offset0:180 offset1:246
	s_waitcnt vmcnt(2)
	ds_write2_b32 v47, v50, v51 offset0:56 offset1:122
	s_waitcnt vmcnt(0)
	ds_write2_b32 v47, v52, v30 offset0:188 offset1:254
	s_waitcnt lgkmcnt(0)
	ds_read2_b32 v[30:31], v37 offset1:33
	s_waitcnt lgkmcnt(0)
	v_cvt_pk_bf16_f32 v30, v30, v31
	ds_read2_b32 v[32:33], v37 offset0:66 offset1:99
	s_waitcnt lgkmcnt(0)
	v_cvt_pk_bf16_f32 v31, v32, v33
	ds_read2_b32 v[32:33], v37 offset0:132 offset1:165
	s_waitcnt lgkmcnt(0)
	v_cvt_pk_bf16_f32 v32, v32, v33
	ds_read2_b32 v[48:49], v37 offset0:198 offset1:231
	s_waitcnt lgkmcnt(0)
	v_cvt_pk_bf16_f32 v33, v48, v49
	v_or_b32_e32 v48, v24, v36
	v_ashrrev_i32_e32 v27, 31, v26
	v_ashrrev_i32_e32 v49, 31, v48
	v_lshl_add_u64 v[26:27], v[26:27], 1, v[10:11]
	v_lshlrev_b64 v[48:49], 11, v[48:49]
	v_lshl_add_u64 v[48:49], v[26:27], 0, v[48:49]
	ds_read2_b32 v[50:51], v37 offset0:8 offset1:41
	global_store_dwordx4 v[48:49], v[30:33], off sc0 sc1
	s_waitcnt lgkmcnt(0)
	s_nop 0
	v_cvt_pk_bf16_f32 v30, v50, v51
	ds_read2_b32 v[32:33], v37 offset0:74 offset1:107
	s_waitcnt lgkmcnt(0)
	v_cvt_pk_bf16_f32 v31, v32, v33
	ds_read2_b32 v[32:33], v37 offset0:140 offset1:173
	s_waitcnt lgkmcnt(0)
	v_cvt_pk_bf16_f32 v32, v32, v33
	ds_read2_b32 v[48:49], v37 offset0:206 offset1:239
	s_waitcnt lgkmcnt(0)
	v_cvt_pk_bf16_f32 v33, v48, v49
	v_or_b32_e32 v48, v24, v38
	v_ashrrev_i32_e32 v49, 31, v48
	v_lshlrev_b64 v[48:49], 11, v[48:49]
	v_lshl_add_u64 v[48:49], v[26:27], 0, v[48:49]
	ds_read2_b32 v[50:51], v37 offset0:16 offset1:49
	global_store_dwordx4 v[48:49], v[30:33], off sc0 sc1
	s_waitcnt lgkmcnt(0)
	s_nop 0
	v_cvt_pk_bf16_f32 v30, v50, v51
	ds_read2_b32 v[32:33], v37 offset0:82 offset1:115
	s_waitcnt lgkmcnt(0)
	v_cvt_pk_bf16_f32 v31, v32, v33
	ds_read2_b32 v[32:33], v37 offset0:148 offset1:181
	s_waitcnt lgkmcnt(0)
	v_cvt_pk_bf16_f32 v32, v32, v33
	ds_read2_b32 v[48:49], v37 offset0:214 offset1:247
	s_waitcnt lgkmcnt(0)
	v_cvt_pk_bf16_f32 v33, v48, v49
	v_or_b32_e32 v48, v24, v39
	v_ashrrev_i32_e32 v49, 31, v48
	v_lshlrev_b64 v[48:49], 11, v[48:49]
	v_or_b32_e32 v24, v24, v40
	v_lshl_add_u64 v[48:49], v[26:27], 0, v[48:49]
	v_ashrrev_i32_e32 v25, 31, v24
	ds_read2_b32 v[50:51], v37 offset0:24 offset1:57
	global_store_dwordx4 v[48:49], v[30:33], off sc0 sc1
	v_lshlrev_b64 v[24:25], 11, v[24:25]
	v_lshl_add_u64 v[24:25], v[26:27], 0, v[24:25]
	s_waitcnt lgkmcnt(0)
	v_cvt_pk_bf16_f32 v30, v50, v51
	ds_read2_b32 v[32:33], v37 offset0:90 offset1:123
	s_waitcnt lgkmcnt(0)
	v_cvt_pk_bf16_f32 v31, v32, v33
	ds_read2_b32 v[32:33], v37 offset0:156 offset1:189
	s_waitcnt lgkmcnt(0)
	v_cvt_pk_bf16_f32 v32, v32, v33
	ds_read2_b32 v[48:49], v37 offset0:222 offset1:255
	s_waitcnt lgkmcnt(0)
	v_cvt_pk_bf16_f32 v33, v48, v49
	global_store_dwordx4 v[24:25], v[30:33], off sc0 sc1
	s_waitcnt lgkmcnt(0)
	s_or_b64 exec, exec, s[4:5]
	s_and_b64 exec, exec, vcc
	s_cbranch_execz .LBB0_22

; #define LAS __attribute__((address_space(3)))
; __device__ __forceinline__ unsigned pk2(float lo, float hi) { return pg8::cvt_pk_bf16(lo, hi); }
; __device__ __forceinline__ void transpose_item(const float* W, int K, int N, bf16* WT, int k0, int n0, int drow0, LAS float* scr, int lane) {
;     float wv[32];
; #pragma unroll
;     for (int i = 0; i < 32; ++i) wv[i] = W[(size_t)(k0 + 2 * i + (lane >> 5)) * N + n0 + (lane & 31)];
; #pragma unroll
;     for (int i = 0; i < 32; ++i) scr[(2 * i + (lane >> 5)) * 33 + (lane & 31)] = wv[i];
;     asm volatile("s_waitcnt lgkmcnt(0)" ::: "memory");
;     const int c = lane & 7;
; #pragma unroll
;     for (int j = 0; j < 4; ++j) { const int n = (lane >> 3) + 8 * j; const LAS float* s = scr + (8 * c) * 33 + n;
;         u32x4 o; o.x = pk2(s[0 * 33], s[1 * 33]); o.y = pk2(s[2 * 33], s[3 * 33]); o.z = pk2(s[4 * 33], s[5 * 33]); o.w = pk2(s[6 * 33], s[7 * 33]);
;         *(u32x4*)(WT + (size_t)(drow0 + n) * K + k0 + 8 * c) = o; }
;     asm volatile("s_waitcnt lgkmcnt(0)" ::: "memory");
; }
; __device__ __forceinline__ bool transpose_job(int& it, const float* W, int K, int N, bf16* WT, int mode, LAS float* scr, int lane) {
;     const int nblk = N / 32, items = (K / 64) * nblk;
;     if (it >= items) { it -= items; return false; }
;     const int kb = it / nblk, nb = it % nblk, n0 = 32 * nb;
;     const int drow0 = mode == 0 ? n0 : (256 * (n0 >> 7) + (n0 & 127) + (mode == 2 ? 128 : 0));
;     transpose_item(W, K, N, WT, 64 * kb, n0, drow0, scr, lane);
.LBB0_56:
	v_mul_hi_i32 v24, v28, s45
	v_lshrrev_b32_e32 v25, 31, v24
	v_ashrrev_i32_e32 v24, 2, v24
	s_load_dwordx2 s[20:21], s[10:11], 0xb0
	v_add_u32_e32 v25, v24, v25
	v_mul_lo_u32 v24, v25, 21
	v_sub_u32_e32 v24, v28, v24
	v_lshlrev_b32_e32 v24, 5, v24
	v_lshlrev_b32_e32 v26, 6, v25
	v_ashrrev_i32_e32 v25, 31, v24
	v_or_b32_e32 v27, v26, v34
	s_waitcnt lgkmcnt(0)
	v_lshl_add_u64 v[30:31], v[24:25], 2, s[20:21]
	v_lshl_add_u64 v[30:31], v[30:31], 0, v[4:5]
	v_or_b32_e32 v25, 2, v27
	v_mad_i64_i32 v[48:49], s[20:21], v25, s46, v[30:31]
	v_or_b32_e32 v25, 4, v27
	v_mad_i64_i32 v[50:51], s[20:21], v25, s46, v[30:31]
	v_or_b32_e32 v25, 6, v27
	v_mad_i64_i32 v[52:53], s[20:21], v25, s46, v[30:31]
	v_or_b32_e32 v25, 8, v27
	v_mad_i64_i32 v[54:55], s[20:21], v25, s46, v[30:31]
	v_or_b32_e32 v25, 10, v27
	v_mad_i64_i32 v[56:57], s[20:21], v25, s46, v[30:31]
	v_or_b32_e32 v25, 12, v27
	v_mad_i64_i32 v[58:59], s[20:21], v25, s46, v[30:31]
	v_or_b32_e32 v25, 14, v27
	v_mad_i64_i32 v[32:33], s[20:21], v27, s46, v[30:31]
	v_mad_i64_i32 v[60:61], s[20:21], v25, s46, v[30:31]
	global_load_dword v25, v[32:33], off
	global_load_dword v29, v[48:49], off
	global_load_dword v62, v[50:51], off
	global_load_dword v63, v[52:53], off
	global_load_dword v64, v[54:55], off
	global_load_dword v65, v[56:57], off
	global_load_dword v66, v[58:59], off
	global_load_dword v67, v[60:61], off
	v_or_b32_e32 v32, 16, v27
	v_or_b32_e32 v48, 18, v27
	v_or_b32_e32 v50, 20, v27
	v_or_b32_e32 v52, 22, v27
	v_or_b32_e32 v54, 24, v27
	v_or_b32_e32 v56, 26, v27
	v_or_b32_e32 v58, 28, v27
	v_or_b32_e32 v60, 30, v27
	v_mad_i64_i32 v[32:33], s[20:21], v32, s46, v[30:31]
	v_mad_i64_i32 v[48:49], s[20:21], v48, s46, v[30:31]
	v_mad_i64_i32 v[50:51], s[20:21], v50, s46, v[30:31]
	v_mad_i64_i32 v[52:53], s[20:21], v52, s46, v[30:31]
	v_mad_i64_i32 v[54:55], s[20:21], v54, s46, v[30:31]
	v_mad_i64_i32 v[56:57], s[20:21], v56, s46, v[30:31]
	v_mad_i64_i32 v[58:59], s[20:21], v58, s46, v[30:31]
	v_mad_i64_i32 v[60:61], s[20:21], v60, s46, v[30:31]
	global_load_dword v68, v[32:33], off
	global_load_dword v69, v[48:49], off
	global_load_dword v70, v[50:51], off
	global_load_dword v71, v[52:53], off
	global_load_dword v72, v[54:55], off
	global_load_dword v73, v[56:57], off
	global_load_dword v74, v[58:59], off
	global_load_dword v75, v[60:61], off
	v_or_b32_e32 v32, 32, v27
	v_or_b32_e32 v48, 34, v27
	v_or_b32_e32 v50, 36, v27
	v_or_b32_e32 v52, 38, v27
	v_or_b32_e32 v54, 40, v27
	v_or_b32_e32 v56, 42, v27
	v_or_b32_e32 v58, 44, v27
	v_or_b32_e32 v60, 46, v27
	v_mad_i64_i32 v[32:33], s[20:21], v32, s46, v[30:31]
	v_mad_i64_i32 v[48:49], s[20:21], v48, s46, v[30:31]
	v_mad_i64_i32 v[50:51], s[20:21], v50, s46, v[30:31]
	v_mad_i64_i32 v[52:53], s[20:21], v52, s46, v[30:31]
	v_mad_i64_i32 v[54:55], s[20:21], v54, s46, v[30:31]
	v_mad_i64_i32 v[56:57], s[20:21], v56, s46, v[30:31]
	v_mad_i64_i32 v[58:59], s[20:21], v58, s46, v[30:31]
	v_mad_i64_i32 v[60:61], s[20:21], v60, s46, v[30:31]
	global_load_dword v76, v[32:33], off
	global_load_dword v77, v[48:49], off
	global_load_dword v78, v[50:51], off
	global_load_dword v79, v[52:53], off
	global_load_dword v81, v[54:55], off
	global_load_dword v82, v[56:57], off
	global_load_dword v83, v[58:59], off
	s_nop 0
	global_load_dword v60, v[60:61], off
	v_or_b32_e32 v32, 48, v27
	v_or_b32_e32 v48, 50, v27
	v_or_b32_e32 v50, 52, v27
	v_or_b32_e32 v52, 54, v27
	v_or_b32_e32 v54, 56, v27
	v_or_b32_e32 v56, 58, v27
	v_or_b32_e32 v58, 60, v27
	v_or_b32_e32 v27, 62, v27
	v_mad_i64_i32 v[32:33], s[20:21], v32, s46, v[30:31]
	v_mad_i64_i32 v[48:49], s[20:21], v48, s46, v[30:31]
	v_mad_i64_i32 v[50:51], s[20:21], v50, s46, v[30:31]
	v_mad_i64_i32 v[52:53], s[20:21], v52, s46, v[30:31]
	v_mad_i64_i32 v[54:55], s[20:21], v54, s46, v[30:31]
	v_mad_i64_i32 v[56:57], s[20:21], v56, s46, v[30:31]
	v_mad_i64_i32 v[58:59], s[20:21], v58, s46, v[30:31]
	v_mad_i64_i32 v[30:31], s[20:21], v27, s46, v[30:31]
	global_load_dword v27, v[32:33], off
	s_nop 0
	global_load_dword v32, v[48:49], off
	global_load_dword v33, v[50:51], off
	s_nop 0
	global_load_dword v48, v[52:53], off
	global_load_dword v49, v[54:55], off
	global_load_dword v50, v[56:57], off
	global_load_dword v51, v[58:59], off
	s_nop 0
	global_load_dword v30, v[30:31], off
	s_waitcnt vmcnt(30)
; #define LAS __attribute__((address_space(3)))
; __device__ __forceinline__ unsigned pk2(float lo, float hi) { return pg8::cvt_pk_bf16(lo, hi); }
; __device__ __forceinline__ void transpose_item(const float* W, int K, int N, bf16* WT, int k0, int n0, int drow0, LAS float* scr, int lane) {
;     ...
;     for (int i = 0; i < 32; ++i) scr[(2 * i + (lane >> 5)) * 33 + (lane & 31)] = wv[i];
;     asm volatile("s_waitcnt lgkmcnt(0)" ::: "memory");
;     const int c = lane & 7;
; #pragma unroll
;     for (int j = 0; j < 4; ++j) { const int n = (lane >> 3) + 8 * j; const LAS float* s = scr + (8 * c) * 33 + n;
;         u32x4 o; o.x = pk2(s[0 * 33], s[1 * 33]); o.y = pk2(s[2 * 33], s[3 * 33]); o.z = pk2(s[4 * 33], s[5 * 33]); o.w = pk2(s[6 * 33], s[7 * 33]);
;         *(u32x4*)(WT + (size_t)(drow0 + n) * K + k0 + 8 * c) = o; }
;     asm volatile("s_waitcnt lgkmcnt(0)" ::: "memory");
	ds_write2_b32 v35, v25, v29 offset1:66
	s_waitcnt vmcnt(28)
	ds_write2_b32 v35, v62, v63 offset0:132 offset1:198
	s_waitcnt vmcnt(26)
	ds_write2_b32 v41, v64, v65 offset0:8 offset1:74
	s_waitcnt vmcnt(24)
	ds_write2_b32 v41, v66, v67 offset0:140 offset1:206
	s_waitcnt vmcnt(22)
	ds_write2_b32 v42, v68, v69 offset0:16 offset1:82
	s_waitcnt vmcnt(20)
	ds_write2_b32 v42, v70, v71 offset0:148 offset1:214
	s_waitcnt vmcnt(18)
	ds_write2_b32 v43, v72, v73 offset0:24 offset1:90
	s_waitcnt vmcnt(16)
	ds_write2_b32 v43, v74, v75 offset0:156 offset1:222
	s_waitcnt vmcnt(14)
	ds_write2_b32 v44, v76, v77 offset0:32 offset1:98
	s_waitcnt vmcnt(12)
	ds_write2_b32 v44, v78, v79 offset0:164 offset1:230
	s_waitcnt vmcnt(10)
	ds_write2_b32 v45, v81, v82 offset0:40 offset1:106
	s_waitcnt vmcnt(8)
	ds_write2_b32 v45, v83, v60 offset0:172 offset1:238
	s_waitcnt vmcnt(6)
	ds_write2_b32 v46, v27, v32 offset0:48 offset1:114
	s_waitcnt vmcnt(4)
	ds_write2_b32 v46, v33, v48 offset0:180 offset1:246
	s_waitcnt vmcnt(2)
	ds_write2_b32 v47, v49, v50 offset0:56 offset1:122
	s_waitcnt vmcnt(0)
	ds_write2_b32 v47, v51, v30 offset0:188 offset1:254
	s_waitcnt lgkmcnt(0)
	ds_read2_b32 v[30:31], v37 offset1:33
	s_waitcnt lgkmcnt(0)
	v_cvt_pk_bf16_f32 v30, v30, v31
	ds_read2_b32 v[32:33], v37 offset0:66 offset1:99
	s_waitcnt lgkmcnt(0)
	v_cvt_pk_bf16_f32 v31, v32, v33
	ds_read2_b32 v[32:33], v37 offset0:132 offset1:165
	s_waitcnt lgkmcnt(0)
	v_cvt_pk_bf16_f32 v32, v32, v33
	ds_read2_b32 v[48:49], v37 offset0:198 offset1:231
	s_waitcnt lgkmcnt(0)
	v_cvt_pk_bf16_f32 v33, v48, v49
	v_or_b32_e32 v48, v24, v36
	v_ashrrev_i32_e32 v27, 31, v26
	v_ashrrev_i32_e32 v49, 31, v48
	v_lshl_add_u64 v[26:27], v[26:27], 1, v[12:13]
	v_lshlrev_b64 v[48:49], 11, v[48:49]
	v_lshl_add_u64 v[48:49], v[26:27], 0, v[48:49]
	ds_read2_b32 v[50:51], v37 offset0:8 offset1:41
	global_store_dwordx4 v[48:49], v[30:33], off sc0 sc1
	s_waitcnt lgkmcnt(0)
	s_nop 0
	v_cvt_pk_bf16_f32 v30, v50, v51
	ds_read2_b32 v[32:33], v37 offset0:74 offset1:107
	s_waitcnt lgkmcnt(0)
	v_cvt_pk_bf16_f32 v31, v32, v33
	ds_read2_b32 v[32:33], v37 offset0:140 offset1:173
	s_waitcnt lgkmcnt(0)
	v_cvt_pk_bf16_f32 v32, v32, v33
	ds_read2_b32 v[48:49], v37 offset0:206 offset1:239
	s_waitcnt lgkmcnt(0)
	v_cvt_pk_bf16_f32 v33, v48, v49
	v_or_b32_e32 v48, v24, v38
	v_ashrrev_i32_e32 v49, 31, v48
	v_lshlrev_b64 v[48:49], 11, v[48:49]
	v_lshl_add_u64 v[48:49], v[26:27], 0, v[48:49]
	ds_read2_b32 v[50:51], v37 offset0:16 offset1:49
	global_store_dwordx4 v[48:49], v[30:33], off sc0 sc1
	s_waitcnt lgkmcnt(0)
	s_nop 0
	v_cvt_pk_bf16_f32 v30, v50, v51
	ds_read2_b32 v[32:33], v37 offset0:82 offset1:115
	s_waitcnt lgkmcnt(0)
	v_cvt_pk_bf16_f32 v31, v32, v33
	ds_read2_b32 v[32:33], v37 offset0:148 offset1:181
	s_waitcnt lgkmcnt(0)
	v_cvt_pk_bf16_f32 v32, v32, v33
	ds_read2_b32 v[48:49], v37 offset0:214 offset1:247
	s_waitcnt lgkmcnt(0)
	v_cvt_pk_bf16_f32 v33, v48, v49
	v_or_b32_e32 v48, v24, v39
	v_ashrrev_i32_e32 v49, 31, v48
	v_lshlrev_b64 v[48:49], 11, v[48:49]
	v_or_b32_e32 v24, v24, v40
	v_lshl_add_u64 v[48:49], v[26:27], 0, v[48:49]
	v_ashrrev_i32_e32 v25, 31, v24
	ds_read2_b32 v[50:51], v37 offset0:24 offset1:57
	global_store_dwordx4 v[48:49], v[30:33], off sc0 sc1
	v_lshlrev_b64 v[24:25], 11, v[24:25]
	v_lshl_add_u64 v[24:25], v[26:27], 0, v[24:25]
	s_waitcnt lgkmcnt(0)
	v_cvt_pk_bf16_f32 v30, v50, v51
	ds_read2_b32 v[32:33], v37 offset0:90 offset1:123
	s_waitcnt lgkmcnt(0)
	v_cvt_pk_bf16_f32 v31, v32, v33
	ds_read2_b32 v[32:33], v37 offset0:156 offset1:189
	s_waitcnt lgkmcnt(0)
	v_cvt_pk_bf16_f32 v32, v32, v33
	ds_read2_b32 v[48:49], v37 offset0:222 offset1:255
	s_waitcnt lgkmcnt(0)
	v_cvt_pk_bf16_f32 v33, v48, v49
	global_store_dwordx4 v[24:25], v[30:33], off sc0 sc1
	s_waitcnt lgkmcnt(0)
	s_or_b64 exec, exec, s[4:5]
	s_and_b64 exec, exec, vcc
	s_cbranch_execz .LBB0_22

; #define LAS __attribute__((address_space(3)))
; __device__ __forceinline__ unsigned pk2(float lo, float hi) { return pg8::cvt_pk_bf16(lo, hi); }
; __device__ __forceinline__ void transpose_item(const float* W, int K, int N, bf16* WT, int k0, int n0, int drow0, LAS float* scr, int lane) {
;     float wv[32];
; #pragma unroll
;     for (int i = 0; i < 32; ++i) wv[i] = W[(size_t)(k0 + 2 * i + (lane >> 5)) * N + n0 + (lane & 31)];
; #pragma unroll
;     for (int i = 0; i < 32; ++i) scr[(2 * i + (lane >> 5)) * 33 + (lane & 31)] = wv[i];
;     asm volatile("s_waitcnt lgkmcnt(0)" ::: "memory");
;     const int c = lane & 7;
; #pragma unroll
;     for (int j = 0; j < 4; ++j) { const int n = (lane >> 3) + 8 * j; const LAS float* s = scr + (8 * c) * 33 + n;
;         u32x4 o; o.x = pk2(s[0 * 33], s[1 * 33]); o.y = pk2(s[2 * 33], s[3 * 33]); o.z = pk2(s[4 * 33], s[5 * 33]); o.w = pk2(s[6 * 33], s[7 * 33]);
;         *(u32x4*)(WT + (size_t)(drow0 + n) * K + k0 + 8 * c) = o; }
;     asm volatile("s_waitcnt lgkmcnt(0)" ::: "memory");
; }
; __device__ __forceinline__ bool transpose_job(int& it, const float* W, int K, int N, bf16* WT, int mode, LAS float* scr, int lane) {
;     const int nblk = N / 32, items = (K / 64) * nblk;
;     if (it >= items) { it -= items; return false; }
;     const int kb = it / nblk, nb = it % nblk, n0 = 32 * nb;
;     const int drow0 = mode == 0 ? n0 : (256 * (n0 >> 7) + (n0 & 127) + (mode == 2 ? 128 : 0));
;     transpose_item(W, K, N, WT, 64 * kb, n0, drow0, scr, lane);
;     return true;
; }
.LBB0_61:
	v_mul_hi_i32 v24, v28, s48
	v_lshrrev_b32_e32 v25, 31, v24
	v_ashrrev_i32_e32 v24, 3, v24
	s_load_dwordx2 s[20:21], s[10:11], 0xc8
	v_add_u32_e32 v25, v24, v25
	v_mul_lo_u32 v24, v25, 48
	v_sub_u32_e32 v24, v28, v24
	v_lshlrev_b32_e32 v24, 5, v24
	v_lshlrev_b32_e32 v26, 6, v25
	v_ashrrev_i32_e32 v25, 31, v24
	v_or_b32_e32 v27, v26, v34
	s_waitcnt lgkmcnt(0)
	v_lshl_add_u64 v[30:31], v[24:25], 2, s[20:21]
	v_lshl_add_u64 v[30:31], v[30:31], 0, v[4:5]
	v_or_b32_e32 v25, 2, v27
	v_mad_i64_i32 v[48:49], s[20:21], v25, s49, v[30:31]
	v_or_b32_e32 v25, 4, v27
	v_mad_i64_i32 v[50:51], s[20:21], v25, s49, v[30:31]
	v_or_b32_e32 v25, 6, v27
	v_mad_i64_i32 v[52:53], s[20:21], v25, s49, v[30:31]
	v_or_b32_e32 v25, 8, v27
	v_mad_i64_i32 v[54:55], s[20:21], v25, s49, v[30:31]
	v_or_b32_e32 v25, 10, v27
	v_mad_i64_i32 v[56:57], s[20:21], v25, s49, v[30:31]
	v_or_b32_e32 v25, 12, v27
	v_mad_i64_i32 v[58:59], s[20:21], v25, s49, v[30:31]
	v_or_b32_e32 v25, 14, v27
	v_mad_i64_i32 v[32:33], s[20:21], v27, s49, v[30:31]
	v_mad_i64_i32 v[60:61], s[20:21], v25, s49, v[30:31]
	global_load_dword v25, v[32:33], off
	global_load_dword v29, v[48:49], off
	global_load_dword v62, v[50:51], off
	global_load_dword v63, v[52:53], off
	global_load_dword v64, v[54:55], off
	global_load_dword v65, v[56:57], off
	global_load_dword v66, v[58:59], off
	global_load_dword v67, v[60:61], off
	v_or_b32_e32 v32, 16, v27
	v_or_b32_e32 v48, 18, v27
	v_or_b32_e32 v50, 20, v27
	v_or_b32_e32 v52, 22, v27
	v_or_b32_e32 v54, 24, v27
	v_or_b32_e32 v56, 26, v27
	v_or_b32_e32 v58, 28, v27
	v_or_b32_e32 v60, 30, v27
	v_mad_i64_i32 v[32:33], s[20:21], v32, s49, v[30:31]
	v_mad_i64_i32 v[48:49], s[20:21], v48, s49, v[30:31]
	v_mad_i64_i32 v[50:51], s[20:21], v50, s49, v[30:31]
	v_mad_i64_i32 v[52:53], s[20:21], v52, s49, v[30:31]
	v_mad_i64_i32 v[54:55], s[20:21], v54, s49, v[30:31]
	v_mad_i64_i32 v[56:57], s[20:21], v56, s49, v[30:31]
	v_mad_i64_i32 v[58:59], s[20:21], v58, s49, v[30:31]
	v_mad_i64_i32 v[60:61], s[20:21], v60, s49, v[30:31]
	global_load_dword v68, v[32:33], off
	global_load_dword v69, v[48:49], off
	global_load_dword v70, v[50:51], off
	global_load_dword v71, v[52:53], off
	global_load_dword v72, v[54:55], off
	global_load_dword v73, v[56:57], off
	global_load_dword v74, v[58:59], off
	global_load_dword v75, v[60:61], off
	v_or_b32_e32 v32, 32, v27
	v_or_b32_e32 v48, 34, v27
	v_or_b32_e32 v50, 36, v27
	v_or_b32_e32 v52, 38, v27
	v_or_b32_e32 v54, 40, v27
	v_or_b32_e32 v56, 42, v27
	v_or_b32_e32 v58, 44, v27
	v_or_b32_e32 v60, 46, v27
	v_mad_i64_i32 v[32:33], s[20:21], v32, s49, v[30:31]
	v_mad_i64_i32 v[48:49], s[20:21], v48, s49, v[30:31]
	v_mad_i64_i32 v[50:51], s[20:21], v50, s49, v[30:31]
	v_mad_i64_i32 v[52:53], s[20:21], v52, s49, v[30:31]
	v_mad_i64_i32 v[54:55], s[20:21], v54, s49, v[30:31]
	v_mad_i64_i32 v[56:57], s[20:21], v56, s49, v[30:31]
	v_mad_i64_i32 v[58:59], s[20:21], v58, s49, v[30:31]
	v_mad_i64_i32 v[60:61], s[20:21], v60, s49, v[30:31]
	global_load_dword v76, v[32:33], off
	global_load_dword v77, v[48:49], off
	global_load_dword v78, v[50:51], off
	global_load_dword v79, v[52:53], off
	global_load_dword v81, v[54:55], off
	global_load_dword v82, v[56:57], off
	global_load_dword v83, v[58:59], off
	s_nop 0
	global_load_dword v60, v[60:61], off
	v_or_b32_e32 v32, 48, v27
	v_or_b32_e32 v48, 50, v27
	v_or_b32_e32 v50, 52, v27
	v_or_b32_e32 v52, 54, v27
	v_or_b32_e32 v54, 56, v27
	v_or_b32_e32 v56, 58, v27
	v_or_b32_e32 v58, 60, v27
	v_or_b32_e32 v27, 62, v27
	v_mad_i64_i32 v[32:33], s[20:21], v32, s49, v[30:31]
	v_mad_i64_i32 v[48:49], s[20:21], v48, s49, v[30:31]
	v_mad_i64_i32 v[50:51], s[20:21], v50, s49, v[30:31]
	v_mad_i64_i32 v[52:53], s[20:21], v52, s49, v[30:31]
	v_mad_i64_i32 v[54:55], s[20:21], v54, s49, v[30:31]
	v_mad_i64_i32 v[56:57], s[20:21], v56, s49, v[30:31]
	v_mad_i64_i32 v[58:59], s[20:21], v58, s49, v[30:31]
	v_mad_i64_i32 v[30:31], s[20:21], v27, s49, v[30:31]
	global_load_dword v27, v[32:33], off
	s_nop 0
	global_load_dword v32, v[48:49], off
	global_load_dword v33, v[50:51], off
	s_nop 0
	global_load_dword v48, v[52:53], off
	global_load_dword v49, v[54:55], off
	global_load_dword v50, v[56:57], off
	global_load_dword v51, v[58:59], off
	s_nop 0
	global_load_dword v30, v[30:31], off
	s_waitcnt vmcnt(30)
	ds_write2_b32 v35, v25, v29 offset1:66
	s_waitcnt vmcnt(28)
	ds_write2_b32 v35, v62, v63 offset0:132 offset1:198
	s_waitcnt vmcnt(26)
	ds_write2_b32 v41, v64, v65 offset0:8 offset1:74
	s_waitcnt vmcnt(24)
	ds_write2_b32 v41, v66, v67 offset0:140 offset1:206
	s_waitcnt vmcnt(22)
	ds_write2_b32 v42, v68, v69 offset0:16 offset1:82
	s_waitcnt vmcnt(20)
	ds_write2_b32 v42, v70, v71 offset0:148 offset1:214
	s_waitcnt vmcnt(18)
	ds_write2_b32 v43, v72, v73 offset0:24 offset1:90
	s_waitcnt vmcnt(16)
	ds_write2_b32 v43, v74, v75 offset0:156 offset1:222
	s_waitcnt vmcnt(14)
	ds_write2_b32 v44, v76, v77 offset0:32 offset1:98
	s_waitcnt vmcnt(12)
	ds_write2_b32 v44, v78, v79 offset0:164 offset1:230
	s_waitcnt vmcnt(10)
	ds_write2_b32 v45, v81, v82 offset0:40 offset1:106
	s_waitcnt vmcnt(8)
	ds_write2_b32 v45, v83, v60 offset0:172 offset1:238
	s_waitcnt vmcnt(6)
	ds_write2_b32 v46, v27, v32 offset0:48 offset1:114
	s_waitcnt vmcnt(4)
	ds_write2_b32 v46, v33, v48 offset0:180 offset1:246
	s_waitcnt vmcnt(2)
	ds_write2_b32 v47, v49, v50 offset0:56 offset1:122
	s_waitcnt vmcnt(0)
	ds_write2_b32 v47, v51, v30 offset0:188 offset1:254
	s_waitcnt lgkmcnt(0)
	ds_read2_b32 v[30:31], v37 offset1:33
	v_or_b32_e32 v25, v24, v36
	s_waitcnt lgkmcnt(0)
	v_cvt_pk_bf16_f32 v30, v30, v31
	ds_read2_b32 v[32:33], v37 offset0:66 offset1:99
	v_ashrrev_i32_e32 v27, 31, v26
	v_mul_lo_u32 v50, v25, s50
	s_waitcnt lgkmcnt(0)
; #define LAS __attribute__((address_space(3)))
; __device__ __forceinline__ unsigned pk2(float lo, float hi) { return pg8::cvt_pk_bf16(lo, hi); }
; __device__ __forceinline__ void transpose_item(const float* W, int K, int N, bf16* WT, int k0, int n0, int drow0, LAS float* scr, int lane) {
;     float wv[32];
; #pragma unroll
;     for (int i = 0; i < 32; ++i) wv[i] = W[(size_t)(k0 + 2 * i + (lane >> 5)) * N + n0 + (lane & 31)];
; #pragma unroll
;     for (int i = 0; i < 32; ++i) scr[(2 * i + (lane >> 5)) * 33 + (lane & 31)] = wv[i];
;     asm volatile("s_waitcnt lgkmcnt(0)" ::: "memory");
;     const int c = lane & 7;
; #pragma unroll
;     for (int j = 0; j < 4; ++j) { const int n = (lane >> 3) + 8 * j; const LAS float* s = scr + (8 * c) * 33 + n;
;         u32x4 o; o.x = pk2(s[0 * 33], s[1 * 33]); o.y = pk2(s[2 * 33], s[3 * 33]); o.z = pk2(s[4 * 33], s[5 * 33]); o.w = pk2(s[6 * 33], s[7 * 33]);
;         *(u32x4*)(WT + (size_t)(drow0 + n) * K + k0 + 8 * c) = o; }
;     asm volatile("s_waitcnt lgkmcnt(0)" ::: "memory");
; }
; __device__ __forceinline__ bool transpose_job(int& it, const float* W, int K, int N, bf16* WT, int mode, LAS float* scr, int lane) {
;     const int nblk = N / 32, items = (K / 64) * nblk;
;     if (it >= items) { it -= items; return false; }
;     const int kb = it / nblk, nb = it % nblk, n0 = 32 * nb;
;     const int drow0 = mode == 0 ? n0 : (256 * (n0 >> 7) + (n0 & 127) + (mode == 2 ? 128 : 0));
;     transpose_item(W, K, N, WT, 64 * kb, n0, drow0, scr, lane);
;     return true;
; }
	v_cvt_pk_bf16_f32 v31, v32, v33
	ds_read2_b32 v[32:33], v37 offset0:132 offset1:165
	v_lshl_add_u64 v[26:27], v[26:27], 1, v[14:15]
	v_ashrrev_i32_e32 v51, 31, v50
	s_waitcnt lgkmcnt(0)
	v_cvt_pk_bf16_f32 v32, v32, v33
	ds_read2_b32 v[48:49], v37 offset0:198 offset1:231
	s_waitcnt lgkmcnt(0)
	v_cvt_pk_bf16_f32 v33, v48, v49
	v_lshl_add_u64 v[50:51], v[50:51], 1, v[26:27]
	v_or_b32_e32 v25, v24, v38
	ds_read2_b32 v[48:49], v37 offset0:8 offset1:41
	global_store_dwordx4 v[50:51], v[30:33], off sc0 sc1
	v_mul_lo_u32 v50, v25, s50
	v_ashrrev_i32_e32 v51, 31, v50
	s_waitcnt lgkmcnt(0)
	v_cvt_pk_bf16_f32 v30, v48, v49
	ds_read2_b32 v[32:33], v37 offset0:74 offset1:107
	s_waitcnt lgkmcnt(0)
	v_cvt_pk_bf16_f32 v31, v32, v33
	ds_read2_b32 v[32:33], v37 offset0:140 offset1:173
	s_waitcnt lgkmcnt(0)
	v_cvt_pk_bf16_f32 v32, v32, v33
	ds_read2_b32 v[48:49], v37 offset0:206 offset1:239
	s_waitcnt lgkmcnt(0)
	v_cvt_pk_bf16_f32 v33, v48, v49
	v_lshl_add_u64 v[50:51], v[50:51], 1, v[26:27]
	v_or_b32_e32 v25, v24, v39
	ds_read2_b32 v[48:49], v37 offset0:16 offset1:49
	global_store_dwordx4 v[50:51], v[30:33], off sc0 sc1
	v_mul_lo_u32 v50, v25, s50
	v_ashrrev_i32_e32 v51, 31, v50
	s_waitcnt lgkmcnt(0)
	v_cvt_pk_bf16_f32 v30, v48, v49
	ds_read2_b32 v[32:33], v37 offset0:82 offset1:115
	s_waitcnt lgkmcnt(0)
	v_cvt_pk_bf16_f32 v31, v32, v33
	ds_read2_b32 v[32:33], v37 offset0:148 offset1:181
	v_or_b32_e32 v24, v24, v40
	s_waitcnt lgkmcnt(0)
	v_cvt_pk_bf16_f32 v32, v32, v33
	ds_read2_b32 v[48:49], v37 offset0:214 offset1:247
	s_waitcnt lgkmcnt(0)
	v_cvt_pk_bf16_f32 v33, v48, v49
	v_lshl_add_u64 v[50:51], v[50:51], 1, v[26:27]
	v_mul_lo_u32 v24, v24, s50
	ds_read2_b32 v[48:49], v37 offset0:24 offset1:57
	global_store_dwordx4 v[50:51], v[30:33], off sc0 sc1
	v_ashrrev_i32_e32 v25, 31, v24
	v_lshl_add_u64 v[24:25], v[24:25], 1, v[26:27]
	s_waitcnt lgkmcnt(0)
	v_cvt_pk_bf16_f32 v30, v48, v49
	ds_read2_b32 v[32:33], v37 offset0:90 offset1:123
	s_waitcnt lgkmcnt(0)
	v_cvt_pk_bf16_f32 v31, v32, v33
	ds_read2_b32 v[32:33], v37 offset0:156 offset1:189
	s_waitcnt lgkmcnt(0)
	v_cvt_pk_bf16_f32 v32, v32, v33
	ds_read2_b32 v[48:49], v37 offset0:222 offset1:255
	s_waitcnt lgkmcnt(0)
	v_cvt_pk_bf16_f32 v33, v48, v49
	global_store_dwordx4 v[24:25], v[30:33], off sc0 sc1
	s_waitcnt lgkmcnt(0)
	s_or_b64 exec, exec, s[4:5]
	s_and_b64 exec, exec, vcc
	s_cbranch_execz .LBB0_22
.LBB0_62:
	v_cmp_lt_i32_e32 vcc, s51, v28
	v_cmp_gt_i32_e64 s[4:5], s52, v28
	s_and_saveexec_b64 s[20:21], s[4:5]
	s_xor_b64 s[4:5], exec, s[20:21]
	s_cbranch_execz .LBB0_64
	v_ashrrev_i32_e32 v24, 31, v28
	v_lshrrev_b32_e32 v24, 26, v24
	s_load_dwordx2 s[20:21], s[10:11], 0xd0
	v_add_u32_e32 v24, v28, v24
	v_and_b32_e32 v26, 0xffffffc0, v24
	v_sub_u32_e32 v24, v28, v26
	v_lshlrev_b32_e32 v24, 5, v24
	v_or_b32_e32 v30, v26, v34
	v_ashrrev_i32_e32 v25, 31, v24
	v_or_b32_e32 v50, 2, v30
	v_or_b32_e32 v52, 4, v30
	v_or_b32_e32 v54, 6, v30
	v_or_b32_e32 v56, 8, v30
	v_or_b32_e32 v58, 10, v30
	v_or_b32_e32 v60, 12, v30
	v_or_b32_e32 v62, 14, v30
	s_waitcnt lgkmcnt(0)
	v_lshl_add_u64 v[32:33], v[24:25], 2, s[20:21]
	v_ashrrev_i32_e32 v31, 31, v30
	v_ashrrev_i32_e32 v51, 31, v50
	v_ashrrev_i32_e32 v53, 31, v52
	v_ashrrev_i32_e32 v55, 31, v54
	v_ashrrev_i32_e32 v57, 31, v56
	v_ashrrev_i32_e32 v59, 31, v58
	v_ashrrev_i32_e32 v61, 31, v60
	v_ashrrev_i32_e32 v63, 31, v62
	v_lshl_add_u64 v[32:33], v[32:33], 0, v[4:5]
	v_lshlrev_b64 v[48:49], 13, v[30:31]
	v_lshlrev_b64 v[50:51], 13, v[50:51]
	v_lshlrev_b64 v[52:53], 13, v[52:53]
	v_lshlrev_b64 v[54:55], 13, v[54:55]
	v_lshlrev_b64 v[56:57], 13, v[56:57]
	v_lshlrev_b64 v[58:59], 13, v[58:59]
	v_lshlrev_b64 v[60:61], 13, v[60:61]
	v_lshlrev_b64 v[62:63], 13, v[62:63]
	v_lshl_add_u64 v[48:49], v[32:33], 0, v[48:49]
	v_lshl_add_u64 v[50:51], v[32:33], 0, v[50:51]
	v_lshl_add_u64 v[52:53], v[32:33], 0, v[52:53]
	v_lshl_add_u64 v[54:55], v[32:33], 0, v[54:55]
	v_lshl_add_u64 v[56:57], v[32:33], 0, v[56:57]
	v_lshl_add_u64 v[58:59], v[32:33], 0, v[58:59]
	v_lshl_add_u64 v[60:61], v[32:33], 0, v[60:61]
	v_lshl_add_u64 v[62:63], v[32:33], 0, v[62:63]
	global_load_dword v25, v[48:49], off
	global_load_dword v27, v[50:51], off
	global_load_dword v29, v[52:53], off
	global_load_dword v64, v[54:55], off
	global_load_dword v65, v[56:57], off
	global_load_dword v66, v[58:59], off
	global_load_dword v67, v[60:61], off
	global_load_dword v68, v[62:63], off
	v_or_b32_e32 v48, 16, v30
	v_or_b32_e32 v50, 18, v30
	v_or_b32_e32 v52, 20, v30
	v_or_b32_e32 v54, 22, v30
	v_or_b32_e32 v56, 24, v30
	v_or_b32_e32 v58, 26, v30
	v_or_b32_e32 v60, 28, v30
	v_or_b32_e32 v62, 30, v30
	v_ashrrev_i32_e32 v49, 31, v48
	v_ashrrev_i32_e32 v51, 31, v50
	v_ashrrev_i32_e32 v53, 31, v52
	v_ashrrev_i32_e32 v55, 31, v54
	v_ashrrev_i32_e32 v57, 31, v56
	v_ashrrev_i32_e32 v59, 31, v58
	v_ashrrev_i32_e32 v61, 31, v60
	v_ashrrev_i32_e32 v63, 31, v62
	v_lshlrev_b64 v[48:49], 13, v[48:49]
	v_lshlrev_b64 v[50:51], 13, v[50:51]
	v_lshlrev_b64 v[52:53], 13, v[52:53]
	v_lshlrev_b64 v[54:55], 13, v[54:55]
	v_lshlrev_b64 v[56:57], 13, v[56:57]
	v_lshlrev_b64 v[58:59], 13, v[58:59]
	v_lshlrev_b64 v[60:61], 13, v[60:61]
	v_lshlrev_b64 v[62:63], 13, v[62:63]
	v_lshl_add_u64 v[48:49], v[32:33], 0, v[48:49]
	v_lshl_add_u64 v[50:51], v[32:33], 0, v[50:51]
	v_lshl_add_u64 v[52:53], v[32:33], 0, v[52:53]
	v_lshl_add_u64 v[54:55], v[32:33], 0, v[54:55]
	v_lshl_add_u64 v[56:57], v[32:33], 0, v[56:57]
	v_lshl_add_u64 v[58:59], v[32:33], 0, v[58:59]
	v_lshl_add_u64 v[60:61], v[32:33], 0, v[60:61]
	v_lshl_add_u64 v[62:63], v[32:33], 0, v[62:63]
	global_load_dword v69, v[48:49], off
	global_load_dword v70, v[50:51], off
; #define LAS __attribute__((address_space(3)))
; __device__ __forceinline__ unsigned pk2(float lo, float hi) { return pg8::cvt_pk_bf16(lo, hi); }
; __device__ __forceinline__ void transpose_item(const float* W, int K, int N, bf16* WT, int k0, int n0, int drow0, LAS float* scr, int lane) {
;     float wv[32];
; #pragma unroll
;     for (int i = 0; i < 32; ++i) wv[i] = W[(size_t)(k0 + 2 * i + (lane >> 5)) * N + n0 + (lane & 31)];
; #pragma unroll
;     for (int i = 0; i < 32; ++i) scr[(2 * i + (lane >> 5)) * 33 + (lane & 31)] = wv[i];
;     asm volatile("s_waitcnt lgkmcnt(0)" ::: "memory");
;     const int c = lane & 7;
; #pragma unroll
;     for (int j = 0; j < 4; ++j) { const int n = (lane >> 3) + 8 * j; const LAS float* s = scr + (8 * c) * 33 + n;
;         u32x4 o; o.x = pk2(s[0 * 33], s[1 * 33]); o.y = pk2(s[2 * 33], s[3 * 33]); o.z = pk2(s[4 * 33], s[5 * 33]); o.w = pk2(s[6 * 33], s[7 * 33]);
;         *(u32x4*)(WT + (size_t)(drow0 + n) * K + k0 + 8 * c) = o; }
;     asm volatile("s_waitcnt lgkmcnt(0)" ::: "memory");
; }
	global_load_dword v71, v[52:53], off
	global_load_dword v72, v[54:55], off
	global_load_dword v73, v[56:57], off
	global_load_dword v74, v[58:59], off
	global_load_dword v75, v[60:61], off
	global_load_dword v76, v[62:63], off
	v_or_b32_e32 v48, 32, v30
	v_or_b32_e32 v50, 34, v30
	v_or_b32_e32 v52, 36, v30
	v_or_b32_e32 v54, 38, v30
	v_or_b32_e32 v56, 40, v30
	v_or_b32_e32 v58, 42, v30
	v_or_b32_e32 v60, 44, v30
	v_or_b32_e32 v62, 46, v30
	v_ashrrev_i32_e32 v49, 31, v48
	v_ashrrev_i32_e32 v51, 31, v50
	v_ashrrev_i32_e32 v53, 31, v52
	v_ashrrev_i32_e32 v55, 31, v54
	v_ashrrev_i32_e32 v57, 31, v56
	v_ashrrev_i32_e32 v59, 31, v58
	v_ashrrev_i32_e32 v61, 31, v60
	v_ashrrev_i32_e32 v63, 31, v62
	v_lshlrev_b64 v[48:49], 13, v[48:49]
	v_lshlrev_b64 v[50:51], 13, v[50:51]
	v_lshlrev_b64 v[52:53], 13, v[52:53]
	v_lshlrev_b64 v[54:55], 13, v[54:55]
	v_lshlrev_b64 v[56:57], 13, v[56:57]
	v_lshlrev_b64 v[58:59], 13, v[58:59]
	v_lshlrev_b64 v[60:61], 13, v[60:61]
	v_lshlrev_b64 v[62:63], 13, v[62:63]
	v_lshl_add_u64 v[48:49], v[32:33], 0, v[48:49]
	v_lshl_add_u64 v[50:51], v[32:33], 0, v[50:51]
	v_lshl_add_u64 v[52:53], v[32:33], 0, v[52:53]
	v_lshl_add_u64 v[54:55], v[32:33], 0, v[54:55]
	v_lshl_add_u64 v[56:57], v[32:33], 0, v[56:57]
	v_lshl_add_u64 v[58:59], v[32:33], 0, v[58:59]
	v_lshl_add_u64 v[60:61], v[32:33], 0, v[60:61]
	v_lshl_add_u64 v[62:63], v[32:33], 0, v[62:63]
	global_load_dword v77, v[48:49], off
	global_load_dword v78, v[50:51], off
	global_load_dword v79, v[52:53], off
	global_load_dword v81, v[54:55], off
	global_load_dword v82, v[56:57], off
	global_load_dword v83, v[58:59], off
	global_load_dword v84, v[60:61], off
	s_nop 0
	global_load_dword v62, v[62:63], off
	v_or_b32_e32 v48, 48, v30
	v_or_b32_e32 v50, 50, v30
	v_or_b32_e32 v52, 52, v30
	v_or_b32_e32 v54, 54, v30
	v_or_b32_e32 v56, 56, v30
	v_or_b32_e32 v58, 58, v30
	v_or_b32_e32 v60, 60, v30
	v_or_b32_e32 v30, 62, v30
	v_ashrrev_i32_e32 v49, 31, v48
	v_ashrrev_i32_e32 v51, 31, v50
	v_ashrrev_i32_e32 v53, 31, v52
	v_ashrrev_i32_e32 v31, 31, v30
	v_lshlrev_b64 v[48:49], 13, v[48:49]
	v_lshlrev_b64 v[50:51], 13, v[50:51]
	v_lshlrev_b64 v[52:53], 13, v[52:53]
	v_ashrrev_i32_e32 v55, 31, v54
	v_ashrrev_i32_e32 v57, 31, v56
	v_ashrrev_i32_e32 v59, 31, v58
	v_ashrrev_i32_e32 v61, 31, v60
	v_lshlrev_b64 v[30:31], 13, v[30:31]
	v_lshl_add_u64 v[48:49], v[32:33], 0, v[48:49]
	v_lshl_add_u64 v[50:51], v[32:33], 0, v[50:51]
	v_lshl_add_u64 v[52:53], v[32:33], 0, v[52:53]
	v_lshlrev_b64 v[54:55], 13, v[54:55]
	v_lshlrev_b64 v[56:57], 13, v[56:57]
	v_lshlrev_b64 v[58:59], 13, v[58:59]
	v_lshlrev_b64 v[60:61], 13, v[60:61]
	v_lshl_add_u64 v[30:31], v[32:33], 0, v[30:31]
	v_lshl_add_u64 v[54:55], v[32:33], 0, v[54:55]
	v_lshl_add_u64 v[56:57], v[32:33], 0, v[56:57]
	v_lshl_add_u64 v[58:59], v[32:33], 0, v[58:59]
	v_lshl_add_u64 v[60:61], v[32:33], 0, v[60:61]
	global_load_dword v32, v[48:49], off
	global_load_dword v33, v[50:51], off
	s_nop 0
	global_load_dword v48, v[52:53], off
	global_load_dword v49, v[54:55], off
	global_load_dword v50, v[56:57], off
	global_load_dword v51, v[58:59], off
	s_nop 0
	global_load_dword v52, v[60:61], off
	s_nop 0
	global_load_dword v30, v[30:31], off
	s_waitcnt vmcnt(30)
	ds_write2_b32 v35, v25, v27 offset1:66
	s_waitcnt vmcnt(28)
	ds_write2_b32 v35, v29, v64 offset0:132 offset1:198
	s_waitcnt vmcnt(26)
	ds_write2_b32 v41, v65, v66 offset0:8 offset1:74
	s_waitcnt vmcnt(24)
	ds_write2_b32 v41, v67, v68 offset0:140 offset1:206
	s_waitcnt vmcnt(22)
	ds_write2_b32 v42, v69, v70 offset0:16 offset1:82
	s_waitcnt vmcnt(20)
	ds_write2_b32 v42, v71, v72 offset0:148 offset1:214
	s_waitcnt vmcnt(18)
	ds_write2_b32 v43, v73, v74 offset0:24 offset1:90
	s_waitcnt vmcnt(16)
	ds_write2_b32 v43, v75, v76 offset0:156 offset1:222
	s_waitcnt vmcnt(14)
	ds_write2_b32 v44, v77, v78 offset0:32 offset1:98
	s_waitcnt vmcnt(12)
	ds_write2_b32 v44, v79, v81 offset0:164 offset1:230
	s_waitcnt vmcnt(10)
	ds_write2_b32 v45, v82, v83 offset0:40 offset1:106
	s_waitcnt vmcnt(8)
	ds_write2_b32 v45, v84, v62 offset0:172 offset1:238
	s_waitcnt vmcnt(6)
	ds_write2_b32 v46, v32, v33 offset0:48 offset1:114
	s_waitcnt vmcnt(4)
	ds_write2_b32 v46, v48, v49 offset0:180 offset1:246
	s_waitcnt vmcnt(2)
	ds_write2_b32 v47, v50, v51 offset0:56 offset1:122
	s_waitcnt vmcnt(0)
	ds_write2_b32 v47, v52, v30 offset0:188 offset1:254
	s_waitcnt lgkmcnt(0)
	ds_read2_b32 v[30:31], v37 offset1:33
	s_waitcnt lgkmcnt(0)
	v_cvt_pk_bf16_f32 v30, v30, v31
	ds_read2_b32 v[32:33], v37 offset0:66 offset1:99
	s_waitcnt lgkmcnt(0)
	v_cvt_pk_bf16_f32 v31, v32, v33
	ds_read2_b32 v[32:33], v37 offset0:132 offset1:165
	s_waitcnt lgkmcnt(0)
	v_cvt_pk_bf16_f32 v32, v32, v33
	ds_read2_b32 v[48:49], v37 offset0:198 offset1:231
	s_waitcnt lgkmcnt(0)
	v_cvt_pk_bf16_f32 v33, v48, v49
	v_or_b32_e32 v48, v24, v36
	v_ashrrev_i32_e32 v27, 31, v26
	v_ashrrev_i32_e32 v49, 31, v48
	v_lshl_add_u64 v[26:27], v[26:27], 1, v[16:17]
	v_lshlrev_b64 v[48:49], 9, v[48:49]
	v_lshl_add_u64 v[48:49], v[26:27], 0, v[48:49]
	ds_read2_b32 v[50:51], v37 offset0:8 offset1:41
	global_store_dwordx4 v[48:49], v[30:33], off sc0 sc1
	s_waitcnt lgkmcnt(0)
	s_nop 0
	v_cvt_pk_bf16_f32 v30, v50, v51
	ds_read2_b32 v[32:33], v37 offset0:74 offset1:107
	s_waitcnt lgkmcnt(0)
	v_cvt_pk_bf16_f32 v31, v32, v33
	ds_read2_b32 v[32:33], v37 offset0:140 offset1:173
	s_waitcnt lgkmcnt(0)
	v_cvt_pk_bf16_f32 v32, v32, v33
	ds_read2_b32 v[48:49], v37 offset0:206 offset1:239
	s_waitcnt lgkmcnt(0)
	v_cvt_pk_bf16_f32 v33, v48, v49
	v_or_b32_e32 v48, v24, v38
	v_ashrrev_i32_e32 v49, 31, v48
	v_lshlrev_b64 v[48:49], 9, v[48:49]
	v_lshl_add_u64 v[48:49], v[26:27], 0, v[48:49]
	ds_read2_b32 v[50:51], v37 offset0:16 offset1:49
	global_store_dwordx4 v[48:49], v[30:33], off sc0 sc1
	s_waitcnt lgkmcnt(0)
	s_nop 0
	v_cvt_pk_bf16_f32 v30, v50, v51
	ds_read2_b32 v[32:33], v37 offset0:82 offset1:115
	s_waitcnt lgkmcnt(0)
	v_cvt_pk_bf16_f32 v31, v32, v33
	ds_read2_b32 v[32:33], v37 offset0:148 offset1:181
	s_waitcnt lgkmcnt(0)
	v_cvt_pk_bf16_f32 v32, v32, v33
	ds_read2_b32 v[48:49], v37 offset0:214 offset1:247
	s_waitcnt lgkmcnt(0)
	v_cvt_pk_bf16_f32 v33, v48, v49
	v_or_b32_e32 v48, v24, v39
	v_ashrrev_i32_e32 v49, 31, v48
	v_lshlrev_b64 v[48:49], 9, v[48:49]
	v_or_b32_e32 v24, v24, v40
	v_lshl_add_u64 v[48:49], v[26:27], 0, v[48:49]
	v_ashrrev_i32_e32 v25, 31, v24
	ds_read2_b32 v[50:51], v37 offset0:24 offset1:57
	global_store_dwordx4 v[48:49], v[30:33], off sc0 sc1
	v_lshlrev_b64 v[24:25], 9, v[24:25]
	v_lshl_add_u64 v[24:25], v[26:27], 0, v[24:25]
	s_waitcnt lgkmcnt(0)
	v_cvt_pk_bf16_f32 v30, v50, v51
	ds_read2_b32 v[32:33], v37 offset0:90 offset1:123
	s_waitcnt lgkmcnt(0)
	v_cvt_pk_bf16_f32 v31, v32, v33
	ds_read2_b32 v[32:33], v37 offset0:156 offset1:189
	s_waitcnt lgkmcnt(0)
	v_cvt_pk_bf16_f32 v32, v32, v33
	ds_read2_b32 v[48:49], v37 offset0:222 offset1:255
	s_waitcnt lgkmcnt(0)
	v_cvt_pk_bf16_f32 v33, v48, v49
	global_store_dwordx4 v[24:25], v[30:33], off sc0 sc1
	s_waitcnt lgkmcnt(0)
; #define LAS __attribute__((address_space(3)))
; __device__ __forceinline__ unsigned pk2(float lo, float hi) { return pg8::cvt_pk_bf16(lo, hi); }
; __device__ __forceinline__ void transpose_item(const float* W, int K, int N, bf16* WT, int k0, int n0, int drow0, LAS float* scr, int lane) {
;     float wv[32];
; #pragma unroll
;     for (int i = 0; i < 32; ++i) wv[i] = W[(size_t)(k0 + 2 * i + (lane >> 5)) * N + n0 + (lane & 31)];
; #pragma unroll
;     for (int i = 0; i < 32; ++i) scr[(2 * i + (lane >> 5)) * 33 + (lane & 31)] = wv[i];
;     asm volatile("s_waitcnt lgkmcnt(0)" ::: "memory");
;     const int c = lane & 7;
; #pragma unroll
;     for (int j = 0; j < 4; ++j) { const int n = (lane >> 3) + 8 * j; const LAS float* s = scr + (8 * c) * 33 + n;
;         u32x4 o; o.x = pk2(s[0 * 33], s[1 * 33]); o.y = pk2(s[2 * 33], s[3 * 33]); o.z = pk2(s[4 * 33], s[5 * 33]); o.w = pk2(s[6 * 33], s[7 * 33]);
;         *(u32x4*)(WT + (size_t)(drow0 + n) * K + k0 + 8 * c) = o; }
;     asm volatile("s_waitcnt lgkmcnt(0)" ::: "memory");
; }
; __device__ __forceinline__ bool transpose_job(int& it, const float* W, int K, int N, bf16* WT, int mode, LAS float* scr, int lane) {
;     const int nblk = N / 32, items = (K / 64) * nblk;
;     if (it >= items) { it -= items; return false; }
;     const int kb = it / nblk, nb = it % nblk, n0 = 32 * nb;
;     const int drow0 = mode == 0 ? n0 : (256 * (n0 >> 7) + (n0 & 127) + (mode == 2 ? 128 : 0));
;     transpose_item(W, K, N, WT, 64 * kb, n0, drow0, scr, lane);
;     return true;
; }
.LBB0_64:
	s_andn2_saveexec_b64 s[4:5], s[4:5]
	v_add_u32_e32 v28, 0xffffff00, v28
	s_or_b64 exec, exec, s[4:5]
	v_cmp_gt_i32_e64 s[4:5], s53, v28
	s_and_b64 s[4:5], vcc, s[4:5]
	s_and_b64 exec, exec, s[4:5]
	s_cbranch_execz .LBB0_22
	v_ashrrev_i32_e32 v24, 31, v28
	v_lshrrev_b32_e32 v24, 27, v24
	s_load_dwordx2 s[4:5], s[10:11], 0xd8
	v_add_u32_e32 v25, v28, v24
	v_and_b32_e32 v24, 0x7ffffe0, v25
	v_sub_u32_e32 v24, v28, v24
	v_lshlrev_b32_e32 v25, 1, v25
	v_lshlrev_b32_e32 v24, 5, v24
	v_and_b32_e32 v26, 0xffffffc0, v25
	v_or_b32_e32 v28, v26, v34
	v_ashrrev_i32_e32 v25, 31, v24
	s_waitcnt lgkmcnt(0)
	v_lshl_add_u64 v[30:31], v[24:25], 2, s[4:5]
	v_ashrrev_i32_e32 v29, 31, v28
	v_or_b32_e32 v48, 2, v28
	v_or_b32_e32 v50, 4, v28
	v_or_b32_e32 v52, 6, v28
	v_or_b32_e32 v54, 8, v28
	v_or_b32_e32 v56, 10, v28
	v_or_b32_e32 v58, 12, v28
	v_or_b32_e32 v60, 14, v28
	v_lshl_add_u64 v[30:31], v[30:31], 0, v[4:5]
	v_lshlrev_b64 v[32:33], 12, v[28:29]
	v_ashrrev_i32_e32 v49, 31, v48
	v_ashrrev_i32_e32 v51, 31, v50
	v_ashrrev_i32_e32 v53, 31, v52
	v_ashrrev_i32_e32 v55, 31, v54
	v_ashrrev_i32_e32 v57, 31, v56
	v_ashrrev_i32_e32 v59, 31, v58
	v_ashrrev_i32_e32 v61, 31, v60
	v_lshl_add_u64 v[32:33], v[30:31], 0, v[32:33]
	v_lshlrev_b64 v[48:49], 12, v[48:49]
	v_lshlrev_b64 v[50:51], 12, v[50:51]
	v_lshlrev_b64 v[52:53], 12, v[52:53]
	v_lshlrev_b64 v[54:55], 12, v[54:55]
	v_lshlrev_b64 v[56:57], 12, v[56:57]
	v_lshlrev_b64 v[58:59], 12, v[58:59]
	v_lshlrev_b64 v[60:61], 12, v[60:61]
	v_lshl_add_u64 v[48:49], v[30:31], 0, v[48:49]
	v_lshl_add_u64 v[50:51], v[30:31], 0, v[50:51]
	v_lshl_add_u64 v[52:53], v[30:31], 0, v[52:53]
	v_lshl_add_u64 v[54:55], v[30:31], 0, v[54:55]
	v_lshl_add_u64 v[56:57], v[30:31], 0, v[56:57]
	v_lshl_add_u64 v[58:59], v[30:31], 0, v[58:59]
	v_lshl_add_u64 v[60:61], v[30:31], 0, v[60:61]
	global_load_dword v4, v[32:33], off
	global_load_dword v25, v[48:49], off
	global_load_dword v27, v[50:51], off
	global_load_dword v62, v[52:53], off
	global_load_dword v63, v[54:55], off
	global_load_dword v64, v[56:57], off
	global_load_dword v65, v[58:59], off
	global_load_dword v66, v[60:61], off
	v_or_b32_e32 v32, 16, v28
	v_ashrrev_i32_e32 v33, 31, v32
	v_or_b32_e32 v48, 18, v28
	v_or_b32_e32 v50, 20, v28
	v_or_b32_e32 v52, 22, v28
	v_or_b32_e32 v54, 24, v28
	v_or_b32_e32 v56, 26, v28
	v_or_b32_e32 v58, 28, v28
	v_or_b32_e32 v60, 30, v28
	v_lshlrev_b64 v[32:33], 12, v[32:33]
	v_ashrrev_i32_e32 v49, 31, v48
	v_ashrrev_i32_e32 v51, 31, v50
	v_ashrrev_i32_e32 v53, 31, v52
	v_ashrrev_i32_e32 v55, 31, v54
	v_ashrrev_i32_e32 v57, 31, v56
	v_ashrrev_i32_e32 v59, 31, v58
	v_ashrrev_i32_e32 v61, 31, v60
	v_lshl_add_u64 v[32:33], v[30:31], 0, v[32:33]
	v_lshlrev_b64 v[48:49], 12, v[48:49]
	v_lshlrev_b64 v[50:51], 12, v[50:51]
	v_lshlrev_b64 v[52:53], 12, v[52:53]
	v_lshlrev_b64 v[54:55], 12, v[54:55]
	v_lshlrev_b64 v[56:57], 12, v[56:57]
	v_lshlrev_b64 v[58:59], 12, v[58:59]
	v_lshlrev_b64 v[60:61], 12, v[60:61]
	v_lshl_add_u64 v[48:49], v[30:31], 0, v[48:49]
	v_lshl_add_u64 v[50:51], v[30:31], 0, v[50:51]
	v_lshl_add_u64 v[52:53], v[30:31], 0, v[52:53]
	v_lshl_add_u64 v[54:55], v[30:31], 0, v[54:55]
	v_lshl_add_u64 v[56:57], v[30:31], 0, v[56:57]
	v_lshl_add_u64 v[58:59], v[30:31], 0, v[58:59]
	v_lshl_add_u64 v[60:61], v[30:31], 0, v[60:61]
	global_load_dword v67, v[32:33], off
	global_load_dword v68, v[48:49], off
	global_load_dword v69, v[50:51], off
	global_load_dword v70, v[52:53], off
	global_load_dword v71, v[54:55], off
	global_load_dword v72, v[56:57], off
	global_load_dword v73, v[58:59], off
	global_load_dword v74, v[60:61], off
	v_or_b32_e32 v32, 32, v28
	v_ashrrev_i32_e32 v33, 31, v32
	v_or_b32_e32 v48, 34, v28
	v_or_b32_e32 v50, 36, v28
	v_or_b32_e32 v52, 38, v28
	v_or_b32_e32 v54, 40, v28
	v_or_b32_e32 v56, 42, v28
	v_or_b32_e32 v58, 44, v28
	v_or_b32_e32 v60, 46, v28
	v_lshlrev_b64 v[32:33], 12, v[32:33]
	v_ashrrev_i32_e32 v49, 31, v48
	v_ashrrev_i32_e32 v51, 31, v50
	v_ashrrev_i32_e32 v53, 31, v52
	v_ashrrev_i32_e32 v55, 31, v54
	v_ashrrev_i32_e32 v57, 31, v56
	v_ashrrev_i32_e32 v59, 31, v58
	v_ashrrev_i32_e32 v61, 31, v60
	v_lshl_add_u64 v[32:33], v[30:31], 0, v[32:33]
	v_lshlrev_b64 v[48:49], 12, v[48:49]
	v_lshlrev_b64 v[50:51], 12, v[50:51]
	v_lshlrev_b64 v[52:53], 12, v[52:53]
	v_lshlrev_b64 v[54:55], 12, v[54:55]
	v_lshlrev_b64 v[56:57], 12, v[56:57]
	v_lshlrev_b64 v[58:59], 12, v[58:59]
	v_lshlrev_b64 v[60:61], 12, v[60:61]
	v_lshl_add_u64 v[48:49], v[30:31], 0, v[48:49]
	v_lshl_add_u64 v[50:51], v[30:31], 0, v[50:51]
	v_lshl_add_u64 v[52:53], v[30:31], 0, v[52:53]
	v_lshl_add_u64 v[54:55], v[30:31], 0, v[54:55]
	v_lshl_add_u64 v[56:57], v[30:31], 0, v[56:57]
	v_lshl_add_u64 v[58:59], v[30:31], 0, v[58:59]
	v_lshl_add_u64 v[60:61], v[30:31], 0, v[60:61]
	global_load_dword v75, v[32:33], off
	global_load_dword v76, v[48:49], off
	global_load_dword v77, v[50:51], off
	global_load_dword v78, v[52:53], off
	global_load_dword v79, v[54:55], off
	global_load_dword v81, v[56:57], off
	global_load_dword v82, v[58:59], off
	global_load_dword v83, v[60:61], off
	v_or_b32_e32 v32, 48, v28
	v_ashrrev_i32_e32 v33, 31, v32
	v_or_b32_e32 v48, 50, v28
	v_or_b32_e32 v50, 52, v28
	v_or_b32_e32 v52, 54, v28
	v_or_b32_e32 v54, 56, v28
	v_or_b32_e32 v56, 58, v28
	v_or_b32_e32 v58, 60, v28
	v_or_b32_e32 v28, 62, v28
	v_lshlrev_b64 v[32:33], 12, v[32:33]
	v_ashrrev_i32_e32 v49, 31, v48
	v_ashrrev_i32_e32 v51, 31, v50
	v_ashrrev_i32_e32 v53, 31, v52
	v_ashrrev_i32_e32 v55, 31, v54
	v_ashrrev_i32_e32 v57, 31, v56
	v_ashrrev_i32_e32 v59, 31, v58
	v_ashrrev_i32_e32 v29, 31, v28
	v_lshl_add_u64 v[32:33], v[30:31], 0, v[32:33]
	v_lshlrev_b64 v[48:49], 12, v[48:49]
	v_lshlrev_b64 v[50:51], 12, v[50:51]
	v_lshlrev_b64 v[52:53], 12, v[52:53]
	v_lshlrev_b64 v[54:55], 12, v[54:55]
	v_lshlrev_b64 v[56:57], 12, v[56:57]
	v_lshlrev_b64 v[58:59], 12, v[58:59]
	v_lshlrev_b64 v[28:29], 12, v[28:29]
	v_lshl_add_u64 v[48:49], v[30:31], 0, v[48:49]
	v_lshl_add_u64 v[50:51], v[30:31], 0, v[50:51]
	v_lshl_add_u64 v[52:53], v[30:31], 0, v[52:53]
	v_lshl_add_u64 v[54:55], v[30:31], 0, v[54:55]
	v_lshl_add_u64 v[56:57], v[30:31], 0, v[56:57]
	v_lshl_add_u64 v[58:59], v[30:31], 0, v[58:59]
	v_lshl_add_u64 v[28:29], v[30:31], 0, v[28:29]
	global_load_dword v30, v[32:33], off
	global_load_dword v31, v[48:49], off
	global_load_dword v60, v[50:51], off
	global_load_dword v61, v[52:53], off
	global_load_dword v84, v[54:55], off
	global_load_dword v85, v[56:57], off
	global_load_dword v86, v[58:59], off
	global_load_dword v87, v[28:29], off
	s_waitcnt vmcnt(30)
; #define LAS __attribute__((address_space(3)))
; __device__ __forceinline__ unsigned pk2(float lo, float hi) { return pg8::cvt_pk_bf16(lo, hi); }
; __device__ __forceinline__ void transpose_item(const float* W, int K, int N, bf16* WT, int k0, int n0, int drow0, LAS float* scr, int lane) {
;     float wv[32];
; #pragma unroll
;     for (int i = 0; i < 32; ++i) wv[i] = W[(size_t)(k0 + 2 * i + (lane >> 5)) * N + n0 + (lane & 31)];
; #pragma unroll
;     for (int i = 0; i < 32; ++i) scr[(2 * i + (lane >> 5)) * 33 + (lane & 31)] = wv[i];
;     asm volatile("s_waitcnt lgkmcnt(0)" ::: "memory");
;     const int c = lane & 7;
; #pragma unroll
;     for (int j = 0; j < 4; ++j) { const int n = (lane >> 3) + 8 * j; const LAS float* s = scr + (8 * c) * 33 + n;
;         u32x4 o; o.x = pk2(s[0 * 33], s[1 * 33]); o.y = pk2(s[2 * 33], s[3 * 33]); o.z = pk2(s[4 * 33], s[5 * 33]); o.w = pk2(s[6 * 33], s[7 * 33]);
;         *(u32x4*)(WT + (size_t)(drow0 + n) * K + k0 + 8 * c) = o; }
;     asm volatile("s_waitcnt lgkmcnt(0)" ::: "memory");
; }
	ds_write2_b32 v35, v4, v25 offset1:66
	s_waitcnt vmcnt(28)
	ds_write2_b32 v35, v27, v62 offset0:132 offset1:198
	s_waitcnt vmcnt(26)
	ds_write2_b32 v41, v63, v64 offset0:8 offset1:74
	s_waitcnt vmcnt(24)
	ds_write2_b32 v41, v65, v66 offset0:140 offset1:206
	s_waitcnt vmcnt(22)
	ds_write2_b32 v42, v67, v68 offset0:16 offset1:82
	s_waitcnt vmcnt(20)
	ds_write2_b32 v42, v69, v70 offset0:148 offset1:214
	s_waitcnt vmcnt(18)
	ds_write2_b32 v43, v71, v72 offset0:24 offset1:90
	s_waitcnt vmcnt(16)
	ds_write2_b32 v43, v73, v74 offset0:156 offset1:222
	s_waitcnt vmcnt(14)
	ds_write2_b32 v44, v75, v76 offset0:32 offset1:98
	s_waitcnt vmcnt(12)
	ds_write2_b32 v44, v77, v78 offset0:164 offset1:230
	s_waitcnt vmcnt(10)
	ds_write2_b32 v45, v79, v81 offset0:40 offset1:106
	s_waitcnt vmcnt(8)
	ds_write2_b32 v45, v82, v83 offset0:172 offset1:238
	s_waitcnt vmcnt(6)
	ds_write2_b32 v46, v30, v31 offset0:48 offset1:114
	s_waitcnt vmcnt(4)
	ds_write2_b32 v46, v60, v61 offset0:180 offset1:246
	s_waitcnt vmcnt(2)
	ds_write2_b32 v47, v84, v85 offset0:56 offset1:122
	s_waitcnt vmcnt(0)
	ds_write2_b32 v47, v86, v87 offset0:188 offset1:254
	s_waitcnt lgkmcnt(0)
	v_ashrrev_i32_e32 v27, 31, v26
	ds_read2_b32 v[28:29], v37 offset1:33
	v_lshl_add_u64 v[48:49], v[26:27], 1, v[18:19]
	v_or_b32_e32 v26, v24, v36
	s_waitcnt lgkmcnt(0)
	v_cvt_pk_bf16_f32 v28, v28, v29
	ds_read2_b32 v[30:31], v37 offset0:66 offset1:99
	v_ashrrev_i32_e32 v27, 31, v26
	s_waitcnt lgkmcnt(0)
	v_cvt_pk_bf16_f32 v29, v30, v31
	ds_read2_b32 v[30:31], v37 offset0:132 offset1:165
	v_lshlrev_b64 v[26:27], 11, v[26:27]
	s_waitcnt lgkmcnt(0)
	v_cvt_pk_bf16_f32 v30, v30, v31
	ds_read2_b32 v[32:33], v37 offset0:198 offset1:231
	v_lshl_add_u64 v[26:27], v[48:49], 0, v[26:27]
	s_waitcnt lgkmcnt(0)
	v_cvt_pk_bf16_f32 v31, v32, v33
	ds_read2_b32 v[32:33], v37 offset0:8 offset1:41
	global_store_dwordx4 v[26:27], v[28:31], off sc0 sc1
	s_waitcnt lgkmcnt(0)
	v_cvt_pk_bf16_f32 v26, v32, v33
	ds_read2_b32 v[28:29], v37 offset0:74 offset1:107
	s_waitcnt lgkmcnt(0)
	v_cvt_pk_bf16_f32 v27, v28, v29
	ds_read2_b32 v[28:29], v37 offset0:140 offset1:173
	s_waitcnt lgkmcnt(0)
	v_cvt_pk_bf16_f32 v28, v28, v29
	ds_read2_b32 v[30:31], v37 offset0:206 offset1:239
	s_waitcnt lgkmcnt(0)
	v_cvt_pk_bf16_f32 v29, v30, v31
	v_or_b32_e32 v30, v24, v38
	v_ashrrev_i32_e32 v31, 31, v30
	v_lshlrev_b64 v[30:31], 11, v[30:31]
	v_lshl_add_u64 v[30:31], v[48:49], 0, v[30:31]
	ds_read2_b32 v[32:33], v37 offset0:16 offset1:49
	global_store_dwordx4 v[30:31], v[26:29], off sc0 sc1
	s_waitcnt lgkmcnt(0)
	s_nop 0
	v_cvt_pk_bf16_f32 v26, v32, v33
	ds_read2_b32 v[28:29], v37 offset0:82 offset1:115
	s_waitcnt lgkmcnt(0)
	v_cvt_pk_bf16_f32 v27, v28, v29
	ds_read2_b32 v[28:29], v37 offset0:148 offset1:181
	s_waitcnt lgkmcnt(0)
	v_cvt_pk_bf16_f32 v28, v28, v29
	ds_read2_b32 v[30:31], v37 offset0:214 offset1:247
	s_waitcnt lgkmcnt(0)
	v_cvt_pk_bf16_f32 v29, v30, v31
	v_or_b32_e32 v30, v24, v39
	v_ashrrev_i32_e32 v31, 31, v30
	v_lshlrev_b64 v[30:31], 11, v[30:31]
	v_or_b32_e32 v24, v24, v40
	v_lshl_add_u64 v[30:31], v[48:49], 0, v[30:31]
	v_ashrrev_i32_e32 v25, 31, v24
	ds_read2_b32 v[32:33], v37 offset0:24 offset1:57
	global_store_dwordx4 v[30:31], v[26:29], off sc0 sc1
	v_lshlrev_b64 v[24:25], 11, v[24:25]
	v_lshl_add_u64 v[24:25], v[48:49], 0, v[24:25]
	s_waitcnt lgkmcnt(0)
	v_cvt_pk_bf16_f32 v26, v32, v33
	ds_read2_b32 v[28:29], v37 offset0:90 offset1:123
	s_waitcnt lgkmcnt(0)
	v_cvt_pk_bf16_f32 v27, v28, v29
	ds_read2_b32 v[28:29], v37 offset0:156 offset1:189
	s_waitcnt lgkmcnt(0)
	v_cvt_pk_bf16_f32 v28, v28, v29
	ds_read2_b32 v[30:31], v37 offset0:222 offset1:255
	s_waitcnt lgkmcnt(0)
	v_cvt_pk_bf16_f32 v29, v30, v31
	global_store_dwordx4 v[24:25], v[26:29], off sc0 sc1
	s_waitcnt lgkmcnt(0)
	s_branch .LBB0_22

.LBB0_70:
	v_add_u32_e32 v7, s14, v7
	v_cmp_lt_i32_e32 vcc, s0, v7
	global_store_dwordx4 v[8:9], v[2:5], off sc0 sc1
	s_or_b64 s[16:17], vcc, s[16:17]
	v_lshl_add_u64 v[8:9], v[8:9], 0, s[6:7]
	s_andn2_b64 exec, exec, s[16:17]
	s_cbranch_execnz .LBB0_70

; __device__ __forceinline__ void norm_mod_phase(ArgsP a, bool from_input, const float* g, const float* modsL, int ishift, int iscale, int nparts, int wave_s_) {
;     ...
;         if ((from_input && row >= NPROMPT) || (row >= NPROMPT && nparts > 0)) {
; #pragma unroll
;             for (int j = 0; j < 4; ++j) *(f32x4*)(X + (size_t)row * DM + 4 * lane + 256 * j) = v[j];
;         }
.LBB0_131:
	s_or_b64 exec, exec, s[28:29]
	s_and_saveexec_b64 s[28:29], s[6:7]
	s_xor_b64 s[6:7], exec, s[28:29]
	s_andn2_saveexec_b64 s[6:7], s[6:7]
	s_cbranch_execz .LBB0_118
	v_mov_b32_e32 v137, v197
	v_lshlrev_b64 v[48:49], 12, v[136:137]
	v_lshl_add_u64 v[48:49], v[132:133], 0, v[48:49]
	s_waitcnt vmcnt(3)
	global_store_dwordx4 v[48:49], v[40:43], off sc0 sc1
	s_waitcnt vmcnt(3)
	global_store_dwordx4 v[48:49], v[36:39], off offset:1024 sc0 sc1
	s_waitcnt vmcnt(3)
	global_store_dwordx4 v[48:49], v[32:35], off offset:2048 sc0 sc1
	s_waitcnt vmcnt(3)
	global_store_dwordx4 v[48:49], v[44:47], off offset:3072 sc0 sc1
	s_branch .LBB0_118

; __device__ __forceinline__ float silu_f(float x) { return x * __builtin_amdgcn_rcpf(1.0f + __expf(-x)); }
; __device__ __forceinline__ u32x4 pack8(const f32x4& a, const f32x4& b) { u32x4 w; w.x = cvt_pk_bf16(a[0], a[1]); w.y = cvt_pk_bf16(a[2], a[3]); w.z = cvt_pk_bf16(b[0], b[1]); w.w = cvt_pk_bf16(b[2], b[3]); return w; }
;     __device__ __forceinline__ void operator()(const f32x4 (&acc)[2][2][4][2], const Unit& u, int wr, int wc, int fr, int fq) const {
;         { int l_; asm volatile("v_mbcnt_lo_u32_b32 %0, -1, 0\n\tv_mbcnt_hi_u32_b32 %0, -1, %0" : "=v"(l_)); fr = l_ & 15; fq = (l_ >> 4) & 3; }
;         const int row0 = u.pm * BM + wr * 64 + fr, col0 = u.pn * 128 + wc * 32 + 8 * fq;
; #pragma unroll
;         for (int ai = 0; ai < 2; ++ai)
; #pragma unroll
;             for (int m = 0; m < 4; ++m) {
;                 f32x4 h0, h1;
; #pragma unroll
;                 for (int j = 0; j < 4; ++j) { h0[j] = silu_f(acc[ai][0][m][0][j]) * acc[ai][1][m][0][j]; h1[j] = silu_f(acc[ai][0][m][1][j]) * acc[ai][1][m][1][j]; }
;                 *(u32x4*)(HID + (size_t)(row0 + ai * HALF + m * 16) * DFF + col0) = pack8(h0, h1);
;             }
;     }
.LBB0_210:
	v_mbcnt_lo_u32_b32 v140, -1, 0
	v_mbcnt_hi_u32_b32 v140, -1, v140
	s_lshl_b32 s17, s47, 7
	v_lshrrev_b32_e32 v141, 1, v140
	v_and_or_b32 v141, v141, 24, s17
	v_or_b32_e32 v142, s40, v141
	v_mul_f32_e32 v141, 0xbfb8aa3b, v124
	v_exp_f32_e32 v141, v141
	v_and_or_b32 v140, v140, 15, s39
	v_lshl_add_u32 v140, s46, 8, v140
	v_ashrrev_i32_e32 v143, 31, v142
	v_add_f32_e32 v141, 1.0, v141
	v_rcp_f32_e32 v141, v141
	s_and_b64 vcc, exec, s[6:7]
	v_mul_f32_e32 v124, v124, v141
	v_mul_f32_e32 v120, v124, v120
	v_mul_f32_e32 v124, 0xbfb8aa3b, v116
	v_exp_f32_e32 v124, v124
	s_nop 0
	v_add_f32_e32 v124, 1.0, v124
	v_rcp_f32_e32 v124, v124
	s_nop 0
	v_mul_f32_e32 v116, v116, v124
	v_mul_f32_e32 v112, v116, v112
	v_mul_f32_e32 v116, 0xbfb8aa3b, v125
	v_exp_f32_e32 v116, v116
	s_nop 0
	v_add_f32_e32 v116, 1.0, v116
	v_rcp_f32_e32 v116, v116
	s_nop 0
	v_mul_f32_e32 v116, v125, v116
	v_mul_f32_e32 v116, v116, v121
	v_mul_f32_e32 v121, 0xbfb8aa3b, v117
	v_exp_f32_e32 v121, v121
	v_cvt_pk_bf16_f32 v116, v120, v116
	s_nop 0
	v_add_f32_e32 v121, 1.0, v121
	v_rcp_f32_e32 v121, v121
	s_nop 0
	v_mul_f32_e32 v117, v117, v121
	v_mul_f32_e32 v121, 0xbfb8aa3b, v118
	v_exp_f32_e32 v121, v121
	v_mul_f32_e32 v113, v117, v113
	v_mul_f32_e32 v117, 0xbfb8aa3b, v126
	v_exp_f32_e32 v117, v117
	v_add_f32_e32 v121, 1.0, v121
	v_rcp_f32_e32 v121, v121
	v_add_f32_e32 v117, 1.0, v117
	v_rcp_f32_e32 v117, v117
	v_mul_f32_e32 v118, v118, v121
	v_mul_f32_e32 v114, v118, v114
	v_mul_f32_e32 v118, 0xbfb8aa3b, v127
	v_exp_f32_e32 v118, v118
	v_mul_f32_e32 v121, 0xbfb8aa3b, v119
	v_exp_f32_e32 v121, v121
	v_mul_f32_e32 v117, v126, v117
	v_add_f32_e32 v118, 1.0, v118
	v_rcp_f32_e32 v118, v118
	v_add_f32_e32 v121, 1.0, v121
	v_rcp_f32_e32 v121, v121
	v_mul_f32_e32 v117, v117, v122
	v_mul_f32_e32 v118, v127, v118
	v_mul_f32_e32 v118, v118, v123
	v_mul_f32_e32 v119, v119, v121
	v_mul_f32_e32 v115, v119, v115
	v_cvt_pk_bf16_f32 v117, v117, v118
	v_cvt_pk_bf16_f32 v118, v112, v113
	v_mov_b64_e32 v[112:113], s[12:13]
	v_cvt_pk_bf16_f32 v119, v114, v115
	v_mad_i64_i32 v[120:121], s[22:23], v140, s85, v[112:113]
	v_lshlrev_b64 v[114:115], 1, v[142:143]
	v_lshl_add_u64 v[120:121], v[120:121], 0, v[114:115]
	global_store_dwordx4 v[120:121], v[116:119], off sc0 sc1
	s_nop 1
	v_mul_f32_e32 v116, 0xbfb8aa3b, v108
	v_exp_f32_e32 v116, v116
	s_nop 0
	v_add_f32_e32 v116, 1.0, v116
	v_rcp_f32_e32 v116, v116
	s_nop 0
	v_mul_f32_e32 v108, v108, v116
	v_mul_f32_e32 v104, v108, v104
	v_mul_f32_e32 v108, 0xbfb8aa3b, v100
	v_exp_f32_e32 v108, v108
	s_nop 0
	v_add_f32_e32 v108, 1.0, v108
	v_rcp_f32_e32 v108, v108
	s_nop 0
	v_mul_f32_e32 v100, v100, v108
	v_mul_f32_e32 v100, v100, v96
	v_mul_f32_e32 v96, 0xbfb8aa3b, v109
	v_exp_f32_e32 v96, v96
	s_nop 0
	v_add_f32_e32 v96, 1.0, v96
	v_rcp_f32_e32 v96, v96
	s_nop 0
	v_mul_f32_e32 v96, v109, v96
	v_mul_f32_e32 v96, v96, v105
	v_mul_f32_e32 v105, 0xbfb8aa3b, v101
	v_exp_f32_e32 v105, v105
	v_cvt_pk_bf16_f32 v96, v104, v96
	s_nop 0
	v_add_f32_e32 v105, 1.0, v105
	v_rcp_f32_e32 v105, v105
	s_nop 0
	v_mul_f32_e32 v101, v101, v105
	v_mul_f32_e32 v105, 0xbfb8aa3b, v102
	v_exp_f32_e32 v105, v105
	v_mul_f32_e32 v101, v101, v97
	v_mul_f32_e32 v97, 0xbfb8aa3b, v110
	v_exp_f32_e32 v97, v97
	v_add_f32_e32 v105, 1.0, v105
	v_rcp_f32_e32 v105, v105
	v_add_f32_e32 v97, 1.0, v97
	v_rcp_f32_e32 v97, v97
	v_mul_f32_e32 v102, v102, v105
	v_mul_f32_e32 v102, v102, v98
	v_mul_f32_e32 v98, 0xbfb8aa3b, v111
	v_exp_f32_e32 v98, v98
	v_mul_f32_e32 v105, 0xbfb8aa3b, v103
	v_exp_f32_e32 v105, v105
	v_mul_f32_e32 v97, v110, v97
	v_add_f32_e32 v98, 1.0, v98
	v_rcp_f32_e32 v98, v98
	v_add_f32_e32 v105, 1.0, v105
	v_rcp_f32_e32 v105, v105
	v_mul_f32_e32 v97, v97, v106
	v_mul_f32_e32 v98, v111, v98
	v_mul_f32_e32 v98, v98, v107
	v_cvt_pk_bf16_f32 v97, v97, v98
	v_cvt_pk_bf16_f32 v98, v100, v101
	v_or_b32_e32 v100, 16, v140
	v_mul_f32_e32 v103, v103, v105
	v_mad_i64_i32 v[100:101], s[22:23], v100, s85, v[112:113]
	v_mul_f32_e32 v99, v103, v99
	v_lshl_add_u64 v[100:101], v[100:101], 0, v[114:115]
	v_cvt_pk_bf16_f32 v99, v102, v99
	global_store_dwordx4 v[100:101], v[96:99], off sc0 sc1
	s_nop 1
	v_mul_f32_e32 v96, 0xbfb8aa3b, v92
	v_exp_f32_e32 v96, v96
	s_nop 0
	v_add_f32_e32 v96, 1.0, v96
	v_rcp_f32_e32 v96, v96
	s_nop 0
	v_mul_f32_e32 v92, v92, v96
	v_mul_f32_e32 v88, v92, v88
	v_mul_f32_e32 v92, 0xbfb8aa3b, v84
	v_exp_f32_e32 v92, v92
	s_nop 0
	v_add_f32_e32 v92, 1.0, v92
	v_rcp_f32_e32 v92, v92
	s_nop 0
	v_mul_f32_e32 v84, v84, v92
	v_mul_f32_e32 v84, v84, v80
	v_mul_f32_e32 v80, 0xbfb8aa3b, v93
	v_exp_f32_e32 v80, v80
	s_nop 0
	v_add_f32_e32 v80, 1.0, v80
	v_rcp_f32_e32 v80, v80
	s_nop 0
	v_mul_f32_e32 v80, v93, v80
	v_mul_f32_e32 v80, v80, v89
	v_mul_f32_e32 v89, 0xbfb8aa3b, v85
	v_exp_f32_e32 v89, v89
	v_cvt_pk_bf16_f32 v80, v88, v80
	s_nop 0
	v_add_f32_e32 v89, 1.0, v89
	v_rcp_f32_e32 v89, v89
	s_nop 0
	v_mul_f32_e32 v85, v85, v89
	v_mul_f32_e32 v89, 0xbfb8aa3b, v86
	v_exp_f32_e32 v89, v89
	v_mul_f32_e32 v85, v85, v81
	v_mul_f32_e32 v81, 0xbfb8aa3b, v94
	v_exp_f32_e32 v81, v81
	v_add_f32_e32 v89, 1.0, v89
	v_rcp_f32_e32 v89, v89
	v_add_f32_e32 v81, 1.0, v81
	v_rcp_f32_e32 v81, v81
	v_mul_f32_e32 v86, v86, v89
	v_mul_f32_e32 v86, v86, v82
	v_mul_f32_e32 v82, 0xbfb8aa3b, v95
	v_exp_f32_e32 v82, v82
	v_mul_f32_e32 v89, 0xbfb8aa3b, v87
	v_exp_f32_e32 v89, v89
	v_mul_f32_e32 v81, v94, v81
	v_add_f32_e32 v82, 1.0, v82
	v_rcp_f32_e32 v82, v82
	v_add_f32_e32 v89, 1.0, v89
	v_rcp_f32_e32 v89, v89
	v_mul_f32_e32 v81, v81, v90
	v_mul_f32_e32 v82, v95, v82
	v_mul_f32_e32 v82, v82, v91
	v_cvt_pk_bf16_f32 v81, v81, v82
	v_cvt_pk_bf16_f32 v82, v84, v85
	v_or_b32_e32 v84, 32, v140
; __device__ __forceinline__ float silu_f(float x) { return x * __builtin_amdgcn_rcpf(1.0f + __expf(-x)); }
; __device__ __forceinline__ u32x4 pack8(const f32x4& a, const f32x4& b) { u32x4 w; w.x = cvt_pk_bf16(a[0], a[1]); w.y = cvt_pk_bf16(a[2], a[3]); w.z = cvt_pk_bf16(b[0], b[1]); w.w = cvt_pk_bf16(b[2], b[3]); return w; }
;     __device__ __forceinline__ void operator()(const f32x4 (&acc)[2][2][4][2], const Unit& u, int wr, int wc, int fr, int fq) const {
;         { int l_; asm volatile("v_mbcnt_lo_u32_b32 %0, -1, 0\n\tv_mbcnt_hi_u32_b32 %0, -1, %0" : "=v"(l_)); fr = l_ & 15; fq = (l_ >> 4) & 3; }
;         const int row0 = u.pm * BM + wr * 64 + fr, col0 = u.pn * 128 + wc * 32 + 8 * fq;
; #pragma unroll
;         for (int ai = 0; ai < 2; ++ai)
; #pragma unroll
;             for (int m = 0; m < 4; ++m) {
;                 f32x4 h0, h1;
; #pragma unroll
;                 for (int j = 0; j < 4; ++j) { h0[j] = silu_f(acc[ai][0][m][0][j]) * acc[ai][1][m][0][j]; h1[j] = silu_f(acc[ai][0][m][1][j]) * acc[ai][1][m][1][j]; }
;                 *(u32x4*)(HID + (size_t)(row0 + ai * HALF + m * 16) * DFF + col0) = pack8(h0, h1);
;             }
;     }
	v_mul_f32_e32 v87, v87, v89
	v_mad_i64_i32 v[84:85], s[22:23], v84, s85, v[112:113]
	v_mul_f32_e32 v83, v87, v83
	v_lshl_add_u64 v[84:85], v[84:85], 0, v[114:115]
	v_cvt_pk_bf16_f32 v83, v86, v83
	global_store_dwordx4 v[84:85], v[80:83], off sc0 sc1
	s_nop 1
	v_mul_f32_e32 v80, 0xbfb8aa3b, v76
	v_exp_f32_e32 v80, v80
	s_nop 0
	v_add_f32_e32 v80, 1.0, v80
	v_rcp_f32_e32 v80, v80
	s_nop 0
	v_mul_f32_e32 v76, v76, v80
	v_mul_f32_e32 v72, v76, v72
	v_mul_f32_e32 v76, 0xbfb8aa3b, v68
	v_exp_f32_e32 v76, v76
	s_nop 0
	v_add_f32_e32 v76, 1.0, v76
	v_rcp_f32_e32 v76, v76
	s_nop 0
	v_mul_f32_e32 v68, v68, v76
	v_mul_f32_e32 v68, v68, v64
	v_mul_f32_e32 v64, 0xbfb8aa3b, v77
	v_exp_f32_e32 v64, v64
	s_nop 0
	v_add_f32_e32 v64, 1.0, v64
	v_rcp_f32_e32 v64, v64
	s_nop 0
	v_mul_f32_e32 v64, v77, v64
	v_mul_f32_e32 v64, v64, v73
	v_mul_f32_e32 v73, 0xbfb8aa3b, v69
	v_exp_f32_e32 v73, v73
	v_cvt_pk_bf16_f32 v64, v72, v64
	s_nop 0
	v_add_f32_e32 v73, 1.0, v73
	v_rcp_f32_e32 v73, v73
	s_nop 0
	v_mul_f32_e32 v69, v69, v73
	v_mul_f32_e32 v73, 0xbfb8aa3b, v70
	v_exp_f32_e32 v73, v73
	v_mul_f32_e32 v69, v69, v65
	v_mul_f32_e32 v65, 0xbfb8aa3b, v78
	v_exp_f32_e32 v65, v65
	v_add_f32_e32 v73, 1.0, v73
	v_rcp_f32_e32 v73, v73
	v_add_f32_e32 v65, 1.0, v65
	v_rcp_f32_e32 v65, v65
	v_mul_f32_e32 v70, v70, v73
	v_mul_f32_e32 v70, v70, v66
	v_mul_f32_e32 v66, 0xbfb8aa3b, v79
	v_exp_f32_e32 v66, v66
	v_mul_f32_e32 v73, 0xbfb8aa3b, v71
	v_exp_f32_e32 v73, v73
	v_mul_f32_e32 v65, v78, v65
	v_add_f32_e32 v66, 1.0, v66
	v_rcp_f32_e32 v66, v66
	v_add_f32_e32 v73, 1.0, v73
	v_rcp_f32_e32 v73, v73
	v_mul_f32_e32 v65, v65, v74
	v_mul_f32_e32 v66, v79, v66
	v_mul_f32_e32 v66, v66, v75
	v_cvt_pk_bf16_f32 v65, v65, v66
	v_cvt_pk_bf16_f32 v66, v68, v69
	v_or_b32_e32 v68, 48, v140
	v_mul_f32_e32 v71, v71, v73
	v_mad_i64_i32 v[68:69], s[22:23], v68, s85, v[112:113]
	v_mul_f32_e32 v67, v71, v67
	v_lshl_add_u64 v[68:69], v[68:69], 0, v[114:115]
	v_cvt_pk_bf16_f32 v67, v70, v67
	global_store_dwordx4 v[68:69], v[64:67], off sc0 sc1
	s_nop 1
	v_mul_f32_e32 v65, 0xbfb8aa3b, v60
	v_exp_f32_e32 v65, v65
	v_add_u32_e32 v64, 0x80, v140
	v_add_f32_e32 v65, 1.0, v65
	v_rcp_f32_e32 v65, v65
	s_nop 0
	v_mul_f32_e32 v60, v60, v65
	v_mul_f32_e32 v56, v60, v56
	v_mul_f32_e32 v60, 0xbfb8aa3b, v52
	v_exp_f32_e32 v60, v60
	s_nop 0
	v_add_f32_e32 v60, 1.0, v60
	v_rcp_f32_e32 v60, v60
	s_nop 0
	v_mul_f32_e32 v52, v52, v60
	v_mul_f32_e32 v52, v52, v48
	v_mul_f32_e32 v48, 0xbfb8aa3b, v61
	v_exp_f32_e32 v48, v48
	s_nop 0
	v_add_f32_e32 v48, 1.0, v48
	v_rcp_f32_e32 v48, v48
	s_nop 0
	v_mul_f32_e32 v48, v61, v48
	v_mul_f32_e32 v48, v48, v57
	v_mul_f32_e32 v57, 0xbfb8aa3b, v53
	v_exp_f32_e32 v57, v57
	v_cvt_pk_bf16_f32 v48, v56, v48
	s_nop 0
	v_add_f32_e32 v57, 1.0, v57
	v_rcp_f32_e32 v57, v57
	s_nop 0
	v_mul_f32_e32 v53, v53, v57
	v_mul_f32_e32 v57, 0xbfb8aa3b, v54
	v_exp_f32_e32 v57, v57
	v_mul_f32_e32 v53, v53, v49
	v_mul_f32_e32 v49, 0xbfb8aa3b, v62
	v_exp_f32_e32 v49, v49
	v_add_f32_e32 v57, 1.0, v57
	v_rcp_f32_e32 v57, v57
	v_add_f32_e32 v49, 1.0, v49
	v_rcp_f32_e32 v49, v49
	v_mul_f32_e32 v54, v54, v57
	v_mul_f32_e32 v54, v54, v50
	v_mul_f32_e32 v50, 0xbfb8aa3b, v63
	v_exp_f32_e32 v50, v50
	v_mul_f32_e32 v57, 0xbfb8aa3b, v55
	v_exp_f32_e32 v57, v57
	v_mul_f32_e32 v49, v62, v49
	v_add_f32_e32 v50, 1.0, v50
	v_rcp_f32_e32 v50, v50
	v_add_f32_e32 v57, 1.0, v57
	v_rcp_f32_e32 v57, v57
	v_mul_f32_e32 v49, v49, v58
	v_mul_f32_e32 v50, v63, v50
	v_mul_f32_e32 v50, v50, v59
	v_mul_f32_e32 v55, v55, v57
	v_cvt_pk_bf16_f32 v49, v49, v50
	v_cvt_pk_bf16_f32 v50, v52, v53
	v_mad_i64_i32 v[52:53], s[22:23], v64, s85, v[112:113]
	v_mul_f32_e32 v51, v55, v51
	v_lshl_add_u64 v[52:53], v[52:53], 0, v[114:115]
	v_cvt_pk_bf16_f32 v51, v54, v51
	global_store_dwordx4 v[52:53], v[48:51], off sc0 sc1
	s_nop 1
	v_mul_f32_e32 v48, 0xbfb8aa3b, v44
	v_exp_f32_e32 v48, v48
	s_nop 0
	v_add_f32_e32 v48, 1.0, v48
	v_rcp_f32_e32 v48, v48
	s_nop 0
	v_mul_f32_e32 v44, v44, v48
	v_mul_f32_e32 v40, v44, v40
	v_mul_f32_e32 v44, 0xbfb8aa3b, v36
	v_exp_f32_e32 v44, v44
	s_nop 0
	v_add_f32_e32 v44, 1.0, v44
	v_rcp_f32_e32 v44, v44
	s_nop 0
	v_mul_f32_e32 v36, v36, v44
	v_mul_f32_e32 v36, v36, v32
	v_mul_f32_e32 v32, 0xbfb8aa3b, v45
	v_exp_f32_e32 v32, v32
	s_nop 0
	v_add_f32_e32 v32, 1.0, v32
	v_rcp_f32_e32 v32, v32
	s_nop 0
	v_mul_f32_e32 v32, v45, v32
	v_mul_f32_e32 v32, v32, v41
	v_mul_f32_e32 v41, 0xbfb8aa3b, v37
	v_exp_f32_e32 v41, v41
	v_cvt_pk_bf16_f32 v32, v40, v32
	s_nop 0
	v_add_f32_e32 v41, 1.0, v41
	v_rcp_f32_e32 v41, v41
	s_nop 0
	v_mul_f32_e32 v37, v37, v41
; __device__ __forceinline__ float silu_f(float x) { return x * __builtin_amdgcn_rcpf(1.0f + __expf(-x)); }
; __device__ __forceinline__ u32x4 pack8(const f32x4& a, const f32x4& b) { u32x4 w; w.x = cvt_pk_bf16(a[0], a[1]); w.y = cvt_pk_bf16(a[2], a[3]); w.z = cvt_pk_bf16(b[0], b[1]); w.w = cvt_pk_bf16(b[2], b[3]); return w; }
; #define PG8_BAR __builtin_amdgcn_s_barrier()
;     __device__ __forceinline__ void operator()(const f32x4 (&acc)[2][2][4][2], const Unit& u, int wr, int wc, int fr, int fq) const {
;         { int l_; asm volatile("v_mbcnt_lo_u32_b32 %0, -1, 0\n\tv_mbcnt_hi_u32_b32 %0, -1, %0" : "=v"(l_)); fr = l_ & 15; fq = (l_ >> 4) & 3; }
;         const int row0 = u.pm * BM + wr * 64 + fr, col0 = u.pn * 128 + wc * 32 + 8 * fq;
; #pragma unroll
;         for (int ai = 0; ai < 2; ++ai)
; #pragma unroll
;             for (int m = 0; m < 4; ++m) {
;                 f32x4 h0, h1;
; #pragma unroll
;                 for (int j = 0; j < 4; ++j) { h0[j] = silu_f(acc[ai][0][m][0][j]) * acc[ai][1][m][0][j]; h1[j] = silu_f(acc[ai][0][m][1][j]) * acc[ai][1][m][1][j]; }
;                 *(u32x4*)(HID + (size_t)(row0 + ai * HALF + m * 16) * DFF + col0) = pack8(h0, h1);
;             }
;     }
; template <class Epi, class Sched, bool ALIGN_EPI = false, bool SP2 = false>
; __device__ __forceinline__ void gemm_phase(PG8_LAS unsigned char* lds, const Gemm g, const Sched& S, const Epi& E, int wave_s_) {
;     ...
;         if constexpr (ALIGN_EPI) { if (wr == 0) PG8_BAR; }
;         if constexpr (!Epi::AFTER_DRAIN) { E(acc, cur, wr, wc, fr, fq); S.done(cur); }
;         if (!has_next) break;
; #pragma unroll
;         for (int a = 0; a < 2; ++a)
; #pragma unroll
;             for (int b = 0; b < 2; ++b)
; #pragma unroll
;                 for (int m = 0; m < 4; ++m)
; #pragma unroll
;                     for (int n = 0; n < 2; ++n) acc[a][b][m][n] = (f32x4){0.f, 0.f, 0.f, 0.f};
;         cur = nxt; cA = nA; cB = nB; ++ui;
;         if constexpr (ALIGN_EPI) { if (wr == 1) PG8_BAR; }
;     }
	v_mul_f32_e32 v41, 0xbfb8aa3b, v38
	v_exp_f32_e32 v41, v41
	v_mul_f32_e32 v37, v37, v33
	v_mul_f32_e32 v33, 0xbfb8aa3b, v46
	v_exp_f32_e32 v33, v33
	v_add_f32_e32 v41, 1.0, v41
	v_rcp_f32_e32 v41, v41
	v_add_f32_e32 v33, 1.0, v33
	v_rcp_f32_e32 v33, v33
	v_mul_f32_e32 v38, v38, v41
	v_mul_f32_e32 v38, v38, v34
	v_mul_f32_e32 v34, 0xbfb8aa3b, v47
	v_exp_f32_e32 v34, v34
	v_mul_f32_e32 v41, 0xbfb8aa3b, v39
	v_exp_f32_e32 v41, v41
	v_mul_f32_e32 v33, v46, v33
	v_add_f32_e32 v34, 1.0, v34
	v_rcp_f32_e32 v34, v34
	v_add_f32_e32 v41, 1.0, v41
	v_rcp_f32_e32 v41, v41
	v_mul_f32_e32 v33, v33, v42
	v_mul_f32_e32 v34, v47, v34
	v_mul_f32_e32 v34, v34, v43
	v_cvt_pk_bf16_f32 v33, v33, v34
	v_cvt_pk_bf16_f32 v34, v36, v37
	v_add_u32_e32 v36, 0x90, v140
	v_mul_f32_e32 v39, v39, v41
	v_mad_i64_i32 v[36:37], s[22:23], v36, s85, v[112:113]
	v_mul_f32_e32 v35, v39, v35
	v_lshl_add_u64 v[36:37], v[36:37], 0, v[114:115]
	v_cvt_pk_bf16_f32 v35, v38, v35
	global_store_dwordx4 v[36:37], v[32:35], off sc0 sc1
	s_nop 1
	v_mul_f32_e32 v32, 0xbfb8aa3b, v28
	v_exp_f32_e32 v32, v32
	s_nop 0
	v_add_f32_e32 v32, 1.0, v32
	v_rcp_f32_e32 v32, v32
	s_nop 0
	v_mul_f32_e32 v28, v28, v32
	v_mul_f32_e32 v24, v28, v24
	v_mul_f32_e32 v28, 0xbfb8aa3b, v20
	v_exp_f32_e32 v28, v28
	s_nop 0
	v_add_f32_e32 v28, 1.0, v28
	v_rcp_f32_e32 v28, v28
	s_nop 0
	v_mul_f32_e32 v20, v20, v28
	v_mul_f32_e32 v20, v20, v16
	v_mul_f32_e32 v16, 0xbfb8aa3b, v29
	v_exp_f32_e32 v16, v16
	s_nop 0
	v_add_f32_e32 v16, 1.0, v16
	v_rcp_f32_e32 v16, v16
	s_nop 0
	v_mul_f32_e32 v16, v29, v16
	v_mul_f32_e32 v16, v16, v25
	v_mul_f32_e32 v25, 0xbfb8aa3b, v21
	v_exp_f32_e32 v25, v25
	v_cvt_pk_bf16_f32 v16, v24, v16
	s_nop 0
	v_add_f32_e32 v25, 1.0, v25
	v_rcp_f32_e32 v25, v25
	s_nop 0
	v_mul_f32_e32 v21, v21, v25
	v_mul_f32_e32 v25, 0xbfb8aa3b, v22
	v_exp_f32_e32 v25, v25
	v_mul_f32_e32 v21, v21, v17
	v_mul_f32_e32 v17, 0xbfb8aa3b, v30
	v_exp_f32_e32 v17, v17
	v_add_f32_e32 v25, 1.0, v25
	v_rcp_f32_e32 v25, v25
	v_add_f32_e32 v17, 1.0, v17
	v_rcp_f32_e32 v17, v17
	v_mul_f32_e32 v22, v22, v25
	v_mul_f32_e32 v22, v22, v18
	v_mul_f32_e32 v18, 0xbfb8aa3b, v31
	v_exp_f32_e32 v18, v18
	v_mul_f32_e32 v25, 0xbfb8aa3b, v23
	v_exp_f32_e32 v25, v25
	v_mul_f32_e32 v17, v30, v17
	v_add_f32_e32 v18, 1.0, v18
	v_rcp_f32_e32 v18, v18
	v_add_f32_e32 v25, 1.0, v25
	v_rcp_f32_e32 v25, v25
	v_mul_f32_e32 v17, v17, v26
	v_mul_f32_e32 v18, v31, v18
	v_mul_f32_e32 v18, v18, v27
	v_cvt_pk_bf16_f32 v17, v17, v18
	v_cvt_pk_bf16_f32 v18, v20, v21
	v_add_u32_e32 v20, 0xa0, v140
	v_mul_f32_e32 v23, v23, v25
	v_mad_i64_i32 v[20:21], s[22:23], v20, s85, v[112:113]
	v_mul_f32_e32 v19, v23, v19
	v_lshl_add_u64 v[20:21], v[20:21], 0, v[114:115]
	v_cvt_pk_bf16_f32 v19, v22, v19
	global_store_dwordx4 v[20:21], v[16:19], off sc0 sc1
	s_nop 1
	v_mul_f32_e32 v16, 0xbfb8aa3b, v12
	v_exp_f32_e32 v16, v16
	s_nop 0
	v_add_f32_e32 v16, 1.0, v16
	v_rcp_f32_e32 v16, v16
	s_nop 0
	v_mul_f32_e32 v12, v12, v16
	v_mul_f32_e32 v8, v12, v8
	v_mul_f32_e32 v12, 0xbfb8aa3b, v4
	v_exp_f32_e32 v12, v12
	s_nop 0
	v_add_f32_e32 v12, 1.0, v12
	v_rcp_f32_e32 v12, v12
	s_nop 0
	v_mul_f32_e32 v4, v4, v12
	v_mul_f32_e32 v4, v4, v0
	v_mul_f32_e32 v0, 0xbfb8aa3b, v13
	v_exp_f32_e32 v0, v0
	s_nop 0
	v_add_f32_e32 v0, 1.0, v0
	v_rcp_f32_e32 v0, v0
	s_nop 0
	v_mul_f32_e32 v0, v13, v0
	v_mul_f32_e32 v0, v0, v9
	v_mul_f32_e32 v9, 0xbfb8aa3b, v5
	v_exp_f32_e32 v9, v9
	v_cvt_pk_bf16_f32 v0, v8, v0
	s_nop 0
	v_add_f32_e32 v9, 1.0, v9
	v_rcp_f32_e32 v9, v9
	s_nop 0
	v_mul_f32_e32 v5, v5, v9
	v_mul_f32_e32 v9, 0xbfb8aa3b, v6
	v_exp_f32_e32 v9, v9
	v_mul_f32_e32 v5, v5, v1
	v_mul_f32_e32 v1, 0xbfb8aa3b, v14
	v_exp_f32_e32 v1, v1
	v_add_f32_e32 v9, 1.0, v9
	v_rcp_f32_e32 v9, v9
	v_add_f32_e32 v1, 1.0, v1
	v_rcp_f32_e32 v1, v1
	v_mul_f32_e32 v6, v6, v9
	v_mul_f32_e32 v6, v6, v2
	v_mul_f32_e32 v2, 0xbfb8aa3b, v15
	v_exp_f32_e32 v2, v2
	v_mul_f32_e32 v9, 0xbfb8aa3b, v7
	v_exp_f32_e32 v9, v9
	v_mul_f32_e32 v1, v14, v1
	v_add_f32_e32 v2, 1.0, v2
	v_rcp_f32_e32 v2, v2
	v_add_f32_e32 v9, 1.0, v9
	v_rcp_f32_e32 v9, v9
	v_mul_f32_e32 v1, v1, v10
	v_mul_f32_e32 v2, v15, v2
	v_mul_f32_e32 v2, v2, v11
	v_cvt_pk_bf16_f32 v1, v1, v2
	v_cvt_pk_bf16_f32 v2, v4, v5
	v_add_u32_e32 v4, 0xb0, v140
	v_mul_f32_e32 v7, v7, v9
	v_mad_i64_i32 v[4:5], s[22:23], v4, s85, v[112:113]
	v_mul_f32_e32 v3, v7, v3
	v_lshl_add_u64 v[4:5], v[4:5], 0, v[114:115]
	s_mov_b64 s[22:23], -1
	v_cvt_pk_bf16_f32 v3, v6, v3
	global_store_dwordx4 v[4:5], v[0:3], off sc0 sc1
	s_cbranch_vccnz .LBB0_195
	s_andn2_b64 vcc, exec, s[10:11]
	s_cbranch_vccnz .LBB0_194
	s_barrier
	s_branch .LBB0_194

;     __device__ __forceinline__ void operator()(const f32x4 (&acc)[2][2][4][2], const Unit& u, int wr, int wc, int fr, int fq) const {
;         { int l_; asm volatile("v_mbcnt_lo_u32_b32 %0, -1, 0\n\tv_mbcnt_hi_u32_b32 %0, -1, %0" : "=v"(l_)); fr = l_ & 15; fq = (l_ >> 4) & 3; }
;         const int slice = u.pm >> 12, row0 = (u.pm & 4095) * BM + wr * 64 + fr, col0 = u.pn * BM + wc * 32 + 4 * fq;
;         const float* mods = (const float*)(ws + WS_MODS) + (size_t)(goff_l >> 16) * NSEQ * NMOD; const int goff = goff_l & 0xffff; float* PART = (float*)(ws + WS_PART);
; #pragma unroll
;         for (int ai = 0; ai < 2; ++ai)
; #pragma unroll
;             for (int mp = 0; mp < 4; mp += 2) {
;                 f32x4 gv[2][4], xv[2][4];
; #pragma unroll
;                 for (int mm = 0; mm < 2; ++mm) {
;                     const int row = row0 + ai * HALF + (mp + mm) * 16; const float* gp = mods + (size_t)cidx_of(row) * NMOD + goff + col0;
;                     const float* xs = ((Xin && row < NPROMPT) ? Xin + (size_t)row * DM : X + (size_t)row * DM) + col0;
; #pragma unroll
;                     for (int q4 = 0; q4 < 4; ++q4) { const int co = (q4 >> 1) * HALF + (q4 & 1) * 16; gv[mm][q4] = *(const f32x4*)(gp + co); if (!slice) xv[mm][q4] = *(const f32x4*)(xs + co); }
;                 }
; #pragma unroll
;                 for (int mm = 0; mm < 2; ++mm) {
;                     const int row = row0 + ai * HALF + (mp + mm) * 16;
; #pragma unroll
;                     for (int q4 = 0; q4 < 4; ++q4) { const int co = (q4 >> 1) * HALF + (q4 & 1) * 16; const f32x4 d = (gv[mm][q4] * fac) * acc[ai][q4 >> 1][mp + mm][q4 & 1];
;                         if (slice) *(f32x4*)(PART + ((size_t)(slice - 1) * NSAMP + (row - NPROMPT)) * DM + col0 + co) = d;
;                         else *(f32x4*)(X + (size_t)row * DM + col0 + co) = xv[mm][q4] + d; }
;                 }
;                 asm volatile("" ::: "memory");
;             }
;     }
.LBB0_311:
	s_ashr_i32 s12, s57, 12
	s_ashr_i32 s13, s12, 31
	s_lshl_b64 s[12:13], s[12:13], 21
	s_add_u32 s12, s52, s12
	s_addc_u32 s13, s53, s13
	v_lshl_add_u64 v[210:211], v[208:209], 2, s[12:13]
	s_mov_b32 s12, 0xffe00000
	s_mov_b32 s13, -1
	v_ashrrev_i32_e32 v225, 31, v224
	s_waitcnt vmcnt(0)
	v_pk_mul_f32 v[188:189], v[188:189], 0.5 op_sel_hi:[1,0]
	v_lshl_add_u64 v[210:211], v[210:211], 0, s[12:13]
	v_lshlrev_b64 v[224:225], 12, v[224:225]
	v_pk_mul_f32 v[190:191], v[190:191], 0.5 op_sel_hi:[1,0]
	v_pk_mul_f32 v[156:157], v[156:157], v[188:189]
	v_cndmask_b32_e64 v188, 0, 1, s[30:31]
	v_lshl_add_u64 v[224:225], v[210:211], 0, v[224:225]
	v_pk_mul_f32 v[158:159], v[158:159], v[190:191]
	v_cmp_ne_u32_e64 s[12:13], 1, v188
	s_andn2_b64 vcc, exec, s[30:31]
	s_mov_b64 s[30:31], -1
	s_cbranch_vccnz .LBB0_313
	s_mov_b64 s[30:31], 0
	global_store_dwordx4 v[224:225], v[156:159], off sc0 sc1
.LBB0_313:
	v_lshl_add_u64 v[188:189], s[16:17], 0, v[222:223]
	s_andn2_b64 vcc, exec, s[30:31]
	v_lshl_add_u64 v[188:189], v[208:209], 2, v[188:189]
	s_cbranch_vccnz .LBB0_315
	v_pk_add_f32 v[158:159], v[158:159], v[102:103]
	v_pk_add_f32 v[156:157], v[156:157], v[100:101]
	global_store_dwordx4 v[188:189], v[156:159], off sc0 sc1
.LBB0_315:
	s_nop 1
	v_pk_mul_f32 v[156:157], v[186:187], 0.5 op_sel_hi:[1,0]
	v_pk_mul_f32 v[158:159], v[184:185], 0.5 op_sel_hi:[1,0]
	v_pk_mul_f32 v[184:185], v[154:155], v[156:157]
	v_pk_mul_f32 v[186:187], v[152:153], v[158:159]
	v_pk_fma_f32 v[154:155], v[154:155], v[156:157], v[98:99]
	v_pk_fma_f32 v[152:153], v[152:153], v[158:159], v[96:97]
	v_cndmask_b32_e64 v157, v225, v189, s[8:9]
	v_cndmask_b32_e64 v156, v224, v188, s[8:9]
	v_cndmask_b32_e64 v155, v185, v155, s[8:9]
	v_cndmask_b32_e64 v154, v184, v154, s[8:9]
	v_cndmask_b32_e64 v153, v187, v153, s[8:9]
	v_cndmask_b32_e64 v152, v186, v152, s[8:9]
	global_store_dwordx4 v[156:157], v[152:155], off offset:64 sc0 sc1
	v_ashrrev_i32_e32 v221, 31, v220
	s_and_b64 vcc, exec, s[12:13]
	v_pk_mul_f32 v[152:153], v[182:183], 0.5 op_sel_hi:[1,0]
	v_pk_mul_f32 v[154:155], v[180:181], 0.5 op_sel_hi:[1,0]
	v_pk_mul_f32 v[158:159], v[150:151], v[152:153]
	v_pk_mul_f32 v[180:181], v[148:149], v[154:155]
	v_pk_fma_f32 v[150:151], v[150:151], v[152:153], v[94:95]
	v_pk_fma_f32 v[148:149], v[148:149], v[154:155], v[92:93]
	v_cndmask_b32_e64 v151, v159, v151, s[8:9]
	v_cndmask_b32_e64 v150, v158, v150, s[8:9]
	v_cndmask_b32_e64 v149, v181, v149, s[8:9]
	v_cndmask_b32_e64 v148, v180, v148, s[8:9]
	global_store_dwordx4 v[156:157], v[148:151], off offset:512 sc0 sc1
	s_mov_b64 s[30:31], -1
	s_nop 0
	v_pk_mul_f32 v[148:149], v[174:175], 0.5 op_sel_hi:[1,0]
	v_pk_mul_f32 v[150:151], v[172:173], 0.5 op_sel_hi:[1,0]
	v_pk_mul_f32 v[152:153], v[142:143], v[148:149]
	v_pk_mul_f32 v[154:155], v[140:141], v[150:151]
	v_pk_fma_f32 v[142:143], v[142:143], v[148:149], v[90:91]
	v_pk_fma_f32 v[140:141], v[140:141], v[150:151], v[88:89]
	v_cndmask_b32_e64 v143, v153, v143, s[8:9]
	v_cndmask_b32_e64 v142, v152, v142, s[8:9]
	v_cndmask_b32_e64 v141, v155, v141, s[8:9]
	v_cndmask_b32_e64 v140, v154, v140, s[8:9]
	global_store_dwordx4 v[156:157], v[140:143], off offset:576 sc0 sc1
	v_pk_mul_f32 v[150:151], v[176:177], 0.5 op_sel_hi:[1,0]
	s_nop 0
	v_lshlrev_b64 v[140:141], 12, v[220:221]
	v_lshl_add_u64 v[148:149], v[210:211], 0, v[140:141]
	v_pk_mul_f32 v[140:141], v[178:179], 0.5 op_sel_hi:[1,0]
	s_nop 0
	v_pk_mul_f32 v[142:143], v[146:147], v[140:141]
	v_pk_mul_f32 v[140:141], v[144:145], v[150:151]
	s_cbranch_vccnz .LBB0_317
	s_mov_b64 s[30:31], 0
	global_store_dwordx4 v[148:149], v[140:143], off sc0 sc1
.LBB0_317:
	s_andn2_b64 vcc, exec, s[30:31]
	v_lshl_add_u64 v[144:145], s[16:17], 0, v[218:219]
	s_cbranch_vccnz .LBB0_319
	v_pk_add_f32 v[142:143], v[142:143], v[82:83]
	v_pk_add_f32 v[140:141], v[140:141], v[80:81]
	v_lshl_add_u64 v[146:147], v[208:209], 2, v[144:145]
	global_store_dwordx4 v[146:147], v[140:143], off sc0 sc1
.LBB0_319:
	s_nop 1
	v_pk_mul_f32 v[140:141], v[170:171], 0.5 op_sel_hi:[1,0]
	v_pk_mul_f32 v[142:143], v[168:169], 0.5 op_sel_hi:[1,0]
	v_pk_mul_f32 v[146:147], v[138:139], v[140:141]
	v_pk_mul_f32 v[150:151], v[136:137], v[142:143]
	v_pk_fma_f32 v[138:139], v[138:139], v[140:141], v[78:79]
	v_pk_fma_f32 v[136:137], v[136:137], v[142:143], v[76:77]
	v_lshl_add_u64 v[140:141], v[144:145], 0, v[216:217]
	v_cndmask_b32_e64 v141, v149, v141, s[8:9]
	v_cndmask_b32_e64 v140, v148, v140, s[8:9]
	v_cndmask_b32_e64 v139, v147, v139, s[8:9]
	v_cndmask_b32_e64 v138, v146, v138, s[8:9]
	v_cndmask_b32_e64 v137, v151, v137, s[8:9]
	v_cndmask_b32_e64 v136, v150, v136, s[8:9]
	global_store_dwordx4 v[140:141], v[136:139], off offset:64 sc0 sc1
	s_nop 1
	v_pk_mul_f32 v[136:137], v[166:167], 0.5 op_sel_hi:[1,0]
	v_pk_mul_f32 v[138:139], v[164:165], 0.5 op_sel_hi:[1,0]
	v_pk_mul_f32 v[142:143], v[134:135], v[136:137]
	v_pk_mul_f32 v[144:145], v[132:133], v[138:139]
	v_pk_fma_f32 v[134:135], v[134:135], v[136:137], v[70:71]
	v_pk_fma_f32 v[132:133], v[132:133], v[138:139], v[68:69]
	v_cndmask_b32_e64 v135, v143, v135, s[8:9]
	v_cndmask_b32_e64 v134, v142, v134, s[8:9]
	v_cndmask_b32_e64 v133, v145, v133, s[8:9]
	v_cndmask_b32_e64 v132, v144, v132, s[8:9]
	global_store_dwordx4 v[140:141], v[132:135], off offset:512 sc0 sc1
	v_add_u32_e32 v164, 0xffff8020, v212
	s_nop 0
	v_pk_mul_f32 v[132:133], v[162:163], 0.5 op_sel_hi:[1,0]
	v_pk_mul_f32 v[134:135], v[160:161], 0.5 op_sel_hi:[1,0]
	v_pk_mul_f32 v[136:137], v[130:131], v[132:133]
	v_pk_mul_f32 v[138:139], v[128:129], v[134:135]
	v_pk_fma_f32 v[130:131], v[130:131], v[132:133], v[66:67]
	v_pk_fma_f32 v[128:129], v[128:129], v[134:135], v[64:65]
	v_cndmask_b32_e64 v131, v137, v131, s[8:9]
	v_cndmask_b32_e64 v130, v136, v130, s[8:9]
	v_cndmask_b32_e64 v129, v139, v129, s[8:9]
	v_cndmask_b32_e64 v128, v138, v128, s[8:9]
	global_store_dwordx4 v[140:141], v[128:131], off offset:576 sc0 sc1
	v_mov_b32_e32 v132, s15
	s_nop 0
	v_or_b32_e32 v130, 32, v212
	v_lshrrev_b32_e32 v128, 5, v164
	v_add_u32_e32 v128, 2, v128
	v_mov_b32_e32 v129, s34
	v_cmp_gt_i32_e32 vcc, s0, v130
	v_mov_b32_e32 v131, s17
	s_nop 0
	v_cndmask_b32_e32 v128, v128, v129, vcc
	v_mad_i64_i32 v[128:129], s[30:31], v128, s80, v[214:215]
	global_load_dwordx4 v[144:147], v[128:129], off
	s_and_b64 vcc, s[24:25], vcc
	v_cndmask_b32_e32 v133, v131, v132, vcc
	v_mov_b32_e32 v131, s16
	v_mov_b32_e32 v132, s14
	v_cndmask_b32_e32 v132, v131, v132, vcc
	v_ashrrev_i32_e32 v131, 31, v130
	v_lshlrev_b64 v[166:167], 12, v[130:131]
	v_lshl_add_u64 v[130:131], v[132:133], 0, v[166:167]
	s_and_b64 vcc, exec, s[10:11]
	v_lshl_add_u64 v[140:141], v[130:131], 0, v[216:217]
	s_cbranch_vccz .LBB0_382
	global_load_dwordx4 v[136:139], v[128:129], off offset:64
	s_and_b64 vcc, exec, s[10:11]
	s_cbranch_vccz .LBB0_383

;     __device__ __forceinline__ void operator()(const f32x4 (&acc)[2][2][4][2], const Unit& u, int wr, int wc, int fr, int fq) const {
;         { int l_; asm volatile("v_mbcnt_lo_u32_b32 %0, -1, 0\n\tv_mbcnt_hi_u32_b32 %0, -1, %0" : "=v"(l_)); fr = l_ & 15; fq = (l_ >> 4) & 3; }
;         const int slice = u.pm >> 12, row0 = (u.pm & 4095) * BM + wr * 64 + fr, col0 = u.pn * BM + wc * 32 + 4 * fq;
;         const float* mods = (const float*)(ws + WS_MODS) + (size_t)(goff_l >> 16) * NSEQ * NMOD; const int goff = goff_l & 0xffff; float* PART = (float*)(ws + WS_PART);
; #pragma unroll
;         for (int ai = 0; ai < 2; ++ai)
; #pragma unroll
;             for (int mp = 0; mp < 4; mp += 2) {
;                 f32x4 gv[2][4], xv[2][4];
; #pragma unroll
;                 for (int mm = 0; mm < 2; ++mm) {
;                     const int row = row0 + ai * HALF + (mp + mm) * 16; const float* gp = mods + (size_t)cidx_of(row) * NMOD + goff + col0;
;                     const float* xs = ((Xin && row < NPROMPT) ? Xin + (size_t)row * DM : X + (size_t)row * DM) + col0;
; #pragma unroll
;                     for (int q4 = 0; q4 < 4; ++q4) { const int co = (q4 >> 1) * HALF + (q4 & 1) * 16; gv[mm][q4] = *(const f32x4*)(gp + co); if (!slice) xv[mm][q4] = *(const f32x4*)(xs + co); }
;                 }
; #pragma unroll
;                 for (int mm = 0; mm < 2; ++mm) {
;                     const int row = row0 + ai * HALF + (mp + mm) * 16;
; #pragma unroll
;                     for (int q4 = 0; q4 < 4; ++q4) { const int co = (q4 >> 1) * HALF + (q4 & 1) * 16; const f32x4 d = (gv[mm][q4] * fac) * acc[ai][q4 >> 1][mp + mm][q4 & 1];
;                         if (slice) *(f32x4*)(PART + ((size_t)(slice - 1) * NSAMP + (row - NPROMPT)) * DM + col0 + co) = d;
;                         else *(f32x4*)(X + (size_t)row * DM + col0 + co) = xv[mm][q4] + d; }
;                 }
;                 asm volatile("" ::: "memory");
;             }
;     }
.LBB0_329:
	v_ashrrev_i32_e32 v165, 31, v164
	v_lshlrev_b64 v[164:165], 12, v[164:165]
	s_waitcnt vmcnt(7)
	v_pk_mul_f32 v[146:147], v[146:147], 0.5 op_sel_hi:[1,0]
	v_pk_mul_f32 v[144:145], v[144:145], 0.5 op_sel_hi:[1,0]
	v_lshl_add_u64 v[164:165], v[210:211], 0, v[164:165]
	v_pk_mul_f32 v[126:127], v[126:127], v[146:147]
	v_pk_mul_f32 v[124:125], v[124:125], v[144:145]
	s_and_b64 vcc, exec, s[12:13]
	s_mov_b64 s[30:31], -1
	s_cbranch_vccnz .LBB0_331
	s_mov_b64 s[30:31], 0
	global_store_dwordx4 v[164:165], v[124:127], off sc0 sc1
.LBB0_331:
	v_lshl_add_u64 v[144:145], s[16:17], 0, v[166:167]
	s_andn2_b64 vcc, exec, s[30:31]
	v_lshl_add_u64 v[144:145], v[208:209], 2, v[144:145]
	s_cbranch_vccnz .LBB0_333
	v_pk_add_f32 v[126:127], v[126:127], v[102:103]
	v_pk_add_f32 v[124:125], v[124:125], v[100:101]
	global_store_dwordx4 v[144:145], v[124:127], off sc0 sc1
.LBB0_333:
	s_waitcnt vmcnt(6)
	s_nop 0
	v_pk_mul_f32 v[124:125], v[138:139], 0.5 op_sel_hi:[1,0]
	v_pk_mul_f32 v[126:127], v[136:137], 0.5 op_sel_hi:[1,0]
	v_pk_mul_f32 v[136:137], v[122:123], v[124:125]
	v_pk_mul_f32 v[138:139], v[120:121], v[126:127]
	v_pk_fma_f32 v[122:123], v[122:123], v[124:125], v[98:99]
	v_pk_fma_f32 v[120:121], v[120:121], v[126:127], v[96:97]
	v_cndmask_b32_e64 v125, v165, v145, s[8:9]
	v_cndmask_b32_e64 v124, v164, v144, s[8:9]
	v_cndmask_b32_e64 v123, v137, v123, s[8:9]
	v_cndmask_b32_e64 v122, v136, v122, s[8:9]
	v_cndmask_b32_e64 v121, v139, v121, s[8:9]
	v_cndmask_b32_e64 v120, v138, v120, s[8:9]
	global_store_dwordx4 v[124:125], v[120:123], off offset:64 sc0 sc1
	v_ashrrev_i32_e32 v163, 31, v162
	s_and_b64 vcc, exec, s[12:13]
	s_waitcnt vmcnt(6)
	v_pk_mul_f32 v[120:121], v[134:135], 0.5 op_sel_hi:[1,0]
	v_pk_mul_f32 v[122:123], v[132:133], 0.5 op_sel_hi:[1,0]
	v_pk_mul_f32 v[126:127], v[118:119], v[120:121]
	v_pk_mul_f32 v[132:133], v[116:117], v[122:123]
	v_pk_fma_f32 v[118:119], v[118:119], v[120:121], v[94:95]
	v_pk_fma_f32 v[116:117], v[116:117], v[122:123], v[92:93]
	v_cndmask_b32_e64 v119, v127, v119, s[8:9]
	v_cndmask_b32_e64 v118, v126, v118, s[8:9]
	v_cndmask_b32_e64 v117, v133, v117, s[8:9]
	v_cndmask_b32_e64 v116, v132, v116, s[8:9]
	global_store_dwordx4 v[124:125], v[116:119], off offset:512 sc0 sc1
	s_mov_b64 s[30:31], -1
	s_waitcnt vmcnt(6)
	v_pk_mul_f32 v[116:117], v[130:131], 0.5 op_sel_hi:[1,0]
	v_pk_mul_f32 v[118:119], v[128:129], 0.5 op_sel_hi:[1,0]
	v_pk_mul_f32 v[120:121], v[110:111], v[116:117]
	v_pk_mul_f32 v[122:123], v[108:109], v[118:119]
	v_pk_fma_f32 v[110:111], v[110:111], v[116:117], v[90:91]
	v_pk_fma_f32 v[108:109], v[108:109], v[118:119], v[88:89]
	v_cndmask_b32_e64 v111, v121, v111, s[8:9]
	v_cndmask_b32_e64 v110, v120, v110, s[8:9]
	v_cndmask_b32_e64 v109, v123, v109, s[8:9]
	v_cndmask_b32_e64 v108, v122, v108, s[8:9]
	global_store_dwordx4 v[124:125], v[108:111], off offset:576 sc0 sc1
	s_waitcnt vmcnt(6)
	v_pk_mul_f32 v[118:119], v[152:153], 0.5 op_sel_hi:[1,0]
	v_lshlrev_b64 v[108:109], 12, v[162:163]
	v_lshl_add_u64 v[116:117], v[210:211], 0, v[108:109]
	v_pk_mul_f32 v[108:109], v[154:155], 0.5 op_sel_hi:[1,0]
	s_nop 0
	v_pk_mul_f32 v[110:111], v[114:115], v[108:109]
	v_pk_mul_f32 v[108:109], v[112:113], v[118:119]
	s_cbranch_vccnz .LBB0_335
	s_mov_b64 s[30:31], 0
	global_store_dwordx4 v[116:117], v[108:111], off sc0 sc1
.LBB0_335:
	s_andn2_b64 vcc, exec, s[30:31]
	v_lshl_add_u64 v[112:113], s[16:17], 0, v[160:161]
	s_cbranch_vccnz .LBB0_337
	v_pk_add_f32 v[110:111], v[110:111], v[82:83]
	v_pk_add_f32 v[108:109], v[108:109], v[80:81]
	v_lshl_add_u64 v[114:115], v[208:209], 2, v[112:113]
	global_store_dwordx4 v[114:115], v[108:111], off sc0 sc1
.LBB0_337:
	s_waitcnt vmcnt(5)
	s_nop 0
	v_pk_mul_f32 v[108:109], v[158:159], 0.5 op_sel_hi:[1,0]
	v_pk_mul_f32 v[110:111], v[156:157], 0.5 op_sel_hi:[1,0]
	v_pk_mul_f32 v[114:115], v[106:107], v[108:109]
	v_pk_mul_f32 v[118:119], v[104:105], v[110:111]
	v_pk_fma_f32 v[106:107], v[106:107], v[108:109], v[78:79]
	v_pk_fma_f32 v[104:105], v[104:105], v[110:111], v[76:77]
	v_lshl_add_u64 v[108:109], v[112:113], 0, v[216:217]
	v_cndmask_b32_e64 v109, v117, v109, s[8:9]
	v_cndmask_b32_e64 v108, v116, v108, s[8:9]
	v_cndmask_b32_e64 v107, v115, v107, s[8:9]
	v_cndmask_b32_e64 v106, v114, v106, s[8:9]
	v_cndmask_b32_e64 v105, v119, v105, s[8:9]
	v_cndmask_b32_e64 v104, v118, v104, s[8:9]
	global_store_dwordx4 v[108:109], v[104:107], off offset:64 sc0 sc1
	v_add_u32_e32 v132, 0xffff8080, v212
	s_movk_i32 s30, 0x7f80
	s_waitcnt vmcnt(5)
	v_pk_mul_f32 v[104:105], v[150:151], 0.5 op_sel_hi:[1,0]
	v_pk_mul_f32 v[106:107], v[148:149], 0.5 op_sel_hi:[1,0]
	v_pk_mul_f32 v[110:111], v[86:87], v[104:105]
	v_pk_mul_f32 v[112:113], v[84:85], v[106:107]
	v_pk_fma_f32 v[86:87], v[86:87], v[104:105], v[70:71]
	v_pk_fma_f32 v[84:85], v[84:85], v[106:107], v[68:69]
	v_cndmask_b32_e64 v87, v111, v87, s[8:9]
	v_cndmask_b32_e64 v86, v110, v86, s[8:9]
	v_cndmask_b32_e64 v85, v113, v85, s[8:9]
	v_cndmask_b32_e64 v84, v112, v84, s[8:9]
	global_store_dwordx4 v[108:109], v[84:87], off offset:512 sc0 sc1
	v_cmp_gt_i32_e32 vcc, s30, v212
	s_waitcnt vmcnt(5)
	v_pk_mul_f32 v[84:85], v[142:143], 0.5 op_sel_hi:[1,0]
	v_pk_mul_f32 v[86:87], v[140:141], 0.5 op_sel_hi:[1,0]
	v_pk_mul_f32 v[104:105], v[74:75], v[84:85]
	v_pk_mul_f32 v[106:107], v[72:73], v[86:87]
	v_pk_fma_f32 v[74:75], v[74:75], v[84:85], v[66:67]
	v_pk_fma_f32 v[72:73], v[72:73], v[86:87], v[64:65]
	v_cndmask_b32_e64 v75, v105, v75, s[8:9]
	v_cndmask_b32_e64 v74, v104, v74, s[8:9]
	v_cndmask_b32_e64 v73, v107, v73, s[8:9]
	v_cndmask_b32_e64 v72, v106, v72, s[8:9]
	global_store_dwordx4 v[108:109], v[72:75], off offset:576 sc0 sc1
	v_mov_b32_e32 v84, s15
	s_nop 0
	v_add_u32_e32 v74, 0x80, v212
	v_lshrrev_b32_e32 v72, 5, v132
	v_ashrrev_i32_e32 v138, 14, v74
	v_add_u32_e32 v72, 2, v72
	v_cndmask_b32_e32 v72, v72, v138, vcc
	v_mad_i64_i32 v[72:73], s[30:31], v72, s80, v[214:215]
	global_load_dwordx4 v[112:115], v[72:73], off
	v_mov_b32_e32 v75, s17
	s_and_b64 vcc, s[24:25], vcc
	v_cndmask_b32_e32 v85, v75, v84, vcc
	v_mov_b32_e32 v75, s16
	v_mov_b32_e32 v84, s14
	v_cndmask_b32_e32 v84, v75, v84, vcc
	v_ashrrev_i32_e32 v75, 31, v74
	v_lshlrev_b64 v[134:135], 12, v[74:75]
	v_lshl_add_u64 v[74:75], v[84:85], 0, v[134:135]
	s_and_b64 vcc, exec, s[10:11]
	v_lshl_add_u64 v[108:109], v[74:75], 0, v[216:217]
	s_cbranch_vccz .LBB0_388
	global_load_dwordx4 v[104:107], v[72:73], off offset:64
	s_and_b64 vcc, exec, s[10:11]
	s_cbranch_vccz .LBB0_389

;     __device__ __forceinline__ void operator()(const f32x4 (&acc)[2][2][4][2], const Unit& u, int wr, int wc, int fr, int fq) const {
;         { int l_; asm volatile("v_mbcnt_lo_u32_b32 %0, -1, 0\n\tv_mbcnt_hi_u32_b32 %0, -1, %0" : "=v"(l_)); fr = l_ & 15; fq = (l_ >> 4) & 3; }
;         const int slice = u.pm >> 12, row0 = (u.pm & 4095) * BM + wr * 64 + fr, col0 = u.pn * BM + wc * 32 + 4 * fq;
;         const float* mods = (const float*)(ws + WS_MODS) + (size_t)(goff_l >> 16) * NSEQ * NMOD; const int goff = goff_l & 0xffff; float* PART = (float*)(ws + WS_PART);
; #pragma unroll
;         for (int ai = 0; ai < 2; ++ai)
; #pragma unroll
;             for (int mp = 0; mp < 4; mp += 2) {
;                 f32x4 gv[2][4], xv[2][4];
; #pragma unroll
;                 for (int mm = 0; mm < 2; ++mm) {
;                     const int row = row0 + ai * HALF + (mp + mm) * 16; const float* gp = mods + (size_t)cidx_of(row) * NMOD + goff + col0;
;                     const float* xs = ((Xin && row < NPROMPT) ? Xin + (size_t)row * DM : X + (size_t)row * DM) + col0;
; #pragma unroll
;                     for (int q4 = 0; q4 < 4; ++q4) { const int co = (q4 >> 1) * HALF + (q4 & 1) * 16; gv[mm][q4] = *(const f32x4*)(gp + co); if (!slice) xv[mm][q4] = *(const f32x4*)(xs + co); }
;                 }
; #pragma unroll
;                 for (int mm = 0; mm < 2; ++mm) {
;                     const int row = row0 + ai * HALF + (mp + mm) * 16;
; #pragma unroll
;                     for (int q4 = 0; q4 < 4; ++q4) { const int co = (q4 >> 1) * HALF + (q4 & 1) * 16; const f32x4 d = (gv[mm][q4] * fac) * acc[ai][q4 >> 1][mp + mm][q4 & 1];
;                         if (slice) *(f32x4*)(PART + ((size_t)(slice - 1) * NSAMP + (row - NPROMPT)) * DM + col0 + co) = d;
;                         else *(f32x4*)(X + (size_t)row * DM + col0 + co) = xv[mm][q4] + d; }
;                 }
;                 asm volatile("" ::: "memory");
;             }
;     }
.LBB0_347:
	v_ashrrev_i32_e32 v133, 31, v132
	v_lshlrev_b64 v[132:133], 12, v[132:133]
	s_waitcnt vmcnt(7)
	v_pk_mul_f32 v[114:115], v[114:115], 0.5 op_sel_hi:[1,0]
	v_pk_mul_f32 v[112:113], v[112:113], 0.5 op_sel_hi:[1,0]
	v_lshl_add_u64 v[132:133], v[210:211], 0, v[132:133]
	v_pk_mul_f32 v[62:63], v[62:63], v[114:115]
	v_pk_mul_f32 v[60:61], v[60:61], v[112:113]
	s_and_b64 vcc, exec, s[12:13]
	s_mov_b64 s[30:31], -1
	s_cbranch_vccnz .LBB0_349
	s_mov_b64 s[30:31], 0
	global_store_dwordx4 v[132:133], v[60:63], off sc0 sc1
.LBB0_349:
	v_lshl_add_u64 v[112:113], s[16:17], 0, v[134:135]
	s_andn2_b64 vcc, exec, s[30:31]
	v_lshl_add_u64 v[112:113], v[208:209], 2, v[112:113]
	s_cbranch_vccnz .LBB0_351
	v_pk_add_f32 v[62:63], v[62:63], v[102:103]
	v_pk_add_f32 v[60:61], v[60:61], v[100:101]
	global_store_dwordx4 v[112:113], v[60:63], off sc0 sc1
.LBB0_351:
	s_waitcnt vmcnt(6)
	s_nop 0
	v_pk_mul_f32 v[60:61], v[106:107], 0.5 op_sel_hi:[1,0]
	v_pk_mul_f32 v[62:63], v[104:105], 0.5 op_sel_hi:[1,0]
	v_pk_mul_f32 v[104:105], v[58:59], v[60:61]
	v_pk_mul_f32 v[106:107], v[56:57], v[62:63]
	v_pk_fma_f32 v[58:59], v[58:59], v[60:61], v[98:99]
	v_pk_fma_f32 v[56:57], v[56:57], v[62:63], v[96:97]
	v_cndmask_b32_e64 v61, v133, v113, s[8:9]
	v_cndmask_b32_e64 v60, v132, v112, s[8:9]
	v_cndmask_b32_e64 v59, v105, v59, s[8:9]
	v_cndmask_b32_e64 v58, v104, v58, s[8:9]
	v_cndmask_b32_e64 v57, v107, v57, s[8:9]
	v_cndmask_b32_e64 v56, v106, v56, s[8:9]
	global_store_dwordx4 v[60:61], v[56:59], off offset:64 sc0 sc1
	v_ashrrev_i32_e32 v131, 31, v130
	s_and_b64 vcc, exec, s[12:13]
	s_waitcnt vmcnt(6)
	v_pk_mul_f32 v[56:57], v[86:87], 0.5 op_sel_hi:[1,0]
	v_pk_mul_f32 v[58:59], v[84:85], 0.5 op_sel_hi:[1,0]
	v_pk_mul_f32 v[62:63], v[54:55], v[56:57]
	v_pk_mul_f32 v[84:85], v[52:53], v[58:59]
	v_pk_fma_f32 v[54:55], v[54:55], v[56:57], v[94:95]
	v_pk_fma_f32 v[52:53], v[52:53], v[58:59], v[92:93]
	v_cndmask_b32_e64 v55, v63, v55, s[8:9]
	v_cndmask_b32_e64 v54, v62, v54, s[8:9]
	v_cndmask_b32_e64 v53, v85, v53, s[8:9]
	v_cndmask_b32_e64 v52, v84, v52, s[8:9]
	global_store_dwordx4 v[60:61], v[52:55], off offset:512 sc0 sc1
	s_mov_b64 s[30:31], -1
	s_waitcnt vmcnt(6)
	v_pk_mul_f32 v[52:53], v[74:75], 0.5 op_sel_hi:[1,0]
	v_pk_mul_f32 v[54:55], v[72:73], 0.5 op_sel_hi:[1,0]
	v_pk_mul_f32 v[56:57], v[46:47], v[52:53]
	v_pk_mul_f32 v[58:59], v[44:45], v[54:55]
	v_pk_fma_f32 v[46:47], v[46:47], v[52:53], v[90:91]
	v_pk_fma_f32 v[44:45], v[44:45], v[54:55], v[88:89]
	v_cndmask_b32_e64 v47, v57, v47, s[8:9]
	v_cndmask_b32_e64 v46, v56, v46, s[8:9]
	v_cndmask_b32_e64 v45, v59, v45, s[8:9]
	v_cndmask_b32_e64 v44, v58, v44, s[8:9]
	global_store_dwordx4 v[60:61], v[44:47], off offset:576 sc0 sc1
	s_waitcnt vmcnt(6)
	v_pk_mul_f32 v[54:55], v[120:121], 0.5 op_sel_hi:[1,0]
	v_lshlrev_b64 v[44:45], 12, v[130:131]
	v_lshl_add_u64 v[52:53], v[210:211], 0, v[44:45]
	v_pk_mul_f32 v[44:45], v[122:123], 0.5 op_sel_hi:[1,0]
	s_nop 0
	v_pk_mul_f32 v[46:47], v[50:51], v[44:45]
	v_pk_mul_f32 v[44:45], v[48:49], v[54:55]
	s_cbranch_vccnz .LBB0_353
	s_mov_b64 s[30:31], 0
	global_store_dwordx4 v[52:53], v[44:47], off sc0 sc1
.LBB0_353:
	s_andn2_b64 vcc, exec, s[30:31]
	v_lshl_add_u64 v[48:49], s[16:17], 0, v[128:129]
	s_cbranch_vccnz .LBB0_355
	v_pk_add_f32 v[46:47], v[46:47], v[82:83]
	v_pk_add_f32 v[44:45], v[44:45], v[80:81]
	v_lshl_add_u64 v[50:51], v[208:209], 2, v[48:49]
	global_store_dwordx4 v[50:51], v[44:47], off sc0 sc1
.LBB0_355:
	s_waitcnt vmcnt(5)
	s_nop 0
	v_pk_mul_f32 v[44:45], v[126:127], 0.5 op_sel_hi:[1,0]
	v_pk_mul_f32 v[46:47], v[124:125], 0.5 op_sel_hi:[1,0]
	v_pk_mul_f32 v[50:51], v[42:43], v[44:45]
	v_pk_mul_f32 v[54:55], v[40:41], v[46:47]
	v_pk_fma_f32 v[42:43], v[42:43], v[44:45], v[78:79]
	v_pk_fma_f32 v[40:41], v[40:41], v[46:47], v[76:77]
	v_lshl_add_u64 v[44:45], v[48:49], 0, v[216:217]
	v_cndmask_b32_e64 v45, v53, v45, s[8:9]
	v_cndmask_b32_e64 v44, v52, v44, s[8:9]
	v_cndmask_b32_e64 v43, v51, v43, s[8:9]
	v_cndmask_b32_e64 v42, v50, v42, s[8:9]
	v_cndmask_b32_e64 v41, v55, v41, s[8:9]
	v_cndmask_b32_e64 v40, v54, v40, s[8:9]
	global_store_dwordx4 v[44:45], v[40:43], off offset:64 sc0 sc1
	v_add_u32_e32 v84, 0xffff80a0, v212
	s_movk_i32 s30, 0x7f60
	s_waitcnt vmcnt(5)
	v_pk_mul_f32 v[40:41], v[118:119], 0.5 op_sel_hi:[1,0]
	v_pk_mul_f32 v[42:43], v[116:117], 0.5 op_sel_hi:[1,0]
	v_pk_mul_f32 v[46:47], v[38:39], v[40:41]
	v_pk_mul_f32 v[48:49], v[36:37], v[42:43]
	v_pk_fma_f32 v[38:39], v[38:39], v[40:41], v[70:71]
	v_pk_fma_f32 v[36:37], v[36:37], v[42:43], v[68:69]
	v_cndmask_b32_e64 v39, v47, v39, s[8:9]
	v_cndmask_b32_e64 v38, v46, v38, s[8:9]
	v_cndmask_b32_e64 v37, v49, v37, s[8:9]
	v_cndmask_b32_e64 v36, v48, v36, s[8:9]
	global_store_dwordx4 v[44:45], v[36:39], off offset:512 sc0 sc1
	v_cmp_gt_i32_e32 vcc, s30, v212
	s_waitcnt vmcnt(5)
	v_pk_mul_f32 v[36:37], v[110:111], 0.5 op_sel_hi:[1,0]
	v_pk_mul_f32 v[38:39], v[108:109], 0.5 op_sel_hi:[1,0]
	v_pk_mul_f32 v[40:41], v[34:35], v[36:37]
	v_pk_mul_f32 v[42:43], v[32:33], v[38:39]
	v_pk_fma_f32 v[34:35], v[34:35], v[36:37], v[66:67]
	v_pk_fma_f32 v[32:33], v[32:33], v[38:39], v[64:65]
	v_cndmask_b32_e64 v35, v41, v35, s[8:9]
	v_cndmask_b32_e64 v34, v40, v34, s[8:9]
	v_cndmask_b32_e64 v33, v43, v33, s[8:9]
	v_cndmask_b32_e64 v32, v42, v32, s[8:9]
	global_store_dwordx4 v[44:45], v[32:35], off offset:576 sc0 sc1
	v_mov_b32_e32 v36, s14
	s_nop 0
	v_lshrrev_b32_e32 v32, 5, v84
	v_add_u32_e32 v32, 2, v32
	v_cndmask_b32_e32 v32, v32, v138, vcc
	v_mad_i64_i32 v[32:33], s[30:31], v32, s80, v[214:215]
	global_load_dwordx4 v[48:51], v[32:33], off
	v_mov_b32_e32 v34, s17
	v_mov_b32_e32 v35, s15
	s_and_b64 vcc, s[24:25], vcc
	v_cndmask_b32_e32 v35, v34, v35, vcc
	v_mov_b32_e32 v34, s16
	v_cndmask_b32_e32 v34, v34, v36, vcc
	v_lshlrev_b64 v[36:37], 12, v[212:213]
	s_mov_b64 s[30:31], 0xa0000
	v_lshl_add_u64 v[86:87], v[36:37], 0, s[30:31]
	v_lshl_add_u64 v[34:35], v[34:35], 0, v[86:87]
	s_and_b64 vcc, exec, s[10:11]
	v_lshl_add_u64 v[44:45], v[34:35], 0, v[216:217]
	s_cbranch_vccz .LBB0_394
	global_load_dwordx4 v[40:43], v[32:33], off offset:64
	s_and_b64 vcc, exec, s[10:11]
	s_cbranch_vccz .LBB0_395

;     __device__ __forceinline__ void operator()(const f32x4 (&acc)[2][2][4][2], const Unit& u, int wr, int wc, int fr, int fq) const {
;         { int l_; asm volatile("v_mbcnt_lo_u32_b32 %0, -1, 0\n\tv_mbcnt_hi_u32_b32 %0, -1, %0" : "=v"(l_)); fr = l_ & 15; fq = (l_ >> 4) & 3; }
;         const int slice = u.pm >> 12, row0 = (u.pm & 4095) * BM + wr * 64 + fr, col0 = u.pn * BM + wc * 32 + 4 * fq;
;         const float* mods = (const float*)(ws + WS_MODS) + (size_t)(goff_l >> 16) * NSEQ * NMOD; const int goff = goff_l & 0xffff; float* PART = (float*)(ws + WS_PART);
; #pragma unroll
;         for (int ai = 0; ai < 2; ++ai)
; #pragma unroll
;             for (int mp = 0; mp < 4; mp += 2) {
;                 f32x4 gv[2][4], xv[2][4];
; #pragma unroll
;                 for (int mm = 0; mm < 2; ++mm) {
;                     const int row = row0 + ai * HALF + (mp + mm) * 16; const float* gp = mods + (size_t)cidx_of(row) * NMOD + goff + col0;
;                     const float* xs = ((Xin && row < NPROMPT) ? Xin + (size_t)row * DM : X + (size_t)row * DM) + col0;
; #pragma unroll
;                     for (int q4 = 0; q4 < 4; ++q4) { const int co = (q4 >> 1) * HALF + (q4 & 1) * 16; gv[mm][q4] = *(const f32x4*)(gp + co); if (!slice) xv[mm][q4] = *(const f32x4*)(xs + co); }
;                 }
; #pragma unroll
;                 for (int mm = 0; mm < 2; ++mm) {
;                     const int row = row0 + ai * HALF + (mp + mm) * 16;
; #pragma unroll
;                     for (int q4 = 0; q4 < 4; ++q4) { const int co = (q4 >> 1) * HALF + (q4 & 1) * 16; const f32x4 d = (gv[mm][q4] * fac) * acc[ai][q4 >> 1][mp + mm][q4 & 1];
;                         if (slice) *(f32x4*)(PART + ((size_t)(slice - 1) * NSAMP + (row - NPROMPT)) * DM + col0 + co) = d;
;                         else *(f32x4*)(X + (size_t)row * DM + col0 + co) = xv[mm][q4] + d; }
;                 }
;                 asm volatile("" ::: "memory");
;             }
;     }
; template <class Epi, class Sched, bool ALIGN_EPI = false, bool SP2 = false>
; __device__ __forceinline__ void gemm_phase(PG8_LAS unsigned char* lds, const Gemm g, const Sched& S, const Epi& E, int wave_s_) {
;     ...
;         if constexpr (ALIGN_EPI) { if (wr == 0) PG8_BAR; }
;         if constexpr (!Epi::AFTER_DRAIN) { E(acc, cur, wr, wc, fr, fq); S.done(cur); }
;         if (!has_next) break;
; #pragma unroll
;         for (int a = 0; a < 2; ++a)
.LBB0_365:
	v_ashrrev_i32_e32 v85, 31, v84
	v_lshlrev_b64 v[84:85], 12, v[84:85]
	s_waitcnt vmcnt(7)
	v_pk_mul_f32 v[50:51], v[50:51], 0.5 op_sel_hi:[1,0]
	v_pk_mul_f32 v[48:49], v[48:49], 0.5 op_sel_hi:[1,0]
	v_lshl_add_u64 v[84:85], v[210:211], 0, v[84:85]
	v_pk_mul_f32 v[30:31], v[30:31], v[50:51]
	v_pk_mul_f32 v[28:29], v[28:29], v[48:49]
	s_and_b64 vcc, exec, s[12:13]
	s_mov_b64 s[10:11], -1
	s_cbranch_vccnz .LBB0_367
	s_mov_b64 s[10:11], 0
	global_store_dwordx4 v[84:85], v[28:31], off sc0 sc1
.LBB0_367:
	v_lshl_add_u64 v[48:49], s[16:17], 0, v[86:87]
	s_andn2_b64 vcc, exec, s[10:11]
	v_lshl_add_u64 v[48:49], v[208:209], 2, v[48:49]
	s_cbranch_vccnz .LBB0_369
	v_pk_add_f32 v[30:31], v[30:31], v[102:103]
	v_pk_add_f32 v[28:29], v[28:29], v[100:101]
	global_store_dwordx4 v[48:49], v[28:31], off sc0 sc1
.LBB0_369:
	s_waitcnt vmcnt(6)
	s_nop 0
	v_pk_mul_f32 v[28:29], v[42:43], 0.5 op_sel_hi:[1,0]
	v_pk_mul_f32 v[30:31], v[40:41], 0.5 op_sel_hi:[1,0]
	v_pk_mul_f32 v[40:41], v[26:27], v[28:29]
	v_pk_mul_f32 v[42:43], v[24:25], v[30:31]
	v_pk_fma_f32 v[26:27], v[26:27], v[28:29], v[98:99]
	v_pk_fma_f32 v[24:25], v[24:25], v[30:31], v[96:97]
	v_cndmask_b32_e64 v29, v85, v49, s[8:9]
	v_cndmask_b32_e64 v28, v84, v48, s[8:9]
	v_cndmask_b32_e64 v27, v41, v27, s[8:9]
	v_cndmask_b32_e64 v26, v40, v26, s[8:9]
	v_cndmask_b32_e64 v25, v43, v25, s[8:9]
	v_cndmask_b32_e64 v24, v42, v24, s[8:9]
	global_store_dwordx4 v[28:29], v[24:27], off offset:64 sc0 sc1
	v_ashrrev_i32_e32 v75, 31, v74
	s_and_b64 vcc, exec, s[12:13]
	s_waitcnt vmcnt(6)
	v_pk_mul_f32 v[24:25], v[38:39], 0.5 op_sel_hi:[1,0]
	v_pk_mul_f32 v[26:27], v[36:37], 0.5 op_sel_hi:[1,0]
	v_pk_mul_f32 v[30:31], v[22:23], v[24:25]
	v_pk_mul_f32 v[36:37], v[20:21], v[26:27]
	v_pk_fma_f32 v[22:23], v[22:23], v[24:25], v[94:95]
	v_pk_fma_f32 v[20:21], v[20:21], v[26:27], v[92:93]
	v_cndmask_b32_e64 v23, v31, v23, s[8:9]
	v_cndmask_b32_e64 v22, v30, v22, s[8:9]
	v_cndmask_b32_e64 v21, v37, v21, s[8:9]
	v_cndmask_b32_e64 v20, v36, v20, s[8:9]
	global_store_dwordx4 v[28:29], v[20:23], off offset:512 sc0 sc1
	s_mov_b64 s[10:11], -1
	s_waitcnt vmcnt(6)
	v_pk_mul_f32 v[20:21], v[34:35], 0.5 op_sel_hi:[1,0]
	v_pk_mul_f32 v[22:23], v[32:33], 0.5 op_sel_hi:[1,0]
	v_pk_mul_f32 v[24:25], v[14:15], v[20:21]
	v_pk_mul_f32 v[26:27], v[12:13], v[22:23]
	v_pk_fma_f32 v[14:15], v[14:15], v[20:21], v[90:91]
	v_pk_fma_f32 v[12:13], v[12:13], v[22:23], v[88:89]
	v_cndmask_b32_e64 v15, v25, v15, s[8:9]
	v_cndmask_b32_e64 v14, v24, v14, s[8:9]
	v_cndmask_b32_e64 v13, v27, v13, s[8:9]
	v_cndmask_b32_e64 v12, v26, v12, s[8:9]
	global_store_dwordx4 v[28:29], v[12:15], off offset:576 sc0 sc1
	s_waitcnt vmcnt(6)
	v_pk_mul_f32 v[22:23], v[56:57], 0.5 op_sel_hi:[1,0]
	v_lshlrev_b64 v[12:13], 12, v[74:75]
	v_lshl_add_u64 v[20:21], v[210:211], 0, v[12:13]
	v_pk_mul_f32 v[12:13], v[58:59], 0.5 op_sel_hi:[1,0]
	s_nop 0
	v_pk_mul_f32 v[14:15], v[18:19], v[12:13]
	v_pk_mul_f32 v[12:13], v[16:17], v[22:23]
	s_cbranch_vccnz .LBB0_371
	s_mov_b64 s[10:11], 0
	global_store_dwordx4 v[20:21], v[12:15], off sc0 sc1
.LBB0_371:
	v_lshl_add_u64 v[16:17], s[16:17], 0, v[72:73]
	s_andn2_b64 vcc, exec, s[10:11]
	v_lshl_add_u64 v[16:17], v[208:209], 2, v[16:17]
	s_cbranch_vccnz .LBB0_373
	v_pk_add_f32 v[14:15], v[14:15], v[82:83]
	v_pk_add_f32 v[12:13], v[12:13], v[80:81]
	global_store_dwordx4 v[16:17], v[12:15], off sc0 sc1
.LBB0_373:
	s_waitcnt vmcnt(5)
	s_nop 0
	v_pk_mul_f32 v[12:13], v[62:63], 0.5 op_sel_hi:[1,0]
	v_pk_mul_f32 v[14:15], v[60:61], 0.5 op_sel_hi:[1,0]
	v_pk_mul_f32 v[18:19], v[10:11], v[12:13]
	v_pk_mul_f32 v[22:23], v[8:9], v[14:15]
	v_pk_fma_f32 v[10:11], v[10:11], v[12:13], v[78:79]
	v_pk_fma_f32 v[8:9], v[8:9], v[14:15], v[76:77]
	v_cndmask_b32_e64 v13, v21, v17, s[8:9]
	v_cndmask_b32_e64 v12, v20, v16, s[8:9]
	v_cndmask_b32_e64 v11, v19, v11, s[8:9]
	v_cndmask_b32_e64 v10, v18, v10, s[8:9]
	v_cndmask_b32_e64 v9, v23, v9, s[8:9]
	v_cndmask_b32_e64 v8, v22, v8, s[8:9]
	global_store_dwordx4 v[12:13], v[8:11], off offset:64 sc0 sc1
	s_and_b64 vcc, exec, s[6:7]
	s_mov_b64 s[6:7], -1
	s_waitcnt vmcnt(5)
	v_pk_mul_f32 v[8:9], v[54:55], 0.5 op_sel_hi:[1,0]
	v_pk_mul_f32 v[10:11], v[52:53], 0.5 op_sel_hi:[1,0]
	v_pk_mul_f32 v[14:15], v[6:7], v[8:9]
	v_pk_mul_f32 v[16:17], v[4:5], v[10:11]
	v_pk_fma_f32 v[6:7], v[6:7], v[8:9], v[70:71]
	v_pk_fma_f32 v[4:5], v[4:5], v[10:11], v[68:69]
	v_cndmask_b32_e64 v7, v15, v7, s[8:9]
	v_cndmask_b32_e64 v6, v14, v6, s[8:9]
	v_cndmask_b32_e64 v5, v17, v5, s[8:9]
	v_cndmask_b32_e64 v4, v16, v4, s[8:9]
	global_store_dwordx4 v[12:13], v[4:7], off offset:512 sc0 sc1
	s_waitcnt vmcnt(5)
	s_nop 0
	v_pk_mul_f32 v[4:5], v[46:47], 0.5 op_sel_hi:[1,0]
	v_pk_mul_f32 v[6:7], v[44:45], 0.5 op_sel_hi:[1,0]
	v_pk_mul_f32 v[8:9], v[2:3], v[4:5]
	v_pk_mul_f32 v[10:11], v[0:1], v[6:7]
	v_pk_fma_f32 v[2:3], v[2:3], v[4:5], v[66:67]
	v_pk_fma_f32 v[0:1], v[0:1], v[6:7], v[64:65]
	v_cndmask_b32_e64 v3, v9, v3, s[8:9]
	v_cndmask_b32_e64 v2, v8, v2, s[8:9]
	v_cndmask_b32_e64 v1, v11, v1, s[8:9]
	v_cndmask_b32_e64 v0, v10, v0, s[8:9]
	global_store_dwordx4 v[12:13], v[0:3], off offset:576 sc0 sc1
	s_cbranch_vccnz .LBB0_283
	s_andn2_b64 vcc, exec, s[20:21]
	s_cbranch_vccnz .LBB0_282
	s_barrier
	s_branch .LBB0_282

; __device__ __forceinline__ void norm_mod_phase(ArgsP a, bool from_input, const float* g, const float* modsL, int ishift, int iscale, int nparts, int wave_s_) {
;     ...
;         if ((from_input && row >= NPROMPT) || (row >= NPROMPT && nparts > 0)) {
; #pragma unroll
;             for (int j = 0; j < 4; ++j) *(f32x4*)(X + (size_t)row * DM + 4 * lane + 256 * j) = v[j];
;         }
.LBB0_461:
	s_or_b64 exec, exec, s[20:21]
	s_and_saveexec_b64 s[20:21], s[8:9]
	s_xor_b64 s[8:9], exec, s[20:21]
	s_andn2_saveexec_b64 s[8:9], s[8:9]
	s_cbranch_execz .LBB0_456
	v_mov_b32_e32 v57, v197
	v_lshlrev_b64 v[60:61], 12, v[56:57]
	v_lshl_add_u64 v[60:61], v[48:49], 0, v[60:61]
	s_waitcnt vmcnt(3)
	global_store_dwordx4 v[60:61], v[44:47], off sc0 sc1
	s_waitcnt vmcnt(3)
	global_store_dwordx4 v[60:61], v[40:43], off offset:1024 sc0 sc1
	s_waitcnt vmcnt(3)
	global_store_dwordx4 v[60:61], v[36:39], off offset:2048 sc0 sc1
	s_waitcnt vmcnt(3)
	global_store_dwordx4 v[60:61], v[32:35], off offset:3072 sc0 sc1
	s_branch .LBB0_456

.LBB0_476:
	v_add_u32_e32 v8, s6, v8
	v_cmp_lt_i32_e64 s[4:5], s1, v8
	global_store_dwordx4 v[6:7], v[0:3], off sc0 sc1
	s_or_b64 s[14:15], s[4:5], s[14:15]
	v_lshl_add_u64 v[6:7], v[6:7], 0, s[12:13]
	s_andn2_b64 exec, exec, s[14:15]
	s_cbranch_execnz .LBB0_476

.LBB0_479:
	v_add_u32_e32 v8, s6, v8
	v_cmp_lt_i32_e32 vcc, s1, v8
	global_store_dwordx4 v[6:7], v[0:3], off sc0 sc1
	s_or_b64 s[12:13], vcc, s[12:13]
	v_lshl_add_u64 v[6:7], v[6:7], 0, s[10:11]
	s_andn2_b64 exec, exec, s[12:13]
	s_cbranch_execnz .LBB0_479

.LBB0_482:
	v_add_u32_e32 v8, s6, v8
	v_cmp_lt_i32_e64 s[4:5], s2, v8
	global_store_dwordx4 v[6:7], v[0:3], off sc0 sc1
	s_or_b64 s[14:15], s[4:5], s[14:15]
	v_lshl_add_u64 v[6:7], v[6:7], 0, s[12:13]
	s_andn2_b64 exec, exec, s[14:15]
	s_cbranch_execnz .LBB0_482

.LBB0_485:
	v_add_u32_e32 v4, s6, v4
	v_cmp_lt_i32_e32 vcc, s2, v4
	global_store_dwordx4 v[6:7], v[0:3], off sc0 sc1
	s_or_b64 s[10:11], vcc, s[10:11]
	v_lshl_add_u64 v[6:7], v[6:7], 0, s[8:9]
	s_andn2_b64 exec, exec, s[10:11]
	s_cbranch_execnz .LBB0_485

; __device__ __forceinline__ u32x4 pack8(const f32x4& a, const f32x4& b) { u32x4 w; w.x = cvt_pk_bf16(a[0], a[1]); w.y = cvt_pk_bf16(a[2], a[3]); w.z = cvt_pk_bf16(b[0], b[1]); w.w = cvt_pk_bf16(b[2], b[3]); return w; }
;     __device__ __forceinline__ void operator()(const f32x4 (&acc)[2][2][4][2], const Unit& u, int wr, int wc, int fr, int fq) const {
;         { int l_; asm volatile("v_mbcnt_lo_u32_b32 %0, -1, 0\n\tv_mbcnt_hi_u32_b32 %0, -1, %0" : "=v"(l_)); fr = l_ & 15; fq = (l_ >> 4) & 3; }
;         const int row0 = u.pm * BM + wr * 64 + fr;
; #pragma unroll
;         for (int bj = 0; bj < 2; ++bj) {
;             const int cbase = u.pn * BM + bj * HALF, reg = cbase >> 7, cw = wc * 32 + 8 * fq;
; #pragma unroll
;             for (int ai = 0; ai < 2; ++ai)
; #pragma unroll
;                 for (int m = 0; m < 4; ++m) {
;                     const int row = row0 + ai * HALF + m * 16; const f32x4 v0 = acc[ai][bj][m][0], v1 = acc[ai][bj][m][1]; const u32x4 w = pack8(v0, v1);
;                     const bool isp = row < NPROMPT; const int b = isp ? (row >> 14) : ((row - NPROMPT) >> 5), s = isp ? (row & (SEQ - 1)) : ((row - NPROMPT) & 31);
;                     if (reg < 4) { *(u32x4*)(Q0 + (size_t)row * 1024 + cbase + cw) = w; }
;                     else if (reg < 12) {
;                         const bool isk = reg < 8; const int c = cbase - (isk ? 512 : 1024) + cw;
;                         const int kr = isp ? row : NPROMPT + b * (LA + 32) + LA + s;
;                         *(u32x4*)((isk ? KA : VA) + (size_t)kr * 512 + c) = w;
;                         float* o = nullptr;
;                         if (isp) { if (s >= SEQ - LA) o = out + (isk ? O_AKP : O_AVP) + (size_t)(b * LA + s - (SEQ - LA)) * 512 + c; }
;                         else o = out + (isk ? O_AKS : O_AVS) + (size_t)(row - NPROMPT) * 512 + c;
;                         if (o) { *(f32x4*)o = v0; *(f32x4*)(o + 4) = v1; }
;                     } else if (reg < 16) { *(u32x4*)(Q0 + (size_t)row * 1024 + 512 + (cbase - 1536) + cw) = w; }
;                     else {
;                         const bool isk = reg == 16; const int c = cw;
;                         const int kr = isp ? row : NPROMPT + b * (LB + 32) + LB + s;
;                         *(u32x4*)((isk ? KB : VB) + (size_t)kr * 128 + c) = w;
.LBB0_565:
	s_lshl_b32 s2, s2, 8
	s_add_i32 s10, s2, s33
	s_lshl_b32 s72, s8, 8
	s_lshl_b32 s2, s8, 1
	s_cmp_gt_i32 s8, 1
	s_cselect_b64 s[14:15], -1, 0
	s_cmp_gt_u32 s2, 11
	s_cselect_b64 s[16:17], -1, 0
	s_cmp_gt_u32 s2, 15
	s_cselect_b64 s[74:75], -1, 0
	s_cmp_eq_u32 s8, 8
	s_cselect_b64 s[68:69], -1, 0
	s_and_b64 s[6:7], s[68:69], exec
	s_mov_b32 s6, 0x2b10000
	s_cselect_b32 s55, s6, 0x2b20000
	s_mov_b32 s6, 0x2180000
	s_cselect_b32 s54, s6, 0x2188000
	s_cmp_lt_u32 s2, 8
	s_cselect_b64 s[66:67], -1, 0
	v_mbcnt_lo_u32_b32 v128, -1, 0
	v_mbcnt_hi_u32_b32 v128, -1, v128
	s_and_b64 s[6:7], s[66:67], exec
	s_movk_i32 s2, 0xfe00
	v_and_b32_e32 v155, 15, v128
	v_lshrrev_b32_e32 v128, 1, v128
	s_cselect_b32 s2, s2, 0xfffffc00
	v_and_or_b32 v154, v128, 24, s84
	s_add_i32 s2, s2, s72
	v_or_b32_e32 v148, s2, v154
	s_and_b64 s[6:7], s[66:67], exec
	s_mov_b32 s2, 0x2a90000
	v_or_b32_e32 v144, s10, v155
	s_cselect_b32 s71, s2, 0x2ad0000
	s_mov_b32 s2, 0x2080000
	s_cselect_b32 s70, s2, 0x2100000
	s_ashr_i32 s20, s10, 14
	v_add_u32_e32 v146, 0xffff8000, v144
	v_lshrrev_b32_e32 v145, 5, v146
	v_mov_b32_e32 v147, s20
	v_cmp_gt_i32_e64 s[8:9], s0, v144
	s_lshl_b32 s59, s20, 7
	s_lshl_b32 s2, s20, 9
	s_movk_i32 s3, 0x7fff
	v_cndmask_b32_e64 v157, v145, v147, s[8:9]
	v_mov_b32_e32 v145, s10
	s_movk_i32 s10, 0x3fcf
	v_ashrrev_i32_e32 v149, 31, v148
	s_addk_i32 s59, 0xc080
	s_addk_i32 s2, 0xc200
	v_cmp_lt_i32_e64 s[6:7], s3, v144
	v_bitop3_b32 v156, v155, s10, v145 bitop3:0xc8
	s_mov_b64 s[10:11], -1
	s_and_b64 vcc, exec, s[14:15]
	v_cvt_pk_bf16_f32 v128, v124, v125
	v_cvt_pk_bf16_f32 v129, v126, v127
	v_cvt_pk_bf16_f32 v130, v120, v121
	v_cvt_pk_bf16_f32 v131, v122, v123
	s_cbranch_vccz .LBB0_583
	s_and_b64 vcc, exec, s[16:17]
	s_cbranch_vccz .LBB0_576
	s_and_b64 vcc, exec, s[74:75]
	s_cbranch_vccz .LBB0_573
	s_movk_i32 s10, 0xa0
	v_mul_lo_u32 v145, v157, s10
	v_or_b32_e32 v145, v145, v155
	v_add_u32_e32 v145, 0x8080, v145
	v_cndmask_b32_e64 v150, v145, v144, s[8:9]
	s_and_b64 s[10:11], s[68:69], exec
	v_ashrrev_i32_e32 v151, 31, v150
	s_cselect_b32 s11, s89, s47
	s_cselect_b32 s10, s88, s46
	v_lshlrev_b64 v[150:151], 8, v[150:151]
	v_lshl_add_u64 v[150:151], s[10:11], 0, v[150:151]
	v_lshlrev_b32_e32 v196, 1, v154
	v_lshl_add_u64 v[150:151], v[150:151], 0, v[196:197]
	global_store_dwordx4 v[150:151], v[128:131], off sc0 sc1
	s_and_saveexec_b64 s[10:11], s[6:7]
	s_xor_b64 s[10:11], exec, s[10:11]
	s_cbranch_execnz .LBB0_928
	s_andn2_saveexec_b64 s[10:11], s[10:11]
	s_cbranch_execnz .LBB0_929

;     __device__ __forceinline__ void operator()(const f32x4 (&acc)[2][2][4][2], const Unit& u, int wr, int wc, int fr, int fq) const {
;     ...
;                         float* o = nullptr;
;                         if (isp) { if (s >= SEQ - LA) o = out + (isk ? O_AKP : O_AVP) + (size_t)(b * LA + s - (SEQ - LA)) * 512 + c; }
;                         else o = out + (isk ? O_AKS : O_AVS) + (size_t)(row - NPROMPT) * 512 + c;
;                         if (o) { *(f32x4*)o = v0; *(f32x4*)(o + 4) = v1; }
;                     } else if (reg < 16) { *(u32x4*)(Q0 + (size_t)row * 1024 + 512 + (cbase - 1536) + cw) = w; }
;                     else {
;                         const bool isk = reg == 16; const int c = cw;
;                         const int kr = isp ? row : NPROMPT + b * (LB + 32) + LB + s;
;                         *(u32x4*)((isk ? KB : VB) + (size_t)kr * 128 + c) = w;
;                         float* o = nullptr;
;                         if (isp) { if (s >= SEQ - LB) o = out + (isk ? O_BKP : O_BVP) + (size_t)(b * LB + s - (SEQ - LB)) * 128 + c; }
;                         else o = out + (isk ? O_BKS : O_BVS) + (size_t)(row - NPROMPT) * 128 + c;
;                         if (o) { *(f32x4*)o = v0; *(f32x4*)(o + 4) = v1; }
.LBB0_571:
	global_store_dwordx4 v[150:151], v[124:127], off sc0 sc1
	global_store_dwordx4 v[150:151], v[120:123], off offset:16 sc0 sc1

;     __device__ __forceinline__ void operator()(const f32x4 (&acc)[2][2][4][2], const Unit& u, int wr, int wc, int fr, int fq) const {
;     ...
;                     if (reg < 4) { *(u32x4*)(Q0 + (size_t)row * 1024 + cbase + cw) = w; }
;                     else if (reg < 12) {
;                         const bool isk = reg < 8; const int c = cbase - (isk ? 512 : 1024) + cw;
;                         const int kr = isp ? row : NPROMPT + b * (LA + 32) + LA + s;
;                         *(u32x4*)((isk ? KA : VA) + (size_t)kr * 512 + c) = w;
;                         float* o = nullptr;
;                         if (isp) { if (s >= SEQ - LA) o = out + (isk ? O_AKP : O_AVP) + (size_t)(b * LA + s - (SEQ - LA)) * 512 + c; }
;                         else o = out + (isk ? O_AKS : O_AVS) + (size_t)(row - NPROMPT) * 512 + c;
;                         if (o) { *(f32x4*)o = v0; *(f32x4*)(o + 4) = v1; }
;                     } else if (reg < 16) { *(u32x4*)(Q0 + (size_t)row * 1024 + 512 + (cbase - 1536) + cw) = w; }
.LBB0_573:
	s_and_b64 vcc, exec, s[10:11]
	s_cbranch_vccz .LBB0_575
	v_ashrrev_i32_e32 v145, 31, v144
	v_lshlrev_b64 v[150:151], 11, v[144:145]
	v_lshl_add_u64 v[150:151], s[50:51], 0, v[150:151]
	v_lshl_add_u64 v[150:151], s[72:73], 1, v[150:151]
	v_lshlrev_b32_e32 v196, 1, v154
	v_lshl_add_u64 v[150:151], v[150:151], 0, v[196:197]
	global_store_dwordx4 v[150:151], v[128:131], off offset:-2048 sc0 sc1

;     __device__ __forceinline__ void operator()(const f32x4 (&acc)[2][2][4][2], const Unit& u, int wr, int wc, int fr, int fq) const {
;     ...
;                     else if (reg < 12) {
;                         const bool isk = reg < 8; const int c = cbase - (isk ? 512 : 1024) + cw;
;                         const int kr = isp ? row : NPROMPT + b * (LA + 32) + LA + s;
;                         *(u32x4*)((isk ? KA : VA) + (size_t)kr * 512 + c) = w;
.LBB0_576:
	s_andn2_b64 vcc, exec, s[10:11]
	s_cbranch_vccnz .LBB0_582
	v_mul_lo_u32 v145, v157, s56
	v_or_b32_e32 v145, v145, v155
	v_add_u32_e32 v145, 0x8200, v145
	v_cndmask_b32_e64 v150, v145, v144, s[8:9]
	s_and_b64 s[10:11], s[66:67], exec
	v_ashrrev_i32_e32 v151, 31, v150
	s_cselect_b32 s11, s1, s87
	s_cselect_b32 s10, s97, s86
	v_lshlrev_b64 v[150:151], 10, v[150:151]
	v_lshl_add_u64 v[150:151], s[10:11], 0, v[150:151]
	v_lshl_add_u64 v[150:151], v[148:149], 1, v[150:151]
	global_store_dwordx4 v[150:151], v[128:131], off sc0 sc1
	s_and_saveexec_b64 s[10:11], s[6:7]
	s_xor_b64 s[10:11], exec, s[10:11]
	s_cbranch_execnz .LBB0_896
	s_andn2_saveexec_b64 s[10:11], s[10:11]
	s_cbranch_execnz .LBB0_897

; __device__ __forceinline__ u32x4 pack8(const f32x4& a, const f32x4& b) { u32x4 w; w.x = cvt_pk_bf16(a[0], a[1]); w.y = cvt_pk_bf16(a[2], a[3]); w.z = cvt_pk_bf16(b[0], b[1]); w.w = cvt_pk_bf16(b[2], b[3]); return w; }
;     __device__ __forceinline__ void operator()(const f32x4 (&acc)[2][2][4][2], const Unit& u, int wr, int wc, int fr, int fq) const {
;     ...
;                     const int row = row0 + ai * HALF + m * 16; const f32x4 v0 = acc[ai][bj][m][0], v1 = acc[ai][bj][m][1]; const u32x4 w = pack8(v0, v1);
;                     const bool isp = row < NPROMPT; const int b = isp ? (row >> 14) : ((row - NPROMPT) >> 5), s = isp ? (row & (SEQ - 1)) : ((row - NPROMPT) & 31);
;                     if (reg < 4) { *(u32x4*)(Q0 + (size_t)row * 1024 + cbase + cw) = w; }
;                     else if (reg < 12) {
;                         const bool isk = reg < 8; const int c = cbase - (isk ? 512 : 1024) + cw;
;                         const int kr = isp ? row : NPROMPT + b * (LA + 32) + LA + s;
;                         *(u32x4*)((isk ? KA : VA) + (size_t)kr * 512 + c) = w;
;                         float* o = nullptr;
;                         if (isp) { if (s >= SEQ - LA) o = out + (isk ? O_AKP : O_AVP) + (size_t)(b * LA + s - (SEQ - LA)) * 512 + c; }
;                         else o = out + (isk ? O_AKS : O_AVS) + (size_t)(row - NPROMPT) * 512 + c;
;                         if (o) { *(f32x4*)o = v0; *(f32x4*)(o + 4) = v1; }
;                     } else if (reg < 16) { *(u32x4*)(Q0 + (size_t)row * 1024 + 512 + (cbase - 1536) + cw) = w; }
;                     else {
;                         const bool isk = reg == 16; const int c = cw;
;                         const int kr = isp ? row : NPROMPT + b * (LB + 32) + LB + s;
;                         *(u32x4*)((isk ? KB : VB) + (size_t)kr * 128 + c) = w;
.LBB0_583:
	s_ashr_i32 s65, s72, 31
	s_mov_b32 s64, s72
	s_andn2_b64 vcc, exec, s[10:11]
	v_ashrrev_i32_e32 v145, 31, v144
	v_lshlrev_b32_e32 v196, 1, v154
	s_cbranch_vccnz .LBB0_585
	v_lshlrev_b64 v[120:121], 11, v[144:145]
	v_lshl_add_u64 v[120:121], s[50:51], 0, v[120:121]
	v_lshl_add_u64 v[120:121], s[64:65], 1, v[120:121]
	v_lshl_add_u64 v[120:121], v[120:121], 0, v[196:197]
	global_store_dwordx4 v[120:121], v[128:131], off sc0 sc1
.LBB0_585:
	v_or_b32_e32 v124, 16, v144
	v_add_u32_e32 v126, 0xffff8010, v144
	v_lshrrev_b32_e32 v125, 5, v126
	v_mov_b32_e32 v127, s20
	v_cmp_gt_i32_e64 s[12:13], s0, v124
	s_movk_i32 s18, 0x3fdf
	v_or_b32_e32 v130, 16, v155
	v_cndmask_b32_e64 v150, v125, v127, s[12:13]
	v_cndmask_b32_e64 v125, 0, 1, s[14:15]
	v_cmp_ne_u32_e64 s[42:43], 1, v125
	v_cndmask_b32_e64 v125, 0, 1, s[16:17]
	v_cmp_lt_i32_e64 s[10:11], s3, v124
	v_bitop3_b32 v131, v144, s18, 16 bitop3:0xc8
	s_mov_b64 s[18:19], -1
	s_andn2_b64 vcc, exec, s[14:15]
	v_cmp_ne_u32_e64 s[40:41], 1, v125
	v_cvt_pk_bf16_f32 v120, v116, v117
	v_cvt_pk_bf16_f32 v121, v118, v119
	v_cvt_pk_bf16_f32 v122, v112, v113
	v_cvt_pk_bf16_f32 v123, v114, v115
	s_cbranch_vccnz .LBB0_603
	s_and_b64 vcc, exec, s[40:41]
	s_mov_b64 s[14:15], -1
	s_cbranch_vccnz .LBB0_596
	s_andn2_b64 vcc, exec, s[74:75]
	s_cbranch_vccnz .LBB0_593
	s_movk_i32 s14, 0xa0
	v_mul_lo_u32 v125, v150, s14
	v_or_b32_e32 v125, v125, v130
	v_add_u32_e32 v125, 0x8080, v125
	v_cndmask_b32_e64 v128, v125, v124, s[12:13]
	s_and_b64 s[14:15], s[68:69], exec
	v_ashrrev_i32_e32 v129, 31, v128
	s_cselect_b32 s15, s89, s47
	s_cselect_b32 s14, s88, s46
	v_lshlrev_b64 v[128:129], 8, v[128:129]
	v_lshl_add_u64 v[128:129], s[14:15], 0, v[128:129]
	v_lshl_add_u64 v[128:129], v[128:129], 0, v[196:197]
	global_store_dwordx4 v[128:129], v[120:123], off sc0 sc1
	s_and_saveexec_b64 s[14:15], s[10:11]
	s_xor_b64 s[14:15], exec, s[14:15]
	s_cbranch_execnz .LBB0_930
	s_andn2_saveexec_b64 s[14:15], s[14:15]
	s_cbranch_execnz .LBB0_931

;     __device__ __forceinline__ void operator()(const f32x4 (&acc)[2][2][4][2], const Unit& u, int wr, int wc, int fr, int fq) const {
;     ...
;                         float* o = nullptr;
;                         if (isp) { if (s >= SEQ - LA) o = out + (isk ? O_AKP : O_AVP) + (size_t)(b * LA + s - (SEQ - LA)) * 512 + c; }
;                         else o = out + (isk ? O_AKS : O_AVS) + (size_t)(row - NPROMPT) * 512 + c;
;                         if (o) { *(f32x4*)o = v0; *(f32x4*)(o + 4) = v1; }
;                     } else if (reg < 16) { *(u32x4*)(Q0 + (size_t)row * 1024 + 512 + (cbase - 1536) + cw) = w; }
;                     else {
;                         const bool isk = reg == 16; const int c = cw;
;                         const int kr = isp ? row : NPROMPT + b * (LB + 32) + LB + s;
;                         *(u32x4*)((isk ? KB : VB) + (size_t)kr * 128 + c) = w;
;                         float* o = nullptr;
;                         if (isp) { if (s >= SEQ - LB) o = out + (isk ? O_BKP : O_BVP) + (size_t)(b * LB + s - (SEQ - LB)) * 128 + c; }
;                         else o = out + (isk ? O_BKS : O_BVS) + (size_t)(row - NPROMPT) * 128 + c;
;                         if (o) { *(f32x4*)o = v0; *(f32x4*)(o + 4) = v1; }
.LBB0_591:
	global_store_dwordx4 v[128:129], v[116:119], off sc0 sc1
	global_store_dwordx4 v[128:129], v[112:115], off offset:16 sc0 sc1

;     __device__ __forceinline__ void operator()(const f32x4 (&acc)[2][2][4][2], const Unit& u, int wr, int wc, int fr, int fq) const {
;     ...
;                     if (reg < 4) { *(u32x4*)(Q0 + (size_t)row * 1024 + cbase + cw) = w; }
;                     else if (reg < 12) {
;                         const bool isk = reg < 8; const int c = cbase - (isk ? 512 : 1024) + cw;
;                         const int kr = isp ? row : NPROMPT + b * (LA + 32) + LA + s;
;                         *(u32x4*)((isk ? KA : VA) + (size_t)kr * 512 + c) = w;
;                         float* o = nullptr;
;                         if (isp) { if (s >= SEQ - LA) o = out + (isk ? O_AKP : O_AVP) + (size_t)(b * LA + s - (SEQ - LA)) * 512 + c; }
;                         else o = out + (isk ? O_AKS : O_AVS) + (size_t)(row - NPROMPT) * 512 + c;
;                         if (o) { *(f32x4*)o = v0; *(f32x4*)(o + 4) = v1; }
;                     } else if (reg < 16) { *(u32x4*)(Q0 + (size_t)row * 1024 + 512 + (cbase - 1536) + cw) = w; }
.LBB0_593:
	s_and_b64 vcc, exec, s[14:15]
	s_cbranch_vccz .LBB0_595
	v_ashrrev_i32_e32 v125, 31, v124
	v_lshlrev_b64 v[128:129], 11, v[124:125]
	v_lshl_add_u64 v[128:129], s[50:51], 0, v[128:129]
	v_lshl_add_u64 v[128:129], s[72:73], 1, v[128:129]
	v_lshl_add_u64 v[128:129], v[128:129], 0, v[196:197]
	global_store_dwordx4 v[128:129], v[120:123], off offset:-2048 sc0 sc1

;     __device__ __forceinline__ void operator()(const f32x4 (&acc)[2][2][4][2], const Unit& u, int wr, int wc, int fr, int fq) const {
;     ...
;                     else if (reg < 12) {
;                         const bool isk = reg < 8; const int c = cbase - (isk ? 512 : 1024) + cw;
;                         const int kr = isp ? row : NPROMPT + b * (LA + 32) + LA + s;
;                         *(u32x4*)((isk ? KA : VA) + (size_t)kr * 512 + c) = w;
.LBB0_596:
	s_andn2_b64 vcc, exec, s[14:15]
	s_cbranch_vccnz .LBB0_602
	v_mul_lo_u32 v125, v150, s56
	v_or_b32_e32 v125, v125, v130
	v_add_u32_e32 v125, 0x8200, v125
	v_cndmask_b32_e64 v128, v125, v124, s[12:13]
	s_and_b64 s[14:15], s[66:67], exec
	v_ashrrev_i32_e32 v129, 31, v128
	s_cselect_b32 s15, s1, s87
	s_cselect_b32 s14, s97, s86
	v_lshlrev_b64 v[128:129], 10, v[128:129]
	v_lshl_add_u64 v[128:129], s[14:15], 0, v[128:129]
	v_lshl_add_u64 v[128:129], v[148:149], 1, v[128:129]
	global_store_dwordx4 v[128:129], v[120:123], off sc0 sc1
	s_and_saveexec_b64 s[14:15], s[10:11]
	s_xor_b64 s[14:15], exec, s[14:15]
	s_cbranch_execnz .LBB0_898
	s_andn2_saveexec_b64 s[14:15], s[14:15]
	s_cbranch_execnz .LBB0_899

; __device__ __forceinline__ u32x4 pack8(const f32x4& a, const f32x4& b) { u32x4 w; w.x = cvt_pk_bf16(a[0], a[1]); w.y = cvt_pk_bf16(a[2], a[3]); w.z = cvt_pk_bf16(b[0], b[1]); w.w = cvt_pk_bf16(b[2], b[3]); return w; }
;     __device__ __forceinline__ void operator()(const f32x4 (&acc)[2][2][4][2], const Unit& u, int wr, int wc, int fr, int fq) const {
;     ...
;                     const int row = row0 + ai * HALF + m * 16; const f32x4 v0 = acc[ai][bj][m][0], v1 = acc[ai][bj][m][1]; const u32x4 w = pack8(v0, v1);
;                     const bool isp = row < NPROMPT; const int b = isp ? (row >> 14) : ((row - NPROMPT) >> 5), s = isp ? (row & (SEQ - 1)) : ((row - NPROMPT) & 31);
;                     if (reg < 4) { *(u32x4*)(Q0 + (size_t)row * 1024 + cbase + cw) = w; }
;                     else if (reg < 12) {
;                         const bool isk = reg < 8; const int c = cbase - (isk ? 512 : 1024) + cw;
;                         const int kr = isp ? row : NPROMPT + b * (LA + 32) + LA + s;
;                         *(u32x4*)((isk ? KA : VA) + (size_t)kr * 512 + c) = w;
;                         float* o = nullptr;
;                         if (isp) { if (s >= SEQ - LA) o = out + (isk ? O_AKP : O_AVP) + (size_t)(b * LA + s - (SEQ - LA)) * 512 + c; }
;                         else o = out + (isk ? O_AKS : O_AVS) + (size_t)(row - NPROMPT) * 512 + c;
;                         if (o) { *(f32x4*)o = v0; *(f32x4*)(o + 4) = v1; }
;                     } else if (reg < 16) { *(u32x4*)(Q0 + (size_t)row * 1024 + 512 + (cbase - 1536) + cw) = w; }
;                     else {
;                         const bool isk = reg == 16; const int c = cw;
;                         const int kr = isp ? row : NPROMPT + b * (LB + 32) + LB + s;
;                         *(u32x4*)((isk ? KB : VB) + (size_t)kr * 128 + c) = w;
.LBB0_603:
	s_andn2_b64 vcc, exec, s[18:19]
	v_ashrrev_i32_e32 v125, 31, v124
	s_cbranch_vccnz .LBB0_605
	v_lshlrev_b64 v[112:113], 11, v[124:125]
	v_lshl_add_u64 v[112:113], s[50:51], 0, v[112:113]
	v_lshl_add_u64 v[112:113], s[64:65], 1, v[112:113]
	v_lshl_add_u64 v[112:113], v[112:113], 0, v[196:197]
	global_store_dwordx4 v[112:113], v[120:123], off sc0 sc1
.LBB0_605:
	v_or_b32_e32 v116, 32, v144
	v_add_u32_e32 v118, 0xffff8020, v144
	v_lshrrev_b32_e32 v117, 5, v118
	v_mov_b32_e32 v119, s20
	v_cmp_gt_i32_e64 s[16:17], s0, v116
	s_movk_i32 s18, 0x3fef
	v_cmp_lt_i32_e64 s[14:15], s3, v116
	v_cndmask_b32_e64 v123, v117, v119, s[16:17]
	v_bitop3_b32 v122, v144, s18, 32 bitop3:0xc8
	s_and_b64 vcc, exec, s[42:43]
	s_mov_b64 s[18:19], -1
	v_cvt_pk_bf16_f32 v112, v108, v109
	v_cvt_pk_bf16_f32 v113, v110, v111
	v_cvt_pk_bf16_f32 v114, v104, v105
	v_cvt_pk_bf16_f32 v115, v106, v107
	s_cbranch_vccnz .LBB0_623
	s_and_b64 vcc, exec, s[40:41]
	s_cbranch_vccnz .LBB0_616
	s_andn2_b64 vcc, exec, s[74:75]
	s_cbranch_vccnz .LBB0_613
	s_movk_i32 s18, 0xa0
	v_mul_lo_u32 v117, v123, s18
	v_or_b32_e32 v117, v117, v155
	v_add_u32_e32 v117, 0x8080, v117
	v_cndmask_b32_e64 v120, v117, v116, s[16:17]
	s_and_b64 s[18:19], s[68:69], exec
	v_ashrrev_i32_e32 v121, 31, v120
	s_cselect_b32 s19, s89, s47
	s_cselect_b32 s18, s88, s46
	v_lshlrev_b64 v[120:121], 8, v[120:121]
	v_lshl_add_u64 v[120:121], s[18:19], 0, v[120:121]
	v_lshl_add_u64 v[120:121], v[120:121], 0, v[196:197]
	global_store_dwordx4 v[120:121], v[112:115], off sc0 sc1
	s_and_saveexec_b64 s[18:19], s[14:15]
	s_xor_b64 s[18:19], exec, s[18:19]
	s_cbranch_execnz .LBB0_932
	s_andn2_saveexec_b64 s[18:19], s[18:19]
	s_cbranch_execnz .LBB0_933

;     __device__ __forceinline__ void operator()(const f32x4 (&acc)[2][2][4][2], const Unit& u, int wr, int wc, int fr, int fq) const {
;     ...
;                         float* o = nullptr;
;                         if (isp) { if (s >= SEQ - LA) o = out + (isk ? O_AKP : O_AVP) + (size_t)(b * LA + s - (SEQ - LA)) * 512 + c; }
;                         else o = out + (isk ? O_AKS : O_AVS) + (size_t)(row - NPROMPT) * 512 + c;
;                         if (o) { *(f32x4*)o = v0; *(f32x4*)(o + 4) = v1; }
;                     } else if (reg < 16) { *(u32x4*)(Q0 + (size_t)row * 1024 + 512 + (cbase - 1536) + cw) = w; }
;                     else {
;                         const bool isk = reg == 16; const int c = cw;
;                         const int kr = isp ? row : NPROMPT + b * (LB + 32) + LB + s;
;                         *(u32x4*)((isk ? KB : VB) + (size_t)kr * 128 + c) = w;
;                         float* o = nullptr;
;                         if (isp) { if (s >= SEQ - LB) o = out + (isk ? O_BKP : O_BVP) + (size_t)(b * LB + s - (SEQ - LB)) * 128 + c; }
;                         else o = out + (isk ? O_BKS : O_BVS) + (size_t)(row - NPROMPT) * 128 + c;
;                         if (o) { *(f32x4*)o = v0; *(f32x4*)(o + 4) = v1; }
.LBB0_611:
	global_store_dwordx4 v[120:121], v[108:111], off sc0 sc1
	global_store_dwordx4 v[120:121], v[104:107], off offset:16 sc0 sc1

;     __device__ __forceinline__ void operator()(const f32x4 (&acc)[2][2][4][2], const Unit& u, int wr, int wc, int fr, int fq) const {
;     ...
;                     if (reg < 4) { *(u32x4*)(Q0 + (size_t)row * 1024 + cbase + cw) = w; }
;                     else if (reg < 12) {
;                         const bool isk = reg < 8; const int c = cbase - (isk ? 512 : 1024) + cw;
;                         const int kr = isp ? row : NPROMPT + b * (LA + 32) + LA + s;
;                         *(u32x4*)((isk ? KA : VA) + (size_t)kr * 512 + c) = w;
;                         float* o = nullptr;
;                         if (isp) { if (s >= SEQ - LA) o = out + (isk ? O_AKP : O_AVP) + (size_t)(b * LA + s - (SEQ - LA)) * 512 + c; }
;                         else o = out + (isk ? O_AKS : O_AVS) + (size_t)(row - NPROMPT) * 512 + c;
;                         if (o) { *(f32x4*)o = v0; *(f32x4*)(o + 4) = v1; }
;                     } else if (reg < 16) { *(u32x4*)(Q0 + (size_t)row * 1024 + 512 + (cbase - 1536) + cw) = w; }
.LBB0_613:
	s_and_b64 vcc, exec, s[18:19]
	s_cbranch_vccz .LBB0_615
	v_ashrrev_i32_e32 v117, 31, v116
	v_lshlrev_b64 v[120:121], 11, v[116:117]
	v_lshl_add_u64 v[120:121], s[50:51], 0, v[120:121]
	v_lshl_add_u64 v[120:121], s[72:73], 1, v[120:121]
	v_lshl_add_u64 v[120:121], v[120:121], 0, v[196:197]
	global_store_dwordx4 v[120:121], v[112:115], off offset:-2048 sc0 sc1

;     __device__ __forceinline__ void operator()(const f32x4 (&acc)[2][2][4][2], const Unit& u, int wr, int wc, int fr, int fq) const {
;     ...
;                     else if (reg < 12) {
;                         const bool isk = reg < 8; const int c = cbase - (isk ? 512 : 1024) + cw;
;                         const int kr = isp ? row : NPROMPT + b * (LA + 32) + LA + s;
;                         *(u32x4*)((isk ? KA : VA) + (size_t)kr * 512 + c) = w;
.LBB0_616:
	s_andn2_b64 vcc, exec, s[18:19]
	s_cbranch_vccnz .LBB0_622
	v_mul_lo_u32 v117, v123, s56
	v_or_b32_e32 v117, v117, v155
	v_add_u32_e32 v117, 0x8200, v117
	v_cndmask_b32_e64 v120, v117, v116, s[16:17]
	s_and_b64 s[18:19], s[66:67], exec
	v_ashrrev_i32_e32 v121, 31, v120
	s_cselect_b32 s19, s1, s87
	s_cselect_b32 s18, s97, s86
	v_lshlrev_b64 v[120:121], 10, v[120:121]
	v_lshl_add_u64 v[120:121], s[18:19], 0, v[120:121]
	v_lshl_add_u64 v[120:121], v[148:149], 1, v[120:121]
	global_store_dwordx4 v[120:121], v[112:115], off sc0 sc1
	s_and_saveexec_b64 s[18:19], s[14:15]
	s_xor_b64 s[18:19], exec, s[18:19]
	s_cbranch_execnz .LBB0_900
	s_andn2_saveexec_b64 s[18:19], s[18:19]
	s_cbranch_execnz .LBB0_901

; __device__ __forceinline__ u32x4 pack8(const f32x4& a, const f32x4& b) { u32x4 w; w.x = cvt_pk_bf16(a[0], a[1]); w.y = cvt_pk_bf16(a[2], a[3]); w.z = cvt_pk_bf16(b[0], b[1]); w.w = cvt_pk_bf16(b[2], b[3]); return w; }
;     __device__ __forceinline__ void operator()(const f32x4 (&acc)[2][2][4][2], const Unit& u, int wr, int wc, int fr, int fq) const {
;     ...
;                     const int row = row0 + ai * HALF + m * 16; const f32x4 v0 = acc[ai][bj][m][0], v1 = acc[ai][bj][m][1]; const u32x4 w = pack8(v0, v1);
;                     const bool isp = row < NPROMPT; const int b = isp ? (row >> 14) : ((row - NPROMPT) >> 5), s = isp ? (row & (SEQ - 1)) : ((row - NPROMPT) & 31);
;                     if (reg < 4) { *(u32x4*)(Q0 + (size_t)row * 1024 + cbase + cw) = w; }
;                     else if (reg < 12) {
;                         const bool isk = reg < 8; const int c = cbase - (isk ? 512 : 1024) + cw;
;                         const int kr = isp ? row : NPROMPT + b * (LA + 32) + LA + s;
;                         *(u32x4*)((isk ? KA : VA) + (size_t)kr * 512 + c) = w;
;                         float* o = nullptr;
;                         if (isp) { if (s >= SEQ - LA) o = out + (isk ? O_AKP : O_AVP) + (size_t)(b * LA + s - (SEQ - LA)) * 512 + c; }
;                         else o = out + (isk ? O_AKS : O_AVS) + (size_t)(row - NPROMPT) * 512 + c;
;                         if (o) { *(f32x4*)o = v0; *(f32x4*)(o + 4) = v1; }
;                     } else if (reg < 16) { *(u32x4*)(Q0 + (size_t)row * 1024 + 512 + (cbase - 1536) + cw) = w; }
;                     else {
;                         const bool isk = reg == 16; const int c = cw;
;                         const int kr = isp ? row : NPROMPT + b * (LB + 32) + LB + s;
;                         *(u32x4*)((isk ? KB : VB) + (size_t)kr * 128 + c) = w;
.LBB0_623:
	s_andn2_b64 vcc, exec, s[18:19]
	v_ashrrev_i32_e32 v117, 31, v116
	s_cbranch_vccnz .LBB0_625
	v_lshlrev_b64 v[104:105], 11, v[116:117]
	v_lshl_add_u64 v[104:105], s[50:51], 0, v[104:105]
	v_lshl_add_u64 v[104:105], s[64:65], 1, v[104:105]
	v_lshl_add_u64 v[104:105], v[104:105], 0, v[196:197]
	global_store_dwordx4 v[104:105], v[112:115], off sc0 sc1
.LBB0_625:
	v_or_b32_e32 v108, 48, v144
	v_add_u32_e32 v110, 0xffff8030, v144
	v_lshrrev_b32_e32 v109, 5, v110
	v_mov_b32_e32 v111, s20
	v_cmp_gt_i32_e64 s[20:21], s0, v108
	s_movk_i32 s22, 0x3fff
	v_cmp_lt_i32_e64 s[18:19], s3, v108
	v_cndmask_b32_e64 v115, v109, v111, s[20:21]
	v_bitop3_b32 v114, v144, s22, 48 bitop3:0xc8
	s_and_b64 vcc, exec, s[42:43]
	s_mov_b64 s[22:23], -1
	s_movk_i32 s3, 0x420
	v_cvt_pk_bf16_f32 v104, v100, v101
	v_cvt_pk_bf16_f32 v105, v102, v103
	v_cvt_pk_bf16_f32 v106, v96, v97
	v_cvt_pk_bf16_f32 v107, v98, v99
	s_cbranch_vccnz .LBB0_643
	s_and_b64 vcc, exec, s[40:41]
	s_cbranch_vccnz .LBB0_636
	s_andn2_b64 vcc, exec, s[74:75]
	s_cbranch_vccnz .LBB0_633
	s_movk_i32 s22, 0xa0
	v_mul_lo_u32 v109, v115, s22
	v_or_b32_e32 v109, v109, v130
	v_add_u32_e32 v109, 0x8080, v109
	v_cndmask_b32_e64 v112, v109, v108, s[20:21]
	s_and_b64 s[22:23], s[68:69], exec
	v_ashrrev_i32_e32 v113, 31, v112
	s_cselect_b32 s23, s89, s47
	s_cselect_b32 s22, s88, s46
	v_lshlrev_b64 v[112:113], 8, v[112:113]
	v_lshl_add_u64 v[112:113], s[22:23], 0, v[112:113]
	v_lshl_add_u64 v[112:113], v[112:113], 0, v[196:197]
	global_store_dwordx4 v[112:113], v[104:107], off sc0 sc1
	s_and_saveexec_b64 s[22:23], s[18:19]
	s_xor_b64 s[22:23], exec, s[22:23]
	s_cbranch_execnz .LBB0_934
	s_andn2_saveexec_b64 s[22:23], s[22:23]
	s_cbranch_execnz .LBB0_935

;     __device__ __forceinline__ void operator()(const f32x4 (&acc)[2][2][4][2], const Unit& u, int wr, int wc, int fr, int fq) const {
;     ...
;                         float* o = nullptr;
;                         if (isp) { if (s >= SEQ - LA) o = out + (isk ? O_AKP : O_AVP) + (size_t)(b * LA + s - (SEQ - LA)) * 512 + c; }
;                         else o = out + (isk ? O_AKS : O_AVS) + (size_t)(row - NPROMPT) * 512 + c;
;                         if (o) { *(f32x4*)o = v0; *(f32x4*)(o + 4) = v1; }
;                     } else if (reg < 16) { *(u32x4*)(Q0 + (size_t)row * 1024 + 512 + (cbase - 1536) + cw) = w; }
;                     else {
;                         const bool isk = reg == 16; const int c = cw;
;                         const int kr = isp ? row : NPROMPT + b * (LB + 32) + LB + s;
;                         *(u32x4*)((isk ? KB : VB) + (size_t)kr * 128 + c) = w;
;                         float* o = nullptr;
;                         if (isp) { if (s >= SEQ - LB) o = out + (isk ? O_BKP : O_BVP) + (size_t)(b * LB + s - (SEQ - LB)) * 128 + c; }
;                         else o = out + (isk ? O_BKS : O_BVS) + (size_t)(row - NPROMPT) * 128 + c;
;                         if (o) { *(f32x4*)o = v0; *(f32x4*)(o + 4) = v1; }
.LBB0_631:
	global_store_dwordx4 v[112:113], v[100:103], off sc0 sc1
	global_store_dwordx4 v[112:113], v[96:99], off offset:16 sc0 sc1

;     __device__ __forceinline__ void operator()(const f32x4 (&acc)[2][2][4][2], const Unit& u, int wr, int wc, int fr, int fq) const {
;     ...
;                     if (reg < 4) { *(u32x4*)(Q0 + (size_t)row * 1024 + cbase + cw) = w; }
;                     else if (reg < 12) {
;                         const bool isk = reg < 8; const int c = cbase - (isk ? 512 : 1024) + cw;
;                         const int kr = isp ? row : NPROMPT + b * (LA + 32) + LA + s;
;                         *(u32x4*)((isk ? KA : VA) + (size_t)kr * 512 + c) = w;
;                         float* o = nullptr;
;                         if (isp) { if (s >= SEQ - LA) o = out + (isk ? O_AKP : O_AVP) + (size_t)(b * LA + s - (SEQ - LA)) * 512 + c; }
;                         else o = out + (isk ? O_AKS : O_AVS) + (size_t)(row - NPROMPT) * 512 + c;
;                         if (o) { *(f32x4*)o = v0; *(f32x4*)(o + 4) = v1; }
;                     } else if (reg < 16) { *(u32x4*)(Q0 + (size_t)row * 1024 + 512 + (cbase - 1536) + cw) = w; }
.LBB0_633:
	s_and_b64 vcc, exec, s[22:23]
	s_cbranch_vccz .LBB0_635
	v_ashrrev_i32_e32 v109, 31, v108
	v_lshlrev_b64 v[112:113], 11, v[108:109]
	v_lshl_add_u64 v[112:113], s[50:51], 0, v[112:113]
	v_lshl_add_u64 v[112:113], s[72:73], 1, v[112:113]
	v_lshl_add_u64 v[112:113], v[112:113], 0, v[196:197]
	global_store_dwordx4 v[112:113], v[104:107], off offset:-2048 sc0 sc1

;     __device__ __forceinline__ void operator()(const f32x4 (&acc)[2][2][4][2], const Unit& u, int wr, int wc, int fr, int fq) const {
;     ...
;                     else if (reg < 12) {
;                         const bool isk = reg < 8; const int c = cbase - (isk ? 512 : 1024) + cw;
;                         const int kr = isp ? row : NPROMPT + b * (LA + 32) + LA + s;
;                         *(u32x4*)((isk ? KA : VA) + (size_t)kr * 512 + c) = w;
.LBB0_636:
	s_andn2_b64 vcc, exec, s[22:23]
	s_cbranch_vccnz .LBB0_642
	v_mul_lo_u32 v109, v115, s56
	v_or_b32_e32 v109, v109, v130
	v_add_u32_e32 v109, 0x8200, v109
	v_cndmask_b32_e64 v112, v109, v108, s[20:21]
	s_and_b64 s[22:23], s[66:67], exec
	v_ashrrev_i32_e32 v113, 31, v112
	s_cselect_b32 s23, s1, s87
	s_cselect_b32 s22, s97, s86
	v_lshlrev_b64 v[112:113], 10, v[112:113]
	v_lshl_add_u64 v[112:113], s[22:23], 0, v[112:113]
	v_lshl_add_u64 v[112:113], v[148:149], 1, v[112:113]
	global_store_dwordx4 v[112:113], v[104:107], off sc0 sc1
	s_and_saveexec_b64 s[22:23], s[18:19]
	s_xor_b64 s[22:23], exec, s[22:23]
	s_cbranch_execnz .LBB0_902
	s_andn2_saveexec_b64 s[22:23], s[22:23]
	s_cbranch_execnz .LBB0_903

; __device__ __forceinline__ u32x4 pack8(const f32x4& a, const f32x4& b) { u32x4 w; w.x = cvt_pk_bf16(a[0], a[1]); w.y = cvt_pk_bf16(a[2], a[3]); w.z = cvt_pk_bf16(b[0], b[1]); w.w = cvt_pk_bf16(b[2], b[3]); return w; }
;     __device__ __forceinline__ void operator()(const f32x4 (&acc)[2][2][4][2], const Unit& u, int wr, int wc, int fr, int fq) const {
;     ...
;                     const int row = row0 + ai * HALF + m * 16; const f32x4 v0 = acc[ai][bj][m][0], v1 = acc[ai][bj][m][1]; const u32x4 w = pack8(v0, v1);
;                     const bool isp = row < NPROMPT; const int b = isp ? (row >> 14) : ((row - NPROMPT) >> 5), s = isp ? (row & (SEQ - 1)) : ((row - NPROMPT) & 31);
;                     if (reg < 4) { *(u32x4*)(Q0 + (size_t)row * 1024 + cbase + cw) = w; }
;                     else if (reg < 12) {
;                         const bool isk = reg < 8; const int c = cbase - (isk ? 512 : 1024) + cw;
;                         const int kr = isp ? row : NPROMPT + b * (LA + 32) + LA + s;
;                         *(u32x4*)((isk ? KA : VA) + (size_t)kr * 512 + c) = w;
;                         float* o = nullptr;
;                         if (isp) { if (s >= SEQ - LA) o = out + (isk ? O_AKP : O_AVP) + (size_t)(b * LA + s - (SEQ - LA)) * 512 + c; }
;                         else o = out + (isk ? O_AKS : O_AVS) + (size_t)(row - NPROMPT) * 512 + c;
;                         if (o) { *(f32x4*)o = v0; *(f32x4*)(o + 4) = v1; }
;                     } else if (reg < 16) { *(u32x4*)(Q0 + (size_t)row * 1024 + 512 + (cbase - 1536) + cw) = w; }
;                     else {
;                         const bool isk = reg == 16; const int c = cw;
;                         const int kr = isp ? row : NPROMPT + b * (LB + 32) + LB + s;
;                         *(u32x4*)((isk ? KB : VB) + (size_t)kr * 128 + c) = w;
.LBB0_643:
	s_andn2_b64 vcc, exec, s[22:23]
	v_ashrrev_i32_e32 v109, 31, v108
	s_cbranch_vccnz .LBB0_645
	v_lshlrev_b64 v[96:97], 11, v[108:109]
	v_lshl_add_u64 v[96:97], s[50:51], 0, v[96:97]
	v_lshl_add_u64 v[96:97], s[64:65], 1, v[96:97]
	v_lshl_add_u64 v[96:97], v[96:97], 0, v[196:197]
	global_store_dwordx4 v[96:97], v[104:107], off sc0 sc1
.LBB0_645:
	v_add_u32_e32 v100, 0x80, v144
	v_ashrrev_i32_e32 v111, 14, v100
	v_mov_b32_e32 v96, 0xffffc080
	v_add_u32_e32 v102, 0xffff8080, v144
	s_movk_i32 s24, 0x7f80
	v_lshl_add_u32 v107, v111, 7, v96
	v_mov_b32_e32 v96, 0xffffc200
	s_movk_i32 s22, 0x7f7f
	v_lshrrev_b32_e32 v101, 5, v102
	v_cmp_gt_i32_e64 s[24:25], s24, v144
	v_lshl_add_u32 v106, v111, 9, v96
	v_cmp_lt_i32_e64 s[22:23], s22, v144
	v_cndmask_b32_e64 v113, v101, v111, s[24:25]
	v_and_b32_e32 v112, 0x3fcf, v100
	s_and_b64 vcc, exec, s[42:43]
	s_mov_b64 s[26:27], -1
	v_cvt_pk_bf16_f32 v96, v92, v93
	v_cvt_pk_bf16_f32 v97, v94, v95
	v_cvt_pk_bf16_f32 v98, v88, v89
	v_cvt_pk_bf16_f32 v99, v90, v91
	s_cbranch_vccnz .LBB0_663
	s_and_b64 vcc, exec, s[40:41]
	s_cbranch_vccnz .LBB0_656
	s_andn2_b64 vcc, exec, s[74:75]
	s_cbranch_vccnz .LBB0_653
	s_movk_i32 s26, 0xa0
	v_mul_lo_u32 v101, v113, s26
	v_or_b32_e32 v101, v101, v155
	v_add_u32_e32 v101, 0x8080, v101
	v_cndmask_b32_e64 v104, v101, v100, s[24:25]
	s_and_b64 s[26:27], s[68:69], exec
	v_ashrrev_i32_e32 v105, 31, v104
	s_cselect_b32 s27, s89, s47
	s_cselect_b32 s26, s88, s46
	v_lshlrev_b64 v[104:105], 8, v[104:105]
	v_lshl_add_u64 v[104:105], s[26:27], 0, v[104:105]
	v_lshl_add_u64 v[104:105], v[104:105], 0, v[196:197]
	global_store_dwordx4 v[104:105], v[96:99], off sc0 sc1
	s_and_saveexec_b64 s[26:27], s[22:23]
	s_xor_b64 s[26:27], exec, s[26:27]
	s_cbranch_execnz .LBB0_936
	s_andn2_saveexec_b64 s[26:27], s[26:27]
	s_cbranch_execnz .LBB0_937

;     __device__ __forceinline__ void operator()(const f32x4 (&acc)[2][2][4][2], const Unit& u, int wr, int wc, int fr, int fq) const {
;     ...
;                         float* o = nullptr;
;                         if (isp) { if (s >= SEQ - LA) o = out + (isk ? O_AKP : O_AVP) + (size_t)(b * LA + s - (SEQ - LA)) * 512 + c; }
;                         else o = out + (isk ? O_AKS : O_AVS) + (size_t)(row - NPROMPT) * 512 + c;
;                         if (o) { *(f32x4*)o = v0; *(f32x4*)(o + 4) = v1; }
;                     } else if (reg < 16) { *(u32x4*)(Q0 + (size_t)row * 1024 + 512 + (cbase - 1536) + cw) = w; }
;                     else {
;                         const bool isk = reg == 16; const int c = cw;
;                         const int kr = isp ? row : NPROMPT + b * (LB + 32) + LB + s;
;                         *(u32x4*)((isk ? KB : VB) + (size_t)kr * 128 + c) = w;
;                         float* o = nullptr;
;                         if (isp) { if (s >= SEQ - LB) o = out + (isk ? O_BKP : O_BVP) + (size_t)(b * LB + s - (SEQ - LB)) * 128 + c; }
;                         else o = out + (isk ? O_BKS : O_BVS) + (size_t)(row - NPROMPT) * 128 + c;
;                         if (o) { *(f32x4*)o = v0; *(f32x4*)(o + 4) = v1; }
.LBB0_651:
	global_store_dwordx4 v[104:105], v[92:95], off sc0 sc1
	global_store_dwordx4 v[104:105], v[88:91], off offset:16 sc0 sc1

;     __device__ __forceinline__ void operator()(const f32x4 (&acc)[2][2][4][2], const Unit& u, int wr, int wc, int fr, int fq) const {
;     ...
;                     if (reg < 4) { *(u32x4*)(Q0 + (size_t)row * 1024 + cbase + cw) = w; }
;                     else if (reg < 12) {
;                         const bool isk = reg < 8; const int c = cbase - (isk ? 512 : 1024) + cw;
;                         const int kr = isp ? row : NPROMPT + b * (LA + 32) + LA + s;
;                         *(u32x4*)((isk ? KA : VA) + (size_t)kr * 512 + c) = w;
;                         float* o = nullptr;
;                         if (isp) { if (s >= SEQ - LA) o = out + (isk ? O_AKP : O_AVP) + (size_t)(b * LA + s - (SEQ - LA)) * 512 + c; }
;                         else o = out + (isk ? O_AKS : O_AVS) + (size_t)(row - NPROMPT) * 512 + c;
;                         if (o) { *(f32x4*)o = v0; *(f32x4*)(o + 4) = v1; }
;                     } else if (reg < 16) { *(u32x4*)(Q0 + (size_t)row * 1024 + 512 + (cbase - 1536) + cw) = w; }
.LBB0_653:
	s_and_b64 vcc, exec, s[26:27]
	s_cbranch_vccz .LBB0_655
	v_ashrrev_i32_e32 v101, 31, v100
	v_lshlrev_b64 v[104:105], 11, v[100:101]
	v_lshl_add_u64 v[104:105], s[50:51], 0, v[104:105]
	v_lshl_add_u64 v[104:105], s[72:73], 1, v[104:105]
	v_lshl_add_u64 v[104:105], v[104:105], 0, v[196:197]
	global_store_dwordx4 v[104:105], v[96:99], off offset:-2048 sc0 sc1

;     __device__ __forceinline__ void operator()(const f32x4 (&acc)[2][2][4][2], const Unit& u, int wr, int wc, int fr, int fq) const {
;     ...
;                     else if (reg < 12) {
;                         const bool isk = reg < 8; const int c = cbase - (isk ? 512 : 1024) + cw;
;                         const int kr = isp ? row : NPROMPT + b * (LA + 32) + LA + s;
;                         *(u32x4*)((isk ? KA : VA) + (size_t)kr * 512 + c) = w;
.LBB0_656:
	s_andn2_b64 vcc, exec, s[26:27]
	s_cbranch_vccnz .LBB0_662
	v_mul_lo_u32 v101, v113, s56
	v_or_b32_e32 v101, v101, v155
	v_add_u32_e32 v101, 0x8200, v101
	v_cndmask_b32_e64 v104, v101, v100, s[24:25]
	s_and_b64 s[26:27], s[66:67], exec
	v_ashrrev_i32_e32 v105, 31, v104
	s_cselect_b32 s27, s1, s87
	s_cselect_b32 s26, s97, s86
	v_lshlrev_b64 v[104:105], 10, v[104:105]
	v_lshl_add_u64 v[104:105], s[26:27], 0, v[104:105]
	v_lshl_add_u64 v[104:105], v[148:149], 1, v[104:105]
	global_store_dwordx4 v[104:105], v[96:99], off sc0 sc1
	s_and_saveexec_b64 s[26:27], s[22:23]
	s_xor_b64 s[26:27], exec, s[26:27]
	s_cbranch_execnz .LBB0_904
	s_andn2_saveexec_b64 s[26:27], s[26:27]
	s_cbranch_execnz .LBB0_905

; __device__ __forceinline__ u32x4 pack8(const f32x4& a, const f32x4& b) { u32x4 w; w.x = cvt_pk_bf16(a[0], a[1]); w.y = cvt_pk_bf16(a[2], a[3]); w.z = cvt_pk_bf16(b[0], b[1]); w.w = cvt_pk_bf16(b[2], b[3]); return w; }
;     __device__ __forceinline__ void operator()(const f32x4 (&acc)[2][2][4][2], const Unit& u, int wr, int wc, int fr, int fq) const {
;     ...
;                     const int row = row0 + ai * HALF + m * 16; const f32x4 v0 = acc[ai][bj][m][0], v1 = acc[ai][bj][m][1]; const u32x4 w = pack8(v0, v1);
;                     const bool isp = row < NPROMPT; const int b = isp ? (row >> 14) : ((row - NPROMPT) >> 5), s = isp ? (row & (SEQ - 1)) : ((row - NPROMPT) & 31);
;                     if (reg < 4) { *(u32x4*)(Q0 + (size_t)row * 1024 + cbase + cw) = w; }
;                     else if (reg < 12) {
;                         const bool isk = reg < 8; const int c = cbase - (isk ? 512 : 1024) + cw;
;                         const int kr = isp ? row : NPROMPT + b * (LA + 32) + LA + s;
;                         *(u32x4*)((isk ? KA : VA) + (size_t)kr * 512 + c) = w;
;                         float* o = nullptr;
;                         if (isp) { if (s >= SEQ - LA) o = out + (isk ? O_AKP : O_AVP) + (size_t)(b * LA + s - (SEQ - LA)) * 512 + c; }
;                         else o = out + (isk ? O_AKS : O_AVS) + (size_t)(row - NPROMPT) * 512 + c;
;                         if (o) { *(f32x4*)o = v0; *(f32x4*)(o + 4) = v1; }
;                     } else if (reg < 16) { *(u32x4*)(Q0 + (size_t)row * 1024 + 512 + (cbase - 1536) + cw) = w; }
;                     else {
;                         const bool isk = reg == 16; const int c = cw;
;                         const int kr = isp ? row : NPROMPT + b * (LB + 32) + LB + s;
;                         *(u32x4*)((isk ? KB : VB) + (size_t)kr * 128 + c) = w;
.LBB0_663:
	s_andn2_b64 vcc, exec, s[26:27]
	v_ashrrev_i32_e32 v101, 31, v100
	s_cbranch_vccnz .LBB0_665
	v_lshlrev_b64 v[88:89], 11, v[100:101]
	v_lshl_add_u64 v[88:89], s[50:51], 0, v[88:89]
	v_lshl_add_u64 v[88:89], s[64:65], 1, v[88:89]
	v_lshl_add_u64 v[88:89], v[88:89], 0, v[196:197]
	global_store_dwordx4 v[88:89], v[96:99], off sc0 sc1
.LBB0_665:
	v_add_u32_e32 v94, 0xffff8090, v144
	s_movk_i32 s28, 0x7f70
	v_add_u32_e32 v92, 0x90, v144
	s_movk_i32 s26, 0x7f6f
	v_lshrrev_b32_e32 v93, 5, v94
	v_cmp_gt_i32_e64 s[28:29], s28, v144
	v_cmp_lt_i32_e64 s[26:27], s26, v144
	v_and_b32_e32 v98, 0x3fdf, v92
	v_cndmask_b32_e64 v99, v93, v111, s[28:29]
	s_and_b64 vcc, exec, s[42:43]
	s_mov_b64 s[30:31], -1
	v_cvt_pk_bf16_f32 v88, v84, v85
	v_cvt_pk_bf16_f32 v89, v86, v87
	v_cvt_pk_bf16_f32 v90, v80, v81
	v_cvt_pk_bf16_f32 v91, v82, v83
	s_cbranch_vccnz .LBB0_683
	s_and_b64 vcc, exec, s[40:41]
	s_cbranch_vccnz .LBB0_676
	s_andn2_b64 vcc, exec, s[74:75]
	s_cbranch_vccnz .LBB0_673
	s_movk_i32 s30, 0xa0
	v_mul_lo_u32 v93, v99, s30
	v_or_b32_e32 v93, v93, v130
	v_add_u32_e32 v93, 0x8080, v93
	v_cndmask_b32_e64 v96, v93, v92, s[28:29]
	s_and_b64 s[30:31], s[68:69], exec
	v_ashrrev_i32_e32 v97, 31, v96
	s_cselect_b32 s31, s89, s47
	s_cselect_b32 s30, s88, s46
	v_lshlrev_b64 v[96:97], 8, v[96:97]
	v_lshl_add_u64 v[96:97], s[30:31], 0, v[96:97]
	v_lshl_add_u64 v[96:97], v[96:97], 0, v[196:197]
	global_store_dwordx4 v[96:97], v[88:91], off sc0 sc1
	s_and_saveexec_b64 s[30:31], s[26:27]
	s_xor_b64 s[30:31], exec, s[30:31]
	s_cbranch_execnz .LBB0_938
	s_andn2_saveexec_b64 s[30:31], s[30:31]
	s_cbranch_execnz .LBB0_939

;     __device__ __forceinline__ void operator()(const f32x4 (&acc)[2][2][4][2], const Unit& u, int wr, int wc, int fr, int fq) const {
;     ...
;                         float* o = nullptr;
;                         if (isp) { if (s >= SEQ - LA) o = out + (isk ? O_AKP : O_AVP) + (size_t)(b * LA + s - (SEQ - LA)) * 512 + c; }
;                         else o = out + (isk ? O_AKS : O_AVS) + (size_t)(row - NPROMPT) * 512 + c;
;                         if (o) { *(f32x4*)o = v0; *(f32x4*)(o + 4) = v1; }
;                     } else if (reg < 16) { *(u32x4*)(Q0 + (size_t)row * 1024 + 512 + (cbase - 1536) + cw) = w; }
;                     else {
;                         const bool isk = reg == 16; const int c = cw;
;                         const int kr = isp ? row : NPROMPT + b * (LB + 32) + LB + s;
;                         *(u32x4*)((isk ? KB : VB) + (size_t)kr * 128 + c) = w;
;                         float* o = nullptr;
;                         if (isp) { if (s >= SEQ - LB) o = out + (isk ? O_BKP : O_BVP) + (size_t)(b * LB + s - (SEQ - LB)) * 128 + c; }
;                         else o = out + (isk ? O_BKS : O_BVS) + (size_t)(row - NPROMPT) * 128 + c;
;                         if (o) { *(f32x4*)o = v0; *(f32x4*)(o + 4) = v1; }
.LBB0_671:
	global_store_dwordx4 v[96:97], v[84:87], off sc0 sc1
	global_store_dwordx4 v[96:97], v[80:83], off offset:16 sc0 sc1

;     __device__ __forceinline__ void operator()(const f32x4 (&acc)[2][2][4][2], const Unit& u, int wr, int wc, int fr, int fq) const {
;     ...
;                     if (reg < 4) { *(u32x4*)(Q0 + (size_t)row * 1024 + cbase + cw) = w; }
;                     else if (reg < 12) {
;                         const bool isk = reg < 8; const int c = cbase - (isk ? 512 : 1024) + cw;
;                         const int kr = isp ? row : NPROMPT + b * (LA + 32) + LA + s;
;                         *(u32x4*)((isk ? KA : VA) + (size_t)kr * 512 + c) = w;
;                         float* o = nullptr;
;                         if (isp) { if (s >= SEQ - LA) o = out + (isk ? O_AKP : O_AVP) + (size_t)(b * LA + s - (SEQ - LA)) * 512 + c; }
;                         else o = out + (isk ? O_AKS : O_AVS) + (size_t)(row - NPROMPT) * 512 + c;
;                         if (o) { *(f32x4*)o = v0; *(f32x4*)(o + 4) = v1; }
;                     } else if (reg < 16) { *(u32x4*)(Q0 + (size_t)row * 1024 + 512 + (cbase - 1536) + cw) = w; }
.LBB0_673:
	s_and_b64 vcc, exec, s[30:31]
	s_cbranch_vccz .LBB0_675
	v_ashrrev_i32_e32 v93, 31, v92
	v_lshlrev_b64 v[96:97], 11, v[92:93]
	v_lshl_add_u64 v[96:97], s[50:51], 0, v[96:97]
	v_lshl_add_u64 v[96:97], s[72:73], 1, v[96:97]
	v_lshl_add_u64 v[96:97], v[96:97], 0, v[196:197]
	global_store_dwordx4 v[96:97], v[88:91], off offset:-2048 sc0 sc1

;     __device__ __forceinline__ void operator()(const f32x4 (&acc)[2][2][4][2], const Unit& u, int wr, int wc, int fr, int fq) const {
;     ...
;                     else if (reg < 12) {
;                         const bool isk = reg < 8; const int c = cbase - (isk ? 512 : 1024) + cw;
;                         const int kr = isp ? row : NPROMPT + b * (LA + 32) + LA + s;
;                         *(u32x4*)((isk ? KA : VA) + (size_t)kr * 512 + c) = w;
.LBB0_676:
	s_andn2_b64 vcc, exec, s[30:31]
	s_cbranch_vccnz .LBB0_682
	v_mul_lo_u32 v93, v99, s56
	v_or_b32_e32 v93, v93, v130
	v_add_u32_e32 v93, 0x8200, v93
	v_cndmask_b32_e64 v96, v93, v92, s[28:29]
	s_and_b64 s[30:31], s[66:67], exec
	v_ashrrev_i32_e32 v97, 31, v96
	s_cselect_b32 s31, s1, s87
	s_cselect_b32 s30, s97, s86
	v_lshlrev_b64 v[96:97], 10, v[96:97]
	v_lshl_add_u64 v[96:97], s[30:31], 0, v[96:97]
	v_lshl_add_u64 v[96:97], v[148:149], 1, v[96:97]
	global_store_dwordx4 v[96:97], v[88:91], off sc0 sc1
	s_and_saveexec_b64 s[30:31], s[26:27]
	s_xor_b64 s[30:31], exec, s[30:31]
	s_cbranch_execnz .LBB0_906
	s_andn2_saveexec_b64 s[30:31], s[30:31]
	s_cbranch_execnz .LBB0_907

; __device__ __forceinline__ u32x4 pack8(const f32x4& a, const f32x4& b) { u32x4 w; w.x = cvt_pk_bf16(a[0], a[1]); w.y = cvt_pk_bf16(a[2], a[3]); w.z = cvt_pk_bf16(b[0], b[1]); w.w = cvt_pk_bf16(b[2], b[3]); return w; }
;     __device__ __forceinline__ void operator()(const f32x4 (&acc)[2][2][4][2], const Unit& u, int wr, int wc, int fr, int fq) const {
;     ...
;                     const int row = row0 + ai * HALF + m * 16; const f32x4 v0 = acc[ai][bj][m][0], v1 = acc[ai][bj][m][1]; const u32x4 w = pack8(v0, v1);
;                     const bool isp = row < NPROMPT; const int b = isp ? (row >> 14) : ((row - NPROMPT) >> 5), s = isp ? (row & (SEQ - 1)) : ((row - NPROMPT) & 31);
;                     if (reg < 4) { *(u32x4*)(Q0 + (size_t)row * 1024 + cbase + cw) = w; }
;                     else if (reg < 12) {
;                         const bool isk = reg < 8; const int c = cbase - (isk ? 512 : 1024) + cw;
;                         const int kr = isp ? row : NPROMPT + b * (LA + 32) + LA + s;
;                         *(u32x4*)((isk ? KA : VA) + (size_t)kr * 512 + c) = w;
;                         float* o = nullptr;
;                         if (isp) { if (s >= SEQ - LA) o = out + (isk ? O_AKP : O_AVP) + (size_t)(b * LA + s - (SEQ - LA)) * 512 + c; }
;                         else o = out + (isk ? O_AKS : O_AVS) + (size_t)(row - NPROMPT) * 512 + c;
;                         if (o) { *(f32x4*)o = v0; *(f32x4*)(o + 4) = v1; }
;                     } else if (reg < 16) { *(u32x4*)(Q0 + (size_t)row * 1024 + 512 + (cbase - 1536) + cw) = w; }
;                     else {
;                         const bool isk = reg == 16; const int c = cw;
;                         const int kr = isp ? row : NPROMPT + b * (LB + 32) + LB + s;
;                         *(u32x4*)((isk ? KB : VB) + (size_t)kr * 128 + c) = w;
.LBB0_683:
	s_andn2_b64 vcc, exec, s[30:31]
	v_ashrrev_i32_e32 v93, 31, v92
	s_cbranch_vccnz .LBB0_685
	v_lshlrev_b64 v[80:81], 11, v[92:93]
	v_lshl_add_u64 v[80:81], s[50:51], 0, v[80:81]
	v_lshl_add_u64 v[80:81], s[64:65], 1, v[80:81]
	v_lshl_add_u64 v[80:81], v[80:81], 0, v[196:197]
	global_store_dwordx4 v[80:81], v[88:91], off sc0 sc1
.LBB0_685:
	v_add_u32_e32 v86, 0xffff80a0, v144
	s_movk_i32 s34, 0x7f60
	v_add_u32_e32 v84, 0xa0, v144
	s_movk_i32 s30, 0x7f5f
	v_lshrrev_b32_e32 v85, 5, v86
	v_cmp_gt_i32_e64 s[36:37], s34, v144
	v_cmp_lt_i32_e64 s[30:31], s30, v144
	v_and_b32_e32 v90, 0x3fef, v84
	v_cndmask_b32_e64 v91, v85, v111, s[36:37]
	s_and_b64 vcc, exec, s[42:43]
	s_mov_b64 s[34:35], -1
	v_cvt_pk_bf16_f32 v80, v76, v77
	v_cvt_pk_bf16_f32 v81, v78, v79
	v_cvt_pk_bf16_f32 v82, v72, v73
	v_cvt_pk_bf16_f32 v83, v74, v75
	s_cbranch_vccnz .LBB0_703
	s_and_b64 vcc, exec, s[40:41]
	s_cbranch_vccnz .LBB0_696
	s_andn2_b64 vcc, exec, s[74:75]
	s_cbranch_vccnz .LBB0_693
	s_movk_i32 s34, 0xa0
	v_mul_lo_u32 v85, v91, s34
	v_or_b32_e32 v85, v85, v155
	v_add_u32_e32 v85, 0x8080, v85
	v_cndmask_b32_e64 v88, v85, v84, s[36:37]
	s_and_b64 s[34:35], s[68:69], exec
	v_ashrrev_i32_e32 v89, 31, v88
	s_cselect_b32 s35, s89, s47
	s_cselect_b32 s34, s88, s46
	v_lshlrev_b64 v[88:89], 8, v[88:89]
	v_lshl_add_u64 v[88:89], s[34:35], 0, v[88:89]
	v_lshl_add_u64 v[88:89], v[88:89], 0, v[196:197]
	global_store_dwordx4 v[88:89], v[80:83], off sc0 sc1
	s_and_saveexec_b64 s[34:35], s[30:31]
	s_xor_b64 s[34:35], exec, s[34:35]
	s_cbranch_execnz .LBB0_940
	s_andn2_saveexec_b64 s[34:35], s[34:35]
	s_cbranch_execnz .LBB0_941

;     __device__ __forceinline__ void operator()(const f32x4 (&acc)[2][2][4][2], const Unit& u, int wr, int wc, int fr, int fq) const {
;     ...
;                         float* o = nullptr;
;                         if (isp) { if (s >= SEQ - LA) o = out + (isk ? O_AKP : O_AVP) + (size_t)(b * LA + s - (SEQ - LA)) * 512 + c; }
;                         else o = out + (isk ? O_AKS : O_AVS) + (size_t)(row - NPROMPT) * 512 + c;
;                         if (o) { *(f32x4*)o = v0; *(f32x4*)(o + 4) = v1; }
;                     } else if (reg < 16) { *(u32x4*)(Q0 + (size_t)row * 1024 + 512 + (cbase - 1536) + cw) = w; }
;                     else {
;                         const bool isk = reg == 16; const int c = cw;
;                         const int kr = isp ? row : NPROMPT + b * (LB + 32) + LB + s;
;                         *(u32x4*)((isk ? KB : VB) + (size_t)kr * 128 + c) = w;
;                         float* o = nullptr;
;                         if (isp) { if (s >= SEQ - LB) o = out + (isk ? O_BKP : O_BVP) + (size_t)(b * LB + s - (SEQ - LB)) * 128 + c; }
;                         else o = out + (isk ? O_BKS : O_BVS) + (size_t)(row - NPROMPT) * 128 + c;
;                         if (o) { *(f32x4*)o = v0; *(f32x4*)(o + 4) = v1; }
.LBB0_691:
	global_store_dwordx4 v[88:89], v[76:79], off sc0 sc1
	global_store_dwordx4 v[88:89], v[72:75], off offset:16 sc0 sc1

;     __device__ __forceinline__ void operator()(const f32x4 (&acc)[2][2][4][2], const Unit& u, int wr, int wc, int fr, int fq) const {
;     ...
;                     if (reg < 4) { *(u32x4*)(Q0 + (size_t)row * 1024 + cbase + cw) = w; }
;                     else if (reg < 12) {
;                         const bool isk = reg < 8; const int c = cbase - (isk ? 512 : 1024) + cw;
;                         const int kr = isp ? row : NPROMPT + b * (LA + 32) + LA + s;
;                         *(u32x4*)((isk ? KA : VA) + (size_t)kr * 512 + c) = w;
;                         float* o = nullptr;
;                         if (isp) { if (s >= SEQ - LA) o = out + (isk ? O_AKP : O_AVP) + (size_t)(b * LA + s - (SEQ - LA)) * 512 + c; }
;                         else o = out + (isk ? O_AKS : O_AVS) + (size_t)(row - NPROMPT) * 512 + c;
;                         if (o) { *(f32x4*)o = v0; *(f32x4*)(o + 4) = v1; }
;                     } else if (reg < 16) { *(u32x4*)(Q0 + (size_t)row * 1024 + 512 + (cbase - 1536) + cw) = w; }
.LBB0_693:
	s_and_b64 vcc, exec, s[34:35]
	s_cbranch_vccz .LBB0_695
	v_ashrrev_i32_e32 v85, 31, v84
	v_lshlrev_b64 v[88:89], 11, v[84:85]
	v_lshl_add_u64 v[88:89], s[50:51], 0, v[88:89]
	v_lshl_add_u64 v[88:89], s[72:73], 1, v[88:89]
	v_lshl_add_u64 v[88:89], v[88:89], 0, v[196:197]
	global_store_dwordx4 v[88:89], v[80:83], off offset:-2048 sc0 sc1

;     __device__ __forceinline__ void operator()(const f32x4 (&acc)[2][2][4][2], const Unit& u, int wr, int wc, int fr, int fq) const {
;     ...
;                     else if (reg < 12) {
;                         const bool isk = reg < 8; const int c = cbase - (isk ? 512 : 1024) + cw;
;                         const int kr = isp ? row : NPROMPT + b * (LA + 32) + LA + s;
;                         *(u32x4*)((isk ? KA : VA) + (size_t)kr * 512 + c) = w;
.LBB0_696:
	s_andn2_b64 vcc, exec, s[34:35]
	s_cbranch_vccnz .LBB0_702
	v_mul_lo_u32 v85, v91, s56
	v_or_b32_e32 v85, v85, v155
	v_add_u32_e32 v85, 0x8200, v85
	v_cndmask_b32_e64 v88, v85, v84, s[36:37]
	s_and_b64 s[34:35], s[66:67], exec
	v_ashrrev_i32_e32 v89, 31, v88
	s_cselect_b32 s35, s1, s87
	s_cselect_b32 s34, s97, s86
	v_lshlrev_b64 v[88:89], 10, v[88:89]
	v_lshl_add_u64 v[88:89], s[34:35], 0, v[88:89]
	v_lshl_add_u64 v[88:89], v[148:149], 1, v[88:89]
	global_store_dwordx4 v[88:89], v[80:83], off sc0 sc1
	s_and_saveexec_b64 s[34:35], s[30:31]
	s_xor_b64 s[34:35], exec, s[34:35]
	s_cbranch_execnz .LBB0_908
	s_andn2_saveexec_b64 s[34:35], s[34:35]
	s_cbranch_execnz .LBB0_909

; __device__ __forceinline__ u32x4 pack8(const f32x4& a, const f32x4& b) { u32x4 w; w.x = cvt_pk_bf16(a[0], a[1]); w.y = cvt_pk_bf16(a[2], a[3]); w.z = cvt_pk_bf16(b[0], b[1]); w.w = cvt_pk_bf16(b[2], b[3]); return w; }
;     __device__ __forceinline__ void operator()(const f32x4 (&acc)[2][2][4][2], const Unit& u, int wr, int wc, int fr, int fq) const {
;     ...
;                     const int row = row0 + ai * HALF + m * 16; const f32x4 v0 = acc[ai][bj][m][0], v1 = acc[ai][bj][m][1]; const u32x4 w = pack8(v0, v1);
;                     const bool isp = row < NPROMPT; const int b = isp ? (row >> 14) : ((row - NPROMPT) >> 5), s = isp ? (row & (SEQ - 1)) : ((row - NPROMPT) & 31);
;                     if (reg < 4) { *(u32x4*)(Q0 + (size_t)row * 1024 + cbase + cw) = w; }
;                     else if (reg < 12) {
;                         const bool isk = reg < 8; const int c = cbase - (isk ? 512 : 1024) + cw;
;                         const int kr = isp ? row : NPROMPT + b * (LA + 32) + LA + s;
;                         *(u32x4*)((isk ? KA : VA) + (size_t)kr * 512 + c) = w;
;                         float* o = nullptr;
;                         if (isp) { if (s >= SEQ - LA) o = out + (isk ? O_AKP : O_AVP) + (size_t)(b * LA + s - (SEQ - LA)) * 512 + c; }
;                         else o = out + (isk ? O_AKS : O_AVS) + (size_t)(row - NPROMPT) * 512 + c;
;                         if (o) { *(f32x4*)o = v0; *(f32x4*)(o + 4) = v1; }
;                     } else if (reg < 16) { *(u32x4*)(Q0 + (size_t)row * 1024 + 512 + (cbase - 1536) + cw) = w; }
;                     else {
;                         const bool isk = reg == 16; const int c = cw;
;                         const int kr = isp ? row : NPROMPT + b * (LB + 32) + LB + s;
;                         *(u32x4*)((isk ? KB : VB) + (size_t)kr * 128 + c) = w;
.LBB0_703:
	s_andn2_b64 vcc, exec, s[34:35]
	v_ashrrev_i32_e32 v85, 31, v84
	s_cbranch_vccnz .LBB0_705
	v_lshlrev_b64 v[72:73], 11, v[84:85]
	v_lshl_add_u64 v[72:73], s[50:51], 0, v[72:73]
	v_lshl_add_u64 v[72:73], s[64:65], 1, v[72:73]
	v_lshl_add_u64 v[72:73], v[72:73], 0, v[196:197]
	global_store_dwordx4 v[72:73], v[80:83], off sc0 sc1
.LBB0_705:
	v_add_u32_e32 v78, 0xffff80b0, v144
	s_movk_i32 s38, 0x7f50
	v_add_u32_e32 v76, 0xb0, v144
	s_movk_i32 s34, 0x7f4f
	v_lshrrev_b32_e32 v77, 5, v78
	v_cmp_gt_i32_e64 s[38:39], s38, v144
	v_cmp_lt_i32_e64 s[34:35], s34, v144
	v_and_b32_e32 v82, 0x3fff, v76
	v_cndmask_b32_e64 v83, v77, v111, s[38:39]
	s_and_b64 vcc, exec, s[42:43]
	s_mov_b64 s[42:43], -1
	v_cvt_pk_bf16_f32 v72, v68, v69
	v_cvt_pk_bf16_f32 v73, v70, v71
	v_cvt_pk_bf16_f32 v74, v64, v65
	v_cvt_pk_bf16_f32 v75, v66, v67
	s_cbranch_vccnz .LBB0_723
	s_and_b64 vcc, exec, s[40:41]
	s_mov_b64 s[40:41], -1
	s_cbranch_vccnz .LBB0_716
	s_andn2_b64 vcc, exec, s[74:75]
	s_cbranch_vccnz .LBB0_713
	s_movk_i32 s40, 0xa0
	v_mul_lo_u32 v77, v83, s40
	v_or_b32_e32 v77, v77, v130
	v_add_u32_e32 v77, 0x8080, v77
	v_cndmask_b32_e64 v80, v77, v76, s[38:39]
	s_and_b64 s[40:41], s[68:69], exec
	v_ashrrev_i32_e32 v81, 31, v80
	s_cselect_b32 s41, s89, s47
	s_cselect_b32 s40, s88, s46
	v_lshlrev_b64 v[80:81], 8, v[80:81]
	v_lshl_add_u64 v[80:81], s[40:41], 0, v[80:81]
	v_lshl_add_u64 v[80:81], v[80:81], 0, v[196:197]
	global_store_dwordx4 v[80:81], v[72:75], off sc0 sc1
	s_and_saveexec_b64 s[40:41], s[34:35]
	s_xor_b64 s[40:41], exec, s[40:41]
	s_cbranch_execnz .LBB0_942
	s_andn2_saveexec_b64 s[40:41], s[40:41]
	s_cbranch_execnz .LBB0_943

;     __device__ __forceinline__ void operator()(const f32x4 (&acc)[2][2][4][2], const Unit& u, int wr, int wc, int fr, int fq) const {
;     ...
;                         float* o = nullptr;
;                         if (isp) { if (s >= SEQ - LA) o = out + (isk ? O_AKP : O_AVP) + (size_t)(b * LA + s - (SEQ - LA)) * 512 + c; }
;                         else o = out + (isk ? O_AKS : O_AVS) + (size_t)(row - NPROMPT) * 512 + c;
;                         if (o) { *(f32x4*)o = v0; *(f32x4*)(o + 4) = v1; }
;                     } else if (reg < 16) { *(u32x4*)(Q0 + (size_t)row * 1024 + 512 + (cbase - 1536) + cw) = w; }
;                     else {
;                         const bool isk = reg == 16; const int c = cw;
;                         const int kr = isp ? row : NPROMPT + b * (LB + 32) + LB + s;
;                         *(u32x4*)((isk ? KB : VB) + (size_t)kr * 128 + c) = w;
;                         float* o = nullptr;
;                         if (isp) { if (s >= SEQ - LB) o = out + (isk ? O_BKP : O_BVP) + (size_t)(b * LB + s - (SEQ - LB)) * 128 + c; }
;                         else o = out + (isk ? O_BKS : O_BVS) + (size_t)(row - NPROMPT) * 128 + c;
;                         if (o) { *(f32x4*)o = v0; *(f32x4*)(o + 4) = v1; }
.LBB0_711:
	global_store_dwordx4 v[80:81], v[68:71], off sc0 sc1
	global_store_dwordx4 v[80:81], v[64:67], off offset:16 sc0 sc1

;     __device__ __forceinline__ void operator()(const f32x4 (&acc)[2][2][4][2], const Unit& u, int wr, int wc, int fr, int fq) const {
;     ...
;                     if (reg < 4) { *(u32x4*)(Q0 + (size_t)row * 1024 + cbase + cw) = w; }
;                     else if (reg < 12) {
;                         const bool isk = reg < 8; const int c = cbase - (isk ? 512 : 1024) + cw;
;                         const int kr = isp ? row : NPROMPT + b * (LA + 32) + LA + s;
;                         *(u32x4*)((isk ? KA : VA) + (size_t)kr * 512 + c) = w;
;                         float* o = nullptr;
;                         if (isp) { if (s >= SEQ - LA) o = out + (isk ? O_AKP : O_AVP) + (size_t)(b * LA + s - (SEQ - LA)) * 512 + c; }
;                         else o = out + (isk ? O_AKS : O_AVS) + (size_t)(row - NPROMPT) * 512 + c;
;                         if (o) { *(f32x4*)o = v0; *(f32x4*)(o + 4) = v1; }
;                     } else if (reg < 16) { *(u32x4*)(Q0 + (size_t)row * 1024 + 512 + (cbase - 1536) + cw) = w; }
.LBB0_713:
	s_and_b64 vcc, exec, s[40:41]
	s_cbranch_vccz .LBB0_715
	v_ashrrev_i32_e32 v77, 31, v76
	v_lshlrev_b64 v[80:81], 11, v[76:77]
	v_lshl_add_u64 v[80:81], s[50:51], 0, v[80:81]
	v_lshl_add_u64 v[80:81], s[72:73], 1, v[80:81]
	v_lshl_add_u64 v[80:81], v[80:81], 0, v[196:197]
	global_store_dwordx4 v[80:81], v[72:75], off offset:-2048 sc0 sc1

;     __device__ __forceinline__ void operator()(const f32x4 (&acc)[2][2][4][2], const Unit& u, int wr, int wc, int fr, int fq) const {
;     ...
;                     else if (reg < 12) {
;                         const bool isk = reg < 8; const int c = cbase - (isk ? 512 : 1024) + cw;
;                         const int kr = isp ? row : NPROMPT + b * (LA + 32) + LA + s;
;                         *(u32x4*)((isk ? KA : VA) + (size_t)kr * 512 + c) = w;
.LBB0_716:
	s_andn2_b64 vcc, exec, s[40:41]
	s_cbranch_vccnz .LBB0_722
	v_mul_lo_u32 v77, v83, s56
	v_or_b32_e32 v77, v77, v130
	v_add_u32_e32 v77, 0x8200, v77
	v_cndmask_b32_e64 v80, v77, v76, s[38:39]
	s_and_b64 s[40:41], s[66:67], exec
	v_ashrrev_i32_e32 v81, 31, v80
	s_cselect_b32 s41, s1, s87
	s_cselect_b32 s40, s97, s86
	v_lshlrev_b64 v[80:81], 10, v[80:81]
	v_lshl_add_u64 v[80:81], s[40:41], 0, v[80:81]
	v_lshl_add_u64 v[80:81], v[148:149], 1, v[80:81]
	global_store_dwordx4 v[80:81], v[72:75], off sc0 sc1
	s_and_saveexec_b64 s[40:41], s[34:35]
	s_xor_b64 s[40:41], exec, s[40:41]
	s_cbranch_execnz .LBB0_910
	s_andn2_saveexec_b64 s[40:41], s[40:41]
	s_cbranch_execnz .LBB0_911

; __device__ __forceinline__ u32x4 pack8(const f32x4& a, const f32x4& b) { u32x4 w; w.x = cvt_pk_bf16(a[0], a[1]); w.y = cvt_pk_bf16(a[2], a[3]); w.z = cvt_pk_bf16(b[0], b[1]); w.w = cvt_pk_bf16(b[2], b[3]); return w; }
;     __device__ __forceinline__ void operator()(const f32x4 (&acc)[2][2][4][2], const Unit& u, int wr, int wc, int fr, int fq) const {
;     ...
;         for (int bj = 0; bj < 2; ++bj) {
;             const int cbase = u.pn * BM + bj * HALF, reg = cbase >> 7, cw = wc * 32 + 8 * fq;
; #pragma unroll
;             for (int ai = 0; ai < 2; ++ai)
; #pragma unroll
;                 for (int m = 0; m < 4; ++m) {
;                     const int row = row0 + ai * HALF + m * 16; const f32x4 v0 = acc[ai][bj][m][0], v1 = acc[ai][bj][m][1]; const u32x4 w = pack8(v0, v1);
;                     const bool isp = row < NPROMPT; const int b = isp ? (row >> 14) : ((row - NPROMPT) >> 5), s = isp ? (row & (SEQ - 1)) : ((row - NPROMPT) & 31);
;                     if (reg < 4) { *(u32x4*)(Q0 + (size_t)row * 1024 + cbase + cw) = w; }
;                     else if (reg < 12) {
;                         const bool isk = reg < 8; const int c = cbase - (isk ? 512 : 1024) + cw;
;                         const int kr = isp ? row : NPROMPT + b * (LA + 32) + LA + s;
;                         *(u32x4*)((isk ? KA : VA) + (size_t)kr * 512 + c) = w;
;                         float* o = nullptr;
;                         if (isp) { if (s >= SEQ - LA) o = out + (isk ? O_AKP : O_AVP) + (size_t)(b * LA + s - (SEQ - LA)) * 512 + c; }
;                         else o = out + (isk ? O_AKS : O_AVS) + (size_t)(row - NPROMPT) * 512 + c;
;                         if (o) { *(f32x4*)o = v0; *(f32x4*)(o + 4) = v1; }
;                     } else if (reg < 16) { *(u32x4*)(Q0 + (size_t)row * 1024 + 512 + (cbase - 1536) + cw) = w; }
;                     else {
;                         const bool isk = reg == 16; const int c = cw;
;                         const int kr = isp ? row : NPROMPT + b * (LB + 32) + LB + s;
;                         *(u32x4*)((isk ? KB : VB) + (size_t)kr * 128 + c) = w;
.LBB0_723:
	s_andn2_b64 vcc, exec, s[42:43]
	v_ashrrev_i32_e32 v77, 31, v76
	s_cbranch_vccnz .LBB0_725
	v_lshlrev_b64 v[64:65], 11, v[76:77]
	v_lshl_add_u64 v[64:65], s[50:51], 0, v[64:65]
	v_lshl_add_u64 v[64:65], s[64:65], 1, v[64:65]
	v_lshl_add_u64 v[64:65], v[64:65], 0, v[196:197]
	global_store_dwordx4 v[64:65], v[72:75], off sc0 sc1
.LBB0_725:
	s_or_b32 s70, s72, 0x80
	s_ashr_i32 s71, s70, 7
	s_cmp_gt_i32 s71, 3
	s_cselect_b64 s[68:69], -1, 0
	s_cmp_gt_u32 s71, 11
	s_cselect_b64 s[40:41], -1, 0
	s_cmp_gt_u32 s71, 15
	s_cselect_b64 s[66:67], -1, 0
	s_cmp_lt_u32 s71, 8
	s_cselect_b64 s[42:43], -1, 0
	s_and_b64 s[54:55], s[42:43], exec
	s_movk_i32 s54, 0xfe00
	s_cselect_b32 s54, s54, 0xfffffc00
	s_add_i32 s70, s54, s70
	s_and_b64 s[54:55], s[42:43], exec
	s_mov_b32 s54, 0x2a90000
	s_cselect_b32 s55, s54, 0x2ad0000
	s_mov_b32 s54, 0x2080000
	v_or_b32_e32 v68, s70, v154
	v_cndmask_b32_e64 v70, 0, 1, s[40:41]
	s_cselect_b32 s54, s54, 0x2100000
	s_cmp_lt_i32 s71, 4
	v_ashrrev_i32_e32 v69, 31, v68
	s_mov_b64 s[74:75], -1
	v_cmp_ne_u32_e64 s[40:41], 1, v70
	v_cvt_pk_bf16_f32 v64, v60, v61
	v_cvt_pk_bf16_f32 v65, v62, v63
	v_cvt_pk_bf16_f32 v66, v56, v57
	v_cvt_pk_bf16_f32 v67, v58, v59
	s_cbranch_scc1 .LBB0_743
	s_and_b64 vcc, exec, s[40:41]
	s_cbranch_vccnz .LBB0_736
	s_andn2_b64 vcc, exec, s[66:67]
	s_cbranch_vccnz .LBB0_733
	s_movk_i32 s70, 0xa0
	v_mul_lo_u32 v70, v157, s70
	v_or_b32_e32 v70, v70, v155
	v_add_u32_e32 v70, 0x8080, v70
	v_cndmask_b32_e64 v70, v70, v144, s[8:9]
	v_ashrrev_i32_e32 v71, 31, v70
	v_lshlrev_b64 v[70:71], 8, v[70:71]
	v_lshl_add_u64 v[70:71], s[46:47], 0, v[70:71]
	v_lshl_add_u64 v[70:71], v[70:71], 0, v[196:197]
	global_store_dwordx4 v[70:71], v[64:67], off sc0 sc1
	s_and_saveexec_b64 s[70:71], s[6:7]
	s_xor_b64 s[74:75], exec, s[70:71]
	s_cbranch_execnz .LBB0_944
	s_andn2_saveexec_b64 s[74:75], s[74:75]
	s_cbranch_execnz .LBB0_945

;     __device__ __forceinline__ void operator()(const f32x4 (&acc)[2][2][4][2], const Unit& u, int wr, int wc, int fr, int fq) const {
;     ...
;                         float* o = nullptr;
;                         if (isp) { if (s >= SEQ - LA) o = out + (isk ? O_AKP : O_AVP) + (size_t)(b * LA + s - (SEQ - LA)) * 512 + c; }
;                         else o = out + (isk ? O_AKS : O_AVS) + (size_t)(row - NPROMPT) * 512 + c;
;                         if (o) { *(f32x4*)o = v0; *(f32x4*)(o + 4) = v1; }
;                     } else if (reg < 16) { *(u32x4*)(Q0 + (size_t)row * 1024 + 512 + (cbase - 1536) + cw) = w; }
;                     else {
;                         const bool isk = reg == 16; const int c = cw;
;                         const int kr = isp ? row : NPROMPT + b * (LB + 32) + LB + s;
;                         *(u32x4*)((isk ? KB : VB) + (size_t)kr * 128 + c) = w;
;                         float* o = nullptr;
;                         if (isp) { if (s >= SEQ - LB) o = out + (isk ? O_BKP : O_BVP) + (size_t)(b * LB + s - (SEQ - LB)) * 128 + c; }
;                         else o = out + (isk ? O_BKS : O_BVS) + (size_t)(row - NPROMPT) * 128 + c;
;                         if (o) { *(f32x4*)o = v0; *(f32x4*)(o + 4) = v1; }
.LBB0_731:
	global_store_dwordx4 v[70:71], v[60:63], off sc0 sc1
	global_store_dwordx4 v[70:71], v[56:59], off offset:16 sc0 sc1

;     __device__ __forceinline__ void operator()(const f32x4 (&acc)[2][2][4][2], const Unit& u, int wr, int wc, int fr, int fq) const {
;     ...
;                     if (reg < 4) { *(u32x4*)(Q0 + (size_t)row * 1024 + cbase + cw) = w; }
;                     else if (reg < 12) {
;                         const bool isk = reg < 8; const int c = cbase - (isk ? 512 : 1024) + cw;
;                         const int kr = isp ? row : NPROMPT + b * (LA + 32) + LA + s;
;                         *(u32x4*)((isk ? KA : VA) + (size_t)kr * 512 + c) = w;
;                         float* o = nullptr;
;                         if (isp) { if (s >= SEQ - LA) o = out + (isk ? O_AKP : O_AVP) + (size_t)(b * LA + s - (SEQ - LA)) * 512 + c; }
;                         else o = out + (isk ? O_AKS : O_AVS) + (size_t)(row - NPROMPT) * 512 + c;
;                         if (o) { *(f32x4*)o = v0; *(f32x4*)(o + 4) = v1; }
;                     } else if (reg < 16) { *(u32x4*)(Q0 + (size_t)row * 1024 + 512 + (cbase - 1536) + cw) = w; }
.LBB0_733:
	s_and_b64 vcc, exec, s[74:75]
	s_cbranch_vccz .LBB0_735
	v_lshlrev_b64 v[70:71], 11, v[144:145]
	v_lshl_add_u64 v[70:71], s[50:51], 0, v[70:71]
	v_lshl_add_u64 v[70:71], s[72:73], 1, v[70:71]
	v_lshl_add_u64 v[70:71], v[70:71], 0, v[196:197]
	global_store_dwordx4 v[70:71], v[64:67], off offset:-1792 sc0 sc1

;     __device__ __forceinline__ void operator()(const f32x4 (&acc)[2][2][4][2], const Unit& u, int wr, int wc, int fr, int fq) const {
;     ...
;                     else if (reg < 12) {
;                         const bool isk = reg < 8; const int c = cbase - (isk ? 512 : 1024) + cw;
;                         const int kr = isp ? row : NPROMPT + b * (LA + 32) + LA + s;
;                         *(u32x4*)((isk ? KA : VA) + (size_t)kr * 512 + c) = w;
.LBB0_736:
	s_andn2_b64 vcc, exec, s[74:75]
	s_cbranch_vccnz .LBB0_742
	v_mul_lo_u32 v70, v157, s56
	v_or_b32_e32 v70, v70, v155
	v_add_u32_e32 v70, 0x8200, v70
	v_cndmask_b32_e64 v70, v70, v144, s[8:9]
	s_and_b64 s[8:9], s[42:43], exec
	v_ashrrev_i32_e32 v71, 31, v70
	s_cselect_b32 s9, s1, s87
	s_cselect_b32 s8, s97, s86
	v_lshlrev_b64 v[70:71], 10, v[70:71]
	v_lshl_add_u64 v[70:71], s[8:9], 0, v[70:71]
	v_lshl_add_u64 v[70:71], v[68:69], 1, v[70:71]
	global_store_dwordx4 v[70:71], v[64:67], off sc0 sc1
	s_and_saveexec_b64 s[8:9], s[6:7]
	s_xor_b64 s[6:7], exec, s[8:9]
	s_cbranch_execnz .LBB0_912
	s_andn2_saveexec_b64 s[6:7], s[6:7]
	s_cbranch_execnz .LBB0_913

; __device__ __forceinline__ u32x4 pack8(const f32x4& a, const f32x4& b) { u32x4 w; w.x = cvt_pk_bf16(a[0], a[1]); w.y = cvt_pk_bf16(a[2], a[3]); w.z = cvt_pk_bf16(b[0], b[1]); w.w = cvt_pk_bf16(b[2], b[3]); return w; }
;     __device__ __forceinline__ void operator()(const f32x4 (&acc)[2][2][4][2], const Unit& u, int wr, int wc, int fr, int fq) const {
;     ...
;                     const int row = row0 + ai * HALF + m * 16; const f32x4 v0 = acc[ai][bj][m][0], v1 = acc[ai][bj][m][1]; const u32x4 w = pack8(v0, v1);
;                     const bool isp = row < NPROMPT; const int b = isp ? (row >> 14) : ((row - NPROMPT) >> 5), s = isp ? (row & (SEQ - 1)) : ((row - NPROMPT) & 31);
;                     if (reg < 4) { *(u32x4*)(Q0 + (size_t)row * 1024 + cbase + cw) = w; }
;                     else if (reg < 12) {
;                         const bool isk = reg < 8; const int c = cbase - (isk ? 512 : 1024) + cw;
;                         const int kr = isp ? row : NPROMPT + b * (LA + 32) + LA + s;
;                         *(u32x4*)((isk ? KA : VA) + (size_t)kr * 512 + c) = w;
;                         float* o = nullptr;
;                         if (isp) { if (s >= SEQ - LA) o = out + (isk ? O_AKP : O_AVP) + (size_t)(b * LA + s - (SEQ - LA)) * 512 + c; }
;                         else o = out + (isk ? O_AKS : O_AVS) + (size_t)(row - NPROMPT) * 512 + c;
;                         if (o) { *(f32x4*)o = v0; *(f32x4*)(o + 4) = v1; }
;                     } else if (reg < 16) { *(u32x4*)(Q0 + (size_t)row * 1024 + 512 + (cbase - 1536) + cw) = w; }
;                     else {
;                         const bool isk = reg == 16; const int c = cw;
;                         const int kr = isp ? row : NPROMPT + b * (LB + 32) + LB + s;
;                         *(u32x4*)((isk ? KB : VB) + (size_t)kr * 128 + c) = w;
.LBB0_743:
	s_andn2_b64 vcc, exec, s[74:75]
	s_cbranch_vccnz .LBB0_745
	v_lshlrev_b64 v[56:57], 11, v[144:145]
	v_lshl_add_u64 v[56:57], s[50:51], 0, v[56:57]
	v_lshl_add_u64 v[56:57], s[64:65], 1, v[56:57]
	v_lshl_add_u64 v[56:57], v[56:57], 0, v[196:197]
	global_store_dwordx4 v[56:57], v[64:67], off offset:256 sc0 sc1
.LBB0_745:
	v_cndmask_b32_e64 v60, 0, 1, s[68:69]
	v_cmp_ne_u32_e64 s[6:7], 1, v60
	s_andn2_b64 vcc, exec, s[68:69]
	s_mov_b64 s[8:9], -1
	v_cvt_pk_bf16_f32 v56, v52, v53
	v_cvt_pk_bf16_f32 v57, v54, v55
	v_cvt_pk_bf16_f32 v58, v48, v49
	v_cvt_pk_bf16_f32 v59, v50, v51
	s_cbranch_vccnz .LBB0_763
	s_and_b64 vcc, exec, s[40:41]
	s_cbranch_vccnz .LBB0_756
	s_andn2_b64 vcc, exec, s[66:67]
	s_cbranch_vccnz .LBB0_753
	s_movk_i32 s8, 0xa0
	v_mul_lo_u32 v60, v150, s8
	v_or_b32_e32 v60, v60, v130
	v_add_u32_e32 v60, 0x8080, v60
	v_cndmask_b32_e64 v60, v60, v124, s[12:13]
	v_ashrrev_i32_e32 v61, 31, v60
	v_lshlrev_b64 v[60:61], 8, v[60:61]
	v_lshl_add_u64 v[60:61], s[46:47], 0, v[60:61]
	v_lshl_add_u64 v[60:61], v[60:61], 0, v[196:197]
	global_store_dwordx4 v[60:61], v[56:59], off sc0 sc1
	s_and_saveexec_b64 s[8:9], s[10:11]
	s_xor_b64 s[8:9], exec, s[8:9]
	s_cbranch_execnz .LBB0_946
	s_andn2_saveexec_b64 s[8:9], s[8:9]
	s_cbranch_execnz .LBB0_947

;     __device__ __forceinline__ void operator()(const f32x4 (&acc)[2][2][4][2], const Unit& u, int wr, int wc, int fr, int fq) const {
;     ...
;                         float* o = nullptr;
;                         if (isp) { if (s >= SEQ - LA) o = out + (isk ? O_AKP : O_AVP) + (size_t)(b * LA + s - (SEQ - LA)) * 512 + c; }
;                         else o = out + (isk ? O_AKS : O_AVS) + (size_t)(row - NPROMPT) * 512 + c;
;                         if (o) { *(f32x4*)o = v0; *(f32x4*)(o + 4) = v1; }
;                     } else if (reg < 16) { *(u32x4*)(Q0 + (size_t)row * 1024 + 512 + (cbase - 1536) + cw) = w; }
;                     else {
;                         const bool isk = reg == 16; const int c = cw;
;                         const int kr = isp ? row : NPROMPT + b * (LB + 32) + LB + s;
;                         *(u32x4*)((isk ? KB : VB) + (size_t)kr * 128 + c) = w;
;                         float* o = nullptr;
;                         if (isp) { if (s >= SEQ - LB) o = out + (isk ? O_BKP : O_BVP) + (size_t)(b * LB + s - (SEQ - LB)) * 128 + c; }
;                         else o = out + (isk ? O_BKS : O_BVS) + (size_t)(row - NPROMPT) * 128 + c;
;                         if (o) { *(f32x4*)o = v0; *(f32x4*)(o + 4) = v1; }
.LBB0_751:
	global_store_dwordx4 v[60:61], v[52:55], off sc0 sc1
	global_store_dwordx4 v[60:61], v[48:51], off offset:16 sc0 sc1

;     __device__ __forceinline__ void operator()(const f32x4 (&acc)[2][2][4][2], const Unit& u, int wr, int wc, int fr, int fq) const {
;     ...
;                     if (reg < 4) { *(u32x4*)(Q0 + (size_t)row * 1024 + cbase + cw) = w; }
;                     else if (reg < 12) {
;                         const bool isk = reg < 8; const int c = cbase - (isk ? 512 : 1024) + cw;
;                         const int kr = isp ? row : NPROMPT + b * (LA + 32) + LA + s;
;                         *(u32x4*)((isk ? KA : VA) + (size_t)kr * 512 + c) = w;
;                         float* o = nullptr;
;                         if (isp) { if (s >= SEQ - LA) o = out + (isk ? O_AKP : O_AVP) + (size_t)(b * LA + s - (SEQ - LA)) * 512 + c; }
;                         else o = out + (isk ? O_AKS : O_AVS) + (size_t)(row - NPROMPT) * 512 + c;
;                         if (o) { *(f32x4*)o = v0; *(f32x4*)(o + 4) = v1; }
;                     } else if (reg < 16) { *(u32x4*)(Q0 + (size_t)row * 1024 + 512 + (cbase - 1536) + cw) = w; }
.LBB0_753:
	s_and_b64 vcc, exec, s[8:9]
	s_cbranch_vccz .LBB0_755
	v_lshlrev_b64 v[60:61], 11, v[124:125]
	v_lshl_add_u64 v[60:61], s[50:51], 0, v[60:61]
	v_lshl_add_u64 v[60:61], s[72:73], 1, v[60:61]
	v_lshl_add_u64 v[60:61], v[60:61], 0, v[196:197]
	global_store_dwordx4 v[60:61], v[56:59], off offset:-1792 sc0 sc1

;     __device__ __forceinline__ void operator()(const f32x4 (&acc)[2][2][4][2], const Unit& u, int wr, int wc, int fr, int fq) const {
;     ...
;                     else if (reg < 12) {
;                         const bool isk = reg < 8; const int c = cbase - (isk ? 512 : 1024) + cw;
;                         const int kr = isp ? row : NPROMPT + b * (LA + 32) + LA + s;
;                         *(u32x4*)((isk ? KA : VA) + (size_t)kr * 512 + c) = w;
.LBB0_756:
	s_andn2_b64 vcc, exec, s[8:9]
	s_cbranch_vccnz .LBB0_762
	v_mul_lo_u32 v60, v150, s56
	v_or_b32_e32 v60, v60, v130
	v_add_u32_e32 v60, 0x8200, v60
	v_cndmask_b32_e64 v60, v60, v124, s[12:13]
	s_and_b64 s[8:9], s[42:43], exec
	v_ashrrev_i32_e32 v61, 31, v60
	s_cselect_b32 s9, s1, s87
	s_cselect_b32 s8, s97, s86
	v_lshlrev_b64 v[60:61], 10, v[60:61]
	v_lshl_add_u64 v[60:61], s[8:9], 0, v[60:61]
	v_lshl_add_u64 v[60:61], v[68:69], 1, v[60:61]
	global_store_dwordx4 v[60:61], v[56:59], off sc0 sc1
	s_and_saveexec_b64 s[8:9], s[10:11]
	s_xor_b64 s[8:9], exec, s[8:9]
	s_cbranch_execnz .LBB0_914
	s_andn2_saveexec_b64 s[8:9], s[8:9]
	s_cbranch_execnz .LBB0_915

; __device__ __forceinline__ u32x4 pack8(const f32x4& a, const f32x4& b) { u32x4 w; w.x = cvt_pk_bf16(a[0], a[1]); w.y = cvt_pk_bf16(a[2], a[3]); w.z = cvt_pk_bf16(b[0], b[1]); w.w = cvt_pk_bf16(b[2], b[3]); return w; }
;     __device__ __forceinline__ void operator()(const f32x4 (&acc)[2][2][4][2], const Unit& u, int wr, int wc, int fr, int fq) const {
;     ...
;                     const int row = row0 + ai * HALF + m * 16; const f32x4 v0 = acc[ai][bj][m][0], v1 = acc[ai][bj][m][1]; const u32x4 w = pack8(v0, v1);
;                     const bool isp = row < NPROMPT; const int b = isp ? (row >> 14) : ((row - NPROMPT) >> 5), s = isp ? (row & (SEQ - 1)) : ((row - NPROMPT) & 31);
;                     if (reg < 4) { *(u32x4*)(Q0 + (size_t)row * 1024 + cbase + cw) = w; }
;                     else if (reg < 12) {
;                         const bool isk = reg < 8; const int c = cbase - (isk ? 512 : 1024) + cw;
;                         const int kr = isp ? row : NPROMPT + b * (LA + 32) + LA + s;
;                         *(u32x4*)((isk ? KA : VA) + (size_t)kr * 512 + c) = w;
;                         float* o = nullptr;
;                         if (isp) { if (s >= SEQ - LA) o = out + (isk ? O_AKP : O_AVP) + (size_t)(b * LA + s - (SEQ - LA)) * 512 + c; }
;                         else o = out + (isk ? O_AKS : O_AVS) + (size_t)(row - NPROMPT) * 512 + c;
;                         if (o) { *(f32x4*)o = v0; *(f32x4*)(o + 4) = v1; }
;                     } else if (reg < 16) { *(u32x4*)(Q0 + (size_t)row * 1024 + 512 + (cbase - 1536) + cw) = w; }
;                     else {
;                         const bool isk = reg == 16; const int c = cw;
;                         const int kr = isp ? row : NPROMPT + b * (LB + 32) + LB + s;
;                         *(u32x4*)((isk ? KB : VB) + (size_t)kr * 128 + c) = w;
.LBB0_763:
	s_andn2_b64 vcc, exec, s[8:9]
	s_cbranch_vccnz .LBB0_765
	v_lshlrev_b64 v[48:49], 11, v[124:125]
	v_lshl_add_u64 v[48:49], s[50:51], 0, v[48:49]
	v_lshl_add_u64 v[48:49], s[64:65], 1, v[48:49]
	v_lshl_add_u64 v[48:49], v[48:49], 0, v[196:197]
	global_store_dwordx4 v[48:49], v[56:59], off offset:256 sc0 sc1
.LBB0_765:
	s_and_b64 vcc, exec, s[6:7]
	s_mov_b64 s[8:9], -1
	v_cvt_pk_bf16_f32 v48, v44, v45
	v_cvt_pk_bf16_f32 v49, v46, v47
	v_cvt_pk_bf16_f32 v50, v40, v41
	v_cvt_pk_bf16_f32 v51, v42, v43
	s_cbranch_vccnz .LBB0_783
	s_and_b64 vcc, exec, s[40:41]
	s_cbranch_vccnz .LBB0_776
	s_andn2_b64 vcc, exec, s[66:67]
	s_cbranch_vccnz .LBB0_773
	s_movk_i32 s8, 0xa0
	v_mul_lo_u32 v52, v123, s8
	v_or_b32_e32 v52, v52, v155
	v_add_u32_e32 v52, 0x8080, v52
	v_cndmask_b32_e64 v52, v52, v116, s[16:17]
	v_ashrrev_i32_e32 v53, 31, v52
	v_lshlrev_b64 v[52:53], 8, v[52:53]
	v_lshl_add_u64 v[52:53], s[46:47], 0, v[52:53]
	v_lshl_add_u64 v[52:53], v[52:53], 0, v[196:197]
	global_store_dwordx4 v[52:53], v[48:51], off sc0 sc1
	s_and_saveexec_b64 s[8:9], s[14:15]
	s_xor_b64 s[8:9], exec, s[8:9]
	s_cbranch_execnz .LBB0_948
	s_andn2_saveexec_b64 s[8:9], s[8:9]
	s_cbranch_execnz .LBB0_949

;     __device__ __forceinline__ void operator()(const f32x4 (&acc)[2][2][4][2], const Unit& u, int wr, int wc, int fr, int fq) const {
;     ...
;                         float* o = nullptr;
;                         if (isp) { if (s >= SEQ - LA) o = out + (isk ? O_AKP : O_AVP) + (size_t)(b * LA + s - (SEQ - LA)) * 512 + c; }
;                         else o = out + (isk ? O_AKS : O_AVS) + (size_t)(row - NPROMPT) * 512 + c;
;                         if (o) { *(f32x4*)o = v0; *(f32x4*)(o + 4) = v1; }
;                     } else if (reg < 16) { *(u32x4*)(Q0 + (size_t)row * 1024 + 512 + (cbase - 1536) + cw) = w; }
;                     else {
;                         const bool isk = reg == 16; const int c = cw;
;                         const int kr = isp ? row : NPROMPT + b * (LB + 32) + LB + s;
;                         *(u32x4*)((isk ? KB : VB) + (size_t)kr * 128 + c) = w;
;                         float* o = nullptr;
;                         if (isp) { if (s >= SEQ - LB) o = out + (isk ? O_BKP : O_BVP) + (size_t)(b * LB + s - (SEQ - LB)) * 128 + c; }
;                         else o = out + (isk ? O_BKS : O_BVS) + (size_t)(row - NPROMPT) * 128 + c;
;                         if (o) { *(f32x4*)o = v0; *(f32x4*)(o + 4) = v1; }
.LBB0_771:
	global_store_dwordx4 v[52:53], v[44:47], off sc0 sc1
	global_store_dwordx4 v[52:53], v[40:43], off offset:16 sc0 sc1

;     __device__ __forceinline__ void operator()(const f32x4 (&acc)[2][2][4][2], const Unit& u, int wr, int wc, int fr, int fq) const {
;     ...
;                     if (reg < 4) { *(u32x4*)(Q0 + (size_t)row * 1024 + cbase + cw) = w; }
;                     else if (reg < 12) {
;                         const bool isk = reg < 8; const int c = cbase - (isk ? 512 : 1024) + cw;
;                         const int kr = isp ? row : NPROMPT + b * (LA + 32) + LA + s;
;                         *(u32x4*)((isk ? KA : VA) + (size_t)kr * 512 + c) = w;
;                         float* o = nullptr;
;                         if (isp) { if (s >= SEQ - LA) o = out + (isk ? O_AKP : O_AVP) + (size_t)(b * LA + s - (SEQ - LA)) * 512 + c; }
;                         else o = out + (isk ? O_AKS : O_AVS) + (size_t)(row - NPROMPT) * 512 + c;
;                         if (o) { *(f32x4*)o = v0; *(f32x4*)(o + 4) = v1; }
;                     } else if (reg < 16) { *(u32x4*)(Q0 + (size_t)row * 1024 + 512 + (cbase - 1536) + cw) = w; }
.LBB0_773:
	s_and_b64 vcc, exec, s[8:9]
	s_cbranch_vccz .LBB0_775
	v_lshlrev_b64 v[52:53], 11, v[116:117]
	v_lshl_add_u64 v[52:53], s[50:51], 0, v[52:53]
	v_lshl_add_u64 v[52:53], s[72:73], 1, v[52:53]
	v_lshl_add_u64 v[52:53], v[52:53], 0, v[196:197]
	global_store_dwordx4 v[52:53], v[48:51], off offset:-1792 sc0 sc1

;     __device__ __forceinline__ void operator()(const f32x4 (&acc)[2][2][4][2], const Unit& u, int wr, int wc, int fr, int fq) const {
;     ...
;                         const bool isk = reg < 8; const int c = cbase - (isk ? 512 : 1024) + cw;
;                         const int kr = isp ? row : NPROMPT + b * (LA + 32) + LA + s;
;                         *(u32x4*)((isk ? KA : VA) + (size_t)kr * 512 + c) = w;
.LBB0_776:
	s_andn2_b64 vcc, exec, s[8:9]
	s_cbranch_vccnz .LBB0_782
	v_mul_lo_u32 v52, v123, s56
	v_or_b32_e32 v52, v52, v155
	v_add_u32_e32 v52, 0x8200, v52
	v_cndmask_b32_e64 v52, v52, v116, s[16:17]
	s_and_b64 s[8:9], s[42:43], exec
	v_ashrrev_i32_e32 v53, 31, v52
	s_cselect_b32 s9, s1, s87
	s_cselect_b32 s8, s97, s86
	v_lshlrev_b64 v[52:53], 10, v[52:53]
	v_lshl_add_u64 v[52:53], s[8:9], 0, v[52:53]
	v_lshl_add_u64 v[52:53], v[68:69], 1, v[52:53]
	global_store_dwordx4 v[52:53], v[48:51], off sc0 sc1
	s_and_saveexec_b64 s[8:9], s[14:15]
	s_xor_b64 s[8:9], exec, s[8:9]
	s_cbranch_execnz .LBB0_916
	s_andn2_saveexec_b64 s[8:9], s[8:9]
	s_cbranch_execnz .LBB0_917

;     __device__ __forceinline__ void operator()(const f32x4 (&acc)[2][2][4][2], const Unit& u, int wr, int wc, int fr, int fq) const {
;     ...
;                     } else if (reg < 16) { *(u32x4*)(Q0 + (size_t)row * 1024 + 512 + (cbase - 1536) + cw) = w; }
;                     else {
;                         const bool isk = reg == 16; const int c = cw;
;                         const int kr = isp ? row : NPROMPT + b * (LB + 32) + LB + s;
;                         *(u32x4*)((isk ? KB : VB) + (size_t)kr * 128 + c) = w;
.LBB0_783:
	s_andn2_b64 vcc, exec, s[8:9]
	s_cbranch_vccnz .LBB0_785
	v_lshlrev_b64 v[40:41], 11, v[116:117]
	v_lshl_add_u64 v[40:41], s[50:51], 0, v[40:41]
	v_lshl_add_u64 v[40:41], s[64:65], 1, v[40:41]
	v_lshl_add_u64 v[40:41], v[40:41], 0, v[196:197]
	global_store_dwordx4 v[40:41], v[48:51], off offset:256 sc0 sc1
.LBB0_785:
	s_and_b64 vcc, exec, s[6:7]
	s_mov_b64 s[8:9], -1
	v_cvt_pk_bf16_f32 v40, v36, v37
	v_cvt_pk_bf16_f32 v41, v38, v39
	v_cvt_pk_bf16_f32 v42, v32, v33
	v_cvt_pk_bf16_f32 v43, v34, v35
	s_cbranch_vccnz .LBB0_803
	s_and_b64 vcc, exec, s[40:41]
	s_cbranch_vccnz .LBB0_796
	s_andn2_b64 vcc, exec, s[66:67]
	s_cbranch_vccnz .LBB0_793
	s_movk_i32 s8, 0xa0
	v_mul_lo_u32 v44, v115, s8
	v_or_b32_e32 v44, v44, v130
	v_add_u32_e32 v44, 0x8080, v44
	v_cndmask_b32_e64 v44, v44, v108, s[20:21]
	v_ashrrev_i32_e32 v45, 31, v44
	v_lshlrev_b64 v[44:45], 8, v[44:45]
	v_lshl_add_u64 v[44:45], s[46:47], 0, v[44:45]
	v_lshl_add_u64 v[44:45], v[44:45], 0, v[196:197]
	global_store_dwordx4 v[44:45], v[40:43], off sc0 sc1
	s_and_saveexec_b64 s[8:9], s[18:19]
	s_xor_b64 s[8:9], exec, s[8:9]
	s_cbranch_execnz .LBB0_950
	s_andn2_saveexec_b64 s[8:9], s[8:9]
	s_cbranch_execnz .LBB0_951

;     __device__ __forceinline__ void operator()(const f32x4 (&acc)[2][2][4][2], const Unit& u, int wr, int wc, int fr, int fq) const {
;     ...
;                         float* o = nullptr;
;                         if (isp) { if (s >= SEQ - LA) o = out + (isk ? O_AKP : O_AVP) + (size_t)(b * LA + s - (SEQ - LA)) * 512 + c; }
;                         else o = out + (isk ? O_AKS : O_AVS) + (size_t)(row - NPROMPT) * 512 + c;
;                         if (o) { *(f32x4*)o = v0; *(f32x4*)(o + 4) = v1; }
;                     } else if (reg < 16) { *(u32x4*)(Q0 + (size_t)row * 1024 + 512 + (cbase - 1536) + cw) = w; }
;                     else {
;                         const bool isk = reg == 16; const int c = cw;
;                         const int kr = isp ? row : NPROMPT + b * (LB + 32) + LB + s;
;                         *(u32x4*)((isk ? KB : VB) + (size_t)kr * 128 + c) = w;
;                         float* o = nullptr;
;                         if (isp) { if (s >= SEQ - LB) o = out + (isk ? O_BKP : O_BVP) + (size_t)(b * LB + s - (SEQ - LB)) * 128 + c; }
;                         else o = out + (isk ? O_BKS : O_BVS) + (size_t)(row - NPROMPT) * 128 + c;
;                         if (o) { *(f32x4*)o = v0; *(f32x4*)(o + 4) = v1; }
.LBB0_791:
	global_store_dwordx4 v[44:45], v[36:39], off sc0 sc1
	global_store_dwordx4 v[44:45], v[32:35], off offset:16 sc0 sc1

;     __device__ __forceinline__ void operator()(const f32x4 (&acc)[2][2][4][2], const Unit& u, int wr, int wc, int fr, int fq) const {
;     ...
;                     if (reg < 4) { *(u32x4*)(Q0 + (size_t)row * 1024 + cbase + cw) = w; }
;                     else if (reg < 12) {
;                         const bool isk = reg < 8; const int c = cbase - (isk ? 512 : 1024) + cw;
;                         const int kr = isp ? row : NPROMPT + b * (LA + 32) + LA + s;
;                         *(u32x4*)((isk ? KA : VA) + (size_t)kr * 512 + c) = w;
;                         float* o = nullptr;
;                         if (isp) { if (s >= SEQ - LA) o = out + (isk ? O_AKP : O_AVP) + (size_t)(b * LA + s - (SEQ - LA)) * 512 + c; }
;                         else o = out + (isk ? O_AKS : O_AVS) + (size_t)(row - NPROMPT) * 512 + c;
;                         if (o) { *(f32x4*)o = v0; *(f32x4*)(o + 4) = v1; }
;                     } else if (reg < 16) { *(u32x4*)(Q0 + (size_t)row * 1024 + 512 + (cbase - 1536) + cw) = w; }
.LBB0_793:
	s_and_b64 vcc, exec, s[8:9]
	s_cbranch_vccz .LBB0_795
	v_lshlrev_b64 v[44:45], 11, v[108:109]
	v_lshl_add_u64 v[44:45], s[50:51], 0, v[44:45]
	v_lshl_add_u64 v[44:45], s[72:73], 1, v[44:45]
	v_lshl_add_u64 v[44:45], v[44:45], 0, v[196:197]
	global_store_dwordx4 v[44:45], v[40:43], off offset:-1792 sc0 sc1

;     __device__ __forceinline__ void operator()(const f32x4 (&acc)[2][2][4][2], const Unit& u, int wr, int wc, int fr, int fq) const {
;     ...
;                         const bool isk = reg < 8; const int c = cbase - (isk ? 512 : 1024) + cw;
;                         const int kr = isp ? row : NPROMPT + b * (LA + 32) + LA + s;
;                         *(u32x4*)((isk ? KA : VA) + (size_t)kr * 512 + c) = w;
.LBB0_796:
	s_andn2_b64 vcc, exec, s[8:9]
	s_cbranch_vccnz .LBB0_802
	v_mul_lo_u32 v44, v115, s56
	v_or_b32_e32 v44, v44, v130
	v_add_u32_e32 v44, 0x8200, v44
	v_cndmask_b32_e64 v44, v44, v108, s[20:21]
	s_and_b64 s[8:9], s[42:43], exec
	v_ashrrev_i32_e32 v45, 31, v44
	s_cselect_b32 s9, s1, s87
	s_cselect_b32 s8, s97, s86
	v_lshlrev_b64 v[44:45], 10, v[44:45]
	v_lshl_add_u64 v[44:45], s[8:9], 0, v[44:45]
	v_lshl_add_u64 v[44:45], v[68:69], 1, v[44:45]
	global_store_dwordx4 v[44:45], v[40:43], off sc0 sc1
	s_and_saveexec_b64 s[8:9], s[18:19]
	s_xor_b64 s[8:9], exec, s[8:9]
	s_cbranch_execnz .LBB0_918
	s_andn2_saveexec_b64 s[8:9], s[8:9]
	s_cbranch_execnz .LBB0_919

;     __device__ __forceinline__ void operator()(const f32x4 (&acc)[2][2][4][2], const Unit& u, int wr, int wc, int fr, int fq) const {
;     ...
;                     } else if (reg < 16) { *(u32x4*)(Q0 + (size_t)row * 1024 + 512 + (cbase - 1536) + cw) = w; }
;                     else {
;                         const bool isk = reg == 16; const int c = cw;
;                         const int kr = isp ? row : NPROMPT + b * (LB + 32) + LB + s;
;                         *(u32x4*)((isk ? KB : VB) + (size_t)kr * 128 + c) = w;
;                         float* o = nullptr;
;                         if (isp) { if (s >= SEQ - LB) o = out + (isk ? O_BKP : O_BVP) + (size_t)(b * LB + s - (SEQ - LB)) * 128 + c; }
;                         else o = out + (isk ? O_BKS : O_BVS) + (size_t)(row - NPROMPT) * 128 + c;
.LBB0_803:
	s_andn2_b64 vcc, exec, s[8:9]
	s_cbranch_vccnz .LBB0_805
	v_lshlrev_b64 v[32:33], 11, v[108:109]
	v_lshl_add_u64 v[32:33], s[50:51], 0, v[32:33]
	v_lshl_add_u64 v[32:33], s[64:65], 1, v[32:33]
	v_lshl_add_u64 v[32:33], v[32:33], 0, v[196:197]
	global_store_dwordx4 v[32:33], v[40:43], off offset:256 sc0 sc1
.LBB0_805:
	s_and_b64 vcc, exec, s[6:7]
	s_mov_b64 s[8:9], -1
	s_movk_i32 s2, 0x220
	v_cvt_pk_bf16_f32 v32, v28, v29
	v_cvt_pk_bf16_f32 v33, v30, v31
	v_cvt_pk_bf16_f32 v34, v24, v25
	v_cvt_pk_bf16_f32 v35, v26, v27
	s_cbranch_vccnz .LBB0_825
	s_and_b64 vcc, exec, s[40:41]
	s_cbranch_vccnz .LBB0_818
	s_andn2_b64 vcc, exec, s[66:67]
	s_cbranch_vccnz .LBB0_815
	s_movk_i32 s2, 0xa0
	v_mul_lo_u32 v36, v113, s2
	v_or_b32_e32 v36, v36, v155
	v_add_u32_e32 v36, 0x8080, v36
	v_cndmask_b32_e64 v36, v36, v100, s[24:25]
	v_ashrrev_i32_e32 v37, 31, v36
	v_lshlrev_b64 v[36:37], 8, v[36:37]
	v_lshl_add_u64 v[36:37], s[46:47], 0, v[36:37]
	v_lshl_add_u64 v[36:37], v[36:37], 0, v[196:197]
	global_store_dwordx4 v[36:37], v[32:35], off sc0 sc1
	s_and_saveexec_b64 s[8:9], s[22:23]
	s_xor_b64 s[8:9], exec, s[8:9]
	s_cbranch_execz .LBB0_810
	v_mov_b32_e32 v103, v197
	v_readlane_b32 s10, v255, 28
	v_lshlrev_b64 v[36:37], 9, v[102:103]
	v_readlane_b32 s11, v255, 29
	v_lshlrev_b32_e32 v38, 2, v154
	v_mov_b32_e32 v39, v197
	v_lshl_add_u64 v[36:37], s[10:11], 0, v[36:37]
	v_lshl_add_u64 v[36:37], v[36:37], 0, v[38:39]

;     __device__ __forceinline__ void operator()(const f32x4 (&acc)[2][2][4][2], const Unit& u, int wr, int wc, int fr, int fq) const {
;     ...
;                         float* o = nullptr;
;                         if (isp) { if (s >= SEQ - LB) o = out + (isk ? O_BKP : O_BVP) + (size_t)(b * LB + s - (SEQ - LB)) * 128 + c; }
;                         else o = out + (isk ? O_BKS : O_BVS) + (size_t)(row - NPROMPT) * 128 + c;
;                         if (o) { *(f32x4*)o = v0; *(f32x4*)(o + 4) = v1; }
.LBB0_812:
	s_or_b64 exec, exec, s[8:9]
	v_cmp_ne_u64_e32 vcc, 0, v[36:37]
	s_and_saveexec_b64 s[8:9], vcc
	s_movk_i32 s2, 0x220
	s_cbranch_execz .LBB0_814
	global_store_dwordx4 v[36:37], v[28:31], off sc0 sc1
	global_store_dwordx4 v[36:37], v[24:27], off offset:16 sc0 sc1

;     __device__ __forceinline__ void operator()(const f32x4 (&acc)[2][2][4][2], const Unit& u, int wr, int wc, int fr, int fq) const {
;     ...
;                     if (reg < 4) { *(u32x4*)(Q0 + (size_t)row * 1024 + cbase + cw) = w; }
;                     else if (reg < 12) {
;                         const bool isk = reg < 8; const int c = cbase - (isk ? 512 : 1024) + cw;
;                         const int kr = isp ? row : NPROMPT + b * (LA + 32) + LA + s;
;                         *(u32x4*)((isk ? KA : VA) + (size_t)kr * 512 + c) = w;
;                         float* o = nullptr;
;                         if (isp) { if (s >= SEQ - LA) o = out + (isk ? O_AKP : O_AVP) + (size_t)(b * LA + s - (SEQ - LA)) * 512 + c; }
;                         else o = out + (isk ? O_AKS : O_AVS) + (size_t)(row - NPROMPT) * 512 + c;
;                         if (o) { *(f32x4*)o = v0; *(f32x4*)(o + 4) = v1; }
;                     } else if (reg < 16) { *(u32x4*)(Q0 + (size_t)row * 1024 + 512 + (cbase - 1536) + cw) = w; }
.LBB0_815:
	s_and_b64 vcc, exec, s[8:9]
	s_cbranch_vccz .LBB0_817
	v_lshlrev_b64 v[36:37], 11, v[100:101]
	v_lshl_add_u64 v[36:37], s[50:51], 0, v[36:37]
	v_lshl_add_u64 v[36:37], s[72:73], 1, v[36:37]
	v_lshl_add_u64 v[36:37], v[36:37], 0, v[196:197]
	global_store_dwordx4 v[36:37], v[32:35], off offset:-1792 sc0 sc1

;     __device__ __forceinline__ void operator()(const f32x4 (&acc)[2][2][4][2], const Unit& u, int wr, int wc, int fr, int fq) const {
;     ...
;                         const bool isk = reg < 8; const int c = cbase - (isk ? 512 : 1024) + cw;
;                         const int kr = isp ? row : NPROMPT + b * (LA + 32) + LA + s;
;                         *(u32x4*)((isk ? KA : VA) + (size_t)kr * 512 + c) = w;
.LBB0_818:
	s_andn2_b64 vcc, exec, s[8:9]
	s_cbranch_vccnz .LBB0_824
	v_mul_lo_u32 v36, v113, s2
	v_or_b32_e32 v36, v36, v155
	v_add_u32_e32 v36, 0x8200, v36
	v_cndmask_b32_e64 v36, v36, v100, s[24:25]
	s_and_b64 s[8:9], s[42:43], exec
	v_ashrrev_i32_e32 v37, 31, v36
	s_cselect_b32 s9, s1, s87
	s_cselect_b32 s8, s97, s86
	v_lshlrev_b64 v[36:37], 10, v[36:37]
	v_lshl_add_u64 v[36:37], s[8:9], 0, v[36:37]
	v_lshl_add_u64 v[36:37], v[68:69], 1, v[36:37]
	global_store_dwordx4 v[36:37], v[32:35], off sc0 sc1
	s_and_saveexec_b64 s[8:9], s[22:23]
	s_xor_b64 s[8:9], exec, s[8:9]
	s_cbranch_execnz .LBB0_920
	s_andn2_saveexec_b64 s[8:9], s[8:9]
	s_cbranch_execnz .LBB0_921

;     __device__ __forceinline__ void operator()(const f32x4 (&acc)[2][2][4][2], const Unit& u, int wr, int wc, int fr, int fq) const {
;     ...
;                         float* o = nullptr;
;                         if (isp) { if (s >= SEQ - LA) o = out + (isk ? O_AKP : O_AVP) + (size_t)(b * LA + s - (SEQ - LA)) * 512 + c; }
;                         else o = out + (isk ? O_AKS : O_AVS) + (size_t)(row - NPROMPT) * 512 + c;
;                         if (o) { *(f32x4*)o = v0; *(f32x4*)(o + 4) = v1; }
;                     } else if (reg < 16) { *(u32x4*)(Q0 + (size_t)row * 1024 + 512 + (cbase - 1536) + cw) = w; }
;                     else {
;                         const bool isk = reg == 16; const int c = cw;
;                         const int kr = isp ? row : NPROMPT + b * (LB + 32) + LB + s;
;                         *(u32x4*)((isk ? KB : VB) + (size_t)kr * 128 + c) = w;
;                         float* o = nullptr;
;                         if (isp) { if (s >= SEQ - LB) o = out + (isk ? O_BKP : O_BVP) + (size_t)(b * LB + s - (SEQ - LB)) * 128 + c; }
;                         else o = out + (isk ? O_BKS : O_BVS) + (size_t)(row - NPROMPT) * 128 + c;
;                         if (o) { *(f32x4*)o = v0; *(f32x4*)(o + 4) = v1; }
.LBB0_822:
	global_store_dwordx4 v[36:37], v[28:31], off sc0 sc1
	global_store_dwordx4 v[36:37], v[24:27], off offset:16 sc0 sc1

;     __device__ __forceinline__ void operator()(const f32x4 (&acc)[2][2][4][2], const Unit& u, int wr, int wc, int fr, int fq) const {
;     ...
;                     } else if (reg < 16) { *(u32x4*)(Q0 + (size_t)row * 1024 + 512 + (cbase - 1536) + cw) = w; }
;                     else {
;                         const bool isk = reg == 16; const int c = cw;
;                         const int kr = isp ? row : NPROMPT + b * (LB + 32) + LB + s;
;                         *(u32x4*)((isk ? KB : VB) + (size_t)kr * 128 + c) = w;
.LBB0_825:
	s_andn2_b64 vcc, exec, s[8:9]
	s_cbranch_vccnz .LBB0_827
	v_lshlrev_b64 v[24:25], 11, v[100:101]
	v_lshl_add_u64 v[24:25], s[50:51], 0, v[24:25]
	v_lshl_add_u64 v[24:25], s[64:65], 1, v[24:25]
	v_lshl_add_u64 v[24:25], v[24:25], 0, v[196:197]
	global_store_dwordx4 v[24:25], v[32:35], off offset:256 sc0 sc1
.LBB0_827:
	s_and_b64 vcc, exec, s[6:7]
	s_mov_b64 s[8:9], -1
	v_cvt_pk_bf16_f32 v24, v20, v21
	v_cvt_pk_bf16_f32 v25, v22, v23
	v_cvt_pk_bf16_f32 v26, v16, v17
	v_cvt_pk_bf16_f32 v27, v18, v19
	s_cbranch_vccnz .LBB0_847
	s_and_b64 vcc, exec, s[40:41]
	s_cbranch_vccnz .LBB0_840
	s_andn2_b64 vcc, exec, s[66:67]
	s_cbranch_vccnz .LBB0_837
	s_movk_i32 s2, 0xa0
	v_mul_lo_u32 v28, v99, s2
	v_or_b32_e32 v28, v28, v130
	v_add_u32_e32 v28, 0x8080, v28
	v_cndmask_b32_e64 v28, v28, v92, s[28:29]
	v_ashrrev_i32_e32 v29, 31, v28
	v_lshlrev_b64 v[28:29], 8, v[28:29]
	v_lshl_add_u64 v[28:29], s[46:47], 0, v[28:29]
	v_lshl_add_u64 v[28:29], v[28:29], 0, v[196:197]
	global_store_dwordx4 v[28:29], v[24:27], off sc0 sc1
	s_and_saveexec_b64 s[8:9], s[26:27]
	s_xor_b64 s[8:9], exec, s[8:9]
	s_cbranch_execz .LBB0_832
	v_mov_b32_e32 v95, v197
	v_readlane_b32 s10, v255, 28
	v_lshlrev_b64 v[28:29], 9, v[94:95]
	v_readlane_b32 s11, v255, 29
	v_lshlrev_b32_e32 v30, 2, v154
	v_mov_b32_e32 v31, v197
	v_lshl_add_u64 v[28:29], s[10:11], 0, v[28:29]
	v_lshl_add_u64 v[28:29], v[28:29], 0, v[30:31]

;     __device__ __forceinline__ void operator()(const f32x4 (&acc)[2][2][4][2], const Unit& u, int wr, int wc, int fr, int fq) const {
;     ...
;                         float* o = nullptr;
;                         if (isp) { if (s >= SEQ - LB) o = out + (isk ? O_BKP : O_BVP) + (size_t)(b * LB + s - (SEQ - LB)) * 128 + c; }
;                         else o = out + (isk ? O_BKS : O_BVS) + (size_t)(row - NPROMPT) * 128 + c;
;                         if (o) { *(f32x4*)o = v0; *(f32x4*)(o + 4) = v1; }
.LBB0_834:
	s_or_b64 exec, exec, s[8:9]
	v_cmp_ne_u64_e32 vcc, 0, v[28:29]
	s_and_saveexec_b64 s[8:9], vcc
	s_movk_i32 s2, 0x220
	s_cbranch_execz .LBB0_836
	global_store_dwordx4 v[28:29], v[20:23], off sc0 sc1
	global_store_dwordx4 v[28:29], v[16:19], off offset:16 sc0 sc1

;     __device__ __forceinline__ void operator()(const f32x4 (&acc)[2][2][4][2], const Unit& u, int wr, int wc, int fr, int fq) const {
;     ...
;                     if (reg < 4) { *(u32x4*)(Q0 + (size_t)row * 1024 + cbase + cw) = w; }
;                     else if (reg < 12) {
;                         const bool isk = reg < 8; const int c = cbase - (isk ? 512 : 1024) + cw;
;                         const int kr = isp ? row : NPROMPT + b * (LA + 32) + LA + s;
;                         *(u32x4*)((isk ? KA : VA) + (size_t)kr * 512 + c) = w;
;                         float* o = nullptr;
;                         if (isp) { if (s >= SEQ - LA) o = out + (isk ? O_AKP : O_AVP) + (size_t)(b * LA + s - (SEQ - LA)) * 512 + c; }
;                         else o = out + (isk ? O_AKS : O_AVS) + (size_t)(row - NPROMPT) * 512 + c;
;                         if (o) { *(f32x4*)o = v0; *(f32x4*)(o + 4) = v1; }
;                     } else if (reg < 16) { *(u32x4*)(Q0 + (size_t)row * 1024 + 512 + (cbase - 1536) + cw) = w; }
.LBB0_837:
	s_and_b64 vcc, exec, s[8:9]
	s_cbranch_vccz .LBB0_839
	v_lshlrev_b64 v[28:29], 11, v[92:93]
	v_lshl_add_u64 v[28:29], s[50:51], 0, v[28:29]
	v_lshl_add_u64 v[28:29], s[72:73], 1, v[28:29]
	v_lshl_add_u64 v[28:29], v[28:29], 0, v[196:197]
	global_store_dwordx4 v[28:29], v[24:27], off offset:-1792 sc0 sc1

;     __device__ __forceinline__ void operator()(const f32x4 (&acc)[2][2][4][2], const Unit& u, int wr, int wc, int fr, int fq) const {
;     ...
;                         const bool isk = reg < 8; const int c = cbase - (isk ? 512 : 1024) + cw;
;                         const int kr = isp ? row : NPROMPT + b * (LA + 32) + LA + s;
;                         *(u32x4*)((isk ? KA : VA) + (size_t)kr * 512 + c) = w;
.LBB0_840:
	s_andn2_b64 vcc, exec, s[8:9]
	s_cbranch_vccnz .LBB0_846
	v_mul_lo_u32 v28, v99, s2
	v_or_b32_e32 v28, v28, v130
	v_add_u32_e32 v28, 0x8200, v28
	v_cndmask_b32_e64 v28, v28, v92, s[28:29]
	s_and_b64 s[8:9], s[42:43], exec
	v_ashrrev_i32_e32 v29, 31, v28
	s_cselect_b32 s9, s1, s87
	s_cselect_b32 s8, s97, s86
	v_lshlrev_b64 v[28:29], 10, v[28:29]
	v_lshl_add_u64 v[28:29], s[8:9], 0, v[28:29]
	v_lshl_add_u64 v[28:29], v[68:69], 1, v[28:29]
	global_store_dwordx4 v[28:29], v[24:27], off sc0 sc1
	s_and_saveexec_b64 s[8:9], s[26:27]
	s_xor_b64 s[8:9], exec, s[8:9]
	s_cbranch_execnz .LBB0_922
	s_andn2_saveexec_b64 s[8:9], s[8:9]
	s_cbranch_execnz .LBB0_923

;     __device__ __forceinline__ void operator()(const f32x4 (&acc)[2][2][4][2], const Unit& u, int wr, int wc, int fr, int fq) const {
;     ...
;                         float* o = nullptr;
;                         if (isp) { if (s >= SEQ - LA) o = out + (isk ? O_AKP : O_AVP) + (size_t)(b * LA + s - (SEQ - LA)) * 512 + c; }
;                         else o = out + (isk ? O_AKS : O_AVS) + (size_t)(row - NPROMPT) * 512 + c;
;                         if (o) { *(f32x4*)o = v0; *(f32x4*)(o + 4) = v1; }
;                     } else if (reg < 16) { *(u32x4*)(Q0 + (size_t)row * 1024 + 512 + (cbase - 1536) + cw) = w; }
;                     else {
;                         const bool isk = reg == 16; const int c = cw;
;                         const int kr = isp ? row : NPROMPT + b * (LB + 32) + LB + s;
;                         *(u32x4*)((isk ? KB : VB) + (size_t)kr * 128 + c) = w;
;                         float* o = nullptr;
;                         if (isp) { if (s >= SEQ - LB) o = out + (isk ? O_BKP : O_BVP) + (size_t)(b * LB + s - (SEQ - LB)) * 128 + c; }
;                         else o = out + (isk ? O_BKS : O_BVS) + (size_t)(row - NPROMPT) * 128 + c;
;                         if (o) { *(f32x4*)o = v0; *(f32x4*)(o + 4) = v1; }
.LBB0_844:
	global_store_dwordx4 v[28:29], v[20:23], off sc0 sc1
	global_store_dwordx4 v[28:29], v[16:19], off offset:16 sc0 sc1

;     __device__ __forceinline__ void operator()(const f32x4 (&acc)[2][2][4][2], const Unit& u, int wr, int wc, int fr, int fq) const {
;     ...
;                     } else if (reg < 16) { *(u32x4*)(Q0 + (size_t)row * 1024 + 512 + (cbase - 1536) + cw) = w; }
;                     else {
;                         const bool isk = reg == 16; const int c = cw;
;                         const int kr = isp ? row : NPROMPT + b * (LB + 32) + LB + s;
;                         *(u32x4*)((isk ? KB : VB) + (size_t)kr * 128 + c) = w;
;                         float* o = nullptr;
;                         if (isp) { if (s >= SEQ - LB) o = out + (isk ? O_BKP : O_BVP) + (size_t)(b * LB + s - (SEQ - LB)) * 128 + c; }
;                         else o = out + (isk ? O_BKS : O_BVS) + (size_t)(row - NPROMPT) * 128 + c;
.LBB0_847:
	s_andn2_b64 vcc, exec, s[8:9]
	s_cbranch_vccnz .LBB0_849
	v_lshlrev_b64 v[16:17], 11, v[92:93]
	v_lshl_add_u64 v[16:17], s[50:51], 0, v[16:17]
	v_lshl_add_u64 v[16:17], s[64:65], 1, v[16:17]
	v_lshl_add_u64 v[16:17], v[16:17], 0, v[196:197]
	global_store_dwordx4 v[16:17], v[24:27], off offset:256 sc0 sc1
.LBB0_849:
	s_and_b64 vcc, exec, s[6:7]
	s_mov_b64 s[8:9], -1
	v_cvt_pk_bf16_f32 v16, v12, v13
	v_cvt_pk_bf16_f32 v17, v14, v15
	v_cvt_pk_bf16_f32 v18, v8, v9
	v_cvt_pk_bf16_f32 v19, v10, v11
	s_cbranch_vccnz .LBB0_869
	s_and_b64 vcc, exec, s[40:41]
	s_cbranch_vccnz .LBB0_862
	s_andn2_b64 vcc, exec, s[66:67]
	s_cbranch_vccnz .LBB0_859
	s_movk_i32 s2, 0xa0
	v_mul_lo_u32 v20, v91, s2
	v_or_b32_e32 v20, v20, v155
	v_add_u32_e32 v20, 0x8080, v20
	v_cndmask_b32_e64 v20, v20, v84, s[36:37]
	v_ashrrev_i32_e32 v21, 31, v20
	v_lshlrev_b64 v[20:21], 8, v[20:21]
	v_lshl_add_u64 v[20:21], s[46:47], 0, v[20:21]
	v_lshl_add_u64 v[20:21], v[20:21], 0, v[196:197]
	global_store_dwordx4 v[20:21], v[16:19], off sc0 sc1
	s_and_saveexec_b64 s[8:9], s[30:31]
	s_xor_b64 s[8:9], exec, s[8:9]
	s_cbranch_execz .LBB0_854
	v_mov_b32_e32 v87, v197
	v_readlane_b32 s10, v255, 28
	v_lshlrev_b64 v[20:21], 9, v[86:87]
	v_readlane_b32 s11, v255, 29
	v_lshlrev_b32_e32 v22, 2, v154
	v_mov_b32_e32 v23, v197
	v_lshl_add_u64 v[20:21], s[10:11], 0, v[20:21]
	v_lshl_add_u64 v[20:21], v[20:21], 0, v[22:23]

;     __device__ __forceinline__ void operator()(const f32x4 (&acc)[2][2][4][2], const Unit& u, int wr, int wc, int fr, int fq) const {
;     ...
;                         float* o = nullptr;
;                         if (isp) { if (s >= SEQ - LB) o = out + (isk ? O_BKP : O_BVP) + (size_t)(b * LB + s - (SEQ - LB)) * 128 + c; }
;                         else o = out + (isk ? O_BKS : O_BVS) + (size_t)(row - NPROMPT) * 128 + c;
;                         if (o) { *(f32x4*)o = v0; *(f32x4*)(o + 4) = v1; }
.LBB0_856:
	s_or_b64 exec, exec, s[8:9]
	v_cmp_ne_u64_e32 vcc, 0, v[20:21]
	s_and_saveexec_b64 s[8:9], vcc
	s_movk_i32 s2, 0x220
	s_cbranch_execz .LBB0_858
	global_store_dwordx4 v[20:21], v[12:15], off sc0 sc1
	global_store_dwordx4 v[20:21], v[8:11], off offset:16 sc0 sc1

;     __device__ __forceinline__ void operator()(const f32x4 (&acc)[2][2][4][2], const Unit& u, int wr, int wc, int fr, int fq) const {
;     ...
;                     if (reg < 4) { *(u32x4*)(Q0 + (size_t)row * 1024 + cbase + cw) = w; }
;                     else if (reg < 12) {
;                         const bool isk = reg < 8; const int c = cbase - (isk ? 512 : 1024) + cw;
;                         const int kr = isp ? row : NPROMPT + b * (LA + 32) + LA + s;
;                         *(u32x4*)((isk ? KA : VA) + (size_t)kr * 512 + c) = w;
;                         float* o = nullptr;
;                         if (isp) { if (s >= SEQ - LA) o = out + (isk ? O_AKP : O_AVP) + (size_t)(b * LA + s - (SEQ - LA)) * 512 + c; }
;                         else o = out + (isk ? O_AKS : O_AVS) + (size_t)(row - NPROMPT) * 512 + c;
;                         if (o) { *(f32x4*)o = v0; *(f32x4*)(o + 4) = v1; }
;                     } else if (reg < 16) { *(u32x4*)(Q0 + (size_t)row * 1024 + 512 + (cbase - 1536) + cw) = w; }
.LBB0_859:
	s_and_b64 vcc, exec, s[8:9]
	s_cbranch_vccz .LBB0_861
	v_lshlrev_b64 v[20:21], 11, v[84:85]
	v_lshl_add_u64 v[20:21], s[50:51], 0, v[20:21]
	v_lshl_add_u64 v[20:21], s[72:73], 1, v[20:21]
	v_lshl_add_u64 v[20:21], v[20:21], 0, v[196:197]
	global_store_dwordx4 v[20:21], v[16:19], off offset:-1792 sc0 sc1

;     __device__ __forceinline__ void operator()(const f32x4 (&acc)[2][2][4][2], const Unit& u, int wr, int wc, int fr, int fq) const {
;     ...
;                         const bool isk = reg < 8; const int c = cbase - (isk ? 512 : 1024) + cw;
;                         const int kr = isp ? row : NPROMPT + b * (LA + 32) + LA + s;
;                         *(u32x4*)((isk ? KA : VA) + (size_t)kr * 512 + c) = w;
.LBB0_862:
	s_andn2_b64 vcc, exec, s[8:9]
	s_cbranch_vccnz .LBB0_868
	v_mul_lo_u32 v20, v91, s2
	v_or_b32_e32 v20, v20, v155
	v_add_u32_e32 v20, 0x8200, v20
	v_cndmask_b32_e64 v20, v20, v84, s[36:37]
	s_and_b64 s[8:9], s[42:43], exec
	v_ashrrev_i32_e32 v21, 31, v20
	s_cselect_b32 s9, s1, s87
	s_cselect_b32 s8, s97, s86
	v_lshlrev_b64 v[20:21], 10, v[20:21]
	v_lshl_add_u64 v[20:21], s[8:9], 0, v[20:21]
	v_lshl_add_u64 v[20:21], v[68:69], 1, v[20:21]
	global_store_dwordx4 v[20:21], v[16:19], off sc0 sc1
	s_and_saveexec_b64 s[8:9], s[30:31]
	s_xor_b64 s[8:9], exec, s[8:9]
	s_cbranch_execnz .LBB0_924
	s_andn2_saveexec_b64 s[8:9], s[8:9]
	s_cbranch_execnz .LBB0_925

;     __device__ __forceinline__ void operator()(const f32x4 (&acc)[2][2][4][2], const Unit& u, int wr, int wc, int fr, int fq) const {
;     ...
;                         float* o = nullptr;
;                         if (isp) { if (s >= SEQ - LA) o = out + (isk ? O_AKP : O_AVP) + (size_t)(b * LA + s - (SEQ - LA)) * 512 + c; }
;                         else o = out + (isk ? O_AKS : O_AVS) + (size_t)(row - NPROMPT) * 512 + c;
;                         if (o) { *(f32x4*)o = v0; *(f32x4*)(o + 4) = v1; }
;                     } else if (reg < 16) { *(u32x4*)(Q0 + (size_t)row * 1024 + 512 + (cbase - 1536) + cw) = w; }
;                     else {
;                         const bool isk = reg == 16; const int c = cw;
;                         const int kr = isp ? row : NPROMPT + b * (LB + 32) + LB + s;
;                         *(u32x4*)((isk ? KB : VB) + (size_t)kr * 128 + c) = w;
;                         float* o = nullptr;
;                         if (isp) { if (s >= SEQ - LB) o = out + (isk ? O_BKP : O_BVP) + (size_t)(b * LB + s - (SEQ - LB)) * 128 + c; }
;                         else o = out + (isk ? O_BKS : O_BVS) + (size_t)(row - NPROMPT) * 128 + c;
;                         if (o) { *(f32x4*)o = v0; *(f32x4*)(o + 4) = v1; }
.LBB0_866:
	global_store_dwordx4 v[20:21], v[12:15], off sc0 sc1
	global_store_dwordx4 v[20:21], v[8:11], off offset:16 sc0 sc1

;     __device__ __forceinline__ void operator()(const f32x4 (&acc)[2][2][4][2], const Unit& u, int wr, int wc, int fr, int fq) const {
;     ...
;                     } else if (reg < 16) { *(u32x4*)(Q0 + (size_t)row * 1024 + 512 + (cbase - 1536) + cw) = w; }
;                     else {
;                         const bool isk = reg == 16; const int c = cw;
;                         const int kr = isp ? row : NPROMPT + b * (LB + 32) + LB + s;
;                         *(u32x4*)((isk ? KB : VB) + (size_t)kr * 128 + c) = w;
;                         float* o = nullptr;
;                         if (isp) { if (s >= SEQ - LB) o = out + (isk ? O_BKP : O_BVP) + (size_t)(b * LB + s - (SEQ - LB)) * 128 + c; }
;                         else o = out + (isk ? O_BKS : O_BVS) + (size_t)(row - NPROMPT) * 128 + c;
.LBB0_869:
	s_andn2_b64 vcc, exec, s[8:9]
	s_cbranch_vccnz .LBB0_871
	v_lshlrev_b64 v[8:9], 11, v[84:85]
	v_lshl_add_u64 v[8:9], s[50:51], 0, v[8:9]
	v_lshl_add_u64 v[8:9], s[64:65], 1, v[8:9]
	v_lshl_add_u64 v[8:9], v[8:9], 0, v[196:197]
	global_store_dwordx4 v[8:9], v[16:19], off offset:256 sc0 sc1
.LBB0_871:
	s_and_b64 vcc, exec, s[6:7]
	s_mov_b64 s[6:7], -1
	v_cvt_pk_bf16_f32 v8, v4, v5
	v_cvt_pk_bf16_f32 v9, v6, v7
	v_cvt_pk_bf16_f32 v10, v0, v1
	v_cvt_pk_bf16_f32 v11, v2, v3
	s_cbranch_vccnz .LBB0_891
	s_and_b64 vcc, exec, s[40:41]
	s_cbranch_vccnz .LBB0_884
	s_andn2_b64 vcc, exec, s[66:67]
	s_cbranch_vccnz .LBB0_881
	s_movk_i32 s2, 0xa0
	v_mul_lo_u32 v12, v83, s2
	v_or_b32_e32 v12, v12, v130
	v_add_u32_e32 v12, 0x8080, v12
	v_cndmask_b32_e64 v12, v12, v76, s[38:39]
	v_ashrrev_i32_e32 v13, 31, v12
	v_lshlrev_b64 v[12:13], 8, v[12:13]
	v_lshl_add_u64 v[12:13], s[46:47], 0, v[12:13]
	v_lshl_add_u64 v[12:13], v[12:13], 0, v[196:197]
	global_store_dwordx4 v[12:13], v[8:11], off sc0 sc1
	v_lshlrev_b32_e32 v12, 2, v154
	s_and_saveexec_b64 s[6:7], s[34:35]
	s_xor_b64 s[6:7], exec, s[6:7]
	s_cbranch_execz .LBB0_876
	v_mov_b32_e32 v79, v197
	v_readlane_b32 s8, v255, 28
	v_lshlrev_b64 v[14:15], 9, v[78:79]
	v_readlane_b32 s9, v255, 29
	v_mov_b32_e32 v13, v197
	s_nop 0
	v_lshl_add_u64 v[14:15], s[8:9], 0, v[14:15]
	v_lshl_add_u64 v[14:15], v[14:15], 0, v[12:13]

;     __device__ __forceinline__ void operator()(const f32x4 (&acc)[2][2][4][2], const Unit& u, int wr, int wc, int fr, int fq) const {
;     ...
;                         float* o = nullptr;
;                         if (isp) { if (s >= SEQ - LB) o = out + (isk ? O_BKP : O_BVP) + (size_t)(b * LB + s - (SEQ - LB)) * 128 + c; }
;                         else o = out + (isk ? O_BKS : O_BVS) + (size_t)(row - NPROMPT) * 128 + c;
;                         if (o) { *(f32x4*)o = v0; *(f32x4*)(o + 4) = v1; }
.LBB0_878:
	s_or_b64 exec, exec, s[6:7]
	v_cmp_ne_u64_e32 vcc, 0, v[14:15]
	s_and_saveexec_b64 s[6:7], vcc
	s_movk_i32 s2, 0x220
	s_cbranch_execz .LBB0_880
	global_store_dwordx4 v[14:15], v[4:7], off sc0 sc1
	global_store_dwordx4 v[14:15], v[0:3], off offset:16 sc0 sc1

;     __device__ __forceinline__ void operator()(const f32x4 (&acc)[2][2][4][2], const Unit& u, int wr, int wc, int fr, int fq) const {
;     ...
;                     if (reg < 4) { *(u32x4*)(Q0 + (size_t)row * 1024 + cbase + cw) = w; }
;                     else if (reg < 12) {
;                         const bool isk = reg < 8; const int c = cbase - (isk ? 512 : 1024) + cw;
;                         const int kr = isp ? row : NPROMPT + b * (LA + 32) + LA + s;
;                         *(u32x4*)((isk ? KA : VA) + (size_t)kr * 512 + c) = w;
;                         float* o = nullptr;
;                         if (isp) { if (s >= SEQ - LA) o = out + (isk ? O_AKP : O_AVP) + (size_t)(b * LA + s - (SEQ - LA)) * 512 + c; }
;                         else o = out + (isk ? O_AKS : O_AVS) + (size_t)(row - NPROMPT) * 512 + c;
;                         if (o) { *(f32x4*)o = v0; *(f32x4*)(o + 4) = v1; }
;                     } else if (reg < 16) { *(u32x4*)(Q0 + (size_t)row * 1024 + 512 + (cbase - 1536) + cw) = w; }
.LBB0_881:
	s_and_b64 vcc, exec, s[6:7]
	s_cbranch_vccz .LBB0_883
	v_lshlrev_b64 v[12:13], 11, v[76:77]
	v_lshl_add_u64 v[12:13], s[50:51], 0, v[12:13]
	v_lshl_add_u64 v[12:13], s[72:73], 1, v[12:13]
	v_lshl_add_u64 v[12:13], v[12:13], 0, v[196:197]
	global_store_dwordx4 v[12:13], v[8:11], off offset:-1792 sc0 sc1

;     __device__ __forceinline__ void operator()(const f32x4 (&acc)[2][2][4][2], const Unit& u, int wr, int wc, int fr, int fq) const {
;     ...
;                         const bool isk = reg < 8; const int c = cbase - (isk ? 512 : 1024) + cw;
;                         const int kr = isp ? row : NPROMPT + b * (LA + 32) + LA + s;
;                         *(u32x4*)((isk ? KA : VA) + (size_t)kr * 512 + c) = w;
.LBB0_884:
	s_andn2_b64 vcc, exec, s[6:7]
	s_cbranch_vccnz .LBB0_890
	v_mul_lo_u32 v12, v83, s2
	v_or_b32_e32 v12, v12, v130
	v_add_u32_e32 v12, 0x8200, v12
	v_cndmask_b32_e64 v12, v12, v76, s[38:39]
	s_and_b64 s[6:7], s[42:43], exec
	v_ashrrev_i32_e32 v13, 31, v12
	s_cselect_b32 s7, s1, s87
	s_cselect_b32 s6, s97, s86
	v_lshlrev_b64 v[12:13], 10, v[12:13]
	v_lshl_add_u64 v[12:13], s[6:7], 0, v[12:13]
	v_lshl_add_u64 v[12:13], v[68:69], 1, v[12:13]
	global_store_dwordx4 v[12:13], v[8:11], off sc0 sc1
	s_and_saveexec_b64 s[6:7], s[34:35]
	s_xor_b64 s[6:7], exec, s[6:7]
	s_cbranch_execnz .LBB0_926
	s_andn2_saveexec_b64 s[6:7], s[6:7]
	s_cbranch_execnz .LBB0_927

;     __device__ __forceinline__ void operator()(const f32x4 (&acc)[2][2][4][2], const Unit& u, int wr, int wc, int fr, int fq) const {
;     ...
;                         float* o = nullptr;
;                         if (isp) { if (s >= SEQ - LA) o = out + (isk ? O_AKP : O_AVP) + (size_t)(b * LA + s - (SEQ - LA)) * 512 + c; }
;                         else o = out + (isk ? O_AKS : O_AVS) + (size_t)(row - NPROMPT) * 512 + c;
;                         if (o) { *(f32x4*)o = v0; *(f32x4*)(o + 4) = v1; }
;                     } else if (reg < 16) { *(u32x4*)(Q0 + (size_t)row * 1024 + 512 + (cbase - 1536) + cw) = w; }
;                     else {
;                         const bool isk = reg == 16; const int c = cw;
;                         const int kr = isp ? row : NPROMPT + b * (LB + 32) + LB + s;
;                         *(u32x4*)((isk ? KB : VB) + (size_t)kr * 128 + c) = w;
;                         float* o = nullptr;
;                         if (isp) { if (s >= SEQ - LB) o = out + (isk ? O_BKP : O_BVP) + (size_t)(b * LB + s - (SEQ - LB)) * 128 + c; }
;                         else o = out + (isk ? O_BKS : O_BVS) + (size_t)(row - NPROMPT) * 128 + c;
;                         if (o) { *(f32x4*)o = v0; *(f32x4*)(o + 4) = v1; }
.LBB0_888:
	global_store_dwordx4 v[12:13], v[4:7], off sc0 sc1
	global_store_dwordx4 v[12:13], v[0:3], off offset:16 sc0 sc1

;     __device__ __forceinline__ void operator()(const f32x4 (&acc)[2][2][4][2], const Unit& u, int wr, int wc, int fr, int fq) const {
;     ...
;                     } else if (reg < 16) { *(u32x4*)(Q0 + (size_t)row * 1024 + 512 + (cbase - 1536) + cw) = w; }
.LBB0_891:
	s_andn2_b64 vcc, exec, s[6:7]
	s_cbranch_vccnz .LBB0_893
	v_lshlrev_b64 v[0:1], 11, v[76:77]
	v_lshl_add_u64 v[0:1], s[50:51], 0, v[0:1]
	v_lshl_add_u64 v[0:1], s[64:65], 1, v[0:1]
	v_lshl_add_u64 v[0:1], v[0:1], 0, v[196:197]
	global_store_dwordx4 v[0:1], v[8:11], off offset:256 sc0 sc1

; __device__ __forceinline__ void zero16(void* p_, int n16, int gtid, int gthreads) { unsigned z = 0u; asm volatile("" : "+v"(z)); for (int i = gtid; i < n16; i += gthreads) ((u32x4*)p_)[i] = (u32x4){z, z, z, z}; }
; __device__ __forceinline__ void prologue_l1(ArgsP a, int wave_s_) {
;     ...
;     cvt_rows(a->in[8], (bf16*)(a->ws + WS_KVN), 16, PAST, 256, NPROMPT, PAST + 32, gtid, gthreads);
;     cvt_rows(a->in[9], (bf16*)(a->ws + WS_KR), 16, PAST, 32, NPROMPT, PAST + 32, gtid, gthreads);
;     zero16(a->ws + WS_KR + (size_t)RKV * 32 * 2, 64 * 32 * 2 / 16, gtid, gthreads);
.LBB0_1110:
	v_add_u32_e32 v4, s4, v4
	s_movk_i32 s1, 0xff
	v_cmp_lt_i32_e32 vcc, s1, v4
	global_store_dwordx4 v[6:7], v[0:3], off sc0 sc1
	s_or_b64 s[10:11], vcc, s[10:11]
	v_lshl_add_u64 v[6:7], v[6:7], 0, s[6:7]
	s_andn2_b64 exec, exec, s[10:11]
	s_cbranch_execnz .LBB0_1110

;     __device__ __forceinline__ void operator()(const f32x4 (&acc)[2][2][4][2], const Unit& u, int wr, int wc, int fr, int fq) const {
;         { int l_; asm volatile("v_mbcnt_lo_u32_b32 %0, -1, 0\n\tv_mbcnt_hi_u32_b32 %0, -1, %0" : "=v"(l_)); fr = l_ & 15; fq = (l_ >> 4) & 3; }
;         const int row0 = u.pm * BM + wr * 64 + fr, col0 = u.pn * BM + wc * 32 + 4 * fq;
; #pragma unroll
;         for (int ai = 0; ai < 2; ++ai)
; #pragma unroll
;             for (int m = 0; m < 4; ++m) { float* xp = C + (size_t)(row0 + ai * HALF + m * 16) * ldc;
; #pragma unroll
;                 for (int bj = 0; bj < 2; ++bj)
; #pragma unroll
;                     for (int n = 0; n < 2; ++n) *(f32x4*)(xp + col0 + bj * HALF + n * 16) = acc[ai][bj][m][n]; }
;     }
.LBB0_1188:
	s_lshl_b32 s15, s36, 8
	v_mbcnt_lo_u32_b32 v136, -1, 0
	v_mbcnt_hi_u32_b32 v136, -1, v136
	s_add_i32 s15, s15, s35
	v_and_or_b32 v142, v136, 15, s15
	s_lshl_b32 s15, s40, 8
	v_lshrrev_b32_e32 v136, 2, v136
	v_and_or_b32 v136, v136, 12, s15
	v_or_b32_e32 v136, s37, v136
	v_ashrrev_i32_e32 v137, 31, v136
	v_mov_b64_e32 v[138:139], s[10:11]
	s_movk_i32 s15, 0xc00
	v_mad_i64_i32 v[140:141], s[18:19], v142, s15, v[138:139]
	v_lshlrev_b64 v[136:137], 2, v[136:137]
	v_lshl_add_u64 v[140:141], v[140:141], 0, v[136:137]
	global_store_dwordx4 v[140:141], v[124:127], off sc0 sc1
	global_store_dwordx4 v[140:141], v[120:123], off offset:64 sc0 sc1
	global_store_dwordx4 v[140:141], v[104:107], off offset:512 sc0 sc1
	global_store_dwordx4 v[140:141], v[96:99], off offset:576 sc0 sc1
	s_and_b64 vcc, exec, s[4:5]
	s_mov_b64 s[4:5], -1
	v_or_b32_e32 v96, 16, v142
	v_mad_i64_i32 v[96:97], s[18:19], v96, s15, v[138:139]
	v_lshl_add_u64 v[96:97], v[96:97], 0, v[136:137]
	global_store_dwordx4 v[96:97], v[116:119], off sc0 sc1
	global_store_dwordx4 v[96:97], v[112:115], off offset:64 sc0 sc1
	global_store_dwordx4 v[96:97], v[88:91], off offset:512 sc0 sc1
	global_store_dwordx4 v[96:97], v[80:83], off offset:576 sc0 sc1
	s_nop 1
	v_or_b32_e32 v80, 32, v142
	v_mad_i64_i32 v[80:81], s[18:19], v80, s15, v[138:139]
	v_lshl_add_u64 v[80:81], v[80:81], 0, v[136:137]
	global_store_dwordx4 v[80:81], v[108:111], off sc0 sc1
	global_store_dwordx4 v[80:81], v[100:103], off offset:64 sc0 sc1
	global_store_dwordx4 v[80:81], v[76:79], off offset:512 sc0 sc1
	global_store_dwordx4 v[80:81], v[72:75], off offset:576 sc0 sc1
	s_nop 1
	v_or_b32_e32 v72, 48, v142
	v_mad_i64_i32 v[72:73], s[18:19], v72, s15, v[138:139]
	v_lshl_add_u64 v[72:73], v[72:73], 0, v[136:137]
	global_store_dwordx4 v[72:73], v[92:95], off sc0 sc1
	global_store_dwordx4 v[72:73], v[84:87], off offset:64 sc0 sc1
	global_store_dwordx4 v[72:73], v[68:71], off offset:512 sc0 sc1
	global_store_dwordx4 v[72:73], v[64:67], off offset:576 sc0 sc1
	s_nop 1
	v_add_u32_e32 v64, 0x80, v142
	v_mad_i64_i32 v[64:65], s[18:19], v64, s15, v[138:139]
	v_lshl_add_u64 v[64:65], v[64:65], 0, v[136:137]
	global_store_dwordx4 v[64:65], v[60:63], off sc0 sc1
	global_store_dwordx4 v[64:65], v[56:59], off offset:64 sc0 sc1
	global_store_dwordx4 v[64:65], v[40:43], off offset:512 sc0 sc1
	global_store_dwordx4 v[64:65], v[32:35], off offset:576 sc0 sc1
	s_nop 1
	v_add_u32_e32 v32, 0x90, v142
	v_mad_i64_i32 v[32:33], s[18:19], v32, s15, v[138:139]
	v_lshl_add_u64 v[32:33], v[32:33], 0, v[136:137]
	global_store_dwordx4 v[32:33], v[52:55], off sc0 sc1
	global_store_dwordx4 v[32:33], v[48:51], off offset:64 sc0 sc1
	global_store_dwordx4 v[32:33], v[24:27], off offset:512 sc0 sc1
	global_store_dwordx4 v[32:33], v[16:19], off offset:576 sc0 sc1
	s_nop 1
	v_add_u32_e32 v16, 0xa0, v142
	v_mad_i64_i32 v[16:17], s[18:19], v16, s15, v[138:139]
	v_lshl_add_u64 v[16:17], v[16:17], 0, v[136:137]
	global_store_dwordx4 v[16:17], v[44:47], off sc0 sc1
	global_store_dwordx4 v[16:17], v[36:39], off offset:64 sc0 sc1
	global_store_dwordx4 v[16:17], v[12:15], off offset:512 sc0 sc1
	global_store_dwordx4 v[16:17], v[8:11], off offset:576 sc0 sc1
	s_nop 1
	v_add_u32_e32 v8, 0xb0, v142
	v_mad_i64_i32 v[8:9], s[18:19], v8, s15, v[138:139]
	v_lshl_add_u64 v[8:9], v[8:9], 0, v[136:137]
	global_store_dwordx4 v[8:9], v[28:31], off sc0 sc1
	global_store_dwordx4 v[8:9], v[20:23], off offset:64 sc0 sc1
	global_store_dwordx4 v[8:9], v[4:7], off offset:512 sc0 sc1
	global_store_dwordx4 v[8:9], v[0:3], off offset:576 sc0 sc1
	s_cbranch_vccnz .LBB0_1173
	s_andn2_b64 vcc, exec, s[8:9]
	s_cbranch_vccnz .LBB0_1172
	s_barrier
	s_branch .LBB0_1172

; __device__ __forceinline__ unsigned f2bf(float f) { unsigned u = __builtin_bit_cast(unsigned, f); return (u + 0x7fffu + ((u >> 16) & 1u)) >> 16; }
; __device__ __forceinline__ unsigned pk2(float lo, float hi) { return pg8::cvt_pk_bf16(lo, hi); }
; __device__ __forceinline__ void mla_norm_phase(ArgsP a, int wave_s_) {
;     ...
;         const bool isp = row < NPROMPT; const int rs = row - NPROMPT, b = rs >> 5, t = rs & 31;
;         const int kvrow = isp ? row : NPROMPT + b * (PAST + 32) + PAST + t; const int pos = isp ? (row & (SEQ - 1)) : PAST + t;
;         float cs_ = 0.f, sn_ = 0.f; if (lane < 16) { cs_ = rope[(size_t)pos * 32 + lane]; sn_ = rope[(size_t)pos * 32 + 16 + lane]; }
;         float ss = 0.f;
; #pragma unroll
;         for (int j = 0; j < 3; ++j) ss += q[j][0] * q[j][0] + q[j][1] * q[j][1];
;         float s2 = (kv[0] * kv[0] + kv[1] * kv[1]) + (kv[2] * kv[2] + kv[3] * kv[3]);
;         const float rq = 1.0f / sqrtf(wave_sum(ss, lane) * (1.0f / 384.0f) + EPS), rk = 1.0f / sqrtf(wave_sum(s2, lane) * (1.0f / 256.0f) + EPS);
; #pragma unroll
;         for (int j = 0; j < 3; ++j) { const f32x2 o = (q[j] * rq) * qgv[j]; *(unsigned*)(QN + (size_t)row * 384 + 2 * lane + 128 * j) = pk2(o[0], o[1]); }
;         const f32x4 ko = (kv * rk) * kgv;
;         float* okv = a->out + (isp ? O_CKVP + (size_t)row * 256 : O_CKVS + (size_t)rs * 256) + 4 * lane; *(f32x4*)okv = ko;
;         u32x2 kw; kw.x = pk2(ko[0], ko[1]); kw.y = pk2(ko[2], ko[3]); *(u32x2*)(KVN + (size_t)kvrow * 256 + 4 * lane) = kw;
;         if (lane < 16) {
;             const float x1 = kr1, x2 = kr2, cs = cs_, sn = sn_;
;             const float o1 = x1 * cs - x2 * sn, o2 = x1 * sn + x2 * cs;
;             float* okr = a->out + (isp ? O_CKRP + (size_t)row * 32 : O_CKRS + (size_t)rs * 32);
;             okr[lane] = o1; okr[16 + lane] = o2;
;             KR[(size_t)kvrow * 32 + lane] = (bf16)f2bf(o1); KR[(size_t)kvrow * 32 + 16 + lane] = (bf16)f2bf(o2);
;         }
.LBB0_1256:
	s_or_b64 exec, exec, s[8:9]
	v_add_u32_e32 v49, 0xffff8000, v12
	v_lshrrev_b32_e32 v55, 5, v49
	v_mul_lo_u32 v55, v55, s3
	v_or_b32_e32 v48, v55, v48
	s_waitcnt vmcnt(3)
	v_mul_f32_e32 v55, v47, v47
	s_waitcnt vmcnt(2)
	v_mul_f32_e32 v56, v45, v45
	v_fmac_f32_e32 v55, v46, v46
	v_fmac_f32_e32 v56, v44, v44
	v_add_f32_e32 v55, v55, v56
	s_waitcnt vmcnt(1)
	v_mul_f32_e32 v56, v43, v43
	v_fmac_f32_e32 v56, v42, v42
	v_add_f32_e32 v55, v56, v55
	v_mov_b32_e32 v56, v197
	s_mov_b32 s2, 0xf800000
	v_add_f32_dpp v55, v55, v55 quad_perm:[1,0,3,2] row_mask:0xf bank_mask:0xf bound_ctrl:1
	s_waitcnt vmcnt(0)
	v_mul_f32_e32 v57, v5, v5
	v_fmac_f32_e32 v57, v4, v4
	v_add_f32_dpp v55, v55, v55 quad_perm:[2,3,0,1] row_mask:0xf bank_mask:0xf bound_ctrl:1
	v_add_u32_e32 v48, 0x8400, v48
	v_cndmask_b32_e64 v48, v48, v12, s[6:7]
	v_add_f32_dpp v55, v55, v55 row_half_mirror row_mask:0xf bank_mask:0xf bound_ctrl:1
	s_nop 1
	v_add_f32_dpp v55, v55, v55 row_mirror row_mask:0xf bank_mask:0xf bound_ctrl:1
	s_nop 1
	v_mov_b32_dpp v56, v55 row_bcast:15 row_mask:0xa bank_mask:0xf
	v_add_f32_e32 v55, v55, v56
	v_mov_b32_e32 v56, v197
	s_nop 1
	v_mov_b32_dpp v56, v55 row_bcast:31 row_mask:0xc bank_mask:0xf
	v_add_f32_e32 v55, v55, v56
	s_nop 0
	v_readlane_b32 s1, v55, 63
	v_mov_b32_e32 v55, 0x3b2aaaab
	s_nop 0
	v_fma_f32 v55, s1, v55, v236
	v_mul_f32_e32 v56, 0x4f800000, v55
	v_cmp_gt_f32_e32 vcc, s2, v55
	s_nop 1
	v_cndmask_b32_e32 v55, v55, v56, vcc
	v_sqrt_f32_e32 v56, v55
	s_nop 0
	v_add_u32_e32 v58, -1, v56
	v_fma_f32 v59, -v58, v56, v55
	v_cmp_ge_f32_e64 s[8:9], 0, v59
	v_add_u32_e32 v59, 1, v56
	s_nop 0
	v_cndmask_b32_e64 v58, v56, v58, s[8:9]
	v_fma_f32 v56, -v59, v56, v55
	v_cmp_lt_f32_e64 s[8:9], 0, v56
	s_nop 1
	v_cndmask_b32_e64 v56, v58, v59, s[8:9]
	v_mul_f32_e32 v58, 0x37800000, v56
	v_cndmask_b32_e32 v56, v56, v58, vcc
	v_cmp_class_f32_e32 vcc, v55, v237
	v_mul_f32_e32 v59, v7, v7
	v_fmac_f32_e32 v59, v6, v6
	v_cndmask_b32_e32 v55, v56, v55, vcc
	v_div_scale_f32 v56, s[8:9], v55, v55, 1.0
	v_rcp_f32_e32 v58, v56
	v_add_f32_e32 v57, v57, v59
	v_fma_f32 v59, -v56, v58, 1.0
	v_fmac_f32_e32 v58, v59, v58
	v_div_scale_f32 v59, vcc, 1.0, v55, 1.0
	v_mul_f32_e32 v60, v59, v58
	v_add_f32_dpp v57, v57, v57 quad_perm:[1,0,3,2] row_mask:0xf bank_mask:0xf bound_ctrl:1
	v_fma_f32 v61, -v56, v60, v59
	v_fmac_f32_e32 v60, v61, v58
	v_add_f32_dpp v57, v57, v57 quad_perm:[2,3,0,1] row_mask:0xf bank_mask:0xf bound_ctrl:1
	v_fma_f32 v56, -v56, v60, v59
	v_mov_b32_e32 v59, v197
	v_add_f32_dpp v57, v57, v57 row_half_mirror row_mask:0xf bank_mask:0xf bound_ctrl:1
	v_div_fmas_f32 v56, v56, v58, v60
	v_div_fixup_f32 v56, v56, v55, 1.0
	v_add_f32_dpp v57, v57, v57 row_mirror row_mask:0xf bank_mask:0xf bound_ctrl:1
	s_nop 1
	v_mov_b32_dpp v59, v57 row_bcast:15 row_mask:0xa bank_mask:0xf
	v_add_f32_e32 v57, v57, v59
	v_mov_b32_e32 v59, v197
	s_nop 1
	v_mov_b32_dpp v59, v57 row_bcast:31 row_mask:0xc bank_mask:0xf
	v_add_f32_e32 v57, v57, v59
	s_nop 0
	v_readlane_b32 s1, v57, 63
	v_mov_b32_e32 v57, 0x3b800000
	s_nop 0
	v_fma_f32 v57, s1, v57, v236
	v_mul_f32_e32 v59, 0x4f800000, v57
	v_cmp_gt_f32_e64 s[8:9], s2, v57
	s_mov_b32 s1, 0x9298000
	s_nop 0
	v_cndmask_b32_e64 v57, v57, v59, s[8:9]
	v_sqrt_f32_e32 v59, v57
	v_pk_mul_f32 v[46:47], v[46:47], v[56:57] op_sel_hi:[1,0]
	v_add_u32_e32 v55, -1, v59
	v_fma_f32 v58, -v55, v59, v57
	v_cmp_ge_f32_e32 vcc, 0, v58
	v_add_u32_e32 v58, 1, v59
	v_pk_mul_f32 v[46:47], v[14:15], v[46:47]
	v_cndmask_b32_e32 v55, v59, v55, vcc
	v_fma_f32 v59, -v58, v59, v57
	v_cmp_lt_f32_e32 vcc, 0, v59
	s_nop 1
	v_cndmask_b32_e32 v55, v55, v58, vcc
	v_mul_f32_e32 v58, 0x37800000, v55
	v_cndmask_b32_e64 v55, v55, v58, s[8:9]
	v_cmp_class_f32_e32 vcc, v57, v237
	v_lshl_add_u64 v[58:59], s[14:15], 0, v[30:31]
	s_nop 0
	v_cndmask_b32_e32 v55, v55, v57, vcc
	v_cvt_pk_bf16_f32 v57, v46, v47
	v_add_co_u32_e32 v46, vcc, s1, v58
	v_pk_mul_f32 v[44:45], v[44:45], v[56:57] op_sel_hi:[1,0]
	s_nop 0
	v_addc_co_u32_e32 v47, vcc, 0, v59, vcc
	v_pk_mul_f32 v[44:45], v[16:17], v[44:45]
	global_store_dword v[46:47], v57, off
	v_cvt_pk_bf16_f32 v44, v44, v45
	global_store_dword v[46:47], v44, off offset:256
	v_div_scale_f32 v44, s[8:9], v55, v55, 1.0
	v_rcp_f32_e32 v45, v44
	v_pk_mul_f32 v[42:43], v[42:43], v[56:57] op_sel_hi:[1,0]
	s_nop 0
	v_pk_mul_f32 v[42:43], v[18:19], v[42:43]
	s_nop 0
	v_cvt_pk_bf16_f32 v42, v42, v43
	global_store_dword v[46:47], v42, off offset:512
	v_fma_f32 v42, -v44, v45, 1.0
	v_fmac_f32_e32 v45, v42, v45
	v_div_scale_f32 v42, vcc, 1.0, v55, 1.0
	v_mul_f32_e32 v43, v42, v45
	v_fma_f32 v46, -v44, v43, v42
	v_fmac_f32_e32 v43, v46, v45
	v_fma_f32 v42, -v44, v43, v42
	v_div_fmas_f32 v42, v42, v45, v43
	s_load_dwordx2 s[8:9], s[10:11], 0xe0
	v_div_fixup_f32 v42, v42, v55, 1.0
	v_pk_mul_f32 v[4:5], v[4:5], v[42:43] op_sel_hi:[1,0]
	v_pk_mul_f32 v[6:7], v[6:7], v[42:43] op_sel_hi:[1,0]
	v_pk_mul_f32 v[42:43], v[0:1], v[4:5]
	v_pk_mul_f32 v[44:45], v[2:3], v[6:7]
	v_cndmask_b32_e64 v5, 0, v13, s[6:7]
	v_cndmask_b32_e64 v4, v49, v12, s[6:7]
	v_mov_b32_e32 v6, 0xacc0000
	v_mov_b32_e32 v7, 0x8640000
	v_cndmask_b32_e64 v196, v6, v7, s[6:7]
	v_lshlrev_b64 v[6:7], 10, v[4:5]
	s_waitcnt lgkmcnt(0)
	v_lshl_add_u64 v[6:7], s[8:9], 0, v[6:7]
	v_lshl_add_u64 v[46:47], v[6:7], 0, v[196:197]
	v_lshlrev_b32_e32 v196, 2, v20
	v_lshl_add_u64 v[46:47], v[46:47], 0, v[196:197]
	v_ashrrev_i32_e32 v49, 31, v48
	global_store_dwordx4 v[46:47], v[42:45], off sc0 sc1
	s_nop 1
	v_cvt_pk_bf16_f32 v42, v42, v43
	v_cvt_pk_bf16_f32 v43, v44, v45
	v_lshlrev_b64 v[44:45], 9, v[48:49]
	v_lshl_add_u64 v[44:45], v[24:25], 0, v[44:45]
	global_store_dwordx2 v[44:45], v[42:43], off
	s_and_saveexec_b64 s[8:9], s[4:5]
	s_cbranch_execz .LBB0_1249
	v_mul_f32_e32 v42, v51, v21
	v_mul_f32_e32 v45, v51, v54
	v_fma_f32 v44, v50, v54, -v42
	v_fmac_f32_e32 v45, v50, v21
	v_mov_b32_e32 v21, 0xad40000
	v_mov_b32_e32 v42, 0xa640000
	s_movk_i32 s1, 0xfc80
	v_cndmask_b32_e64 v196, v21, v42, s[6:7]
	v_mad_u64_u32 v[6:7], s[6:7], v4, s1, v[6:7]
	v_mov_b32_e32 v42, v7
	v_mad_u64_u32 v[42:43], s[6:7], v5, s1, v[42:43]
	v_sub_u32_e32 v7, v42, v4
	v_lshl_add_u64 v[4:5], v[6:7], 0, v[196:197]
	v_mov_b32_e32 v21, v197
	v_lshl_add_u64 v[4:5], v[4:5], 0, v[20:21]
	global_store_dword v[4:5], v44, off
	global_store_dword v[4:5], v45, off offset:64
	v_bfe_u32 v4, v44, 16, 1
	s_movk_i32 s1, 0x7fff
	v_add3_u32 v6, v44, v4, s1
	v_lshlrev_b64 v[4:5], 6, v[48:49]
	v_lshl_add_u64 v[4:5], v[28:29], 0, v[4:5]
	global_store_short_d16_hi v[4:5], v6, off
	v_bfe_u32 v6, v45, 16, 1
	v_add3_u32 v6, v45, v6, s1
	global_store_short_d16_hi v[4:5], v6, off offset:32
	s_branch .LBB0_1249

; #define TIDX() tidx_from(wave_s_)
; __device__ __forceinline__ int BIDX() { int v = blockIdx.x; asm volatile("" : "+s"(v)); return v; }
; __device__ __forceinline__ int GDIM() { int v = gridDim.x; asm volatile("" : "+s"(v)); return v; }
; __device__ __forceinline__ ArgsP get_args() { ArgsP p = (ArgsP)__builtin_amdgcn_kernarg_segment_ptr(); asm volatile("" : "+s"(p)); return p; }
; __device__ __forceinline__ void zero16(void* p_, int n16, int gtid, int gthreads) { unsigned z = 0u; asm volatile("" : "+v"(z)); for (int i = gtid; i < n16; i += gthreads) ((u32x4*)p_)[i] = (u32x4){z, z, z, z}; }
; __global__ void __launch_bounds__(NT, 2) fwd_megakernel(Args a_unused) {
;     ...
;             {   ArgsP a = get_args(); unsigned char* ws = a->ws; const int gtid = BIDX() * NT + TIDX(), gthreads = GDIM() * NT;
;                 zero16(ws + WS_KC + (size_t)RKV * 1024 * 2, 64 * 1024 * 2 / 16, gtid, gthreads); zero16(ws + WS_VC + (size_t)RKV * 1024 * 2, 64 * 1024 * 2 / 16, gtid, gthreads); }
.LBB0_1313:
	v_add_u32_e32 v8, s6, v8
	v_cmp_lt_i32_e64 s[4:5], s67, v8
	global_store_dwordx4 v[6:7], v[0:3], off sc0 sc1
	s_or_b64 s[14:15], s[4:5], s[14:15]
	v_lshl_add_u64 v[6:7], v[6:7], 0, s[12:13]
	s_andn2_b64 exec, exec, s[14:15]
	s_cbranch_execnz .LBB0_1313

; #define TIDX() tidx_from(wave_s_)
; __device__ __forceinline__ int BIDX() { int v = blockIdx.x; asm volatile("" : "+s"(v)); return v; }
; __device__ __forceinline__ int GDIM() { int v = gridDim.x; asm volatile("" : "+s"(v)); return v; }
; __device__ __forceinline__ ArgsP get_args() { ArgsP p = (ArgsP)__builtin_amdgcn_kernarg_segment_ptr(); asm volatile("" : "+s"(p)); return p; }
; __device__ __forceinline__ void zero16(void* p_, int n16, int gtid, int gthreads) { unsigned z = 0u; asm volatile("" : "+v"(z)); for (int i = gtid; i < n16; i += gthreads) ((u32x4*)p_)[i] = (u32x4){z, z, z, z}; }
; __global__ void __launch_bounds__(NT, 2) fwd_megakernel(Args a_unused) {
;     ...
;             {   ArgsP a = get_args(); unsigned char* ws = a->ws; const int gtid = BIDX() * NT + TIDX(), gthreads = GDIM() * NT;
;                 zero16(ws + WS_KC + (size_t)RKV * 1024 * 2, 64 * 1024 * 2 / 16, gtid, gthreads); zero16(ws + WS_VC + (size_t)RKV * 1024 * 2, 64 * 1024 * 2 / 16, gtid, gthreads); }
.LBB0_1316:
	v_add_u32_e32 v4, s6, v4
	v_cmp_lt_i32_e32 vcc, s67, v4
	global_store_dwordx4 v[6:7], v[0:3], off sc0 sc1
	s_or_b64 s[10:11], vcc, s[10:11]
	v_lshl_add_u64 v[6:7], v[6:7], 0, s[8:9]
	s_andn2_b64 exec, exec, s[10:11]
	s_cbranch_execnz .LBB0_1316

; __device__ __forceinline__ u32x4 pack8(const f32x4& a, const f32x4& b) { u32x4 w; w.x = cvt_pk_bf16(a[0], a[1]); w.y = cvt_pk_bf16(a[2], a[3]); w.z = cvt_pk_bf16(b[0], b[1]); w.w = cvt_pk_bf16(b[2], b[3]); return w; }
;     __device__ __forceinline__ void operator()(const f32x4 (&acc)[2][2][4][2], const Unit& u, int wr, int wc, int fr, int fq) const {
;         { int l_; asm volatile("v_mbcnt_lo_u32_b32 %0, -1, 0\n\tv_mbcnt_hi_u32_b32 %0, -1, %0" : "=v"(l_)); fr = l_ & 15; fq = (l_ >> 4) & 3; }
;         const int row0 = u.pm * BM + wr * 64 + fr, col0 = u.pn * BM + wc * 32 + 8 * fq;
; #pragma unroll
;         for (int ai = 0; ai < 2; ++ai)
; #pragma unroll
;             for (int m = 0; m < 4; ++m) { bf16_t* xp = C + (size_t)(row0 + ai * HALF + m * 16) * ldc + col0;
; #pragma unroll
;                 for (int bj = 0; bj < 2; ++bj) *(u32x4*)(xp + bj * HALF) = pack8(acc[ai][bj][m][0], acc[ai][bj][m][1]); }
;     }
.LBB0_1341:
	s_lshl_b32 s16, s43, 8
	v_mbcnt_lo_u32_b32 v138, -1, 0
	v_mbcnt_hi_u32_b32 v138, -1, v138
	s_add_i32 s16, s16, s35
	v_and_or_b32 v146, v138, 15, s16
	s_lshl_b32 s16, s44, 8
	v_lshrrev_b32_e32 v138, 1, v138
	v_and_or_b32 v138, v138, 24, s16
	v_or_b32_e32 v140, s36, v138
	v_ashrrev_i32_e32 v141, 31, v140
	v_mov_b64_e32 v[138:139], s[10:11]
	s_movk_i32 s18, 0xc00
	v_mad_i64_i32 v[144:145], s[16:17], v146, s18, v[138:139]
	v_lshlrev_b64 v[140:141], 1, v[140:141]
	v_lshl_add_u64 v[144:145], v[144:145], 0, v[140:141]
	v_cvt_pk_bf16_f32 v124, v124, v125
	v_cvt_pk_bf16_f32 v125, v126, v127
	v_cvt_pk_bf16_f32 v126, v120, v121
	v_cvt_pk_bf16_f32 v127, v122, v123
	global_store_dwordx4 v[144:145], v[124:127], off sc0 sc1
	v_cvt_pk_bf16_f32 v112, v112, v113
	v_cvt_pk_bf16_f32 v113, v114, v115
	v_cvt_pk_bf16_f32 v114, v104, v105
	v_or_b32_e32 v104, 16, v146
	v_mad_i64_i32 v[104:105], s[16:17], v104, s18, v[138:139]
	v_cvt_pk_bf16_f32 v115, v106, v107
	global_store_dwordx4 v[144:145], v[112:115], off offset:256 sc0 sc1
	s_and_b64 vcc, exec, s[4:5]
	s_mov_b64 s[4:5], -1
	v_lshl_add_u64 v[112:113], v[104:105], 0, v[140:141]
	v_cvt_pk_bf16_f32 v104, v116, v117
	v_cvt_pk_bf16_f32 v105, v118, v119
	v_cvt_pk_bf16_f32 v106, v108, v109
	v_cvt_pk_bf16_f32 v107, v110, v111
	global_store_dwordx4 v[112:113], v[104:107], off sc0 sc1
	v_cvt_pk_bf16_f32 v96, v96, v97
	v_cvt_pk_bf16_f32 v97, v98, v99
	v_cvt_pk_bf16_f32 v98, v88, v89
	v_or_b32_e32 v88, 32, v146
	v_mad_i64_i32 v[88:89], s[16:17], v88, s18, v[138:139]
	v_cvt_pk_bf16_f32 v99, v90, v91
	global_store_dwordx4 v[112:113], v[96:99], off offset:256 sc0 sc1
	s_nop 1
	v_lshl_add_u64 v[96:97], v[88:89], 0, v[140:141]
	v_cvt_pk_bf16_f32 v88, v100, v101
	v_cvt_pk_bf16_f32 v89, v102, v103
	v_cvt_pk_bf16_f32 v90, v92, v93
	v_cvt_pk_bf16_f32 v91, v94, v95
	global_store_dwordx4 v[96:97], v[88:91], off sc0 sc1
	v_cvt_pk_bf16_f32 v80, v80, v81
	v_cvt_pk_bf16_f32 v81, v82, v83
	v_cvt_pk_bf16_f32 v82, v72, v73
	v_or_b32_e32 v72, 48, v146
	v_mad_i64_i32 v[72:73], s[16:17], v72, s18, v[138:139]
	v_cvt_pk_bf16_f32 v83, v74, v75
	global_store_dwordx4 v[96:97], v[80:83], off offset:256 sc0 sc1
	s_nop 1
	v_lshl_add_u64 v[80:81], v[72:73], 0, v[140:141]
	v_cvt_pk_bf16_f32 v72, v84, v85
	v_cvt_pk_bf16_f32 v73, v86, v87
	v_cvt_pk_bf16_f32 v74, v76, v77
	v_cvt_pk_bf16_f32 v75, v78, v79
	global_store_dwordx4 v[80:81], v[72:75], off sc0 sc1
	v_cvt_pk_bf16_f32 v68, v68, v69
	v_cvt_pk_bf16_f32 v69, v70, v71
	v_cvt_pk_bf16_f32 v70, v64, v65
	v_add_u32_e32 v64, 0x80, v146
	v_mad_i64_i32 v[64:65], s[16:17], v64, s18, v[138:139]
	v_lshl_add_u64 v[64:65], v[64:65], 0, v[140:141]
	v_cvt_pk_bf16_f32 v71, v66, v67
	global_store_dwordx4 v[80:81], v[68:71], off offset:256 sc0 sc1
	v_cvt_pk_bf16_f32 v60, v60, v61
	v_cvt_pk_bf16_f32 v61, v62, v63
	v_cvt_pk_bf16_f32 v62, v56, v57
	v_cvt_pk_bf16_f32 v63, v58, v59
	global_store_dwordx4 v[64:65], v[60:63], off sc0 sc1
	v_cvt_pk_bf16_f32 v48, v48, v49
	v_cvt_pk_bf16_f32 v49, v50, v51
	v_cvt_pk_bf16_f32 v50, v40, v41
	v_add_u32_e32 v40, 0x90, v146
	v_mad_i64_i32 v[40:41], s[16:17], v40, s18, v[138:139]
	v_cvt_pk_bf16_f32 v51, v42, v43
	global_store_dwordx4 v[64:65], v[48:51], off offset:256 sc0 sc1
	s_nop 1
	v_lshl_add_u64 v[48:49], v[40:41], 0, v[140:141]
	v_cvt_pk_bf16_f32 v40, v52, v53
	v_cvt_pk_bf16_f32 v41, v54, v55
	v_cvt_pk_bf16_f32 v42, v44, v45
	v_cvt_pk_bf16_f32 v43, v46, v47
	global_store_dwordx4 v[48:49], v[40:43], off sc0 sc1
	v_cvt_pk_bf16_f32 v32, v32, v33
	v_cvt_pk_bf16_f32 v33, v34, v35
	v_cvt_pk_bf16_f32 v34, v24, v25
	v_add_u32_e32 v24, 0xa0, v146
	v_mad_i64_i32 v[24:25], s[16:17], v24, s18, v[138:139]
	v_cvt_pk_bf16_f32 v35, v26, v27
	global_store_dwordx4 v[48:49], v[32:35], off offset:256 sc0 sc1
	s_nop 1
	v_lshl_add_u64 v[32:33], v[24:25], 0, v[140:141]
	v_cvt_pk_bf16_f32 v24, v36, v37
	v_cvt_pk_bf16_f32 v25, v38, v39
	v_cvt_pk_bf16_f32 v26, v28, v29
	v_cvt_pk_bf16_f32 v27, v30, v31
	global_store_dwordx4 v[32:33], v[24:27], off sc0 sc1
	v_cvt_pk_bf16_f32 v16, v16, v17
	v_cvt_pk_bf16_f32 v17, v18, v19
	v_cvt_pk_bf16_f32 v18, v8, v9
	v_add_u32_e32 v8, 0xb0, v146
	v_mad_i64_i32 v[8:9], s[16:17], v8, s18, v[138:139]
	v_cvt_pk_bf16_f32 v19, v10, v11
	global_store_dwordx4 v[32:33], v[16:19], off offset:256 sc0 sc1
	s_nop 1
	v_lshl_add_u64 v[16:17], v[8:9], 0, v[140:141]
	v_cvt_pk_bf16_f32 v8, v20, v21
	v_cvt_pk_bf16_f32 v9, v22, v23
	v_cvt_pk_bf16_f32 v10, v12, v13
	v_cvt_pk_bf16_f32 v11, v14, v15
	global_store_dwordx4 v[16:17], v[8:11], off sc0 sc1
	v_cvt_pk_bf16_f32 v4, v4, v5
	v_cvt_pk_bf16_f32 v5, v6, v7
	v_cvt_pk_bf16_f32 v6, v0, v1
	v_cvt_pk_bf16_f32 v7, v2, v3
	global_store_dwordx4 v[16:17], v[4:7], off offset:256 sc0 sc1
	s_cbranch_vccnz .LBB0_1326
	s_andn2_b64 vcc, exec, s[8:9]
	s_cbranch_vccnz .LBB0_1325
	s_barrier
	s_branch .LBB0_1325

; __device__ __forceinline__ u32x4 pack8(const f32x4& a, const f32x4& b) { u32x4 w; w.x = cvt_pk_bf16(a[0], a[1]); w.y = cvt_pk_bf16(a[2], a[3]); w.z = cvt_pk_bf16(b[0], b[1]); w.w = cvt_pk_bf16(b[2], b[3]); return w; }
;     __device__ __forceinline__ void operator()(const f32x4 (&acc)[2][2][4][2], const Unit& u, int wr, int wc, int fr, int fq) const {
;         { int l_; asm volatile("v_mbcnt_lo_u32_b32 %0, -1, 0\n\tv_mbcnt_hi_u32_b32 %0, -1, %0" : "=v"(l_)); fr = l_ & 15; fq = (l_ >> 4) & 3; }
;         const int row0 = u.pm * BM + wr * 64 + fr;
; #pragma unroll
;         for (int bj = 0; bj < 2; ++bj) {
;             const int head = (u.pn * BM + bj * HALF) >> 7; bf16_t* dst = (wc < 2 ? KC : VC) + head * 64 + (wc & 1) * 32 + 8 * fq;
; #pragma unroll
;             for (int ai = 0; ai < 2; ++ai)
; #pragma unroll
;                 for (int m = 0; m < 4; ++m) *(u32x4*)(dst + (size_t)(row0 + ai * HALF + m * 16) * 1024) = pack8(acc[ai][bj][m][0], acc[ai][bj][m][1]);
;         }
;     }
.LBB0_1361:
	s_lshl_b32 s16, s54, 7
	s_lshl_b32 s13, s53, 8
	s_ashr_i32 s17, s16, 31
	s_add_i32 s13, s13, s45
	s_lshl_b64 s[16:17], s[16:17], 1
	v_mbcnt_lo_u32_b32 v139, -1, 0
	v_mbcnt_hi_u32_b32 v139, -1, v139
	s_add_u32 s16, s50, s16
	v_and_or_b32 v138, v139, 15, s13
	s_addc_u32 s17, s51, s17
	v_and_b32_e32 v196, 48, v139
	v_ashrrev_i32_e32 v139, 31, v138
	v_lshl_add_u64 v[140:141], s[16:17], 0, v[196:197]
	v_cvt_pk_bf16_f32 v124, v124, v125
	v_cvt_pk_bf16_f32 v125, v126, v127
	v_cvt_pk_bf16_f32 v126, v120, v121
	v_lshlrev_b64 v[120:121], 11, v[138:139]
	v_lshl_add_u64 v[120:121], v[140:141], 0, v[120:121]
	v_cvt_pk_bf16_f32 v127, v122, v123
	global_store_dwordx4 v[120:121], v[124:127], off sc0 sc1
	v_cvt_pk_bf16_f32 v116, v116, v117
	v_cvt_pk_bf16_f32 v117, v118, v119
	v_cvt_pk_bf16_f32 v118, v112, v113
	v_or_b32_e32 v112, 16, v138
	v_ashrrev_i32_e32 v113, 31, v112
	v_lshlrev_b64 v[112:113], 11, v[112:113]
	v_lshl_add_u64 v[112:113], v[140:141], 0, v[112:113]
	v_cvt_pk_bf16_f32 v119, v114, v115
	global_store_dwordx4 v[112:113], v[116:119], off sc0 sc1
	v_cvt_pk_bf16_f32 v108, v108, v109
	v_cvt_pk_bf16_f32 v109, v110, v111
	v_cvt_pk_bf16_f32 v110, v104, v105
	v_or_b32_e32 v104, 32, v138
	v_ashrrev_i32_e32 v105, 31, v104
	v_lshlrev_b64 v[104:105], 11, v[104:105]
	v_lshl_add_u64 v[104:105], v[140:141], 0, v[104:105]
	v_cvt_pk_bf16_f32 v111, v106, v107
	global_store_dwordx4 v[104:105], v[108:111], off sc0 sc1
	v_cvt_pk_bf16_f32 v100, v100, v101
	v_cvt_pk_bf16_f32 v101, v102, v103
	v_cvt_pk_bf16_f32 v102, v96, v97
	v_or_b32_e32 v96, 48, v138
	v_ashrrev_i32_e32 v97, 31, v96
	v_lshlrev_b64 v[96:97], 11, v[96:97]
	v_lshl_add_u64 v[96:97], v[140:141], 0, v[96:97]
	s_mov_b32 s13, 0x40000
	v_cvt_pk_bf16_f32 v103, v98, v99
	global_store_dwordx4 v[96:97], v[100:103], off sc0 sc1
	v_cvt_pk_bf16_f32 v92, v92, v93
	v_cvt_pk_bf16_f32 v93, v94, v95
	v_cvt_pk_bf16_f32 v94, v88, v89
	v_cvt_pk_bf16_f32 v95, v90, v91
	v_add_co_u32_e32 v90, vcc, s13, v120
	s_mov_b32 s13, 0x48000
	s_nop 0
	v_addc_co_u32_e32 v91, vcc, 0, v121, vcc
	global_store_dwordx4 v[90:91], v[92:95], off sc0 sc1
	v_cvt_pk_bf16_f32 v84, v84, v85
	v_cvt_pk_bf16_f32 v85, v86, v87
	v_cvt_pk_bf16_f32 v86, v80, v81
	v_cvt_pk_bf16_f32 v87, v82, v83
	v_add_co_u32_e32 v82, vcc, s13, v120
	s_mov_b32 s13, 0x50000
	s_nop 0
	v_addc_co_u32_e32 v83, vcc, 0, v121, vcc
	s_mov_b64 s[16:17], 0x40000
	global_store_dwordx4 v[82:83], v[84:87], off sc0 sc1
	v_cvt_pk_bf16_f32 v72, v72, v73
	v_cvt_pk_bf16_f32 v73, v74, v75
	v_cvt_pk_bf16_f32 v74, v64, v65
	v_cvt_pk_bf16_f32 v75, v66, v67
	v_add_co_u32_e32 v66, vcc, s13, v120
	v_lshl_add_u64 v[88:89], v[120:121], 0, s[16:17]
	s_mov_b64 s[16:17], 0x48000
	v_addc_co_u32_e32 v67, vcc, 0, v121, vcc
	s_mov_b32 s13, 0x58000
	v_lshl_add_u64 v[80:81], v[120:121], 0, s[16:17]
	s_mov_b64 s[16:17], 0x50000
	global_store_dwordx4 v[66:67], v[72:75], off sc0 sc1
	v_cvt_pk_bf16_f32 v56, v56, v57
	v_cvt_pk_bf16_f32 v57, v58, v59
	v_cvt_pk_bf16_f32 v58, v48, v49
	v_add_co_u32_e32 v48, vcc, s13, v120
	v_lshl_add_u64 v[64:65], v[120:121], 0, s[16:17]
	s_mov_b64 s[16:17], 0x58000
	v_addc_co_u32_e32 v49, vcc, 0, v121, vcc
	v_cvt_pk_bf16_f32 v59, v50, v51
	v_lshl_add_u64 v[66:67], v[120:121], 0, s[16:17]
	global_store_dwordx4 v[48:49], v[56:59], off sc0 sc1
	v_cvt_pk_bf16_f32 v48, v76, v77
	v_cvt_pk_bf16_f32 v49, v78, v79
	v_cvt_pk_bf16_f32 v50, v68, v69
	v_cvt_pk_bf16_f32 v51, v70, v71
	s_and_b64 vcc, exec, s[4:5]
	s_mov_b64 s[4:5], -1
	global_store_dwordx4 v[120:121], v[48:51], off offset:128 sc0 sc1
	s_nop 1
	v_cvt_pk_bf16_f32 v48, v60, v61
	v_cvt_pk_bf16_f32 v49, v62, v63
	v_cvt_pk_bf16_f32 v50, v52, v53
	v_cvt_pk_bf16_f32 v51, v54, v55
	global_store_dwordx4 v[112:113], v[48:51], off offset:128 sc0 sc1
	v_cvt_pk_bf16_f32 v44, v44, v45
	v_cvt_pk_bf16_f32 v45, v46, v47
	v_cvt_pk_bf16_f32 v46, v40, v41
	v_cvt_pk_bf16_f32 v47, v42, v43
	global_store_dwordx4 v[104:105], v[44:47], off offset:128 sc0 sc1
	v_cvt_pk_bf16_f32 v36, v36, v37
	v_cvt_pk_bf16_f32 v37, v38, v39
	v_cvt_pk_bf16_f32 v38, v32, v33
	v_cvt_pk_bf16_f32 v39, v34, v35
	global_store_dwordx4 v[96:97], v[36:39], off offset:128 sc0 sc1
	v_cvt_pk_bf16_f32 v28, v28, v29
	v_cvt_pk_bf16_f32 v29, v30, v31
	v_cvt_pk_bf16_f32 v30, v24, v25
	v_cvt_pk_bf16_f32 v31, v26, v27
	global_store_dwordx4 v[88:89], v[28:31], off offset:128 sc0 sc1
	v_cvt_pk_bf16_f32 v20, v20, v21
	v_cvt_pk_bf16_f32 v21, v22, v23
	v_cvt_pk_bf16_f32 v22, v16, v17
	v_cvt_pk_bf16_f32 v23, v18, v19
	global_store_dwordx4 v[80:81], v[20:23], off offset:128 sc0 sc1
	v_cvt_pk_bf16_f32 v12, v12, v13
	v_cvt_pk_bf16_f32 v13, v14, v15
	v_cvt_pk_bf16_f32 v14, v8, v9
	v_cvt_pk_bf16_f32 v15, v10, v11
	global_store_dwordx4 v[64:65], v[12:15], off offset:128 sc0 sc1
	v_cvt_pk_bf16_f32 v4, v4, v5
	v_cvt_pk_bf16_f32 v5, v6, v7
	v_cvt_pk_bf16_f32 v6, v0, v1
	v_cvt_pk_bf16_f32 v7, v2, v3
	global_store_dwordx4 v[66:67], v[4:7], off offset:128 sc0 sc1
	s_cbranch_vccnz .LBB0_1350
	s_andn2_b64 vcc, exec, s[8:9]
	s_cbranch_vccnz .LBB0_1349
	s_barrier
	s_branch .LBB0_1349

;     __device__ __forceinline__ void operator()(const f32x4 (&acc)[2][2][4][2], const Unit& u, int wr, int wc, int fr, int fq) const {
;     ...
;         const int slice = u.pm >> 12, row0 = (u.pm & 4095) * BM + wr * 64 + fr, col0 = u.pn * BM + wc * 32 + 4 * fq;
;         const float* mods = (const float*)(ws + WS_MODS) + (size_t)(goff_l >> 16) * NSEQ * NMOD; const int goff = goff_l & 0xffff; float* PART = (float*)(ws + WS_PART);
; #pragma unroll
;         for (int ai = 0; ai < 2; ++ai)
; #pragma unroll
;             for (int mp = 0; mp < 4; mp += 2) {
;                 f32x4 gv[2][4], xv[2][4];
; #pragma unroll
;                 for (int mm = 0; mm < 2; ++mm) {
;                     const int row = row0 + ai * HALF + (mp + mm) * 16; const float* gp = mods + (size_t)cidx_of(row) * NMOD + goff + col0;
;                     const float* xs = ((Xin && row < NPROMPT) ? Xin + (size_t)row * DM : X + (size_t)row * DM) + col0;
; #pragma unroll
;                     for (int q4 = 0; q4 < 4; ++q4) { const int co = (q4 >> 1) * HALF + (q4 & 1) * 16; gv[mm][q4] = *(const f32x4*)(gp + co); if (!slice) xv[mm][q4] = *(const f32x4*)(xs + co); }
;                 }
; #pragma unroll
;                 for (int mm = 0; mm < 2; ++mm) {
;                     const int row = row0 + ai * HALF + (mp + mm) * 16;
; #pragma unroll
;                     for (int q4 = 0; q4 < 4; ++q4) { const int co = (q4 >> 1) * HALF + (q4 & 1) * 16; const f32x4 d = (gv[mm][q4] * fac) * acc[ai][q4 >> 1][mp + mm][q4 & 1];
;                         if (slice) *(f32x4*)(PART + ((size_t)(slice - 1) * NSAMP + (row - NPROMPT)) * DM + col0 + co) = d;
;                         else *(f32x4*)(X + (size_t)row * DM + col0 + co) = xv[mm][q4] + d; }
;                 }
;                 asm volatile("" ::: "memory");
;             }
.LBB0_1594:
	s_ashr_i32 s8, s54, 12
	s_ashr_i32 s9, s8, 31
	s_lshl_b64 s[8:9], s[8:9], 21
	s_add_u32 s8, s50, s8
	s_addc_u32 s9, s51, s9
	v_lshl_add_u64 v[198:199], v[212:213], 2, s[8:9]
	s_mov_b32 s8, 0xffe00000
	s_mov_b32 s9, -1
	s_waitcnt vmcnt(0)
	v_pk_mul_f32 v[156:157], v[156:157], v[188:189]
	v_cndmask_b32_e64 v188, 0, 1, s[26:27]
	v_lshl_add_u64 v[208:209], v[198:199], 0, s[8:9]
	v_pk_mul_f32 v[158:159], v[158:159], v[190:191]
	v_cmp_ne_u32_e64 s[8:9], 1, v188
	s_andn2_b64 vcc, exec, s[26:27]
	s_mov_b64 s[26:27], -1
	s_cbranch_vccnz .LBB0_1596
	v_ashrrev_i32_e32 v223, 31, v222
	v_lshlrev_b64 v[188:189], 12, v[222:223]
	v_lshl_add_u64 v[188:189], v[208:209], 0, v[188:189]
	s_mov_b64 s[26:27], 0
	global_store_dwordx4 v[188:189], v[156:159], off sc0 sc1
.LBB0_1596:
	s_andn2_b64 vcc, exec, s[26:27]
	s_cbranch_vccnz .LBB0_1598
	v_pk_add_f32 v[158:159], v[158:159], v[122:123]
	v_pk_add_f32 v[156:157], v[156:157], v[120:121]
	v_mov_b64_e32 v[188:189], v[220:221]
	global_store_dwordx4 v[220:221], v[156:159], off sc0 sc1
.LBB0_1598:
	s_nop 1
	v_pk_mul_f32 v[156:157], v[154:155], v[186:187]
	v_pk_mul_f32 v[158:159], v[152:153], v[184:185]
	v_pk_fma_f32 v[154:155], v[154:155], v[186:187], v[118:119]
	v_pk_fma_f32 v[152:153], v[152:153], v[184:185], v[116:117]
	v_cndmask_b32_e64 v155, v157, v155, s[6:7]
	v_cndmask_b32_e64 v154, v156, v154, s[6:7]
	v_cndmask_b32_e64 v153, v159, v153, s[6:7]
	v_cndmask_b32_e64 v152, v158, v152, s[6:7]
	global_store_dwordx4 v[188:189], v[152:155], off offset:64 sc0 sc1
	s_and_b64 vcc, exec, s[8:9]
	s_mov_b64 s[26:27], -1
	v_pk_mul_f32 v[152:153], v[150:151], v[178:179]
	v_pk_mul_f32 v[154:155], v[148:149], v[176:177]
	v_pk_fma_f32 v[150:151], v[150:151], v[178:179], v[114:115]
	v_pk_fma_f32 v[148:149], v[148:149], v[176:177], v[112:113]
	v_cndmask_b32_e64 v151, v153, v151, s[6:7]
	v_cndmask_b32_e64 v150, v152, v150, s[6:7]
	v_cndmask_b32_e64 v149, v155, v149, s[6:7]
	v_cndmask_b32_e64 v148, v154, v148, s[6:7]
	global_store_dwordx4 v[188:189], v[148:151], off offset:512 sc0 sc1
	s_nop 1
	v_pk_mul_f32 v[148:149], v[142:143], v[174:175]
	v_pk_mul_f32 v[150:151], v[140:141], v[172:173]
	v_pk_fma_f32 v[142:143], v[142:143], v[174:175], v[110:111]
	v_pk_fma_f32 v[140:141], v[140:141], v[172:173], v[108:109]
	v_cndmask_b32_e64 v143, v149, v143, s[6:7]
	v_cndmask_b32_e64 v142, v148, v142, s[6:7]
	v_cndmask_b32_e64 v141, v151, v141, s[6:7]
	v_cndmask_b32_e64 v140, v150, v140, s[6:7]
	global_store_dwordx4 v[188:189], v[140:143], off offset:576 sc0 sc1
	s_nop 1
	v_pk_mul_f32 v[142:143], v[146:147], v[182:183]
	v_pk_mul_f32 v[140:141], v[144:145], v[180:181]
	s_cbranch_vccnz .LBB0_1600
	v_ashrrev_i32_e32 v219, 31, v218
	v_lshlrev_b64 v[144:145], 12, v[218:219]
	v_lshl_add_u64 v[144:145], v[208:209], 0, v[144:145]
	s_mov_b64 s[26:27], 0
	global_store_dwordx4 v[144:145], v[140:143], off sc0 sc1
.LBB0_1600:
	s_andn2_b64 vcc, exec, s[26:27]
	s_cbranch_vccnz .LBB0_1602
	v_pk_add_f32 v[142:143], v[142:143], v[102:103]
	v_pk_add_f32 v[140:141], v[140:141], v[100:101]
	v_mov_b64_e32 v[144:145], v[216:217]
	global_store_dwordx4 v[216:217], v[140:143], off sc0 sc1
.LBB0_1602:
	s_nop 1
	v_pk_mul_f32 v[140:141], v[138:139], v[170:171]
	v_pk_mul_f32 v[142:143], v[136:137], v[168:169]
	v_pk_fma_f32 v[138:139], v[138:139], v[170:171], v[98:99]
	v_pk_fma_f32 v[136:137], v[136:137], v[168:169], v[96:97]
	v_cndmask_b32_e64 v139, v141, v139, s[6:7]
	v_cndmask_b32_e64 v138, v140, v138, s[6:7]
	v_cndmask_b32_e64 v137, v143, v137, s[6:7]
	v_cndmask_b32_e64 v136, v142, v136, s[6:7]
	global_store_dwordx4 v[144:145], v[136:139], off offset:64 sc0 sc1
	s_nop 1
	v_pk_mul_f32 v[136:137], v[134:135], v[166:167]
	v_pk_mul_f32 v[138:139], v[132:133], v[164:165]
	v_pk_fma_f32 v[134:135], v[134:135], v[166:167], v[94:95]
	v_pk_fma_f32 v[132:133], v[132:133], v[164:165], v[92:93]
	v_cndmask_b32_e64 v135, v137, v135, s[6:7]
	v_cndmask_b32_e64 v134, v136, v134, s[6:7]
	v_cndmask_b32_e64 v133, v139, v133, s[6:7]
	v_cndmask_b32_e64 v132, v138, v132, s[6:7]
	global_store_dwordx4 v[144:145], v[132:135], off offset:512 sc0 sc1
	v_add_u32_e32 v166, 0xffff8020, v210
	s_nop 0
	v_pk_mul_f32 v[132:133], v[130:131], v[162:163]
	v_pk_mul_f32 v[134:135], v[128:129], v[160:161]
	v_pk_fma_f32 v[130:131], v[130:131], v[162:163], v[90:91]
	v_pk_fma_f32 v[128:129], v[128:129], v[160:161], v[88:89]
	v_cndmask_b32_e64 v131, v133, v131, s[6:7]
	v_cndmask_b32_e64 v130, v132, v130, s[6:7]
	v_cndmask_b32_e64 v129, v135, v129, s[6:7]
	v_cndmask_b32_e64 v128, v134, v128, s[6:7]
	global_store_dwordx4 v[144:145], v[128:131], off offset:576 sc0 sc1
	s_nop 1
	v_or_b32_e32 v130, 32, v210
	v_lshrrev_b32_e32 v128, 5, v166
	v_add_u32_e32 v128, 2, v128
	v_mov_b32_e32 v129, s21
	v_cmp_gt_i32_e32 vcc, s0, v130
	v_ashrrev_i32_e32 v131, 31, v130
	v_lshlrev_b64 v[130:131], 12, v[130:131]
	v_cndmask_b32_e32 v128, v128, v129, vcc
	v_mad_i64_i32 v[128:129], s[26:27], v128, s80, v[214:215]
	global_load_dwordx4 v[156:159], v[128:129], off
	v_lshl_add_u64 v[130:131], s[12:13], 0, v[130:131]
	s_and_b64 vcc, exec, s[10:11]
	v_lshl_add_u64 v[164:165], v[212:213], 2, v[130:131]
	s_cbranch_vccz .LBB0_1665
	global_load_dwordx4 v[152:155], v[128:129], off offset:64
	s_and_b64 vcc, exec, s[10:11]
	s_cbranch_vccz .LBB0_1666

;     __device__ __forceinline__ void operator()(const f32x4 (&acc)[2][2][4][2], const Unit& u, int wr, int wc, int fr, int fq) const {
;     ...
;         const int slice = u.pm >> 12, row0 = (u.pm & 4095) * BM + wr * 64 + fr, col0 = u.pn * BM + wc * 32 + 4 * fq;
;         const float* mods = (const float*)(ws + WS_MODS) + (size_t)(goff_l >> 16) * NSEQ * NMOD; const int goff = goff_l & 0xffff; float* PART = (float*)(ws + WS_PART);
; #pragma unroll
;         for (int ai = 0; ai < 2; ++ai)
; #pragma unroll
;             for (int mp = 0; mp < 4; mp += 2) {
;                 f32x4 gv[2][4], xv[2][4];
; #pragma unroll
;                 for (int mm = 0; mm < 2; ++mm) {
;                     const int row = row0 + ai * HALF + (mp + mm) * 16; const float* gp = mods + (size_t)cidx_of(row) * NMOD + goff + col0;
;                     const float* xs = ((Xin && row < NPROMPT) ? Xin + (size_t)row * DM : X + (size_t)row * DM) + col0;
; #pragma unroll
;                     for (int q4 = 0; q4 < 4; ++q4) { const int co = (q4 >> 1) * HALF + (q4 & 1) * 16; gv[mm][q4] = *(const f32x4*)(gp + co); if (!slice) xv[mm][q4] = *(const f32x4*)(xs + co); }
;                 }
; #pragma unroll
;                 for (int mm = 0; mm < 2; ++mm) {
;                     const int row = row0 + ai * HALF + (mp + mm) * 16;
; #pragma unroll
;                     for (int q4 = 0; q4 < 4; ++q4) { const int co = (q4 >> 1) * HALF + (q4 & 1) * 16; const f32x4 d = (gv[mm][q4] * fac) * acc[ai][q4 >> 1][mp + mm][q4 & 1];
;                         if (slice) *(f32x4*)(PART + ((size_t)(slice - 1) * NSAMP + (row - NPROMPT)) * DM + col0 + co) = d;
;                         else *(f32x4*)(X + (size_t)row * DM + col0 + co) = xv[mm][q4] + d; }
;                 }
;                 asm volatile("" ::: "memory");
;             }
.LBB0_1612:
	s_waitcnt vmcnt(7)
	v_pk_mul_f32 v[126:127], v[126:127], v[158:159]
	v_pk_mul_f32 v[124:125], v[124:125], v[156:157]
	s_and_b64 vcc, exec, s[8:9]
	s_mov_b64 s[26:27], -1
	s_cbranch_vccnz .LBB0_1614
	v_ashrrev_i32_e32 v167, 31, v166
	v_lshlrev_b64 v[156:157], 12, v[166:167]
	v_lshl_add_u64 v[156:157], v[208:209], 0, v[156:157]
	s_mov_b64 s[26:27], 0
	global_store_dwordx4 v[156:157], v[124:127], off sc0 sc1
.LBB0_1614:
	s_andn2_b64 vcc, exec, s[26:27]
	s_cbranch_vccnz .LBB0_1616
	v_pk_add_f32 v[126:127], v[126:127], v[122:123]
	v_pk_add_f32 v[124:125], v[124:125], v[120:121]
	v_mov_b64_e32 v[156:157], v[164:165]
	global_store_dwordx4 v[164:165], v[124:127], off sc0 sc1
.LBB0_1616:
	s_waitcnt vmcnt(6)
	s_nop 0
	v_pk_mul_f32 v[124:125], v[106:107], v[154:155]
	v_pk_mul_f32 v[126:127], v[104:105], v[152:153]
	v_pk_fma_f32 v[106:107], v[106:107], v[154:155], v[118:119]
	v_pk_fma_f32 v[104:105], v[104:105], v[152:153], v[116:117]
	v_cndmask_b32_e64 v107, v125, v107, s[6:7]
	v_cndmask_b32_e64 v106, v124, v106, s[6:7]
	v_cndmask_b32_e64 v105, v127, v105, s[6:7]
	v_cndmask_b32_e64 v104, v126, v104, s[6:7]
	global_store_dwordx4 v[156:157], v[104:107], off offset:64 sc0 sc1
	s_and_b64 vcc, exec, s[8:9]
	s_mov_b64 s[26:27], -1
	s_waitcnt vmcnt(6)
	v_pk_mul_f32 v[104:105], v[86:87], v[146:147]
	v_pk_mul_f32 v[106:107], v[84:85], v[144:145]
	v_pk_fma_f32 v[86:87], v[86:87], v[146:147], v[114:115]
	v_pk_fma_f32 v[84:85], v[84:85], v[144:145], v[112:113]
	v_cndmask_b32_e64 v87, v105, v87, s[6:7]
	v_cndmask_b32_e64 v86, v104, v86, s[6:7]
	v_cndmask_b32_e64 v85, v107, v85, s[6:7]
	v_cndmask_b32_e64 v84, v106, v84, s[6:7]
	global_store_dwordx4 v[156:157], v[84:87], off offset:512 sc0 sc1
	s_waitcnt vmcnt(6)
	s_nop 0
	v_pk_mul_f32 v[84:85], v[78:79], v[142:143]
	v_pk_mul_f32 v[86:87], v[76:77], v[140:141]
	v_pk_fma_f32 v[78:79], v[78:79], v[142:143], v[110:111]
	v_pk_fma_f32 v[76:77], v[76:77], v[140:141], v[108:109]
	v_cndmask_b32_e64 v79, v85, v79, s[6:7]
	v_cndmask_b32_e64 v78, v84, v78, s[6:7]
	v_cndmask_b32_e64 v77, v87, v77, s[6:7]
	v_cndmask_b32_e64 v76, v86, v76, s[6:7]
	global_store_dwordx4 v[156:157], v[76:79], off offset:576 sc0 sc1
	s_waitcnt vmcnt(6)
	s_nop 0
	v_pk_mul_f32 v[78:79], v[82:83], v[150:151]
	v_pk_mul_f32 v[76:77], v[80:81], v[148:149]
	s_cbranch_vccnz .LBB0_1618
	v_ashrrev_i32_e32 v163, 31, v162
	v_lshlrev_b64 v[80:81], 12, v[162:163]
	v_lshl_add_u64 v[80:81], v[208:209], 0, v[80:81]
	s_mov_b64 s[26:27], 0
	global_store_dwordx4 v[80:81], v[76:79], off sc0 sc1
.LBB0_1618:
	s_andn2_b64 vcc, exec, s[26:27]
	s_cbranch_vccnz .LBB0_1620
	v_pk_add_f32 v[78:79], v[78:79], v[102:103]
	v_pk_add_f32 v[76:77], v[76:77], v[100:101]
	v_mov_b64_e32 v[80:81], v[160:161]
	global_store_dwordx4 v[160:161], v[76:79], off sc0 sc1
.LBB0_1620:
	s_waitcnt vmcnt(5)
	s_nop 0
	v_pk_mul_f32 v[76:77], v[74:75], v[138:139]
	v_pk_mul_f32 v[78:79], v[72:73], v[136:137]
	v_pk_fma_f32 v[74:75], v[74:75], v[138:139], v[98:99]
	v_pk_fma_f32 v[72:73], v[72:73], v[136:137], v[96:97]
	v_cndmask_b32_e64 v75, v77, v75, s[6:7]
	v_cndmask_b32_e64 v74, v76, v74, s[6:7]
	v_cndmask_b32_e64 v73, v79, v73, s[6:7]
	v_cndmask_b32_e64 v72, v78, v72, s[6:7]
	global_store_dwordx4 v[80:81], v[72:75], off offset:64 sc0 sc1
	s_movk_i32 s21, 0x7f80
	v_cmp_gt_i32_e32 vcc, s21, v210
	s_waitcnt vmcnt(5)
	v_pk_mul_f32 v[72:73], v[70:71], v[134:135]
	v_pk_mul_f32 v[74:75], v[68:69], v[132:133]
	v_pk_fma_f32 v[70:71], v[70:71], v[134:135], v[94:95]
	v_pk_fma_f32 v[68:69], v[68:69], v[132:133], v[92:93]
	v_cndmask_b32_e64 v71, v73, v71, s[6:7]
	v_cndmask_b32_e64 v70, v72, v70, s[6:7]
	v_cndmask_b32_e64 v69, v75, v69, s[6:7]
	v_cndmask_b32_e64 v68, v74, v68, s[6:7]
	global_store_dwordx4 v[80:81], v[68:71], off offset:512 sc0 sc1
	v_add_u32_e32 v134, 0xffff8080, v210
	s_waitcnt vmcnt(5)
	v_pk_mul_f32 v[68:69], v[66:67], v[130:131]
	v_pk_mul_f32 v[70:71], v[64:65], v[128:129]
	v_pk_fma_f32 v[66:67], v[66:67], v[130:131], v[90:91]
	v_pk_fma_f32 v[64:65], v[64:65], v[128:129], v[88:89]
	v_cndmask_b32_e64 v67, v69, v67, s[6:7]
	v_cndmask_b32_e64 v66, v68, v66, s[6:7]
	v_cndmask_b32_e64 v65, v71, v65, s[6:7]
	v_cndmask_b32_e64 v64, v70, v64, s[6:7]
	global_store_dwordx4 v[80:81], v[64:67], off offset:576 sc0 sc1
	s_nop 1
	v_add_u32_e32 v66, 0x80, v210
	v_lshrrev_b32_e32 v64, 5, v134
	v_ashrrev_i32_e32 v136, 14, v66
	v_add_u32_e32 v64, 2, v64
	v_cndmask_b32_e32 v64, v64, v136, vcc
	v_mad_i64_i32 v[64:65], s[26:27], v64, s80, v[214:215]
	global_load_dwordx4 v[124:127], v[64:65], off
	v_ashrrev_i32_e32 v67, 31, v66
	v_lshlrev_b64 v[66:67], 12, v[66:67]
	v_lshl_add_u64 v[66:67], s[12:13], 0, v[66:67]
	s_and_b64 vcc, exec, s[10:11]
	v_lshl_add_u64 v[132:133], v[212:213], 2, v[66:67]
	s_cbranch_vccz .LBB0_1671
	global_load_dwordx4 v[84:87], v[64:65], off offset:64
	s_and_b64 vcc, exec, s[10:11]
	s_cbranch_vccz .LBB0_1672

;     __device__ __forceinline__ void operator()(const f32x4 (&acc)[2][2][4][2], const Unit& u, int wr, int wc, int fr, int fq) const {
;     ...
;         const int slice = u.pm >> 12, row0 = (u.pm & 4095) * BM + wr * 64 + fr, col0 = u.pn * BM + wc * 32 + 4 * fq;
;         const float* mods = (const float*)(ws + WS_MODS) + (size_t)(goff_l >> 16) * NSEQ * NMOD; const int goff = goff_l & 0xffff; float* PART = (float*)(ws + WS_PART);
; #pragma unroll
;         for (int ai = 0; ai < 2; ++ai)
; #pragma unroll
;             for (int mp = 0; mp < 4; mp += 2) {
;                 f32x4 gv[2][4], xv[2][4];
; #pragma unroll
;                 for (int mm = 0; mm < 2; ++mm) {
;                     const int row = row0 + ai * HALF + (mp + mm) * 16; const float* gp = mods + (size_t)cidx_of(row) * NMOD + goff + col0;
;                     const float* xs = ((Xin && row < NPROMPT) ? Xin + (size_t)row * DM : X + (size_t)row * DM) + col0;
; #pragma unroll
;                     for (int q4 = 0; q4 < 4; ++q4) { const int co = (q4 >> 1) * HALF + (q4 & 1) * 16; gv[mm][q4] = *(const f32x4*)(gp + co); if (!slice) xv[mm][q4] = *(const f32x4*)(xs + co); }
;                 }
; #pragma unroll
;                 for (int mm = 0; mm < 2; ++mm) {
;                     const int row = row0 + ai * HALF + (mp + mm) * 16;
; #pragma unroll
;                     for (int q4 = 0; q4 < 4; ++q4) { const int co = (q4 >> 1) * HALF + (q4 & 1) * 16; const f32x4 d = (gv[mm][q4] * fac) * acc[ai][q4 >> 1][mp + mm][q4 & 1];
;                         if (slice) *(f32x4*)(PART + ((size_t)(slice - 1) * NSAMP + (row - NPROMPT)) * DM + col0 + co) = d;
;                         else *(f32x4*)(X + (size_t)row * DM + col0 + co) = xv[mm][q4] + d; }
;                 }
;                 asm volatile("" ::: "memory");
;             }
.LBB0_1630:
	s_waitcnt vmcnt(7)
	v_pk_mul_f32 v[62:63], v[62:63], v[126:127]
	v_pk_mul_f32 v[60:61], v[60:61], v[124:125]
	s_and_b64 vcc, exec, s[8:9]
	s_mov_b64 s[26:27], -1
	s_cbranch_vccnz .LBB0_1632
	v_ashrrev_i32_e32 v135, 31, v134
	v_lshlrev_b64 v[124:125], 12, v[134:135]
	v_lshl_add_u64 v[124:125], v[208:209], 0, v[124:125]
	s_mov_b64 s[26:27], 0
	global_store_dwordx4 v[124:125], v[60:63], off sc0 sc1
.LBB0_1632:
	s_andn2_b64 vcc, exec, s[26:27]
	s_cbranch_vccnz .LBB0_1634
	v_pk_add_f32 v[62:63], v[62:63], v[122:123]
	v_pk_add_f32 v[60:61], v[60:61], v[120:121]
	v_mov_b64_e32 v[124:125], v[132:133]
	global_store_dwordx4 v[132:133], v[60:63], off sc0 sc1
.LBB0_1634:
	s_waitcnt vmcnt(6)
	s_nop 0
	v_pk_mul_f32 v[60:61], v[58:59], v[86:87]
	v_pk_mul_f32 v[62:63], v[56:57], v[84:85]
	v_pk_fma_f32 v[58:59], v[58:59], v[86:87], v[118:119]
	v_pk_fma_f32 v[56:57], v[56:57], v[84:85], v[116:117]
	v_cndmask_b32_e64 v59, v61, v59, s[6:7]
	v_cndmask_b32_e64 v58, v60, v58, s[6:7]
	v_cndmask_b32_e64 v57, v63, v57, s[6:7]
	v_cndmask_b32_e64 v56, v62, v56, s[6:7]
	global_store_dwordx4 v[124:125], v[56:59], off offset:64 sc0 sc1
	s_and_b64 vcc, exec, s[8:9]
	s_mov_b64 s[26:27], -1
	s_waitcnt vmcnt(6)
	v_pk_mul_f32 v[56:57], v[54:55], v[82:83]
	v_pk_mul_f32 v[58:59], v[52:53], v[80:81]
	v_pk_fma_f32 v[54:55], v[54:55], v[82:83], v[114:115]
	v_pk_fma_f32 v[52:53], v[52:53], v[80:81], v[112:113]
	v_cndmask_b32_e64 v55, v57, v55, s[6:7]
	v_cndmask_b32_e64 v54, v56, v54, s[6:7]
	v_cndmask_b32_e64 v53, v59, v53, s[6:7]
	v_cndmask_b32_e64 v52, v58, v52, s[6:7]
	global_store_dwordx4 v[124:125], v[52:55], off offset:512 sc0 sc1
	s_waitcnt vmcnt(6)
	s_nop 0
	v_pk_mul_f32 v[52:53], v[46:47], v[74:75]
	v_pk_mul_f32 v[54:55], v[44:45], v[72:73]
	v_pk_fma_f32 v[46:47], v[46:47], v[74:75], v[110:111]
	v_pk_fma_f32 v[44:45], v[44:45], v[72:73], v[108:109]
	v_cndmask_b32_e64 v47, v53, v47, s[6:7]
	v_cndmask_b32_e64 v46, v52, v46, s[6:7]
	v_cndmask_b32_e64 v45, v55, v45, s[6:7]
	v_cndmask_b32_e64 v44, v54, v44, s[6:7]
	global_store_dwordx4 v[124:125], v[44:47], off offset:576 sc0 sc1
	s_waitcnt vmcnt(6)
	s_nop 0
	v_pk_mul_f32 v[46:47], v[50:51], v[106:107]
	v_pk_mul_f32 v[44:45], v[48:49], v[104:105]
	s_cbranch_vccnz .LBB0_1636
	v_ashrrev_i32_e32 v131, 31, v130
	v_lshlrev_b64 v[48:49], 12, v[130:131]
	v_lshl_add_u64 v[48:49], v[208:209], 0, v[48:49]
	s_mov_b64 s[26:27], 0
	global_store_dwordx4 v[48:49], v[44:47], off sc0 sc1
.LBB0_1636:
	s_andn2_b64 vcc, exec, s[26:27]
	s_cbranch_vccnz .LBB0_1638
	v_pk_add_f32 v[46:47], v[46:47], v[102:103]
	v_pk_add_f32 v[44:45], v[44:45], v[100:101]
	v_mov_b64_e32 v[48:49], v[128:129]
	global_store_dwordx4 v[128:129], v[44:47], off sc0 sc1
.LBB0_1638:
	s_waitcnt vmcnt(5)
	s_nop 0
	v_pk_mul_f32 v[44:45], v[42:43], v[78:79]
	v_pk_mul_f32 v[46:47], v[40:41], v[76:77]
	v_pk_fma_f32 v[42:43], v[42:43], v[78:79], v[98:99]
	v_pk_fma_f32 v[40:41], v[40:41], v[76:77], v[96:97]
	v_cndmask_b32_e64 v43, v45, v43, s[6:7]
	v_cndmask_b32_e64 v42, v44, v42, s[6:7]
	v_cndmask_b32_e64 v41, v47, v41, s[6:7]
	v_cndmask_b32_e64 v40, v46, v40, s[6:7]
	global_store_dwordx4 v[48:49], v[40:43], off offset:64 sc0 sc1
	s_movk_i32 s21, 0x7f60
	v_cmp_gt_i32_e32 vcc, s21, v210
	s_waitcnt vmcnt(5)
	v_pk_mul_f32 v[40:41], v[38:39], v[70:71]
	v_pk_mul_f32 v[42:43], v[36:37], v[68:69]
	v_pk_fma_f32 v[38:39], v[38:39], v[70:71], v[94:95]
	v_pk_fma_f32 v[36:37], v[36:37], v[68:69], v[92:93]
	v_cndmask_b32_e64 v39, v41, v39, s[6:7]
	v_cndmask_b32_e64 v38, v40, v38, s[6:7]
	v_cndmask_b32_e64 v37, v43, v37, s[6:7]
	v_cndmask_b32_e64 v36, v42, v36, s[6:7]
	global_store_dwordx4 v[48:49], v[36:39], off offset:512 sc0 sc1
	v_add_u32_e32 v70, 0xffff80a0, v210
	s_waitcnt vmcnt(5)
	v_pk_mul_f32 v[36:37], v[34:35], v[66:67]
	v_pk_mul_f32 v[38:39], v[32:33], v[64:65]
	v_pk_fma_f32 v[34:35], v[34:35], v[66:67], v[90:91]
	v_pk_fma_f32 v[32:33], v[32:33], v[64:65], v[88:89]
	v_cndmask_b32_e64 v35, v37, v35, s[6:7]
	v_cndmask_b32_e64 v34, v36, v34, s[6:7]
	v_cndmask_b32_e64 v33, v39, v33, s[6:7]
	v_cndmask_b32_e64 v32, v38, v32, s[6:7]
	global_store_dwordx4 v[48:49], v[32:35], off offset:576 sc0 sc1
	s_nop 1
	v_lshrrev_b32_e32 v32, 5, v70
	v_add_u32_e32 v32, 2, v32
	v_cndmask_b32_e32 v32, v32, v136, vcc
	v_mad_i64_i32 v[32:33], s[26:27], v32, s80, v[214:215]
	global_load_dwordx4 v[60:63], v[32:33], off
	v_lshlrev_b64 v[34:35], 12, v[210:211]
	v_lshl_add_u64 v[34:35], s[12:13], 0, v[34:35]
	v_lshl_add_u64 v[34:35], v[212:213], 2, v[34:35]
	s_mov_b64 s[26:27], 0xa0000
	s_and_b64 vcc, exec, s[10:11]
	v_lshl_add_u64 v[68:69], v[34:35], 0, s[26:27]
	s_cbranch_vccz .LBB0_1677
	global_load_dwordx4 v[52:55], v[32:33], off offset:64
	s_and_b64 vcc, exec, s[10:11]
	s_cbranch_vccz .LBB0_1678

;     __device__ __forceinline__ void operator()(const f32x4 (&acc)[2][2][4][2], const Unit& u, int wr, int wc, int fr, int fq) const {
;     ...
;         const int slice = u.pm >> 12, row0 = (u.pm & 4095) * BM + wr * 64 + fr, col0 = u.pn * BM + wc * 32 + 4 * fq;
;         const float* mods = (const float*)(ws + WS_MODS) + (size_t)(goff_l >> 16) * NSEQ * NMOD; const int goff = goff_l & 0xffff; float* PART = (float*)(ws + WS_PART);
; #pragma unroll
;         for (int ai = 0; ai < 2; ++ai)
; #pragma unroll
;             for (int mp = 0; mp < 4; mp += 2) {
;                 f32x4 gv[2][4], xv[2][4];
; #pragma unroll
;                 for (int mm = 0; mm < 2; ++mm) {
;                     const int row = row0 + ai * HALF + (mp + mm) * 16; const float* gp = mods + (size_t)cidx_of(row) * NMOD + goff + col0;
;                     const float* xs = ((Xin && row < NPROMPT) ? Xin + (size_t)row * DM : X + (size_t)row * DM) + col0;
; #pragma unroll
;                     for (int q4 = 0; q4 < 4; ++q4) { const int co = (q4 >> 1) * HALF + (q4 & 1) * 16; gv[mm][q4] = *(const f32x4*)(gp + co); if (!slice) xv[mm][q4] = *(const f32x4*)(xs + co); }
;                 }
; #pragma unroll
;                 for (int mm = 0; mm < 2; ++mm) {
;                     const int row = row0 + ai * HALF + (mp + mm) * 16;
; #pragma unroll
;                     for (int q4 = 0; q4 < 4; ++q4) { const int co = (q4 >> 1) * HALF + (q4 & 1) * 16; const f32x4 d = (gv[mm][q4] * fac) * acc[ai][q4 >> 1][mp + mm][q4 & 1];
;                         if (slice) *(f32x4*)(PART + ((size_t)(slice - 1) * NSAMP + (row - NPROMPT)) * DM + col0 + co) = d;
;                         else *(f32x4*)(X + (size_t)row * DM + col0 + co) = xv[mm][q4] + d; }
;                 }
;                 asm volatile("" ::: "memory");
;             }
.LBB0_1648:
	s_waitcnt vmcnt(7)
	v_pk_mul_f32 v[30:31], v[30:31], v[62:63]
	v_pk_mul_f32 v[28:29], v[28:29], v[60:61]
	s_and_b64 vcc, exec, s[8:9]
	s_mov_b64 s[10:11], -1
	s_cbranch_vccnz .LBB0_1650
	v_ashrrev_i32_e32 v71, 31, v70
	v_lshlrev_b64 v[60:61], 12, v[70:71]
	v_lshl_add_u64 v[60:61], v[208:209], 0, v[60:61]
	s_mov_b64 s[10:11], 0
	global_store_dwordx4 v[60:61], v[28:31], off sc0 sc1
.LBB0_1650:
	s_andn2_b64 vcc, exec, s[10:11]
	s_cbranch_vccnz .LBB0_1652
	v_pk_add_f32 v[30:31], v[30:31], v[122:123]
	v_pk_add_f32 v[28:29], v[28:29], v[120:121]
	v_mov_b64_e32 v[60:61], v[68:69]
	global_store_dwordx4 v[68:69], v[28:31], off sc0 sc1
.LBB0_1652:
	s_waitcnt vmcnt(6)
	s_nop 0
	v_pk_mul_f32 v[28:29], v[26:27], v[54:55]
	v_pk_mul_f32 v[30:31], v[24:25], v[52:53]
	v_pk_fma_f32 v[26:27], v[26:27], v[54:55], v[118:119]
	v_pk_fma_f32 v[24:25], v[24:25], v[52:53], v[116:117]
	v_cndmask_b32_e64 v27, v29, v27, s[6:7]
	v_cndmask_b32_e64 v26, v28, v26, s[6:7]
	v_cndmask_b32_e64 v25, v31, v25, s[6:7]
	v_cndmask_b32_e64 v24, v30, v24, s[6:7]
	global_store_dwordx4 v[60:61], v[24:27], off offset:64 sc0 sc1
	s_and_b64 vcc, exec, s[8:9]
	s_mov_b64 s[8:9], -1
	s_waitcnt vmcnt(6)
	v_pk_mul_f32 v[24:25], v[22:23], v[50:51]
	v_pk_mul_f32 v[26:27], v[20:21], v[48:49]
	v_pk_fma_f32 v[22:23], v[22:23], v[50:51], v[114:115]
	v_pk_fma_f32 v[20:21], v[20:21], v[48:49], v[112:113]
	v_cndmask_b32_e64 v23, v25, v23, s[6:7]
	v_cndmask_b32_e64 v22, v24, v22, s[6:7]
	v_cndmask_b32_e64 v21, v27, v21, s[6:7]
	v_cndmask_b32_e64 v20, v26, v20, s[6:7]
	global_store_dwordx4 v[60:61], v[20:23], off offset:512 sc0 sc1
	s_waitcnt vmcnt(6)
	s_nop 0
	v_pk_mul_f32 v[20:21], v[14:15], v[42:43]
	v_pk_mul_f32 v[22:23], v[12:13], v[40:41]
	v_pk_fma_f32 v[14:15], v[14:15], v[42:43], v[110:111]
	v_pk_fma_f32 v[12:13], v[12:13], v[40:41], v[108:109]
	v_cndmask_b32_e64 v15, v21, v15, s[6:7]
	v_cndmask_b32_e64 v14, v20, v14, s[6:7]
	v_cndmask_b32_e64 v13, v23, v13, s[6:7]
	v_cndmask_b32_e64 v12, v22, v12, s[6:7]
	global_store_dwordx4 v[60:61], v[12:15], off offset:576 sc0 sc1
	s_waitcnt vmcnt(6)
	s_nop 0
	v_pk_mul_f32 v[14:15], v[18:19], v[58:59]
	v_pk_mul_f32 v[12:13], v[16:17], v[56:57]
	s_cbranch_vccnz .LBB0_1654
	v_ashrrev_i32_e32 v67, 31, v66
	v_lshlrev_b64 v[16:17], 12, v[66:67]
	v_lshl_add_u64 v[16:17], v[208:209], 0, v[16:17]
	s_mov_b64 s[8:9], 0
	global_store_dwordx4 v[16:17], v[12:15], off sc0 sc1
.LBB0_1654:
	s_andn2_b64 vcc, exec, s[8:9]
	s_cbranch_vccnz .LBB0_1656
	v_pk_add_f32 v[14:15], v[14:15], v[102:103]
	v_pk_add_f32 v[12:13], v[12:13], v[100:101]
	v_mov_b64_e32 v[16:17], v[64:65]
	global_store_dwordx4 v[64:65], v[12:15], off sc0 sc1
.LBB0_1656:
	s_waitcnt vmcnt(5)
	s_nop 0
	v_pk_mul_f32 v[12:13], v[10:11], v[46:47]
	v_pk_mul_f32 v[14:15], v[8:9], v[44:45]
	v_pk_fma_f32 v[10:11], v[10:11], v[46:47], v[98:99]
	v_pk_fma_f32 v[8:9], v[8:9], v[44:45], v[96:97]
	v_cndmask_b32_e64 v11, v13, v11, s[6:7]
	v_cndmask_b32_e64 v10, v12, v10, s[6:7]
	v_cndmask_b32_e64 v9, v15, v9, s[6:7]
	v_cndmask_b32_e64 v8, v14, v8, s[6:7]
	global_store_dwordx4 v[16:17], v[8:11], off offset:64 sc0 sc1
	s_and_b64 vcc, exec, s[4:5]
	s_mov_b64 s[4:5], -1
	s_waitcnt vmcnt(5)
	v_pk_mul_f32 v[8:9], v[6:7], v[38:39]
	v_pk_mul_f32 v[10:11], v[4:5], v[36:37]
	v_pk_fma_f32 v[6:7], v[6:7], v[38:39], v[94:95]
	v_pk_fma_f32 v[4:5], v[4:5], v[36:37], v[92:93]
	v_cndmask_b32_e64 v7, v9, v7, s[6:7]
	v_cndmask_b32_e64 v6, v8, v6, s[6:7]
	v_cndmask_b32_e64 v5, v11, v5, s[6:7]
	v_cndmask_b32_e64 v4, v10, v4, s[6:7]
	global_store_dwordx4 v[16:17], v[4:7], off offset:512 sc0 sc1
	s_waitcnt vmcnt(5)
	s_nop 0
	v_pk_mul_f32 v[4:5], v[2:3], v[34:35]
	v_pk_mul_f32 v[6:7], v[0:1], v[32:33]
	v_pk_fma_f32 v[2:3], v[2:3], v[34:35], v[90:91]
	v_pk_fma_f32 v[0:1], v[0:1], v[32:33], v[88:89]
	v_cndmask_b32_e64 v3, v5, v3, s[6:7]
	v_cndmask_b32_e64 v2, v4, v2, s[6:7]
	v_cndmask_b32_e64 v1, v7, v1, s[6:7]
	v_cndmask_b32_e64 v0, v6, v0, s[6:7]
	global_store_dwordx4 v[16:17], v[0:3], off offset:576 sc0 sc1
	s_cbranch_vccnz .LBB0_1566
	s_andn2_b64 vcc, exec, s[16:17]
	s_cbranch_vccnz .LBB0_1565
	s_barrier
	s_branch .LBB0_1565

; __device__ __forceinline__ void norm_mod_phase(ArgsP a, bool from_input, const float* g, const float* modsL, int ishift, int iscale, int nparts, int wave_s_) {
;     ...
;         if ((from_input && row >= NPROMPT) || (row >= NPROMPT && nparts > 0)) {
; #pragma unroll
;             for (int j = 0; j < 4; ++j) *(f32x4*)(X + (size_t)row * DM + 4 * lane + 256 * j) = v[j];
;         }
.LBB0_1744:
	s_or_b64 exec, exec, s[18:19]
	s_and_saveexec_b64 s[18:19], s[6:7]
	s_xor_b64 s[6:7], exec, s[18:19]
	s_andn2_saveexec_b64 s[6:7], s[6:7]
	s_cbranch_execz .LBB0_1739
	v_mov_b32_e32 v57, v197
	v_lshlrev_b64 v[60:61], 12, v[56:57]
	v_lshl_add_u64 v[60:61], v[48:49], 0, v[60:61]
	s_waitcnt vmcnt(3)
	global_store_dwordx4 v[60:61], v[44:47], off sc0 sc1
	s_waitcnt vmcnt(3)
	global_store_dwordx4 v[60:61], v[40:43], off offset:1024 sc0 sc1
	s_waitcnt vmcnt(3)
	global_store_dwordx4 v[60:61], v[36:39], off offset:2048 sc0 sc1
	s_waitcnt vmcnt(3)
	global_store_dwordx4 v[60:61], v[20:23], off offset:3072 sc0 sc1
	s_branch .LBB0_1739

; __device__ __forceinline__ float silu_f(float x) { return x * __builtin_amdgcn_rcpf(1.0f + __expf(-x)); }
; __device__ __forceinline__ u32x4 pack8(const f32x4& a, const f32x4& b) { u32x4 w; w.x = cvt_pk_bf16(a[0], a[1]); w.y = cvt_pk_bf16(a[2], a[3]); w.z = cvt_pk_bf16(b[0], b[1]); w.w = cvt_pk_bf16(b[2], b[3]); return w; }
;     __device__ __forceinline__ void operator()(const f32x4 (&acc)[2][2][4][2], const Unit& u, int wr, int wc, int fr, int fq) const {
;         { int l_; asm volatile("v_mbcnt_lo_u32_b32 %0, -1, 0\n\tv_mbcnt_hi_u32_b32 %0, -1, %0" : "=v"(l_)); fr = l_ & 15; fq = (l_ >> 4) & 3; }
;         const int row0 = u.pm * BM + wr * 64 + fr, col0 = u.pn * 128 + wc * 32 + 8 * fq;
; #pragma unroll
;         for (int ai = 0; ai < 2; ++ai)
; #pragma unroll
;             for (int m = 0; m < 4; ++m) {
;                 f32x4 h0, h1;
; #pragma unroll
;                 for (int j = 0; j < 4; ++j) { h0[j] = silu_f(acc[ai][0][m][0][j]) * acc[ai][1][m][0][j]; h1[j] = silu_f(acc[ai][0][m][1][j]) * acc[ai][1][m][1][j]; }
;                 *(u32x4*)(HID + (size_t)(row0 + ai * HALF + m * 16) * DFF + col0) = pack8(h0, h1);
;             }
.LBB0_1823:
	v_mbcnt_lo_u32_b32 v140, -1, 0
	v_mbcnt_hi_u32_b32 v140, -1, v140
	s_lshl_b32 s15, s44, 7
	v_lshrrev_b32_e32 v141, 1, v140
	v_and_or_b32 v141, v141, 24, s15
	v_or_b32_e32 v142, s37, v141
	v_mul_f32_e32 v141, 0xbfb8aa3b, v124
	v_exp_f32_e32 v141, v141
	v_and_or_b32 v140, v140, 15, s36
	v_lshl_add_u32 v140, s43, 8, v140
	v_ashrrev_i32_e32 v143, 31, v142
	v_add_f32_e32 v141, 1.0, v141
	v_rcp_f32_e32 v141, v141
	s_and_b64 vcc, exec, s[4:5]
	v_mul_f32_e32 v124, v124, v141
	v_mul_f32_e32 v120, v124, v120
	v_mul_f32_e32 v124, 0xbfb8aa3b, v116
	v_exp_f32_e32 v124, v124
	s_nop 0
	v_add_f32_e32 v124, 1.0, v124
	v_rcp_f32_e32 v124, v124
	s_nop 0
	v_mul_f32_e32 v116, v116, v124
	v_mul_f32_e32 v112, v116, v112
	v_mul_f32_e32 v116, 0xbfb8aa3b, v125
	v_exp_f32_e32 v116, v116
	s_nop 0
	v_add_f32_e32 v116, 1.0, v116
	v_rcp_f32_e32 v116, v116
	s_nop 0
	v_mul_f32_e32 v116, v125, v116
	v_mul_f32_e32 v116, v116, v121
	v_mul_f32_e32 v121, 0xbfb8aa3b, v117
	v_exp_f32_e32 v121, v121
	v_cvt_pk_bf16_f32 v116, v120, v116
	s_nop 0
	v_add_f32_e32 v121, 1.0, v121
	v_rcp_f32_e32 v121, v121
	s_nop 0
	v_mul_f32_e32 v117, v117, v121
	v_mul_f32_e32 v121, 0xbfb8aa3b, v118
	v_exp_f32_e32 v121, v121
	v_mul_f32_e32 v113, v117, v113
	v_mul_f32_e32 v117, 0xbfb8aa3b, v126
	v_exp_f32_e32 v117, v117
	v_add_f32_e32 v121, 1.0, v121
	v_rcp_f32_e32 v121, v121
	v_add_f32_e32 v117, 1.0, v117
	v_rcp_f32_e32 v117, v117
	v_mul_f32_e32 v118, v118, v121
	v_mul_f32_e32 v114, v118, v114
	v_mul_f32_e32 v118, 0xbfb8aa3b, v127
	v_exp_f32_e32 v118, v118
	v_mul_f32_e32 v121, 0xbfb8aa3b, v119
	v_exp_f32_e32 v121, v121
	v_mul_f32_e32 v117, v126, v117
	v_add_f32_e32 v118, 1.0, v118
	v_rcp_f32_e32 v118, v118
	v_add_f32_e32 v121, 1.0, v121
	v_rcp_f32_e32 v121, v121
	v_mul_f32_e32 v117, v117, v122
	v_mul_f32_e32 v118, v127, v118
	v_mul_f32_e32 v118, v118, v123
	v_mul_f32_e32 v119, v119, v121
	v_mul_f32_e32 v115, v119, v115
	v_cvt_pk_bf16_f32 v117, v117, v118
	v_cvt_pk_bf16_f32 v118, v112, v113
	v_mov_b64_e32 v[112:113], s[10:11]
	v_cvt_pk_bf16_f32 v119, v114, v115
	v_mad_i64_i32 v[120:121], s[18:19], v140, s85, v[112:113]
	v_lshlrev_b64 v[114:115], 1, v[142:143]
	v_lshl_add_u64 v[120:121], v[120:121], 0, v[114:115]
	global_store_dwordx4 v[120:121], v[116:119], off sc0 sc1
	s_nop 1
	v_mul_f32_e32 v116, 0xbfb8aa3b, v108
	v_exp_f32_e32 v116, v116
	s_nop 0
	v_add_f32_e32 v116, 1.0, v116
	v_rcp_f32_e32 v116, v116
	s_nop 0
	v_mul_f32_e32 v108, v108, v116
	v_mul_f32_e32 v104, v108, v104
	v_mul_f32_e32 v108, 0xbfb8aa3b, v100
	v_exp_f32_e32 v108, v108
	s_nop 0
	v_add_f32_e32 v108, 1.0, v108
	v_rcp_f32_e32 v108, v108
	s_nop 0
	v_mul_f32_e32 v100, v100, v108
	v_mul_f32_e32 v100, v100, v96
	v_mul_f32_e32 v96, 0xbfb8aa3b, v109
	v_exp_f32_e32 v96, v96
	s_nop 0
	v_add_f32_e32 v96, 1.0, v96
	v_rcp_f32_e32 v96, v96
	s_nop 0
	v_mul_f32_e32 v96, v109, v96
	v_mul_f32_e32 v96, v96, v105
	v_mul_f32_e32 v105, 0xbfb8aa3b, v101
	v_exp_f32_e32 v105, v105
	v_cvt_pk_bf16_f32 v96, v104, v96
	s_nop 0
	v_add_f32_e32 v105, 1.0, v105
	v_rcp_f32_e32 v105, v105
	s_nop 0
	v_mul_f32_e32 v101, v101, v105
	v_mul_f32_e32 v105, 0xbfb8aa3b, v102
	v_exp_f32_e32 v105, v105
	v_mul_f32_e32 v101, v101, v97
	v_mul_f32_e32 v97, 0xbfb8aa3b, v110
	v_exp_f32_e32 v97, v97
	v_add_f32_e32 v105, 1.0, v105
	v_rcp_f32_e32 v105, v105
	v_add_f32_e32 v97, 1.0, v97
	v_rcp_f32_e32 v97, v97
	v_mul_f32_e32 v102, v102, v105
	v_mul_f32_e32 v102, v102, v98
	v_mul_f32_e32 v98, 0xbfb8aa3b, v111
	v_exp_f32_e32 v98, v98
	v_mul_f32_e32 v105, 0xbfb8aa3b, v103
	v_exp_f32_e32 v105, v105
	v_mul_f32_e32 v97, v110, v97
	v_add_f32_e32 v98, 1.0, v98
	v_rcp_f32_e32 v98, v98
	v_add_f32_e32 v105, 1.0, v105
	v_rcp_f32_e32 v105, v105
	v_mul_f32_e32 v97, v97, v106
	v_mul_f32_e32 v98, v111, v98
	v_mul_f32_e32 v98, v98, v107
	v_cvt_pk_bf16_f32 v97, v97, v98
	v_cvt_pk_bf16_f32 v98, v100, v101
	v_or_b32_e32 v100, 16, v140
	v_mul_f32_e32 v103, v103, v105
	v_mad_i64_i32 v[100:101], s[18:19], v100, s85, v[112:113]
	v_mul_f32_e32 v99, v103, v99
	v_lshl_add_u64 v[100:101], v[100:101], 0, v[114:115]
	v_cvt_pk_bf16_f32 v99, v102, v99
	global_store_dwordx4 v[100:101], v[96:99], off sc0 sc1
	s_nop 1
	v_mul_f32_e32 v96, 0xbfb8aa3b, v92
	v_exp_f32_e32 v96, v96
	s_nop 0
	v_add_f32_e32 v96, 1.0, v96
	v_rcp_f32_e32 v96, v96
	s_nop 0
	v_mul_f32_e32 v92, v92, v96
	v_mul_f32_e32 v88, v92, v88
	v_mul_f32_e32 v92, 0xbfb8aa3b, v84
	v_exp_f32_e32 v92, v92
	s_nop 0
	v_add_f32_e32 v92, 1.0, v92
	v_rcp_f32_e32 v92, v92
	s_nop 0
	v_mul_f32_e32 v84, v84, v92
	v_mul_f32_e32 v84, v84, v80
	v_mul_f32_e32 v80, 0xbfb8aa3b, v93
	v_exp_f32_e32 v80, v80
	s_nop 0
	v_add_f32_e32 v80, 1.0, v80
	v_rcp_f32_e32 v80, v80
	s_nop 0
	v_mul_f32_e32 v80, v93, v80
	v_mul_f32_e32 v80, v80, v89
	v_mul_f32_e32 v89, 0xbfb8aa3b, v85
	v_exp_f32_e32 v89, v89
	v_cvt_pk_bf16_f32 v80, v88, v80
	s_nop 0
	v_add_f32_e32 v89, 1.0, v89
	v_rcp_f32_e32 v89, v89
	s_nop 0
	v_mul_f32_e32 v85, v85, v89
	v_mul_f32_e32 v89, 0xbfb8aa3b, v86
	v_exp_f32_e32 v89, v89
	v_mul_f32_e32 v85, v85, v81
	v_mul_f32_e32 v81, 0xbfb8aa3b, v94
	v_exp_f32_e32 v81, v81
	v_add_f32_e32 v89, 1.0, v89
	v_rcp_f32_e32 v89, v89
	v_add_f32_e32 v81, 1.0, v81
	v_rcp_f32_e32 v81, v81
	v_mul_f32_e32 v86, v86, v89
	v_mul_f32_e32 v86, v86, v82
	v_mul_f32_e32 v82, 0xbfb8aa3b, v95
	v_exp_f32_e32 v82, v82
	v_mul_f32_e32 v89, 0xbfb8aa3b, v87
	v_exp_f32_e32 v89, v89
	v_mul_f32_e32 v81, v94, v81
	v_add_f32_e32 v82, 1.0, v82
	v_rcp_f32_e32 v82, v82
	v_add_f32_e32 v89, 1.0, v89
	v_rcp_f32_e32 v89, v89
	v_mul_f32_e32 v81, v81, v90
	v_mul_f32_e32 v82, v95, v82
	v_mul_f32_e32 v82, v82, v91
	v_cvt_pk_bf16_f32 v81, v81, v82
	v_cvt_pk_bf16_f32 v82, v84, v85
	v_or_b32_e32 v84, 32, v140
; __device__ __forceinline__ float silu_f(float x) { return x * __builtin_amdgcn_rcpf(1.0f + __expf(-x)); }
; __device__ __forceinline__ u32x4 pack8(const f32x4& a, const f32x4& b) { u32x4 w; w.x = cvt_pk_bf16(a[0], a[1]); w.y = cvt_pk_bf16(a[2], a[3]); w.z = cvt_pk_bf16(b[0], b[1]); w.w = cvt_pk_bf16(b[2], b[3]); return w; }
;     __device__ __forceinline__ void operator()(const f32x4 (&acc)[2][2][4][2], const Unit& u, int wr, int wc, int fr, int fq) const {
;         { int l_; asm volatile("v_mbcnt_lo_u32_b32 %0, -1, 0\n\tv_mbcnt_hi_u32_b32 %0, -1, %0" : "=v"(l_)); fr = l_ & 15; fq = (l_ >> 4) & 3; }
;         const int row0 = u.pm * BM + wr * 64 + fr, col0 = u.pn * 128 + wc * 32 + 8 * fq;
; #pragma unroll
;         for (int ai = 0; ai < 2; ++ai)
; #pragma unroll
;             for (int m = 0; m < 4; ++m) {
;                 f32x4 h0, h1;
; #pragma unroll
;                 for (int j = 0; j < 4; ++j) { h0[j] = silu_f(acc[ai][0][m][0][j]) * acc[ai][1][m][0][j]; h1[j] = silu_f(acc[ai][0][m][1][j]) * acc[ai][1][m][1][j]; }
;                 *(u32x4*)(HID + (size_t)(row0 + ai * HALF + m * 16) * DFF + col0) = pack8(h0, h1);
;             }
	v_mul_f32_e32 v87, v87, v89
	v_mad_i64_i32 v[84:85], s[18:19], v84, s85, v[112:113]
	v_mul_f32_e32 v83, v87, v83
	v_lshl_add_u64 v[84:85], v[84:85], 0, v[114:115]
	v_cvt_pk_bf16_f32 v83, v86, v83
	global_store_dwordx4 v[84:85], v[80:83], off sc0 sc1
	s_nop 1
	v_mul_f32_e32 v80, 0xbfb8aa3b, v76
	v_exp_f32_e32 v80, v80
	s_nop 0
	v_add_f32_e32 v80, 1.0, v80
	v_rcp_f32_e32 v80, v80
	s_nop 0
	v_mul_f32_e32 v76, v76, v80
	v_mul_f32_e32 v72, v76, v72
	v_mul_f32_e32 v76, 0xbfb8aa3b, v68
	v_exp_f32_e32 v76, v76
	s_nop 0
	v_add_f32_e32 v76, 1.0, v76
	v_rcp_f32_e32 v76, v76
	s_nop 0
	v_mul_f32_e32 v68, v68, v76
	v_mul_f32_e32 v68, v68, v64
	v_mul_f32_e32 v64, 0xbfb8aa3b, v77
	v_exp_f32_e32 v64, v64
	s_nop 0
	v_add_f32_e32 v64, 1.0, v64
	v_rcp_f32_e32 v64, v64
	s_nop 0
	v_mul_f32_e32 v64, v77, v64
	v_mul_f32_e32 v64, v64, v73
	v_mul_f32_e32 v73, 0xbfb8aa3b, v69
	v_exp_f32_e32 v73, v73
	v_cvt_pk_bf16_f32 v64, v72, v64
	s_nop 0
	v_add_f32_e32 v73, 1.0, v73
	v_rcp_f32_e32 v73, v73
	s_nop 0
	v_mul_f32_e32 v69, v69, v73
	v_mul_f32_e32 v73, 0xbfb8aa3b, v70
	v_exp_f32_e32 v73, v73
	v_mul_f32_e32 v69, v69, v65
	v_mul_f32_e32 v65, 0xbfb8aa3b, v78
	v_exp_f32_e32 v65, v65
	v_add_f32_e32 v73, 1.0, v73
	v_rcp_f32_e32 v73, v73
	v_add_f32_e32 v65, 1.0, v65
	v_rcp_f32_e32 v65, v65
	v_mul_f32_e32 v70, v70, v73
	v_mul_f32_e32 v70, v70, v66
	v_mul_f32_e32 v66, 0xbfb8aa3b, v79
	v_exp_f32_e32 v66, v66
	v_mul_f32_e32 v73, 0xbfb8aa3b, v71
	v_exp_f32_e32 v73, v73
	v_mul_f32_e32 v65, v78, v65
	v_add_f32_e32 v66, 1.0, v66
	v_rcp_f32_e32 v66, v66
	v_add_f32_e32 v73, 1.0, v73
	v_rcp_f32_e32 v73, v73
	v_mul_f32_e32 v65, v65, v74
	v_mul_f32_e32 v66, v79, v66
	v_mul_f32_e32 v66, v66, v75
	v_cvt_pk_bf16_f32 v65, v65, v66
	v_cvt_pk_bf16_f32 v66, v68, v69
	v_or_b32_e32 v68, 48, v140
	v_mul_f32_e32 v71, v71, v73
	v_mad_i64_i32 v[68:69], s[18:19], v68, s85, v[112:113]
	v_mul_f32_e32 v67, v71, v67
	v_lshl_add_u64 v[68:69], v[68:69], 0, v[114:115]
	v_cvt_pk_bf16_f32 v67, v70, v67
	global_store_dwordx4 v[68:69], v[64:67], off sc0 sc1
	s_nop 1
	v_mul_f32_e32 v65, 0xbfb8aa3b, v60
	v_exp_f32_e32 v65, v65
	v_add_u32_e32 v64, 0x80, v140
	v_add_f32_e32 v65, 1.0, v65
	v_rcp_f32_e32 v65, v65
	s_nop 0
	v_mul_f32_e32 v60, v60, v65
	v_mul_f32_e32 v56, v60, v56
	v_mul_f32_e32 v60, 0xbfb8aa3b, v52
	v_exp_f32_e32 v60, v60
	s_nop 0
	v_add_f32_e32 v60, 1.0, v60
	v_rcp_f32_e32 v60, v60
	s_nop 0
	v_mul_f32_e32 v52, v52, v60
	v_mul_f32_e32 v52, v52, v48
	v_mul_f32_e32 v48, 0xbfb8aa3b, v61
	v_exp_f32_e32 v48, v48
	s_nop 0
	v_add_f32_e32 v48, 1.0, v48
	v_rcp_f32_e32 v48, v48
	s_nop 0
	v_mul_f32_e32 v48, v61, v48
	v_mul_f32_e32 v48, v48, v57
	v_mul_f32_e32 v57, 0xbfb8aa3b, v53
	v_exp_f32_e32 v57, v57
	v_cvt_pk_bf16_f32 v48, v56, v48
	s_nop 0
	v_add_f32_e32 v57, 1.0, v57
	v_rcp_f32_e32 v57, v57
	s_nop 0
	v_mul_f32_e32 v53, v53, v57
	v_mul_f32_e32 v57, 0xbfb8aa3b, v54
	v_exp_f32_e32 v57, v57
	v_mul_f32_e32 v53, v53, v49
	v_mul_f32_e32 v49, 0xbfb8aa3b, v62
	v_exp_f32_e32 v49, v49
	v_add_f32_e32 v57, 1.0, v57
	v_rcp_f32_e32 v57, v57
	v_add_f32_e32 v49, 1.0, v49
	v_rcp_f32_e32 v49, v49
	v_mul_f32_e32 v54, v54, v57
	v_mul_f32_e32 v54, v54, v50
	v_mul_f32_e32 v50, 0xbfb8aa3b, v63
	v_exp_f32_e32 v50, v50
	v_mul_f32_e32 v57, 0xbfb8aa3b, v55
	v_exp_f32_e32 v57, v57
	v_mul_f32_e32 v49, v62, v49
	v_add_f32_e32 v50, 1.0, v50
	v_rcp_f32_e32 v50, v50
	v_add_f32_e32 v57, 1.0, v57
	v_rcp_f32_e32 v57, v57
	v_mul_f32_e32 v49, v49, v58
	v_mul_f32_e32 v50, v63, v50
	v_mul_f32_e32 v50, v50, v59
	v_mul_f32_e32 v55, v55, v57
	v_cvt_pk_bf16_f32 v49, v49, v50
	v_cvt_pk_bf16_f32 v50, v52, v53
	v_mad_i64_i32 v[52:53], s[18:19], v64, s85, v[112:113]
	v_mul_f32_e32 v51, v55, v51
	v_lshl_add_u64 v[52:53], v[52:53], 0, v[114:115]
	v_cvt_pk_bf16_f32 v51, v54, v51
	global_store_dwordx4 v[52:53], v[48:51], off sc0 sc1
	s_nop 1
	v_mul_f32_e32 v48, 0xbfb8aa3b, v44
	v_exp_f32_e32 v48, v48
	s_nop 0
	v_add_f32_e32 v48, 1.0, v48
	v_rcp_f32_e32 v48, v48
	s_nop 0
	v_mul_f32_e32 v44, v44, v48
	v_mul_f32_e32 v40, v44, v40
	v_mul_f32_e32 v44, 0xbfb8aa3b, v36
	v_exp_f32_e32 v44, v44
	s_nop 0
	v_add_f32_e32 v44, 1.0, v44
	v_rcp_f32_e32 v44, v44
	s_nop 0
	v_mul_f32_e32 v36, v36, v44
	v_mul_f32_e32 v36, v36, v32
	v_mul_f32_e32 v32, 0xbfb8aa3b, v45
	v_exp_f32_e32 v32, v32
	s_nop 0
	v_add_f32_e32 v32, 1.0, v32
	v_rcp_f32_e32 v32, v32
	s_nop 0
	v_mul_f32_e32 v32, v45, v32
	v_mul_f32_e32 v32, v32, v41
	v_mul_f32_e32 v41, 0xbfb8aa3b, v37
	v_exp_f32_e32 v41, v41
	v_cvt_pk_bf16_f32 v32, v40, v32
	s_nop 0
	v_add_f32_e32 v41, 1.0, v41
	v_rcp_f32_e32 v41, v41
	s_nop 0
	v_mul_f32_e32 v37, v37, v41
; __device__ __forceinline__ float silu_f(float x) { return x * __builtin_amdgcn_rcpf(1.0f + __expf(-x)); }
; __device__ __forceinline__ u32x4 pack8(const f32x4& a, const f32x4& b) { u32x4 w; w.x = cvt_pk_bf16(a[0], a[1]); w.y = cvt_pk_bf16(a[2], a[3]); w.z = cvt_pk_bf16(b[0], b[1]); w.w = cvt_pk_bf16(b[2], b[3]); return w; }
;     __device__ __forceinline__ void operator()(const f32x4 (&acc)[2][2][4][2], const Unit& u, int wr, int wc, int fr, int fq) const {
;         { int l_; asm volatile("v_mbcnt_lo_u32_b32 %0, -1, 0\n\tv_mbcnt_hi_u32_b32 %0, -1, %0" : "=v"(l_)); fr = l_ & 15; fq = (l_ >> 4) & 3; }
;         const int row0 = u.pm * BM + wr * 64 + fr, col0 = u.pn * 128 + wc * 32 + 8 * fq;
; #pragma unroll
;         for (int ai = 0; ai < 2; ++ai)
; #pragma unroll
;             for (int m = 0; m < 4; ++m) {
;                 f32x4 h0, h1;
; #pragma unroll
;                 for (int j = 0; j < 4; ++j) { h0[j] = silu_f(acc[ai][0][m][0][j]) * acc[ai][1][m][0][j]; h1[j] = silu_f(acc[ai][0][m][1][j]) * acc[ai][1][m][1][j]; }
;                 *(u32x4*)(HID + (size_t)(row0 + ai * HALF + m * 16) * DFF + col0) = pack8(h0, h1);
;             }
	v_mul_f32_e32 v41, 0xbfb8aa3b, v38
	v_exp_f32_e32 v41, v41
	v_mul_f32_e32 v37, v37, v33
	v_mul_f32_e32 v33, 0xbfb8aa3b, v46
	v_exp_f32_e32 v33, v33
	v_add_f32_e32 v41, 1.0, v41
	v_rcp_f32_e32 v41, v41
	v_add_f32_e32 v33, 1.0, v33
	v_rcp_f32_e32 v33, v33
	v_mul_f32_e32 v38, v38, v41
	v_mul_f32_e32 v38, v38, v34
	v_mul_f32_e32 v34, 0xbfb8aa3b, v47
	v_exp_f32_e32 v34, v34
	v_mul_f32_e32 v41, 0xbfb8aa3b, v39
	v_exp_f32_e32 v41, v41
	v_mul_f32_e32 v33, v46, v33
	v_add_f32_e32 v34, 1.0, v34
	v_rcp_f32_e32 v34, v34
	v_add_f32_e32 v41, 1.0, v41
	v_rcp_f32_e32 v41, v41
	v_mul_f32_e32 v33, v33, v42
	v_mul_f32_e32 v34, v47, v34
	v_mul_f32_e32 v34, v34, v43
	v_cvt_pk_bf16_f32 v33, v33, v34
	v_cvt_pk_bf16_f32 v34, v36, v37
	v_add_u32_e32 v36, 0x90, v140
	v_mul_f32_e32 v39, v39, v41
	v_mad_i64_i32 v[36:37], s[18:19], v36, s85, v[112:113]
	v_mul_f32_e32 v35, v39, v35
	v_lshl_add_u64 v[36:37], v[36:37], 0, v[114:115]
	v_cvt_pk_bf16_f32 v35, v38, v35
	global_store_dwordx4 v[36:37], v[32:35], off sc0 sc1
	s_nop 1
	v_mul_f32_e32 v32, 0xbfb8aa3b, v28
	v_exp_f32_e32 v32, v32
	s_nop 0
	v_add_f32_e32 v32, 1.0, v32
	v_rcp_f32_e32 v32, v32
	s_nop 0
	v_mul_f32_e32 v28, v28, v32
	v_mul_f32_e32 v24, v28, v24
	v_mul_f32_e32 v28, 0xbfb8aa3b, v20
	v_exp_f32_e32 v28, v28
	s_nop 0
	v_add_f32_e32 v28, 1.0, v28
	v_rcp_f32_e32 v28, v28
	s_nop 0
	v_mul_f32_e32 v20, v20, v28
	v_mul_f32_e32 v20, v20, v16
	v_mul_f32_e32 v16, 0xbfb8aa3b, v29
	v_exp_f32_e32 v16, v16
	s_nop 0
	v_add_f32_e32 v16, 1.0, v16
	v_rcp_f32_e32 v16, v16
	s_nop 0
	v_mul_f32_e32 v16, v29, v16
	v_mul_f32_e32 v16, v16, v25
	v_mul_f32_e32 v25, 0xbfb8aa3b, v21
	v_exp_f32_e32 v25, v25
	v_cvt_pk_bf16_f32 v16, v24, v16
	s_nop 0
	v_add_f32_e32 v25, 1.0, v25
	v_rcp_f32_e32 v25, v25
	s_nop 0
	v_mul_f32_e32 v21, v21, v25
	v_mul_f32_e32 v25, 0xbfb8aa3b, v22
	v_exp_f32_e32 v25, v25
	v_mul_f32_e32 v21, v21, v17
	v_mul_f32_e32 v17, 0xbfb8aa3b, v30
	v_exp_f32_e32 v17, v17
	v_add_f32_e32 v25, 1.0, v25
	v_rcp_f32_e32 v25, v25
	v_add_f32_e32 v17, 1.0, v17
	v_rcp_f32_e32 v17, v17
	v_mul_f32_e32 v22, v22, v25
	v_mul_f32_e32 v22, v22, v18
	v_mul_f32_e32 v18, 0xbfb8aa3b, v31
	v_exp_f32_e32 v18, v18
	v_mul_f32_e32 v25, 0xbfb8aa3b, v23
	v_exp_f32_e32 v25, v25
	v_mul_f32_e32 v17, v30, v17
	v_add_f32_e32 v18, 1.0, v18
	v_rcp_f32_e32 v18, v18
	v_add_f32_e32 v25, 1.0, v25
	v_rcp_f32_e32 v25, v25
	v_mul_f32_e32 v17, v17, v26
	v_mul_f32_e32 v18, v31, v18
	v_mul_f32_e32 v18, v18, v27
	v_cvt_pk_bf16_f32 v17, v17, v18
	v_cvt_pk_bf16_f32 v18, v20, v21
	v_add_u32_e32 v20, 0xa0, v140
	v_mul_f32_e32 v23, v23, v25
	v_mad_i64_i32 v[20:21], s[18:19], v20, s85, v[112:113]
	v_mul_f32_e32 v19, v23, v19
	v_lshl_add_u64 v[20:21], v[20:21], 0, v[114:115]
	v_cvt_pk_bf16_f32 v19, v22, v19
	global_store_dwordx4 v[20:21], v[16:19], off sc0 sc1
	s_nop 1
	v_mul_f32_e32 v16, 0xbfb8aa3b, v12
	v_exp_f32_e32 v16, v16
	s_nop 0
	v_add_f32_e32 v16, 1.0, v16
	v_rcp_f32_e32 v16, v16
	s_nop 0
	v_mul_f32_e32 v12, v12, v16
	v_mul_f32_e32 v8, v12, v8
	v_mul_f32_e32 v12, 0xbfb8aa3b, v4
	v_exp_f32_e32 v12, v12
	s_nop 0
	v_add_f32_e32 v12, 1.0, v12
	v_rcp_f32_e32 v12, v12
	s_nop 0
	v_mul_f32_e32 v4, v4, v12
	v_mul_f32_e32 v4, v4, v0
	v_mul_f32_e32 v0, 0xbfb8aa3b, v13
	v_exp_f32_e32 v0, v0
	s_nop 0
	v_add_f32_e32 v0, 1.0, v0
	v_rcp_f32_e32 v0, v0
	s_nop 0
	v_mul_f32_e32 v0, v13, v0
	v_mul_f32_e32 v0, v0, v9
	v_mul_f32_e32 v9, 0xbfb8aa3b, v5
	v_exp_f32_e32 v9, v9
	v_cvt_pk_bf16_f32 v0, v8, v0
	s_nop 0
	v_add_f32_e32 v9, 1.0, v9
	v_rcp_f32_e32 v9, v9
	s_nop 0
	v_mul_f32_e32 v5, v5, v9
	v_mul_f32_e32 v9, 0xbfb8aa3b, v6
	v_exp_f32_e32 v9, v9
	v_mul_f32_e32 v5, v5, v1
	v_mul_f32_e32 v1, 0xbfb8aa3b, v14
	v_exp_f32_e32 v1, v1
	v_add_f32_e32 v9, 1.0, v9
	v_rcp_f32_e32 v9, v9
	v_add_f32_e32 v1, 1.0, v1
	v_rcp_f32_e32 v1, v1
	v_mul_f32_e32 v6, v6, v9
	v_mul_f32_e32 v6, v6, v2
	v_mul_f32_e32 v2, 0xbfb8aa3b, v15
	v_exp_f32_e32 v2, v2
	v_mul_f32_e32 v9, 0xbfb8aa3b, v7
	v_exp_f32_e32 v9, v9
	v_mul_f32_e32 v1, v14, v1
	v_add_f32_e32 v2, 1.0, v2
	v_rcp_f32_e32 v2, v2
	v_add_f32_e32 v9, 1.0, v9
	v_rcp_f32_e32 v9, v9
	v_mul_f32_e32 v1, v1, v10
	v_mul_f32_e32 v2, v15, v2
	v_mul_f32_e32 v2, v2, v11
	v_cvt_pk_bf16_f32 v1, v1, v2
	v_cvt_pk_bf16_f32 v2, v4, v5
	v_add_u32_e32 v4, 0xb0, v140
	v_mul_f32_e32 v7, v7, v9
	v_mad_i64_i32 v[4:5], s[18:19], v4, s85, v[112:113]
	v_mul_f32_e32 v3, v7, v3
	v_lshl_add_u64 v[4:5], v[4:5], 0, v[114:115]
	s_mov_b64 s[18:19], -1
	v_cvt_pk_bf16_f32 v3, v6, v3
	global_store_dwordx4 v[4:5], v[0:3], off sc0 sc1
	s_cbranch_vccnz .LBB0_1808
	s_andn2_b64 vcc, exec, s[8:9]
	s_cbranch_vccnz .LBB0_1807
	s_barrier
	s_branch .LBB0_1807

;     __device__ __forceinline__ void operator()(const f32x4 (&acc)[2][2][4][2], const Unit& u, int wr, int wc, int fr, int fq) const {
;     ...
;         const int slice = u.pm >> 12, row0 = (u.pm & 4095) * BM + wr * 64 + fr, col0 = u.pn * BM + wc * 32 + 4 * fq;
;         const float* mods = (const float*)(ws + WS_MODS) + (size_t)(goff_l >> 16) * NSEQ * NMOD; const int goff = goff_l & 0xffff; float* PART = (float*)(ws + WS_PART);
; #pragma unroll
;         for (int ai = 0; ai < 2; ++ai)
; #pragma unroll
;             for (int mp = 0; mp < 4; mp += 2) {
;                 f32x4 gv[2][4], xv[2][4];
; #pragma unroll
;                 for (int mm = 0; mm < 2; ++mm) {
;                     const int row = row0 + ai * HALF + (mp + mm) * 16; const float* gp = mods + (size_t)cidx_of(row) * NMOD + goff + col0;
;                     const float* xs = ((Xin && row < NPROMPT) ? Xin + (size_t)row * DM : X + (size_t)row * DM) + col0;
; #pragma unroll
;                     for (int q4 = 0; q4 < 4; ++q4) { const int co = (q4 >> 1) * HALF + (q4 & 1) * 16; gv[mm][q4] = *(const f32x4*)(gp + co); if (!slice) xv[mm][q4] = *(const f32x4*)(xs + co); }
;                 }
; #pragma unroll
;                 for (int mm = 0; mm < 2; ++mm) {
;                     const int row = row0 + ai * HALF + (mp + mm) * 16;
; #pragma unroll
;                     for (int q4 = 0; q4 < 4; ++q4) { const int co = (q4 >> 1) * HALF + (q4 & 1) * 16; const f32x4 d = (gv[mm][q4] * fac) * acc[ai][q4 >> 1][mp + mm][q4 & 1];
;                         if (slice) *(f32x4*)(PART + ((size_t)(slice - 1) * NSAMP + (row - NPROMPT)) * DM + col0 + co) = d;
;                         else *(f32x4*)(X + (size_t)row * DM + col0 + co) = xv[mm][q4] + d; }
;                 }
;                 asm volatile("" ::: "memory");
;             }
.LBB0_1921:
	s_ashr_i32 s8, s51, 12
	s_ashr_i32 s9, s8, 31
	s_lshl_b64 s[8:9], s[8:9], 21
	s_add_u32 s8, s46, s8
	s_addc_u32 s9, s47, s9
	v_lshl_add_u64 v[198:199], v[212:213], 2, s[8:9]
	s_mov_b32 s8, 0xffe00000
	s_waitcnt vmcnt(0)
	v_pk_mul_f32 v[188:189], v[188:189], 0.5 op_sel_hi:[1,0]
	s_mov_b32 s9, -1
	v_pk_mul_f32 v[190:191], v[190:191], 0.5 op_sel_hi:[1,0]
	v_pk_mul_f32 v[156:157], v[156:157], v[188:189]
	v_cndmask_b32_e64 v188, 0, 1, s[24:25]
	v_lshl_add_u64 v[208:209], v[198:199], 0, s[8:9]
	v_pk_mul_f32 v[158:159], v[158:159], v[190:191]
	v_cmp_ne_u32_e64 s[8:9], 1, v188
	s_andn2_b64 vcc, exec, s[24:25]
	s_mov_b64 s[24:25], -1
	s_cbranch_vccnz .LBB0_1923
	v_ashrrev_i32_e32 v223, 31, v222
	v_lshlrev_b64 v[188:189], 12, v[222:223]
	v_lshl_add_u64 v[188:189], v[208:209], 0, v[188:189]
	s_mov_b64 s[24:25], 0
	global_store_dwordx4 v[188:189], v[156:159], off sc0 sc1
.LBB0_1923:
	s_andn2_b64 vcc, exec, s[24:25]
	s_cbranch_vccnz .LBB0_1925
	v_pk_add_f32 v[158:159], v[158:159], v[122:123]
	v_pk_add_f32 v[156:157], v[156:157], v[120:121]
	v_mov_b64_e32 v[188:189], v[220:221]
	global_store_dwordx4 v[220:221], v[156:159], off sc0 sc1
.LBB0_1925:
	s_nop 1
	v_pk_mul_f32 v[156:157], v[186:187], 0.5 op_sel_hi:[1,0]
	v_pk_mul_f32 v[158:159], v[184:185], 0.5 op_sel_hi:[1,0]
	v_pk_mul_f32 v[184:185], v[154:155], v[156:157]
	v_pk_mul_f32 v[186:187], v[152:153], v[158:159]
	v_pk_fma_f32 v[154:155], v[154:155], v[156:157], v[114:115]
	v_pk_fma_f32 v[152:153], v[152:153], v[158:159], v[112:113]
	v_cndmask_b32_e64 v155, v185, v155, s[6:7]
	v_cndmask_b32_e64 v154, v184, v154, s[6:7]
	v_cndmask_b32_e64 v153, v187, v153, s[6:7]
	v_cndmask_b32_e64 v152, v186, v152, s[6:7]
	global_store_dwordx4 v[188:189], v[152:155], off offset:64 sc0 sc1
	s_and_b64 vcc, exec, s[8:9]
	s_mov_b64 s[24:25], -1
	v_pk_mul_f32 v[152:153], v[182:183], 0.5 op_sel_hi:[1,0]
	v_pk_mul_f32 v[154:155], v[180:181], 0.5 op_sel_hi:[1,0]
	v_pk_mul_f32 v[156:157], v[150:151], v[152:153]
	v_pk_mul_f32 v[158:159], v[148:149], v[154:155]
	v_pk_fma_f32 v[150:151], v[150:151], v[152:153], v[110:111]
	v_pk_fma_f32 v[148:149], v[148:149], v[154:155], v[108:109]
	v_cndmask_b32_e64 v151, v157, v151, s[6:7]
	v_cndmask_b32_e64 v150, v156, v150, s[6:7]
	v_cndmask_b32_e64 v149, v159, v149, s[6:7]
	v_cndmask_b32_e64 v148, v158, v148, s[6:7]
	global_store_dwordx4 v[188:189], v[148:151], off offset:512 sc0 sc1
	s_nop 1
	v_pk_mul_f32 v[148:149], v[174:175], 0.5 op_sel_hi:[1,0]
	v_pk_mul_f32 v[150:151], v[172:173], 0.5 op_sel_hi:[1,0]
	v_pk_mul_f32 v[152:153], v[142:143], v[148:149]
	v_pk_mul_f32 v[154:155], v[140:141], v[150:151]
	v_pk_fma_f32 v[142:143], v[142:143], v[148:149], v[106:107]
	v_pk_fma_f32 v[140:141], v[140:141], v[150:151], v[104:105]
	v_cndmask_b32_e64 v143, v153, v143, s[6:7]
	v_cndmask_b32_e64 v142, v152, v142, s[6:7]
	v_cndmask_b32_e64 v141, v155, v141, s[6:7]
	v_cndmask_b32_e64 v140, v154, v140, s[6:7]
	global_store_dwordx4 v[188:189], v[140:143], off offset:576 sc0 sc1
	v_pk_mul_f32 v[148:149], v[176:177], 0.5 op_sel_hi:[1,0]
	s_nop 0
	v_pk_mul_f32 v[140:141], v[178:179], 0.5 op_sel_hi:[1,0]
	s_nop 0
	v_pk_mul_f32 v[142:143], v[146:147], v[140:141]
	v_pk_mul_f32 v[140:141], v[144:145], v[148:149]
	s_cbranch_vccnz .LBB0_1927
	v_ashrrev_i32_e32 v219, 31, v218
	v_lshlrev_b64 v[144:145], 12, v[218:219]
	v_lshl_add_u64 v[144:145], v[208:209], 0, v[144:145]
	s_mov_b64 s[24:25], 0
	global_store_dwordx4 v[144:145], v[140:143], off sc0 sc1
.LBB0_1927:
	s_andn2_b64 vcc, exec, s[24:25]
	s_cbranch_vccnz .LBB0_1929
	v_pk_add_f32 v[142:143], v[142:143], v[102:103]
	v_pk_add_f32 v[140:141], v[140:141], v[100:101]
	v_mov_b64_e32 v[144:145], v[216:217]
	global_store_dwordx4 v[216:217], v[140:143], off sc0 sc1
.LBB0_1929:
	s_nop 1
	v_pk_mul_f32 v[140:141], v[170:171], 0.5 op_sel_hi:[1,0]
	v_pk_mul_f32 v[142:143], v[168:169], 0.5 op_sel_hi:[1,0]
	v_pk_mul_f32 v[146:147], v[138:139], v[140:141]
	v_pk_mul_f32 v[148:149], v[136:137], v[142:143]
	v_pk_fma_f32 v[138:139], v[138:139], v[140:141], v[94:95]
	v_pk_fma_f32 v[136:137], v[136:137], v[142:143], v[92:93]
	v_cndmask_b32_e64 v139, v147, v139, s[6:7]
	v_cndmask_b32_e64 v138, v146, v138, s[6:7]
	v_cndmask_b32_e64 v137, v149, v137, s[6:7]
	v_cndmask_b32_e64 v136, v148, v136, s[6:7]
	global_store_dwordx4 v[144:145], v[136:139], off offset:64 sc0 sc1
	s_nop 1
	v_pk_mul_f32 v[136:137], v[166:167], 0.5 op_sel_hi:[1,0]
	v_pk_mul_f32 v[138:139], v[164:165], 0.5 op_sel_hi:[1,0]
	v_pk_mul_f32 v[140:141], v[134:135], v[136:137]
	v_pk_mul_f32 v[142:143], v[132:133], v[138:139]
	v_pk_fma_f32 v[134:135], v[134:135], v[136:137], v[86:87]
	v_pk_fma_f32 v[132:133], v[132:133], v[138:139], v[84:85]
	v_cndmask_b32_e64 v135, v141, v135, s[6:7]
	v_cndmask_b32_e64 v134, v140, v134, s[6:7]
	v_cndmask_b32_e64 v133, v143, v133, s[6:7]
	v_cndmask_b32_e64 v132, v142, v132, s[6:7]
	global_store_dwordx4 v[144:145], v[132:135], off offset:512 sc0 sc1
	v_add_u32_e32 v166, 0xffff8020, v210
	s_nop 0
	v_pk_mul_f32 v[132:133], v[162:163], 0.5 op_sel_hi:[1,0]
	v_pk_mul_f32 v[134:135], v[160:161], 0.5 op_sel_hi:[1,0]
	v_pk_mul_f32 v[136:137], v[130:131], v[132:133]
	v_pk_mul_f32 v[138:139], v[128:129], v[134:135]
	v_pk_fma_f32 v[130:131], v[130:131], v[132:133], v[78:79]
	v_pk_fma_f32 v[128:129], v[128:129], v[134:135], v[76:77]
	v_cndmask_b32_e64 v131, v137, v131, s[6:7]
	v_cndmask_b32_e64 v130, v136, v130, s[6:7]
	v_cndmask_b32_e64 v129, v139, v129, s[6:7]
	v_cndmask_b32_e64 v128, v138, v128, s[6:7]
	global_store_dwordx4 v[144:145], v[128:131], off offset:576 sc0 sc1
	s_nop 1
	v_or_b32_e32 v130, 32, v210
	v_lshrrev_b32_e32 v128, 5, v166
	v_add_u32_e32 v128, 2, v128
	v_mov_b32_e32 v129, s26
	v_cmp_gt_i32_e32 vcc, s0, v130
	v_ashrrev_i32_e32 v131, 31, v130
	v_lshlrev_b64 v[130:131], 12, v[130:131]
	v_cndmask_b32_e32 v128, v128, v129, vcc
	v_mad_i64_i32 v[128:129], s[24:25], v128, s80, v[214:215]
	global_load_dwordx4 v[156:159], v[128:129], off
	v_lshl_add_u64 v[130:131], s[12:13], 0, v[130:131]
	s_and_b64 vcc, exec, s[10:11]
	v_lshl_add_u64 v[164:165], v[212:213], 2, v[130:131]
	s_cbranch_vccz .LBB0_1992
	global_load_dwordx4 v[152:155], v[128:129], off offset:64
	s_and_b64 vcc, exec, s[10:11]
	s_cbranch_vccz .LBB0_1993

;     __device__ __forceinline__ void operator()(const f32x4 (&acc)[2][2][4][2], const Unit& u, int wr, int wc, int fr, int fq) const {
;     ...
;         const int slice = u.pm >> 12, row0 = (u.pm & 4095) * BM + wr * 64 + fr, col0 = u.pn * BM + wc * 32 + 4 * fq;
;         const float* mods = (const float*)(ws + WS_MODS) + (size_t)(goff_l >> 16) * NSEQ * NMOD; const int goff = goff_l & 0xffff; float* PART = (float*)(ws + WS_PART);
; #pragma unroll
;         for (int ai = 0; ai < 2; ++ai)
; #pragma unroll
;             for (int mp = 0; mp < 4; mp += 2) {
;                 f32x4 gv[2][4], xv[2][4];
; #pragma unroll
;                 for (int mm = 0; mm < 2; ++mm) {
;                     const int row = row0 + ai * HALF + (mp + mm) * 16; const float* gp = mods + (size_t)cidx_of(row) * NMOD + goff + col0;
;                     const float* xs = ((Xin && row < NPROMPT) ? Xin + (size_t)row * DM : X + (size_t)row * DM) + col0;
; #pragma unroll
;                     for (int q4 = 0; q4 < 4; ++q4) { const int co = (q4 >> 1) * HALF + (q4 & 1) * 16; gv[mm][q4] = *(const f32x4*)(gp + co); if (!slice) xv[mm][q4] = *(const f32x4*)(xs + co); }
;                 }
; #pragma unroll
;                 for (int mm = 0; mm < 2; ++mm) {
;                     const int row = row0 + ai * HALF + (mp + mm) * 16;
; #pragma unroll
;                     for (int q4 = 0; q4 < 4; ++q4) { const int co = (q4 >> 1) * HALF + (q4 & 1) * 16; const f32x4 d = (gv[mm][q4] * fac) * acc[ai][q4 >> 1][mp + mm][q4 & 1];
;                         if (slice) *(f32x4*)(PART + ((size_t)(slice - 1) * NSAMP + (row - NPROMPT)) * DM + col0 + co) = d;
;                         else *(f32x4*)(X + (size_t)row * DM + col0 + co) = xv[mm][q4] + d; }
;                 }
;                 asm volatile("" ::: "memory");
;             }
.LBB0_1939:
	s_waitcnt vmcnt(7)
	v_pk_mul_f32 v[158:159], v[158:159], 0.5 op_sel_hi:[1,0]
	v_pk_mul_f32 v[156:157], v[156:157], 0.5 op_sel_hi:[1,0]
	v_pk_mul_f32 v[126:127], v[126:127], v[158:159]
	v_pk_mul_f32 v[124:125], v[124:125], v[156:157]
	s_and_b64 vcc, exec, s[8:9]
	s_mov_b64 s[24:25], -1
	s_cbranch_vccnz .LBB0_1941
	v_ashrrev_i32_e32 v167, 31, v166
	v_lshlrev_b64 v[156:157], 12, v[166:167]
	v_lshl_add_u64 v[156:157], v[208:209], 0, v[156:157]
	s_mov_b64 s[24:25], 0
	global_store_dwordx4 v[156:157], v[124:127], off sc0 sc1
.LBB0_1941:
	s_andn2_b64 vcc, exec, s[24:25]
	s_cbranch_vccnz .LBB0_1943
	v_pk_add_f32 v[126:127], v[126:127], v[122:123]
	v_pk_add_f32 v[124:125], v[124:125], v[120:121]
	v_mov_b64_e32 v[156:157], v[164:165]
	global_store_dwordx4 v[164:165], v[124:127], off sc0 sc1
.LBB0_1943:
	s_waitcnt vmcnt(6)
	s_nop 0
	v_pk_mul_f32 v[124:125], v[154:155], 0.5 op_sel_hi:[1,0]
	v_pk_mul_f32 v[126:127], v[152:153], 0.5 op_sel_hi:[1,0]
	v_pk_mul_f32 v[152:153], v[118:119], v[124:125]
	v_pk_mul_f32 v[154:155], v[116:117], v[126:127]
	v_pk_fma_f32 v[118:119], v[118:119], v[124:125], v[114:115]
	v_pk_fma_f32 v[116:117], v[116:117], v[126:127], v[112:113]
	v_cndmask_b32_e64 v119, v153, v119, s[6:7]
	v_cndmask_b32_e64 v118, v152, v118, s[6:7]
	v_cndmask_b32_e64 v117, v155, v117, s[6:7]
	v_cndmask_b32_e64 v116, v154, v116, s[6:7]
	global_store_dwordx4 v[156:157], v[116:119], off offset:64 sc0 sc1
	s_and_b64 vcc, exec, s[8:9]
	s_mov_b64 s[24:25], -1
	s_waitcnt vmcnt(6)
	v_pk_mul_f32 v[116:117], v[150:151], 0.5 op_sel_hi:[1,0]
	v_pk_mul_f32 v[118:119], v[148:149], 0.5 op_sel_hi:[1,0]
	v_pk_mul_f32 v[124:125], v[98:99], v[116:117]
	v_pk_mul_f32 v[126:127], v[96:97], v[118:119]
	v_pk_fma_f32 v[98:99], v[98:99], v[116:117], v[110:111]
	v_pk_fma_f32 v[96:97], v[96:97], v[118:119], v[108:109]
	v_cndmask_b32_e64 v99, v125, v99, s[6:7]
	v_cndmask_b32_e64 v98, v124, v98, s[6:7]
	v_cndmask_b32_e64 v97, v127, v97, s[6:7]
	v_cndmask_b32_e64 v96, v126, v96, s[6:7]
	global_store_dwordx4 v[156:157], v[96:99], off offset:512 sc0 sc1
	s_waitcnt vmcnt(6)
	s_nop 0
	v_pk_mul_f32 v[96:97], v[142:143], 0.5 op_sel_hi:[1,0]
	v_pk_mul_f32 v[98:99], v[140:141], 0.5 op_sel_hi:[1,0]
	v_pk_mul_f32 v[116:117], v[82:83], v[96:97]
	v_pk_mul_f32 v[118:119], v[80:81], v[98:99]
	v_pk_fma_f32 v[82:83], v[82:83], v[96:97], v[106:107]
	v_pk_fma_f32 v[80:81], v[80:81], v[98:99], v[104:105]
	v_cndmask_b32_e64 v83, v117, v83, s[6:7]
	v_cndmask_b32_e64 v82, v116, v82, s[6:7]
	v_cndmask_b32_e64 v81, v119, v81, s[6:7]
	v_cndmask_b32_e64 v80, v118, v80, s[6:7]
	global_store_dwordx4 v[156:157], v[80:83], off offset:576 sc0 sc1
	s_waitcnt vmcnt(6)
	v_pk_mul_f32 v[96:97], v[144:145], 0.5 op_sel_hi:[1,0]
	v_pk_mul_f32 v[80:81], v[146:147], 0.5 op_sel_hi:[1,0]
	s_nop 0
	v_pk_mul_f32 v[82:83], v[90:91], v[80:81]
	v_pk_mul_f32 v[80:81], v[88:89], v[96:97]
	s_cbranch_vccnz .LBB0_1945
	v_ashrrev_i32_e32 v163, 31, v162
	v_lshlrev_b64 v[88:89], 12, v[162:163]
	v_lshl_add_u64 v[88:89], v[208:209], 0, v[88:89]
	s_mov_b64 s[24:25], 0
	global_store_dwordx4 v[88:89], v[80:83], off sc0 sc1
.LBB0_1945:
	s_andn2_b64 vcc, exec, s[24:25]
	s_cbranch_vccnz .LBB0_1947
	v_pk_add_f32 v[82:83], v[82:83], v[102:103]
	v_pk_add_f32 v[80:81], v[80:81], v[100:101]
	v_mov_b64_e32 v[88:89], v[160:161]
	global_store_dwordx4 v[160:161], v[80:83], off sc0 sc1
.LBB0_1947:
	s_waitcnt vmcnt(5)
	s_nop 0
	v_pk_mul_f32 v[80:81], v[138:139], 0.5 op_sel_hi:[1,0]
	v_pk_mul_f32 v[82:83], v[136:137], 0.5 op_sel_hi:[1,0]
	v_pk_mul_f32 v[90:91], v[74:75], v[80:81]
	v_pk_mul_f32 v[96:97], v[72:73], v[82:83]
	v_pk_fma_f32 v[74:75], v[74:75], v[80:81], v[94:95]
	v_pk_fma_f32 v[72:73], v[72:73], v[82:83], v[92:93]
	v_cndmask_b32_e64 v75, v91, v75, s[6:7]
	v_cndmask_b32_e64 v74, v90, v74, s[6:7]
	v_cndmask_b32_e64 v73, v97, v73, s[6:7]
	v_cndmask_b32_e64 v72, v96, v72, s[6:7]
	global_store_dwordx4 v[88:89], v[72:75], off offset:64 sc0 sc1
	s_movk_i32 s24, 0x7f80
	v_cmp_gt_i32_e32 vcc, s24, v210
	s_waitcnt vmcnt(5)
	v_pk_mul_f32 v[72:73], v[134:135], 0.5 op_sel_hi:[1,0]
	v_pk_mul_f32 v[74:75], v[132:133], 0.5 op_sel_hi:[1,0]
	v_pk_mul_f32 v[80:81], v[70:71], v[72:73]
	v_pk_mul_f32 v[82:83], v[68:69], v[74:75]
	v_pk_fma_f32 v[70:71], v[70:71], v[72:73], v[86:87]
	v_pk_fma_f32 v[68:69], v[68:69], v[74:75], v[84:85]
	v_cndmask_b32_e64 v71, v81, v71, s[6:7]
	v_cndmask_b32_e64 v70, v80, v70, s[6:7]
	v_cndmask_b32_e64 v69, v83, v69, s[6:7]
	v_cndmask_b32_e64 v68, v82, v68, s[6:7]
	global_store_dwordx4 v[88:89], v[68:71], off offset:512 sc0 sc1
	v_add_u32_e32 v134, 0xffff8080, v210
	s_waitcnt vmcnt(5)
	v_pk_mul_f32 v[68:69], v[130:131], 0.5 op_sel_hi:[1,0]
	v_pk_mul_f32 v[70:71], v[128:129], 0.5 op_sel_hi:[1,0]
	v_pk_mul_f32 v[72:73], v[66:67], v[68:69]
	v_pk_mul_f32 v[74:75], v[64:65], v[70:71]
	v_pk_fma_f32 v[66:67], v[66:67], v[68:69], v[78:79]
	v_pk_fma_f32 v[64:65], v[64:65], v[70:71], v[76:77]
	v_cndmask_b32_e64 v67, v73, v67, s[6:7]
	v_cndmask_b32_e64 v66, v72, v66, s[6:7]
	v_cndmask_b32_e64 v65, v75, v65, s[6:7]
	v_cndmask_b32_e64 v64, v74, v64, s[6:7]
	global_store_dwordx4 v[88:89], v[64:67], off offset:576 sc0 sc1
	s_nop 1
	v_add_u32_e32 v66, 0x80, v210
	v_lshrrev_b32_e32 v64, 5, v134
	v_ashrrev_i32_e32 v136, 14, v66
	v_add_u32_e32 v64, 2, v64
	v_cndmask_b32_e32 v64, v64, v136, vcc
	v_mad_i64_i32 v[64:65], s[24:25], v64, s80, v[214:215]
	global_load_dwordx4 v[124:127], v[64:65], off
	v_ashrrev_i32_e32 v67, 31, v66
	v_lshlrev_b64 v[66:67], 12, v[66:67]
	v_lshl_add_u64 v[66:67], s[12:13], 0, v[66:67]
	s_and_b64 vcc, exec, s[10:11]
	v_lshl_add_u64 v[132:133], v[212:213], 2, v[66:67]
	s_cbranch_vccz .LBB0_1998
	global_load_dwordx4 v[96:99], v[64:65], off offset:64
	s_and_b64 vcc, exec, s[10:11]
	s_cbranch_vccz .LBB0_1999

;     __device__ __forceinline__ void operator()(const f32x4 (&acc)[2][2][4][2], const Unit& u, int wr, int wc, int fr, int fq) const {
;     ...
;         const int slice = u.pm >> 12, row0 = (u.pm & 4095) * BM + wr * 64 + fr, col0 = u.pn * BM + wc * 32 + 4 * fq;
;         const float* mods = (const float*)(ws + WS_MODS) + (size_t)(goff_l >> 16) * NSEQ * NMOD; const int goff = goff_l & 0xffff; float* PART = (float*)(ws + WS_PART);
; #pragma unroll
;         for (int ai = 0; ai < 2; ++ai)
; #pragma unroll
;             for (int mp = 0; mp < 4; mp += 2) {
;                 f32x4 gv[2][4], xv[2][4];
; #pragma unroll
;                 for (int mm = 0; mm < 2; ++mm) {
;                     const int row = row0 + ai * HALF + (mp + mm) * 16; const float* gp = mods + (size_t)cidx_of(row) * NMOD + goff + col0;
;                     const float* xs = ((Xin && row < NPROMPT) ? Xin + (size_t)row * DM : X + (size_t)row * DM) + col0;
; #pragma unroll
;                     for (int q4 = 0; q4 < 4; ++q4) { const int co = (q4 >> 1) * HALF + (q4 & 1) * 16; gv[mm][q4] = *(const f32x4*)(gp + co); if (!slice) xv[mm][q4] = *(const f32x4*)(xs + co); }
;                 }
; #pragma unroll
;                 for (int mm = 0; mm < 2; ++mm) {
;                     const int row = row0 + ai * HALF + (mp + mm) * 16;
; #pragma unroll
;                     for (int q4 = 0; q4 < 4; ++q4) { const int co = (q4 >> 1) * HALF + (q4 & 1) * 16; const f32x4 d = (gv[mm][q4] * fac) * acc[ai][q4 >> 1][mp + mm][q4 & 1];
;                         if (slice) *(f32x4*)(PART + ((size_t)(slice - 1) * NSAMP + (row - NPROMPT)) * DM + col0 + co) = d;
;                         else *(f32x4*)(X + (size_t)row * DM + col0 + co) = xv[mm][q4] + d; }
;                 }
;                 asm volatile("" ::: "memory");
;             }
.LBB0_1957:
	s_waitcnt vmcnt(7)
	v_pk_mul_f32 v[126:127], v[126:127], 0.5 op_sel_hi:[1,0]
	v_pk_mul_f32 v[124:125], v[124:125], 0.5 op_sel_hi:[1,0]
	v_pk_mul_f32 v[62:63], v[62:63], v[126:127]
	v_pk_mul_f32 v[60:61], v[60:61], v[124:125]
	s_and_b64 vcc, exec, s[8:9]
	s_mov_b64 s[24:25], -1
	s_cbranch_vccnz .LBB0_1959
	v_ashrrev_i32_e32 v135, 31, v134
	v_lshlrev_b64 v[124:125], 12, v[134:135]
	v_lshl_add_u64 v[124:125], v[208:209], 0, v[124:125]
	s_mov_b64 s[24:25], 0
	global_store_dwordx4 v[124:125], v[60:63], off sc0 sc1
.LBB0_1959:
	s_andn2_b64 vcc, exec, s[24:25]
	s_cbranch_vccnz .LBB0_1961
	v_pk_add_f32 v[62:63], v[62:63], v[122:123]
	v_pk_add_f32 v[60:61], v[60:61], v[120:121]
	v_mov_b64_e32 v[124:125], v[132:133]
	global_store_dwordx4 v[132:133], v[60:63], off sc0 sc1
.LBB0_1961:
	s_waitcnt vmcnt(6)
	s_nop 0
	v_pk_mul_f32 v[60:61], v[98:99], 0.5 op_sel_hi:[1,0]
	v_pk_mul_f32 v[62:63], v[96:97], 0.5 op_sel_hi:[1,0]
	v_pk_mul_f32 v[96:97], v[58:59], v[60:61]
	v_pk_mul_f32 v[98:99], v[56:57], v[62:63]
	v_pk_fma_f32 v[58:59], v[58:59], v[60:61], v[114:115]
	v_pk_fma_f32 v[56:57], v[56:57], v[62:63], v[112:113]
	v_cndmask_b32_e64 v59, v97, v59, s[6:7]
	v_cndmask_b32_e64 v58, v96, v58, s[6:7]
	v_cndmask_b32_e64 v57, v99, v57, s[6:7]
	v_cndmask_b32_e64 v56, v98, v56, s[6:7]
	global_store_dwordx4 v[124:125], v[56:59], off offset:64 sc0 sc1
	s_and_b64 vcc, exec, s[8:9]
	s_mov_b64 s[24:25], -1
	s_waitcnt vmcnt(6)
	v_pk_mul_f32 v[56:57], v[90:91], 0.5 op_sel_hi:[1,0]
	v_pk_mul_f32 v[58:59], v[88:89], 0.5 op_sel_hi:[1,0]
	v_pk_mul_f32 v[60:61], v[54:55], v[56:57]
	v_pk_mul_f32 v[62:63], v[52:53], v[58:59]
	v_pk_fma_f32 v[54:55], v[54:55], v[56:57], v[110:111]
	v_pk_fma_f32 v[52:53], v[52:53], v[58:59], v[108:109]
	v_cndmask_b32_e64 v55, v61, v55, s[6:7]
	v_cndmask_b32_e64 v54, v60, v54, s[6:7]
	v_cndmask_b32_e64 v53, v63, v53, s[6:7]
	v_cndmask_b32_e64 v52, v62, v52, s[6:7]
	global_store_dwordx4 v[124:125], v[52:55], off offset:512 sc0 sc1
	s_waitcnt vmcnt(6)
	s_nop 0
	v_pk_mul_f32 v[52:53], v[82:83], 0.5 op_sel_hi:[1,0]
	v_pk_mul_f32 v[54:55], v[80:81], 0.5 op_sel_hi:[1,0]
	v_pk_mul_f32 v[56:57], v[46:47], v[52:53]
	v_pk_mul_f32 v[58:59], v[44:45], v[54:55]
	v_pk_fma_f32 v[46:47], v[46:47], v[52:53], v[106:107]
	v_pk_fma_f32 v[44:45], v[44:45], v[54:55], v[104:105]
	v_cndmask_b32_e64 v47, v57, v47, s[6:7]
	v_cndmask_b32_e64 v46, v56, v46, s[6:7]
	v_cndmask_b32_e64 v45, v59, v45, s[6:7]
	v_cndmask_b32_e64 v44, v58, v44, s[6:7]
	global_store_dwordx4 v[124:125], v[44:47], off offset:576 sc0 sc1
	s_waitcnt vmcnt(6)
	v_pk_mul_f32 v[52:53], v[116:117], 0.5 op_sel_hi:[1,0]
	v_pk_mul_f32 v[44:45], v[118:119], 0.5 op_sel_hi:[1,0]
	s_nop 0
	v_pk_mul_f32 v[46:47], v[50:51], v[44:45]
	v_pk_mul_f32 v[44:45], v[48:49], v[52:53]
	s_cbranch_vccnz .LBB0_1963
	v_ashrrev_i32_e32 v131, 31, v130
	v_lshlrev_b64 v[48:49], 12, v[130:131]
	v_lshl_add_u64 v[48:49], v[208:209], 0, v[48:49]
	s_mov_b64 s[24:25], 0
	global_store_dwordx4 v[48:49], v[44:47], off sc0 sc1
.LBB0_1963:
	s_andn2_b64 vcc, exec, s[24:25]
	s_cbranch_vccnz .LBB0_1965
	v_pk_add_f32 v[46:47], v[46:47], v[102:103]
	v_pk_add_f32 v[44:45], v[44:45], v[100:101]
	v_mov_b64_e32 v[48:49], v[128:129]
	global_store_dwordx4 v[128:129], v[44:47], off sc0 sc1
.LBB0_1965:
	s_waitcnt vmcnt(5)
	s_nop 0
	v_pk_mul_f32 v[44:45], v[74:75], 0.5 op_sel_hi:[1,0]
	v_pk_mul_f32 v[46:47], v[72:73], 0.5 op_sel_hi:[1,0]
	v_pk_mul_f32 v[50:51], v[42:43], v[44:45]
	v_pk_mul_f32 v[52:53], v[40:41], v[46:47]
	v_pk_fma_f32 v[42:43], v[42:43], v[44:45], v[94:95]
	v_pk_fma_f32 v[40:41], v[40:41], v[46:47], v[92:93]
	v_cndmask_b32_e64 v43, v51, v43, s[6:7]
	v_cndmask_b32_e64 v42, v50, v42, s[6:7]
	v_cndmask_b32_e64 v41, v53, v41, s[6:7]
	v_cndmask_b32_e64 v40, v52, v40, s[6:7]
	global_store_dwordx4 v[48:49], v[40:43], off offset:64 sc0 sc1
	s_movk_i32 s24, 0x7f60
	v_cmp_gt_i32_e32 vcc, s24, v210
	s_waitcnt vmcnt(5)
	v_pk_mul_f32 v[40:41], v[70:71], 0.5 op_sel_hi:[1,0]
	v_pk_mul_f32 v[42:43], v[68:69], 0.5 op_sel_hi:[1,0]
	v_pk_mul_f32 v[44:45], v[38:39], v[40:41]
	v_pk_mul_f32 v[46:47], v[36:37], v[42:43]
	v_pk_fma_f32 v[38:39], v[38:39], v[40:41], v[86:87]
	v_pk_fma_f32 v[36:37], v[36:37], v[42:43], v[84:85]
	v_cndmask_b32_e64 v39, v45, v39, s[6:7]
	v_cndmask_b32_e64 v38, v44, v38, s[6:7]
	v_cndmask_b32_e64 v37, v47, v37, s[6:7]
	v_cndmask_b32_e64 v36, v46, v36, s[6:7]
	global_store_dwordx4 v[48:49], v[36:39], off offset:512 sc0 sc1
	v_add_u32_e32 v70, 0xffff80a0, v210
	s_waitcnt vmcnt(5)
	v_pk_mul_f32 v[36:37], v[66:67], 0.5 op_sel_hi:[1,0]
	v_pk_mul_f32 v[38:39], v[64:65], 0.5 op_sel_hi:[1,0]
	v_pk_mul_f32 v[40:41], v[34:35], v[36:37]
	v_pk_mul_f32 v[42:43], v[32:33], v[38:39]
	v_pk_fma_f32 v[34:35], v[34:35], v[36:37], v[78:79]
	v_pk_fma_f32 v[32:33], v[32:33], v[38:39], v[76:77]
	v_cndmask_b32_e64 v35, v41, v35, s[6:7]
	v_cndmask_b32_e64 v34, v40, v34, s[6:7]
	v_cndmask_b32_e64 v33, v43, v33, s[6:7]
	v_cndmask_b32_e64 v32, v42, v32, s[6:7]
	global_store_dwordx4 v[48:49], v[32:35], off offset:576 sc0 sc1
	s_nop 1
	v_lshrrev_b32_e32 v32, 5, v70
	v_add_u32_e32 v32, 2, v32
	v_cndmask_b32_e32 v32, v32, v136, vcc
	v_mad_i64_i32 v[32:33], s[24:25], v32, s80, v[214:215]
	global_load_dwordx4 v[60:63], v[32:33], off
	v_lshlrev_b64 v[34:35], 12, v[210:211]
	v_lshl_add_u64 v[34:35], s[12:13], 0, v[34:35]
	v_lshl_add_u64 v[34:35], v[212:213], 2, v[34:35]
	s_mov_b64 s[24:25], 0xa0000
	s_and_b64 vcc, exec, s[10:11]
	v_lshl_add_u64 v[68:69], v[34:35], 0, s[24:25]
	s_cbranch_vccz .LBB0_2004
	global_load_dwordx4 v[52:55], v[32:33], off offset:64
	s_and_b64 vcc, exec, s[10:11]
	s_cbranch_vccz .LBB0_2005

;     __device__ __forceinline__ void operator()(const f32x4 (&acc)[2][2][4][2], const Unit& u, int wr, int wc, int fr, int fq) const {
;     ...
;         const int slice = u.pm >> 12, row0 = (u.pm & 4095) * BM + wr * 64 + fr, col0 = u.pn * BM + wc * 32 + 4 * fq;
;         const float* mods = (const float*)(ws + WS_MODS) + (size_t)(goff_l >> 16) * NSEQ * NMOD; const int goff = goff_l & 0xffff; float* PART = (float*)(ws + WS_PART);
; #pragma unroll
;         for (int ai = 0; ai < 2; ++ai)
; #pragma unroll
;             for (int mp = 0; mp < 4; mp += 2) {
;                 f32x4 gv[2][4], xv[2][4];
; #pragma unroll
;                 for (int mm = 0; mm < 2; ++mm) {
;                     const int row = row0 + ai * HALF + (mp + mm) * 16; const float* gp = mods + (size_t)cidx_of(row) * NMOD + goff + col0;
;                     const float* xs = ((Xin && row < NPROMPT) ? Xin + (size_t)row * DM : X + (size_t)row * DM) + col0;
; #pragma unroll
;                     for (int q4 = 0; q4 < 4; ++q4) { const int co = (q4 >> 1) * HALF + (q4 & 1) * 16; gv[mm][q4] = *(const f32x4*)(gp + co); if (!slice) xv[mm][q4] = *(const f32x4*)(xs + co); }
;                 }
; #pragma unroll
;                 for (int mm = 0; mm < 2; ++mm) {
;                     const int row = row0 + ai * HALF + (mp + mm) * 16;
; #pragma unroll
;                     for (int q4 = 0; q4 < 4; ++q4) { const int co = (q4 >> 1) * HALF + (q4 & 1) * 16; const f32x4 d = (gv[mm][q4] * fac) * acc[ai][q4 >> 1][mp + mm][q4 & 1];
;                         if (slice) *(f32x4*)(PART + ((size_t)(slice - 1) * NSAMP + (row - NPROMPT)) * DM + col0 + co) = d;
;                         else *(f32x4*)(X + (size_t)row * DM + col0 + co) = xv[mm][q4] + d; }
;                 }
;                 asm volatile("" ::: "memory");
;             }
.LBB0_1975:
	s_waitcnt vmcnt(7)
	v_pk_mul_f32 v[62:63], v[62:63], 0.5 op_sel_hi:[1,0]
	v_pk_mul_f32 v[60:61], v[60:61], 0.5 op_sel_hi:[1,0]
	v_pk_mul_f32 v[30:31], v[30:31], v[62:63]
	v_pk_mul_f32 v[28:29], v[28:29], v[60:61]
	s_and_b64 vcc, exec, s[8:9]
	s_mov_b64 s[10:11], -1
	s_cbranch_vccnz .LBB0_1977
	v_ashrrev_i32_e32 v71, 31, v70
	v_lshlrev_b64 v[60:61], 12, v[70:71]
	v_lshl_add_u64 v[60:61], v[208:209], 0, v[60:61]
	s_mov_b64 s[10:11], 0
	global_store_dwordx4 v[60:61], v[28:31], off sc0 sc1

;     __device__ __forceinline__ void operator()(const f32x4 (&acc)[2][2][4][2], const Unit& u, int wr, int wc, int fr, int fq) const {
;     ...
;         const int slice = u.pm >> 12, row0 = (u.pm & 4095) * BM + wr * 64 + fr, col0 = u.pn * BM + wc * 32 + 4 * fq;
;         const float* mods = (const float*)(ws + WS_MODS) + (size_t)(goff_l >> 16) * NSEQ * NMOD; const int goff = goff_l & 0xffff; float* PART = (float*)(ws + WS_PART);
; #pragma unroll
;         for (int ai = 0; ai < 2; ++ai)
; #pragma unroll
;             for (int mp = 0; mp < 4; mp += 2) {
;                 f32x4 gv[2][4], xv[2][4];
; #pragma unroll
;                 for (int mm = 0; mm < 2; ++mm) {
;                     const int row = row0 + ai * HALF + (mp + mm) * 16; const float* gp = mods + (size_t)cidx_of(row) * NMOD + goff + col0;
;                     const float* xs = ((Xin && row < NPROMPT) ? Xin + (size_t)row * DM : X + (size_t)row * DM) + col0;
; #pragma unroll
;                     for (int q4 = 0; q4 < 4; ++q4) { const int co = (q4 >> 1) * HALF + (q4 & 1) * 16; gv[mm][q4] = *(const f32x4*)(gp + co); if (!slice) xv[mm][q4] = *(const f32x4*)(xs + co); }
;                 }
; #pragma unroll
;                 for (int mm = 0; mm < 2; ++mm) {
;                     const int row = row0 + ai * HALF + (mp + mm) * 16;
; #pragma unroll
;                     for (int q4 = 0; q4 < 4; ++q4) { const int co = (q4 >> 1) * HALF + (q4 & 1) * 16; const f32x4 d = (gv[mm][q4] * fac) * acc[ai][q4 >> 1][mp + mm][q4 & 1];
;                         if (slice) *(f32x4*)(PART + ((size_t)(slice - 1) * NSAMP + (row - NPROMPT)) * DM + col0 + co) = d;
;                         else *(f32x4*)(X + (size_t)row * DM + col0 + co) = xv[mm][q4] + d; }
;                 }
;                 asm volatile("" ::: "memory");
;             }
.LBB0_1979:
	s_waitcnt vmcnt(6)
	s_nop 0
	v_pk_mul_f32 v[28:29], v[54:55], 0.5 op_sel_hi:[1,0]
	v_pk_mul_f32 v[30:31], v[52:53], 0.5 op_sel_hi:[1,0]
	v_pk_mul_f32 v[52:53], v[26:27], v[28:29]
	v_pk_mul_f32 v[54:55], v[24:25], v[30:31]
	v_pk_fma_f32 v[26:27], v[26:27], v[28:29], v[114:115]
	v_pk_fma_f32 v[24:25], v[24:25], v[30:31], v[112:113]
	v_cndmask_b32_e64 v27, v53, v27, s[6:7]
	v_cndmask_b32_e64 v26, v52, v26, s[6:7]
	v_cndmask_b32_e64 v25, v55, v25, s[6:7]
	v_cndmask_b32_e64 v24, v54, v24, s[6:7]
	global_store_dwordx4 v[60:61], v[24:27], off offset:64 sc0 sc1
	s_and_b64 vcc, exec, s[8:9]
	s_mov_b64 s[8:9], -1
	s_waitcnt vmcnt(6)
	v_pk_mul_f32 v[24:25], v[50:51], 0.5 op_sel_hi:[1,0]
	v_pk_mul_f32 v[26:27], v[48:49], 0.5 op_sel_hi:[1,0]
	v_pk_mul_f32 v[28:29], v[22:23], v[24:25]
	v_pk_mul_f32 v[30:31], v[20:21], v[26:27]
	v_pk_fma_f32 v[22:23], v[22:23], v[24:25], v[110:111]
	v_pk_fma_f32 v[20:21], v[20:21], v[26:27], v[108:109]
	v_cndmask_b32_e64 v23, v29, v23, s[6:7]
	v_cndmask_b32_e64 v22, v28, v22, s[6:7]
	v_cndmask_b32_e64 v21, v31, v21, s[6:7]
	v_cndmask_b32_e64 v20, v30, v20, s[6:7]
	global_store_dwordx4 v[60:61], v[20:23], off offset:512 sc0 sc1
	s_waitcnt vmcnt(6)
	s_nop 0
	v_pk_mul_f32 v[20:21], v[46:47], 0.5 op_sel_hi:[1,0]
	v_pk_mul_f32 v[22:23], v[44:45], 0.5 op_sel_hi:[1,0]
	v_pk_mul_f32 v[24:25], v[14:15], v[20:21]
	v_pk_mul_f32 v[26:27], v[12:13], v[22:23]
	v_pk_fma_f32 v[14:15], v[14:15], v[20:21], v[106:107]
	v_pk_fma_f32 v[12:13], v[12:13], v[22:23], v[104:105]
	v_cndmask_b32_e64 v15, v25, v15, s[6:7]
	v_cndmask_b32_e64 v14, v24, v14, s[6:7]
	v_cndmask_b32_e64 v13, v27, v13, s[6:7]
	v_cndmask_b32_e64 v12, v26, v12, s[6:7]
	global_store_dwordx4 v[60:61], v[12:15], off offset:576 sc0 sc1
	s_waitcnt vmcnt(6)
	v_pk_mul_f32 v[20:21], v[56:57], 0.5 op_sel_hi:[1,0]
	v_pk_mul_f32 v[12:13], v[58:59], 0.5 op_sel_hi:[1,0]
	s_nop 0
	v_pk_mul_f32 v[14:15], v[18:19], v[12:13]
	v_pk_mul_f32 v[12:13], v[16:17], v[20:21]
	s_cbranch_vccnz .LBB0_1981
	v_ashrrev_i32_e32 v67, 31, v66
	v_lshlrev_b64 v[16:17], 12, v[66:67]
	v_lshl_add_u64 v[16:17], v[208:209], 0, v[16:17]
	s_mov_b64 s[8:9], 0
	global_store_dwordx4 v[16:17], v[12:15], off sc0 sc1

;     __device__ __forceinline__ void operator()(const f32x4 (&acc)[2][2][4][2], const Unit& u, int wr, int wc, int fr, int fq) const {
;     ...
;         const int slice = u.pm >> 12, row0 = (u.pm & 4095) * BM + wr * 64 + fr, col0 = u.pn * BM + wc * 32 + 4 * fq;
;         const float* mods = (const float*)(ws + WS_MODS) + (size_t)(goff_l >> 16) * NSEQ * NMOD; const int goff = goff_l & 0xffff; float* PART = (float*)(ws + WS_PART);
; #pragma unroll
;         for (int ai = 0; ai < 2; ++ai)
; #pragma unroll
;             for (int mp = 0; mp < 4; mp += 2) {
;                 f32x4 gv[2][4], xv[2][4];
; #pragma unroll
;                 for (int mm = 0; mm < 2; ++mm) {
;                     const int row = row0 + ai * HALF + (mp + mm) * 16; const float* gp = mods + (size_t)cidx_of(row) * NMOD + goff + col0;
;                     const float* xs = ((Xin && row < NPROMPT) ? Xin + (size_t)row * DM : X + (size_t)row * DM) + col0;
; #pragma unroll
;                     for (int q4 = 0; q4 < 4; ++q4) { const int co = (q4 >> 1) * HALF + (q4 & 1) * 16; gv[mm][q4] = *(const f32x4*)(gp + co); if (!slice) xv[mm][q4] = *(const f32x4*)(xs + co); }
;                 }
; #pragma unroll
;                 for (int mm = 0; mm < 2; ++mm) {
;                     const int row = row0 + ai * HALF + (mp + mm) * 16;
; #pragma unroll
;                     for (int q4 = 0; q4 < 4; ++q4) { const int co = (q4 >> 1) * HALF + (q4 & 1) * 16; const f32x4 d = (gv[mm][q4] * fac) * acc[ai][q4 >> 1][mp + mm][q4 & 1];
;                         if (slice) *(f32x4*)(PART + ((size_t)(slice - 1) * NSAMP + (row - NPROMPT)) * DM + col0 + co) = d;
;                         else *(f32x4*)(X + (size_t)row * DM + col0 + co) = xv[mm][q4] + d; }
;                 }
;                 asm volatile("" ::: "memory");
;             }
.LBB0_1983:
	s_waitcnt vmcnt(5)
	s_nop 0
	v_pk_mul_f32 v[12:13], v[42:43], 0.5 op_sel_hi:[1,0]
	v_pk_mul_f32 v[14:15], v[40:41], 0.5 op_sel_hi:[1,0]
	v_pk_mul_f32 v[18:19], v[10:11], v[12:13]
	v_pk_mul_f32 v[20:21], v[8:9], v[14:15]
	v_pk_fma_f32 v[10:11], v[10:11], v[12:13], v[94:95]
	v_pk_fma_f32 v[8:9], v[8:9], v[14:15], v[92:93]
	v_cndmask_b32_e64 v11, v19, v11, s[6:7]
	v_cndmask_b32_e64 v10, v18, v10, s[6:7]
	v_cndmask_b32_e64 v9, v21, v9, s[6:7]
	v_cndmask_b32_e64 v8, v20, v8, s[6:7]
	global_store_dwordx4 v[16:17], v[8:11], off offset:64 sc0 sc1
	s_and_b64 vcc, exec, s[4:5]
	s_mov_b64 s[4:5], -1
	s_waitcnt vmcnt(5)
	v_pk_mul_f32 v[8:9], v[38:39], 0.5 op_sel_hi:[1,0]
	v_pk_mul_f32 v[10:11], v[36:37], 0.5 op_sel_hi:[1,0]
	v_pk_mul_f32 v[12:13], v[6:7], v[8:9]
	v_pk_mul_f32 v[14:15], v[4:5], v[10:11]
	v_pk_fma_f32 v[6:7], v[6:7], v[8:9], v[86:87]
	v_pk_fma_f32 v[4:5], v[4:5], v[10:11], v[84:85]
	v_cndmask_b32_e64 v7, v13, v7, s[6:7]
	v_cndmask_b32_e64 v6, v12, v6, s[6:7]
	v_cndmask_b32_e64 v5, v15, v5, s[6:7]
	v_cndmask_b32_e64 v4, v14, v4, s[6:7]
	global_store_dwordx4 v[16:17], v[4:7], off offset:512 sc0 sc1
	s_waitcnt vmcnt(5)
	s_nop 0
	v_pk_mul_f32 v[4:5], v[34:35], 0.5 op_sel_hi:[1,0]
	v_pk_mul_f32 v[6:7], v[32:33], 0.5 op_sel_hi:[1,0]
	v_pk_mul_f32 v[8:9], v[2:3], v[4:5]
	v_pk_mul_f32 v[10:11], v[0:1], v[6:7]
	v_pk_fma_f32 v[2:3], v[2:3], v[4:5], v[78:79]
	v_pk_fma_f32 v[0:1], v[0:1], v[6:7], v[76:77]
	v_cndmask_b32_e64 v3, v9, v3, s[6:7]
	v_cndmask_b32_e64 v2, v8, v2, s[6:7]
	v_cndmask_b32_e64 v1, v11, v1, s[6:7]
	v_cndmask_b32_e64 v0, v10, v0, s[6:7]
	global_store_dwordx4 v[16:17], v[0:3], off offset:576 sc0 sc1
	s_cbranch_vccnz .LBB0_1893
	s_andn2_b64 vcc, exec, s[16:17]
	s_cbranch_vccnz .LBB0_1892
	s_barrier
	s_branch .LBB0_1892

; __device__ __forceinline__ void final_norm_phase(ArgsP a, int wave_s_) {
;     ...
;         if (row >= NPROMPT) { int l2 = lane; asm volatile("" : "+v"(l2)); const float* pp = (const float*)(a->ws + WS_PART) + (size_t)(row - NPROMPT) * DM + 4 * l2;
;             for (int s = 0; s < 11; ++s)
; #pragma unroll
;                 for (int j = 0; j < 4; ++j) v[j] = v[j] + *(const f32x4*)(pp + (size_t)s * NSAMP * DM + 256 * j); }
;         float ss = 0.f;
; #pragma unroll
;         for (int j = 0; j < 4; ++j) ss += (v[j][0] * v[j][0] + v[j][1] * v[j][1]) + (v[j][2] * v[j][2] + v[j][3] * v[j][3]);
;         const float rs = 1.0f / sqrtf(wave_sum(ss, lane) * (1.0f / DM) + EPS);
; #pragma unroll
;         for (int j = 0; j < 4; ++j) *(f32x4*)(xr + 4 * lane + 256 * j) = (v[j] * rs) * gv[j];
; #pragma unroll
;         for (int j = 0; j < 4; ++j) v[j] = vn[j];
;     }
.LBB0_2065:
	s_or_b64 exec, exec, s[4:5]
	s_waitcnt vmcnt(3)
	v_mul_f32_e32 v48, v45, v45
	v_mul_f32_e32 v49, v47, v47
	v_fmac_f32_e32 v48, v44, v44
	v_fmac_f32_e32 v49, v46, v46
	v_add_f32_e32 v48, v48, v49
	s_waitcnt vmcnt(2)
	v_mul_f32_e32 v49, v41, v41
	v_mul_f32_e32 v50, v43, v43
	v_fmac_f32_e32 v49, v40, v40
	v_fmac_f32_e32 v50, v42, v42
	v_add_f32_e32 v49, v49, v50
	v_add_f32_e32 v48, v48, v49
	s_waitcnt vmcnt(1)
	v_mul_f32_e32 v49, v33, v33
	v_mul_f32_e32 v50, v35, v35
	v_fmac_f32_e32 v49, v32, v32
	v_fmac_f32_e32 v50, v34, v34
	v_add_f32_e32 v49, v49, v50
	v_add_f32_e32 v48, v49, v48
	s_waitcnt vmcnt(0)
	v_mul_f32_e32 v49, v37, v37
	v_mul_f32_e32 v50, v39, v39
	v_fmac_f32_e32 v49, v36, v36
	v_fmac_f32_e32 v50, v38, v38
	v_add_f32_e32 v49, v49, v50
	v_add_f32_e32 v48, v49, v48
	v_mov_b32_e32 v49, 0
	s_and_b64 s[2:3], exec, s[2:3]
	v_add_f32_dpp v48, v48, v48 quad_perm:[1,0,3,2] row_mask:0xf bank_mask:0xf bound_ctrl:1
	s_or_b64 s[10:11], s[2:3], s[10:11]
	v_mov_b32_e32 v128, v140
	v_add_f32_dpp v48, v48, v48 quad_perm:[2,3,0,1] row_mask:0xf bank_mask:0xf bound_ctrl:1
	s_nop 1
	v_add_f32_dpp v48, v48, v48 row_half_mirror row_mask:0xf bank_mask:0xf bound_ctrl:1
	s_nop 1
	v_add_f32_dpp v48, v48, v48 row_mirror row_mask:0xf bank_mask:0xf bound_ctrl:1
	s_nop 1
	v_mov_b32_dpp v49, v48 row_bcast:15 row_mask:0xa bank_mask:0xf
	v_add_f32_e32 v48, v48, v49
	v_mov_b32_e32 v49, 0
	s_nop 1
	v_mov_b32_dpp v49, v48 row_bcast:31 row_mask:0xc bank_mask:0xf
	v_add_f32_e32 v48, v48, v49
	s_nop 0
	v_readlane_b32 s4, v48, 63
	s_nop 1
	v_fma_f32 v48, s4, v139, v137
	v_mul_f32_e32 v49, 0x4f800000, v48
	v_cmp_gt_f32_e32 vcc, s24, v48
	s_nop 1
	v_cndmask_b32_e32 v48, v48, v49, vcc
	v_sqrt_f32_e32 v49, v48
	s_nop 0
	v_add_u32_e32 v50, -1, v49
	v_fma_f32 v51, -v50, v49, v48
	v_cmp_ge_f32_e64 s[4:5], 0, v51
	v_add_u32_e32 v51, 1, v49
	s_nop 0
	v_cndmask_b32_e64 v50, v49, v50, s[4:5]
	v_fma_f32 v49, -v51, v49, v48
	v_cmp_lt_f32_e64 s[4:5], 0, v49
	s_nop 1
	v_cndmask_b32_e64 v49, v50, v51, s[4:5]
	v_mul_f32_e32 v50, 0x37800000, v49
	v_cndmask_b32_e32 v49, v49, v50, vcc
	v_cmp_class_f32_e32 vcc, v48, v138
	s_nop 1
	v_cndmask_b32_e32 v48, v49, v48, vcc
	v_div_scale_f32 v49, s[4:5], v48, v48, 1.0
	v_rcp_f32_e32 v50, v49
	s_nop 0
	v_fma_f32 v51, -v49, v50, 1.0
	v_fmac_f32_e32 v50, v51, v50
	v_div_scale_f32 v51, vcc, 1.0, v48, 1.0
	v_mul_f32_e32 v52, v51, v50
	v_fma_f32 v53, -v49, v52, v51
	v_fmac_f32_e32 v52, v53, v50
	v_fma_f32 v49, -v49, v52, v51
	v_div_fmas_f32 v49, v49, v50, v52
	v_div_fixup_f32 v48, v49, v48, 1.0
	v_pk_mul_f32 v[32:33], v[32:33], v[48:49] op_sel_hi:[1,0]
	v_pk_mul_f32 v[34:35], v[34:35], v[48:49] op_sel_hi:[1,0]
	v_pk_mul_f32 v[32:33], v[8:9], v[32:33]
	v_pk_mul_f32 v[34:35], v[10:11], v[34:35]
	v_pk_mul_f32 v[44:45], v[44:45], v[48:49] op_sel_hi:[1,0]
	v_pk_mul_f32 v[46:47], v[46:47], v[48:49] op_sel_hi:[1,0]
	v_pk_mul_f32 v[40:41], v[40:41], v[48:49] op_sel_hi:[1,0]
	v_pk_mul_f32 v[42:43], v[42:43], v[48:49] op_sel_hi:[1,0]
	global_store_dwordx4 v[132:133], v[32:35], off sc0 sc1
	v_pk_mul_f32 v[46:47], v[2:3], v[46:47]
	v_pk_mul_f32 v[44:45], v[0:1], v[44:45]
	v_pk_mul_f32 v[32:33], v[36:37], v[48:49] op_sel_hi:[1,0]
	v_pk_mul_f32 v[34:35], v[38:39], v[48:49] op_sel_hi:[1,0]
	v_pk_mul_f32 v[42:43], v[6:7], v[42:43]
	v_pk_mul_f32 v[40:41], v[4:5], v[40:41]
	v_pk_mul_f32 v[34:35], v[14:15], v[34:35]
	v_pk_mul_f32 v[32:33], v[12:13], v[32:33]
	global_store_dwordx4 v[132:133], v[44:47], off offset:-2048 sc0 sc1
	global_store_dwordx4 v[132:133], v[40:43], off offset:-1024 sc0 sc1
	global_store_dwordx4 v[132:133], v[32:35], off offset:1024 sc0 sc1
	v_lshl_add_u64 v[132:133], v[132:133], 0, s[8:9]
	v_mov_b32_e32 v44, v16
	v_mov_b32_e32 v45, v17
	v_mov_b32_e32 v46, v18
	v_mov_b32_e32 v47, v19
	v_mov_b32_e32 v40, v20
	v_mov_b32_e32 v41, v21
	v_mov_b32_e32 v42, v22
	v_mov_b32_e32 v43, v23
	v_mov_b32_e32 v32, v24
	v_mov_b32_e32 v33, v25
	v_mov_b32_e32 v34, v26
	v_mov_b32_e32 v35, v27
	v_mov_b32_e32 v36, v28
	v_mov_b32_e32 v37, v29
	v_mov_b32_e32 v38, v30
	v_mov_b32_e32 v39, v31
	s_andn2_b64 exec, exec, s[10:11]
	s_cbranch_execz .LBB0_2070
